# P15 hand-written: K~^T tile stores as 64 contiguous bytes per channel (four back-to-back 16-byte stores per 32 tokens)
# speedup vs baseline: 1.0272x; 1.0134x over previous
; DEV int tidx() { return tidx_full() & 255; }
; #define VBID ((int)blockIdx.x * 2 + vhalf())
; DEV void phase_p15(const Params& p, int g) {
;     ...
;   for (int it = VBID; it < 1024; it += NVB) {
;     const int tid = tidx();
;     const int cidx = it >> 1, dir = it & 1;
;     u16* Qp = QK + (size_t)(2 * dir) * NTOK * 512;
;     u16* Kp = Qp + (size_t)NTOK * 512;
;     float lb[2], G[2];
; #pragma unroll
;     for (int cc = 0; cc < 2; ++cc) {
;       const int c = tid + 256 * cc;
;       const float a0 = p.in[I_LB][(0 * 2 + dir) * 512 + c];
;       const float a1 = p.in[I_LB][(1 * 2 + dir) * 512 + c];
;       lb[cc] = 1.f / (1.f + __expf(a1 - a0));
;       G[cc] = 0.f;
;     }
;     u16 xr[3][2][8], qr[3][2][8];
;     ...
;     P15_LOAD(0, 0);
;     P15_LOAD(1, 1);
.LBB0_617:
	v_readfirstlane_b32 s16, v202
	v_readlane_b32 s19, v251, 62
	v_readlane_b32 s0, v251, 41
	v_readlane_b32 s1, v251, 42
	v_readlane_b32 s2, v252, 19
	v_readlane_b32 s3, v252, 20
	v_readlane_b32 s4, v251, 54
	v_readlane_b32 s5, v251, 55
	v_readlane_b32 s12, v249, 22
	v_readlane_b32 s13, v249, 23
	s_bfe_u32 s17, s16, 0x10008
	s_bfe_u32 s18, s16, 0x20006
	s_lshr_b32 s19, s19, 1
	s_lshr_b32 s8, s18, 1
	s_and_b32 s18, s18, 1
	s_lshl_b32 s8, s8, 8
	s_add_u32 s20, s19, s8
	s_mov_b32 s30, 0x800000
	s_mov_b32 s31, 0x3f317217
	s_mov_b32 s34, 0x7f800000
	v_and_b32_e32 v112, 63, v202
	v_lshlrev_b32_e32 v112, 2, v112
	s_lshl_b32 s8, s18, 8
	v_add_u32_e32 v112, s8, v112
	v_lshlrev_b32_e32 v115, 7, v112
	v_lshlrev_b32_e32 v92, 2, v112
	v_lshlrev_b32_e32 v112, 1, v112
	s_lshl_b32 s8, s17, 10
	s_add_u32 s8, s8, 0x800
	v_add_u32_e32 v113, s8, v112
	v_add_u32_e32 v114, 0x2000000, v112
	s_lshl_b32 s8, s17, 11
	v_add_u32_e32 v93, s8, v92
	v_add_u32_e32 v94, 0x1000, v93
	global_load_dwordx4 v[96:99], v93, s[12:13]
	global_load_dwordx4 v[100:103], v94, s[12:13]
	v_mov_b32_e32 v104, v92
	s_lshl_b32 s8, s17, 9
	s_add_u32 s8, s8, s20
	s_lshl_b32 s8, s8, 11
	s_add_u32 s6, s4, s8
	s_addc_u32 s7, s5, 0
	s_add_u32 s6, s6, 0x3b4c100
	s_addc_u32 s7, s7, 0
	s_lshl_b32 s8, s20, 1
	s_add_u32 s8, s8, s17
	s_lshl_b32 s8, s8, 16
	s_add_u32 s4, s4, s8
	s_addc_u32 s5, s5, 0
	s_add_u32 s4, s4, 0x3d4c100
	s_addc_u32 s5, s5, 0
	s_mul_i32 s8, s17, 0x40
	s_add_u32 s4, s4, s8
	s_addc_u32 s5, s5, 0
	s_lshl_b32 s8, s20, 6
	s_mul_i32 s9, s17, 63
	s_add_u32 s8, s8, s9
	s_mul_i32 s9, s8, 0x1400
	s_add_u32 s0, s0, s9
	s_addc_u32 s1, s1, 0
	s_lshl_b32 s9, s8, 10
	s_add_u32 s2, s2, s9
	s_addc_u32 s3, s3, 0
	s_lshl_b32 s9, s17, 26
	s_add_u32 s2, s2, s9
	s_addc_u32 s3, s3, 0
	s_waitcnt vmcnt(0)
	v_sub_f32_e32 v92, v100, v96
	v_mul_f32_e32 v92, 0x3fb8aa3b, v92
	v_exp_f32_e32 v92, v92
	s_nop 0
	v_add_f32_e32 v92, 1.0, v92
	v_div_scale_f32 v76, s[8:9], v92, v92, 1.0
	v_rcp_f32_e32 v77, v76
	s_nop 0
	v_fma_f32 v78, -v76, v77, 1.0
	v_fmac_f32_e32 v77, v78, v77
	v_div_scale_f32 v78, vcc, 1.0, v92, 1.0
	v_mul_f32_e32 v79, v78, v77
	v_fma_f32 v80, -v76, v79, v78
	v_fmac_f32_e32 v79, v80, v77
	v_fma_f32 v76, -v76, v79, v78
	v_div_fmas_f32 v76, v76, v77, v79
	v_div_fixup_f32 v68, v76, v92, 1.0
	v_sub_f32_e32 v72, 1.0, v68
	v_mov_b32_e32 v64, 0
	v_sub_f32_e32 v93, v101, v97
	v_mul_f32_e32 v93, 0x3fb8aa3b, v93
	v_exp_f32_e32 v93, v93
	s_nop 0
	v_add_f32_e32 v93, 1.0, v93
	v_div_scale_f32 v76, s[8:9], v93, v93, 1.0
	v_rcp_f32_e32 v77, v76
	s_nop 0
	v_fma_f32 v78, -v76, v77, 1.0
	v_fmac_f32_e32 v77, v78, v77
	v_div_scale_f32 v78, vcc, 1.0, v93, 1.0
	v_mul_f32_e32 v79, v78, v77
	v_fma_f32 v80, -v76, v79, v78
	v_fmac_f32_e32 v79, v80, v77
	v_fma_f32 v76, -v76, v79, v78
	v_div_fmas_f32 v76, v76, v77, v79
	v_div_fixup_f32 v69, v76, v93, 1.0
	v_sub_f32_e32 v73, 1.0, v69
	v_mov_b32_e32 v65, 0
	v_sub_f32_e32 v94, v102, v98
	v_mul_f32_e32 v94, 0x3fb8aa3b, v94
	v_exp_f32_e32 v94, v94
	s_nop 0
	v_add_f32_e32 v94, 1.0, v94
	v_div_scale_f32 v76, s[8:9], v94, v94, 1.0
	v_rcp_f32_e32 v77, v76
	s_nop 0
	v_fma_f32 v78, -v76, v77, 1.0
	v_fmac_f32_e32 v77, v78, v77
	v_div_scale_f32 v78, vcc, 1.0, v94, 1.0
	v_mul_f32_e32 v79, v78, v77
	v_fma_f32 v80, -v76, v79, v78
	v_fmac_f32_e32 v79, v80, v77
	v_fma_f32 v76, -v76, v79, v78
	v_div_fmas_f32 v76, v76, v77, v79
	v_div_fixup_f32 v70, v76, v94, 1.0
	v_sub_f32_e32 v74, 1.0, v70
	v_mov_b32_e32 v66, 0
	v_sub_f32_e32 v95, v103, v99
	v_mul_f32_e32 v95, 0x3fb8aa3b, v95
	v_exp_f32_e32 v95, v95
	s_nop 0
	v_add_f32_e32 v95, 1.0, v95
	v_div_scale_f32 v76, s[8:9], v95, v95, 1.0
	v_rcp_f32_e32 v77, v76
	s_nop 0
	v_fma_f32 v78, -v76, v77, 1.0
	v_fmac_f32_e32 v77, v78, v77
	v_div_scale_f32 v78, vcc, 1.0, v95, 1.0
	v_mul_f32_e32 v79, v78, v77
	v_fma_f32 v80, -v76, v79, v78
	v_fmac_f32_e32 v79, v80, v77
	v_fma_f32 v76, -v76, v79, v78
	v_div_fmas_f32 v76, v76, v77, v79
	v_div_fixup_f32 v71, v76, v95, 1.0
	v_sub_f32_e32 v75, 1.0, v71
	v_mov_b32_e32 v67, 0
	v_mov_b32_e32 v115, v115
	v_mov_b32_e32 v109, v104
	v_mov_b32_e32 v164, v104
	s_cmp_eq_u32 s17, 0
	s_cbranch_scc0 .Lp15_d1
	global_load_dwordx2 v[0:1], v113, s[0:1]
	global_load_dwordx2 v[2:3], v112, s[0:1]
	s_add_u32 s0, s0, 0x1400
	s_addc_u32 s1, s1, 0
	global_load_dwordx2 v[4:5], v113, s[0:1]
	global_load_dwordx2 v[6:7], v112, s[0:1]
	s_add_u32 s0, s0, 0x1400
	s_addc_u32 s1, s1, 0
	global_load_dwordx2 v[8:9], v113, s[0:1]
	global_load_dwordx2 v[10:11], v112, s[0:1]
	s_add_u32 s0, s0, 0x1400
	s_addc_u32 s1, s1, 0
	global_load_dwordx2 v[12:13], v113, s[0:1]
	global_load_dwordx2 v[14:15], v112, s[0:1]
	s_add_u32 s0, s0, 0x1400
	s_addc_u32 s1, s1, 0
	global_load_dwordx2 v[16:17], v113, s[0:1]
	global_load_dwordx2 v[18:19], v112, s[0:1]
	s_add_u32 s0, s0, 0x1400
	s_addc_u32 s1, s1, 0
	global_load_dwordx2 v[20:21], v113, s[0:1]
	global_load_dwordx2 v[22:23], v112, s[0:1]
	s_add_u32 s0, s0, 0x1400
	s_addc_u32 s1, s1, 0
	global_load_dwordx2 v[24:25], v113, s[0:1]
	global_load_dwordx2 v[26:27], v112, s[0:1]
	s_add_u32 s0, s0, 0x1400
	s_addc_u32 s1, s1, 0
	global_load_dwordx2 v[28:29], v113, s[0:1]
	global_load_dwordx2 v[30:31], v112, s[0:1]
	s_add_u32 s0, s0, 0x1400
	s_addc_u32 s1, s1, 0
	global_load_dwordx2 v[32:33], v113, s[0:1]
	global_load_dwordx2 v[34:35], v112, s[0:1]
	s_add_u32 s0, s0, 0x1400
	s_addc_u32 s1, s1, 0
	global_load_dwordx2 v[36:37], v113, s[0:1]
	global_load_dwordx2 v[38:39], v112, s[0:1]
	s_add_u32 s0, s0, 0x1400
	s_addc_u32 s1, s1, 0
	global_load_dwordx2 v[40:41], v113, s[0:1]
	global_load_dwordx2 v[42:43], v112, s[0:1]
	s_add_u32 s0, s0, 0x1400
	s_addc_u32 s1, s1, 0
	global_load_dwordx2 v[44:45], v113, s[0:1]
	global_load_dwordx2 v[46:47], v112, s[0:1]
	s_add_u32 s0, s0, 0x1400
	s_addc_u32 s1, s1, 0
	global_load_dwordx2 v[48:49], v113, s[0:1]
	global_load_dwordx2 v[50:51], v112, s[0:1]
	s_add_u32 s0, s0, 0x1400
	s_addc_u32 s1, s1, 0
	global_load_dwordx2 v[52:53], v113, s[0:1]
	global_load_dwordx2 v[54:55], v112, s[0:1]
	s_add_u32 s0, s0, 0x1400
	s_addc_u32 s1, s1, 0
	global_load_dwordx2 v[56:57], v113, s[0:1]
	global_load_dwordx2 v[58:59], v112, s[0:1]
	s_add_u32 s0, s0, 0x1400
	s_addc_u32 s1, s1, 0
	global_load_dwordx2 v[60:61], v113, s[0:1]
	global_load_dwordx2 v[62:63], v112, s[0:1]
	s_add_u32 s0, s0, 0x1400
	s_addc_u32 s1, s1, 0
	s_mov_b32 s35, 0
	s_waitcnt vmcnt(16)
; DEV u16 f2bf(float f) { return (u16)(pack2(f, f) & 0xffffu); }
; DEV float bf2f(u16 h) { return __uint_as_float(((unsigned)h) << 16); }
; DEV float sigmoid_f(float x) { return __builtin_amdgcn_rcpf(1.f + __expf(-x)); }
; DEV void phase_p15(const Params& p, int g) {
;     ...
;         for (int e = 0; e < 8; ++e) {
;           const int jj = j8 * 8 + e;
;           const int j = dir ? 63 - jj : jj;
;           const size_t tok = (size_t)cidx * 64 + j;
;           const float f = lb[cc] + (1.f - lb[cc]) * sigmoid_f(bf2f(xr[st][cc][e]));
;           G[cc] += __logf(f);
;           const float eg = __expf(G[cc]), ig = __expf(-G[cc]);
;           Qp[tok * 512 + c] = f2bf(bf2f(qr[st][cc][e]) * eg);
;           const u16 kk = f2bf((1.f - f) * ig);
;           Kp[tok * 512 + c] = kk;
;           kb[e] = kk;
;         }
.Lp15_d0_loop:
	s_waitcnt vmcnt(48)
	v_lshlrev_b32_e32 v92, 16, v0
	v_and_b32_e32 v93, 0xffff0000, v0
	v_lshlrev_b32_e32 v94, 16, v1
	v_and_b32_e32 v95, 0xffff0000, v1
	v_mul_f32_e32 v92, 0xbfb8aa3b, v92
	v_mul_f32_e32 v93, 0xbfb8aa3b, v93
	v_mul_f32_e32 v94, 0xbfb8aa3b, v94
	v_mul_f32_e32 v95, 0xbfb8aa3b, v95
	v_exp_f32_e32 v92, v92
	v_exp_f32_e32 v93, v93
	v_exp_f32_e32 v94, v94
	v_exp_f32_e32 v95, v95
	v_add_f32_e32 v92, 1.0, v92
	v_add_f32_e32 v93, 1.0, v93
	v_add_f32_e32 v94, 1.0, v94
	v_add_f32_e32 v95, 1.0, v95
	v_rcp_f32_e32 v92, v92
	v_rcp_f32_e32 v93, v93
	v_rcp_f32_e32 v94, v94
	v_rcp_f32_e32 v95, v95
	v_fma_f32 v96, v72, v92, v68
	v_fma_f32 v97, v73, v93, v69
	v_fma_f32 v98, v74, v94, v70
	v_fma_f32 v99, v75, v95, v71
	v_cmp_gt_f32_e64 s[22:23], s30, v96
	v_cmp_gt_f32_e64 s[24:25], s30, v97
	v_cmp_gt_f32_e64 s[26:27], s30, v98
	v_cmp_gt_f32_e64 s[28:29], s30, v99
	v_cndmask_b32_e64 v92, 0, 32, s[22:23]
	v_cndmask_b32_e64 v93, 0, 32, s[24:25]
	v_cndmask_b32_e64 v94, 0, 32, s[26:27]
	v_cndmask_b32_e64 v95, 0, 32, s[28:29]
	v_ldexp_f32 v92, v96, v92
	v_ldexp_f32 v93, v97, v93
	v_ldexp_f32 v94, v98, v94
	v_ldexp_f32 v95, v99, v95
	v_log_f32_e32 v92, v92
	v_log_f32_e32 v93, v93
	v_log_f32_e32 v94, v94
	v_log_f32_e32 v95, v95
	v_mul_f32_e32 v100, 0x3f317217, v92
	v_mul_f32_e32 v101, 0x3f317217, v93
	v_mul_f32_e32 v102, 0x3f317217, v94
	v_mul_f32_e32 v103, 0x3f317217, v95
	v_fma_f32 v100, v92, s31, -v100
	v_fma_f32 v101, v93, s31, -v101
	v_fma_f32 v102, v94, s31, -v102
	v_fma_f32 v103, v95, s31, -v103
	v_fmac_f32_e32 v100, 0x3377d1cf, v92
	v_fmac_f32_e32 v101, 0x3377d1cf, v93
	v_fmac_f32_e32 v102, 0x3377d1cf, v94
	v_fmac_f32_e32 v103, 0x3377d1cf, v95
	v_fmac_f32_e32 v100, 0x3f317217, v92
	v_fmac_f32_e32 v101, 0x3f317217, v93
	v_fmac_f32_e32 v102, 0x3f317217, v94
	v_fmac_f32_e32 v103, 0x3f317217, v95
	v_cmp_lt_f32_e64 vcc, |v92|, s34
	v_cndmask_b32_e32 v92, v92, v100, vcc
	v_cmp_lt_f32_e64 vcc, |v93|, s34
	v_cndmask_b32_e32 v93, v93, v101, vcc
	v_cmp_lt_f32_e64 vcc, |v94|, s34
	v_cndmask_b32_e32 v94, v94, v102, vcc
	v_cmp_lt_f32_e64 vcc, |v95|, s34
	v_cndmask_b32_e32 v95, v95, v103, vcc
	v_cndmask_b32_e64 v100, 0, v213, s[22:23]
	v_cndmask_b32_e64 v101, 0, v213, s[24:25]
	v_cndmask_b32_e64 v102, 0, v213, s[26:27]
	v_cndmask_b32_e64 v103, 0, v213, s[28:29]
	v_sub_f32_e32 v92, v92, v100
	v_sub_f32_e32 v93, v93, v101
	v_sub_f32_e32 v94, v94, v102
	v_sub_f32_e32 v95, v95, v103
	v_add_f32_e32 v64, v64, v92
	v_add_f32_e32 v65, v65, v93
	v_add_f32_e32 v66, v66, v94
	v_add_f32_e32 v67, v67, v95
	v_mul_f32_e32 v92, 0xbfb8aa3b, v64
	v_mul_f32_e32 v93, 0xbfb8aa3b, v65
	v_mul_f32_e32 v94, 0xbfb8aa3b, v66
	v_mul_f32_e32 v95, 0xbfb8aa3b, v67
	v_mul_f32_e32 v100, 0x3fb8aa3b, v64
	v_mul_f32_e32 v101, 0x3fb8aa3b, v65
	v_mul_f32_e32 v102, 0x3fb8aa3b, v66
	v_mul_f32_e32 v103, 0x3fb8aa3b, v67
	v_exp_f32_e32 v92, v92
	v_exp_f32_e32 v93, v93
	v_exp_f32_e32 v94, v94
	v_exp_f32_e32 v95, v95
	v_exp_f32_e32 v100, v100
	v_exp_f32_e32 v101, v101
	v_exp_f32_e32 v102, v102
	v_exp_f32_e32 v103, v103
	v_sub_f32_e32 v96, 1.0, v96
	v_sub_f32_e32 v97, 1.0, v97
	v_sub_f32_e32 v98, 1.0, v98
	v_sub_f32_e32 v99, 1.0, v99
	v_mul_f32_e32 v96, v96, v92
	v_mul_f32_e32 v97, v97, v93
	v_mul_f32_e32 v98, v98, v94
	v_mul_f32_e32 v99, v99, v95
	v_lshlrev_b32_e32 v92, 16, v2
	v_and_b32_e32 v93, 0xffff0000, v2
	v_lshlrev_b32_e32 v94, 16, v3
	v_and_b32_e32 v95, 0xffff0000, v3
	v_mul_f32_e32 v92, v92, v100
	v_mul_f32_e32 v93, v93, v101
	v_mul_f32_e32 v94, v94, v102
	v_mul_f32_e32 v95, v95, v103
	v_cvt_pk_bf16_f32 v108, v92, v93
	v_cvt_pk_bf16_f32 v109, v94, v95
	v_cvt_pk_bf16_f32 v110, v96, v97
	v_cvt_pk_bf16_f32 v111, v98, v99
	global_store_dwordx2 v112, v[108:109], s[2:3]
	global_store_dwordx2 v114, v[110:111], s[2:3]
	s_add_u32 s2, s2, 0x400
	s_addc_u32 s3, s3, 0
	v_mov_b32_e32 v104, v96
	v_mov_b32_e32 v105, v97
	v_mov_b32_e32 v106, v98
	v_mov_b32_e32 v107, v99
	v_lshlrev_b32_e32 v92, 16, v4
	v_and_b32_e32 v93, 0xffff0000, v4
	v_lshlrev_b32_e32 v94, 16, v5
	v_and_b32_e32 v95, 0xffff0000, v5
	v_mul_f32_e32 v92, 0xbfb8aa3b, v92
	v_mul_f32_e32 v93, 0xbfb8aa3b, v93
	v_mul_f32_e32 v94, 0xbfb8aa3b, v94
	v_mul_f32_e32 v95, 0xbfb8aa3b, v95
	v_exp_f32_e32 v92, v92
	v_exp_f32_e32 v93, v93
	v_exp_f32_e32 v94, v94
	v_exp_f32_e32 v95, v95
	v_add_f32_e32 v92, 1.0, v92
	v_add_f32_e32 v93, 1.0, v93
	v_add_f32_e32 v94, 1.0, v94
	v_add_f32_e32 v95, 1.0, v95
	v_rcp_f32_e32 v92, v92
	v_rcp_f32_e32 v93, v93
	v_rcp_f32_e32 v94, v94
	v_rcp_f32_e32 v95, v95
	v_fma_f32 v96, v72, v92, v68
	v_fma_f32 v97, v73, v93, v69
	v_fma_f32 v98, v74, v94, v70
	v_fma_f32 v99, v75, v95, v71
	v_cmp_gt_f32_e64 s[22:23], s30, v96
	v_cmp_gt_f32_e64 s[24:25], s30, v97
	v_cmp_gt_f32_e64 s[26:27], s30, v98
	v_cmp_gt_f32_e64 s[28:29], s30, v99
	v_cndmask_b32_e64 v92, 0, 32, s[22:23]
	v_cndmask_b32_e64 v93, 0, 32, s[24:25]
	v_cndmask_b32_e64 v94, 0, 32, s[26:27]
	v_cndmask_b32_e64 v95, 0, 32, s[28:29]
	v_ldexp_f32 v92, v96, v92
	v_ldexp_f32 v93, v97, v93
	v_ldexp_f32 v94, v98, v94
	v_ldexp_f32 v95, v99, v95
	v_log_f32_e32 v92, v92
	v_log_f32_e32 v93, v93
	v_log_f32_e32 v94, v94
	v_log_f32_e32 v95, v95
	v_mul_f32_e32 v100, 0x3f317217, v92
	v_mul_f32_e32 v101, 0x3f317217, v93
	v_mul_f32_e32 v102, 0x3f317217, v94
	v_mul_f32_e32 v103, 0x3f317217, v95
	v_fma_f32 v100, v92, s31, -v100
	v_fma_f32 v101, v93, s31, -v101
	v_fma_f32 v102, v94, s31, -v102
	v_fma_f32 v103, v95, s31, -v103
	v_fmac_f32_e32 v100, 0x3377d1cf, v92
	v_fmac_f32_e32 v101, 0x3377d1cf, v93
	v_fmac_f32_e32 v102, 0x3377d1cf, v94
	v_fmac_f32_e32 v103, 0x3377d1cf, v95
	v_fmac_f32_e32 v100, 0x3f317217, v92
	v_fmac_f32_e32 v101, 0x3f317217, v93
	v_fmac_f32_e32 v102, 0x3f317217, v94
; DEV u16 f2bf(float f) { return (u16)(pack2(f, f) & 0xffffu); }
; DEV float bf2f(u16 h) { return __uint_as_float(((unsigned)h) << 16); }
; DEV float sigmoid_f(float x) { return __builtin_amdgcn_rcpf(1.f + __expf(-x)); }
; DEV void phase_p15(const Params& p, int g) {
;     ...
;         for (int e = 0; e < 8; ++e) {
;           const int jj = j8 * 8 + e;
;           const int j = dir ? 63 - jj : jj;
;           const size_t tok = (size_t)cidx * 64 + j;
;           const float f = lb[cc] + (1.f - lb[cc]) * sigmoid_f(bf2f(xr[st][cc][e]));
;           G[cc] += __logf(f);
;           const float eg = __expf(G[cc]), ig = __expf(-G[cc]);
;           Qp[tok * 512 + c] = f2bf(bf2f(qr[st][cc][e]) * eg);
;           const u16 kk = f2bf((1.f - f) * ig);
;           Kp[tok * 512 + c] = kk;
;           kb[e] = kk;
;         }
;     ...
;         w.x = dir ? (kb[7] | (kb[6] << 16)) : (kb[0] | (kb[1] << 16));
;         w.y = dir ? (kb[5] | (kb[4] << 16)) : (kb[2] | (kb[3] << 16));
;         w.z = dir ? (kb[3] | (kb[2] << 16)) : (kb[4] | (kb[5] << 16));
;         w.w = dir ? (kb[1] | (kb[0] << 16)) : (kb[6] | (kb[7] << 16));
	v_fmac_f32_e32 v103, 0x3f317217, v95
	v_cmp_lt_f32_e64 vcc, |v92|, s34
	v_cndmask_b32_e32 v92, v92, v100, vcc
	v_cmp_lt_f32_e64 vcc, |v93|, s34
	v_cndmask_b32_e32 v93, v93, v101, vcc
	v_cmp_lt_f32_e64 vcc, |v94|, s34
	v_cndmask_b32_e32 v94, v94, v102, vcc
	v_cmp_lt_f32_e64 vcc, |v95|, s34
	v_cndmask_b32_e32 v95, v95, v103, vcc
	v_cndmask_b32_e64 v100, 0, v213, s[22:23]
	v_cndmask_b32_e64 v101, 0, v213, s[24:25]
	v_cndmask_b32_e64 v102, 0, v213, s[26:27]
	v_cndmask_b32_e64 v103, 0, v213, s[28:29]
	v_sub_f32_e32 v92, v92, v100
	v_sub_f32_e32 v93, v93, v101
	v_sub_f32_e32 v94, v94, v102
	v_sub_f32_e32 v95, v95, v103
	v_add_f32_e32 v64, v64, v92
	v_add_f32_e32 v65, v65, v93
	v_add_f32_e32 v66, v66, v94
	v_add_f32_e32 v67, v67, v95
	v_mul_f32_e32 v92, 0xbfb8aa3b, v64
	v_mul_f32_e32 v93, 0xbfb8aa3b, v65
	v_mul_f32_e32 v94, 0xbfb8aa3b, v66
	v_mul_f32_e32 v95, 0xbfb8aa3b, v67
	v_mul_f32_e32 v100, 0x3fb8aa3b, v64
	v_mul_f32_e32 v101, 0x3fb8aa3b, v65
	v_mul_f32_e32 v102, 0x3fb8aa3b, v66
	v_mul_f32_e32 v103, 0x3fb8aa3b, v67
	v_exp_f32_e32 v92, v92
	v_exp_f32_e32 v93, v93
	v_exp_f32_e32 v94, v94
	v_exp_f32_e32 v95, v95
	v_exp_f32_e32 v100, v100
	v_exp_f32_e32 v101, v101
	v_exp_f32_e32 v102, v102
	v_exp_f32_e32 v103, v103
	v_sub_f32_e32 v96, 1.0, v96
	v_sub_f32_e32 v97, 1.0, v97
	v_sub_f32_e32 v98, 1.0, v98
	v_sub_f32_e32 v99, 1.0, v99
	v_mul_f32_e32 v96, v96, v92
	v_mul_f32_e32 v97, v97, v93
	v_mul_f32_e32 v98, v98, v94
	v_mul_f32_e32 v99, v99, v95
	v_lshlrev_b32_e32 v92, 16, v6
	v_and_b32_e32 v93, 0xffff0000, v6
	v_lshlrev_b32_e32 v94, 16, v7
	v_and_b32_e32 v95, 0xffff0000, v7
	v_mul_f32_e32 v92, v92, v100
	v_mul_f32_e32 v93, v93, v101
	v_mul_f32_e32 v94, v94, v102
	v_mul_f32_e32 v95, v95, v103
	v_cvt_pk_bf16_f32 v108, v92, v93
	v_cvt_pk_bf16_f32 v109, v94, v95
	v_cvt_pk_bf16_f32 v110, v96, v97
	v_cvt_pk_bf16_f32 v111, v98, v99
	global_store_dwordx2 v112, v[108:109], s[2:3]
	global_store_dwordx2 v114, v[110:111], s[2:3]
	s_add_u32 s2, s2, 0x400
	s_addc_u32 s3, s3, 0
	v_cvt_pk_bf16_f32 v116, v104, v96
	v_cvt_pk_bf16_f32 v132, v105, v97
	v_cvt_pk_bf16_f32 v166, v106, v98
	v_cvt_pk_bf16_f32 v182, v107, v99
	v_lshlrev_b32_e32 v92, 16, v8
	v_and_b32_e32 v93, 0xffff0000, v8
	v_lshlrev_b32_e32 v94, 16, v9
	v_and_b32_e32 v95, 0xffff0000, v9
	v_mul_f32_e32 v92, 0xbfb8aa3b, v92
	v_mul_f32_e32 v93, 0xbfb8aa3b, v93
	v_mul_f32_e32 v94, 0xbfb8aa3b, v94
	v_mul_f32_e32 v95, 0xbfb8aa3b, v95
	v_exp_f32_e32 v92, v92
	v_exp_f32_e32 v93, v93
	v_exp_f32_e32 v94, v94
	v_exp_f32_e32 v95, v95
	v_add_f32_e32 v92, 1.0, v92
	v_add_f32_e32 v93, 1.0, v93
	v_add_f32_e32 v94, 1.0, v94
	v_add_f32_e32 v95, 1.0, v95
	v_rcp_f32_e32 v92, v92
	v_rcp_f32_e32 v93, v93
	v_rcp_f32_e32 v94, v94
	v_rcp_f32_e32 v95, v95
	v_fma_f32 v96, v72, v92, v68
	v_fma_f32 v97, v73, v93, v69
	v_fma_f32 v98, v74, v94, v70
	v_fma_f32 v99, v75, v95, v71
	v_cmp_gt_f32_e64 s[22:23], s30, v96
	v_cmp_gt_f32_e64 s[24:25], s30, v97
	v_cmp_gt_f32_e64 s[26:27], s30, v98
	v_cmp_gt_f32_e64 s[28:29], s30, v99
	v_cndmask_b32_e64 v92, 0, 32, s[22:23]
	v_cndmask_b32_e64 v93, 0, 32, s[24:25]
	v_cndmask_b32_e64 v94, 0, 32, s[26:27]
	v_cndmask_b32_e64 v95, 0, 32, s[28:29]
	v_ldexp_f32 v92, v96, v92
	v_ldexp_f32 v93, v97, v93
	v_ldexp_f32 v94, v98, v94
	v_ldexp_f32 v95, v99, v95
	v_log_f32_e32 v92, v92
	v_log_f32_e32 v93, v93
	v_log_f32_e32 v94, v94
	v_log_f32_e32 v95, v95
	v_mul_f32_e32 v100, 0x3f317217, v92
	v_mul_f32_e32 v101, 0x3f317217, v93
	v_mul_f32_e32 v102, 0x3f317217, v94
	v_mul_f32_e32 v103, 0x3f317217, v95
	v_fma_f32 v100, v92, s31, -v100
	v_fma_f32 v101, v93, s31, -v101
	v_fma_f32 v102, v94, s31, -v102
	v_fma_f32 v103, v95, s31, -v103
	v_fmac_f32_e32 v100, 0x3377d1cf, v92
	v_fmac_f32_e32 v101, 0x3377d1cf, v93
	v_fmac_f32_e32 v102, 0x3377d1cf, v94
	v_fmac_f32_e32 v103, 0x3377d1cf, v95
	v_fmac_f32_e32 v100, 0x3f317217, v92
	v_fmac_f32_e32 v101, 0x3f317217, v93
	v_fmac_f32_e32 v102, 0x3f317217, v94
	v_fmac_f32_e32 v103, 0x3f317217, v95
	v_cmp_lt_f32_e64 vcc, |v92|, s34
	v_cndmask_b32_e32 v92, v92, v100, vcc
	v_cmp_lt_f32_e64 vcc, |v93|, s34
	v_cndmask_b32_e32 v93, v93, v101, vcc
	v_cmp_lt_f32_e64 vcc, |v94|, s34
	v_cndmask_b32_e32 v94, v94, v102, vcc
	v_cmp_lt_f32_e64 vcc, |v95|, s34
	v_cndmask_b32_e32 v95, v95, v103, vcc
	v_cndmask_b32_e64 v100, 0, v213, s[22:23]
	v_cndmask_b32_e64 v101, 0, v213, s[24:25]
	v_cndmask_b32_e64 v102, 0, v213, s[26:27]
	v_cndmask_b32_e64 v103, 0, v213, s[28:29]
	v_sub_f32_e32 v92, v92, v100
	v_sub_f32_e32 v93, v93, v101
	v_sub_f32_e32 v94, v94, v102
	v_sub_f32_e32 v95, v95, v103
	v_add_f32_e32 v64, v64, v92
	v_add_f32_e32 v65, v65, v93
	v_add_f32_e32 v66, v66, v94
	v_add_f32_e32 v67, v67, v95
	v_mul_f32_e32 v92, 0xbfb8aa3b, v64
	v_mul_f32_e32 v93, 0xbfb8aa3b, v65
	v_mul_f32_e32 v94, 0xbfb8aa3b, v66
	v_mul_f32_e32 v95, 0xbfb8aa3b, v67
	v_mul_f32_e32 v100, 0x3fb8aa3b, v64
	v_mul_f32_e32 v101, 0x3fb8aa3b, v65
	v_mul_f32_e32 v102, 0x3fb8aa3b, v66
	v_mul_f32_e32 v103, 0x3fb8aa3b, v67
	v_exp_f32_e32 v92, v92
	v_exp_f32_e32 v93, v93
	v_exp_f32_e32 v94, v94
	v_exp_f32_e32 v95, v95
	v_exp_f32_e32 v100, v100
	v_exp_f32_e32 v101, v101
	v_exp_f32_e32 v102, v102
	v_exp_f32_e32 v103, v103
	v_sub_f32_e32 v96, 1.0, v96
	v_sub_f32_e32 v97, 1.0, v97
	v_sub_f32_e32 v98, 1.0, v98
	v_sub_f32_e32 v99, 1.0, v99
	v_mul_f32_e32 v96, v96, v92
	v_mul_f32_e32 v97, v97, v93
	v_mul_f32_e32 v98, v98, v94
	v_mul_f32_e32 v99, v99, v95
	v_lshlrev_b32_e32 v92, 16, v10
	v_and_b32_e32 v93, 0xffff0000, v10
	v_lshlrev_b32_e32 v94, 16, v11
	v_and_b32_e32 v95, 0xffff0000, v11
	v_mul_f32_e32 v92, v92, v100
	v_mul_f32_e32 v93, v93, v101
	v_mul_f32_e32 v94, v94, v102
	v_mul_f32_e32 v95, v95, v103
	v_cvt_pk_bf16_f32 v108, v92, v93
; DEV u16 f2bf(float f) { return (u16)(pack2(f, f) & 0xffffu); }
; DEV float bf2f(u16 h) { return __uint_as_float(((unsigned)h) << 16); }
; DEV float sigmoid_f(float x) { return __builtin_amdgcn_rcpf(1.f + __expf(-x)); }
; DEV void phase_p15(const Params& p, int g) {
;     ...
;         for (int e = 0; e < 8; ++e) {
;           const int jj = j8 * 8 + e;
;           const int j = dir ? 63 - jj : jj;
;           const size_t tok = (size_t)cidx * 64 + j;
;           const float f = lb[cc] + (1.f - lb[cc]) * sigmoid_f(bf2f(xr[st][cc][e]));
;           G[cc] += __logf(f);
;           const float eg = __expf(G[cc]), ig = __expf(-G[cc]);
;           Qp[tok * 512 + c] = f2bf(bf2f(qr[st][cc][e]) * eg);
;           const u16 kk = f2bf((1.f - f) * ig);
;           Kp[tok * 512 + c] = kk;
;           kb[e] = kk;
;         }
;     ...
;         w.x = dir ? (kb[7] | (kb[6] << 16)) : (kb[0] | (kb[1] << 16));
;         w.y = dir ? (kb[5] | (kb[4] << 16)) : (kb[2] | (kb[3] << 16));
;         w.z = dir ? (kb[3] | (kb[2] << 16)) : (kb[4] | (kb[5] << 16));
;         w.w = dir ? (kb[1] | (kb[0] << 16)) : (kb[6] | (kb[7] << 16));
	v_cvt_pk_bf16_f32 v109, v94, v95
	v_cvt_pk_bf16_f32 v110, v96, v97
	v_cvt_pk_bf16_f32 v111, v98, v99
	global_store_dwordx2 v112, v[108:109], s[2:3]
	global_store_dwordx2 v114, v[110:111], s[2:3]
	s_add_u32 s2, s2, 0x400
	s_addc_u32 s3, s3, 0
	v_mov_b32_e32 v104, v96
	v_mov_b32_e32 v105, v97
	v_mov_b32_e32 v106, v98
	v_mov_b32_e32 v107, v99
	v_lshlrev_b32_e32 v92, 16, v12
	v_and_b32_e32 v93, 0xffff0000, v12
	v_lshlrev_b32_e32 v94, 16, v13
	v_and_b32_e32 v95, 0xffff0000, v13
	v_mul_f32_e32 v92, 0xbfb8aa3b, v92
	v_mul_f32_e32 v93, 0xbfb8aa3b, v93
	v_mul_f32_e32 v94, 0xbfb8aa3b, v94
	v_mul_f32_e32 v95, 0xbfb8aa3b, v95
	v_exp_f32_e32 v92, v92
	v_exp_f32_e32 v93, v93
	v_exp_f32_e32 v94, v94
	v_exp_f32_e32 v95, v95
	v_add_f32_e32 v92, 1.0, v92
	v_add_f32_e32 v93, 1.0, v93
	v_add_f32_e32 v94, 1.0, v94
	v_add_f32_e32 v95, 1.0, v95
	v_rcp_f32_e32 v92, v92
	v_rcp_f32_e32 v93, v93
	v_rcp_f32_e32 v94, v94
	v_rcp_f32_e32 v95, v95
	v_fma_f32 v96, v72, v92, v68
	v_fma_f32 v97, v73, v93, v69
	v_fma_f32 v98, v74, v94, v70
	v_fma_f32 v99, v75, v95, v71
	v_cmp_gt_f32_e64 s[22:23], s30, v96
	v_cmp_gt_f32_e64 s[24:25], s30, v97
	v_cmp_gt_f32_e64 s[26:27], s30, v98
	v_cmp_gt_f32_e64 s[28:29], s30, v99
	v_cndmask_b32_e64 v92, 0, 32, s[22:23]
	v_cndmask_b32_e64 v93, 0, 32, s[24:25]
	v_cndmask_b32_e64 v94, 0, 32, s[26:27]
	v_cndmask_b32_e64 v95, 0, 32, s[28:29]
	v_ldexp_f32 v92, v96, v92
	v_ldexp_f32 v93, v97, v93
	v_ldexp_f32 v94, v98, v94
	v_ldexp_f32 v95, v99, v95
	v_log_f32_e32 v92, v92
	v_log_f32_e32 v93, v93
	v_log_f32_e32 v94, v94
	v_log_f32_e32 v95, v95
	v_mul_f32_e32 v100, 0x3f317217, v92
	v_mul_f32_e32 v101, 0x3f317217, v93
	v_mul_f32_e32 v102, 0x3f317217, v94
	v_mul_f32_e32 v103, 0x3f317217, v95
	v_fma_f32 v100, v92, s31, -v100
	v_fma_f32 v101, v93, s31, -v101
	v_fma_f32 v102, v94, s31, -v102
	v_fma_f32 v103, v95, s31, -v103
	v_fmac_f32_e32 v100, 0x3377d1cf, v92
	v_fmac_f32_e32 v101, 0x3377d1cf, v93
	v_fmac_f32_e32 v102, 0x3377d1cf, v94
	v_fmac_f32_e32 v103, 0x3377d1cf, v95
	v_fmac_f32_e32 v100, 0x3f317217, v92
	v_fmac_f32_e32 v101, 0x3f317217, v93
	v_fmac_f32_e32 v102, 0x3f317217, v94
	v_fmac_f32_e32 v103, 0x3f317217, v95
	v_cmp_lt_f32_e64 vcc, |v92|, s34
	v_cndmask_b32_e32 v92, v92, v100, vcc
	v_cmp_lt_f32_e64 vcc, |v93|, s34
	v_cndmask_b32_e32 v93, v93, v101, vcc
	v_cmp_lt_f32_e64 vcc, |v94|, s34
	v_cndmask_b32_e32 v94, v94, v102, vcc
	v_cmp_lt_f32_e64 vcc, |v95|, s34
	v_cndmask_b32_e32 v95, v95, v103, vcc
	v_cndmask_b32_e64 v100, 0, v213, s[22:23]
	v_cndmask_b32_e64 v101, 0, v213, s[24:25]
	v_cndmask_b32_e64 v102, 0, v213, s[26:27]
	v_cndmask_b32_e64 v103, 0, v213, s[28:29]
	v_sub_f32_e32 v92, v92, v100
	v_sub_f32_e32 v93, v93, v101
	v_sub_f32_e32 v94, v94, v102
	v_sub_f32_e32 v95, v95, v103
	v_add_f32_e32 v64, v64, v92
	v_add_f32_e32 v65, v65, v93
	v_add_f32_e32 v66, v66, v94
	v_add_f32_e32 v67, v67, v95
	v_mul_f32_e32 v92, 0xbfb8aa3b, v64
	v_mul_f32_e32 v93, 0xbfb8aa3b, v65
	v_mul_f32_e32 v94, 0xbfb8aa3b, v66
	v_mul_f32_e32 v95, 0xbfb8aa3b, v67
	v_mul_f32_e32 v100, 0x3fb8aa3b, v64
	v_mul_f32_e32 v101, 0x3fb8aa3b, v65
	v_mul_f32_e32 v102, 0x3fb8aa3b, v66
	v_mul_f32_e32 v103, 0x3fb8aa3b, v67
	v_exp_f32_e32 v92, v92
	v_exp_f32_e32 v93, v93
	v_exp_f32_e32 v94, v94
	v_exp_f32_e32 v95, v95
	v_exp_f32_e32 v100, v100
	v_exp_f32_e32 v101, v101
	v_exp_f32_e32 v102, v102
	v_exp_f32_e32 v103, v103
	v_sub_f32_e32 v96, 1.0, v96
	v_sub_f32_e32 v97, 1.0, v97
	v_sub_f32_e32 v98, 1.0, v98
	v_sub_f32_e32 v99, 1.0, v99
	v_mul_f32_e32 v96, v96, v92
	v_mul_f32_e32 v97, v97, v93
	v_mul_f32_e32 v98, v98, v94
	v_mul_f32_e32 v99, v99, v95
	v_lshlrev_b32_e32 v92, 16, v14
	v_and_b32_e32 v93, 0xffff0000, v14
	v_lshlrev_b32_e32 v94, 16, v15
	v_and_b32_e32 v95, 0xffff0000, v15
	v_mul_f32_e32 v92, v92, v100
	v_mul_f32_e32 v93, v93, v101
	v_mul_f32_e32 v94, v94, v102
	v_mul_f32_e32 v95, v95, v103
	v_cvt_pk_bf16_f32 v108, v92, v93
	v_cvt_pk_bf16_f32 v109, v94, v95
	v_cvt_pk_bf16_f32 v110, v96, v97
	v_cvt_pk_bf16_f32 v111, v98, v99
	global_store_dwordx2 v112, v[108:109], s[2:3]
	global_store_dwordx2 v114, v[110:111], s[2:3]
	s_add_u32 s2, s2, 0x400
	s_addc_u32 s3, s3, 0
	v_cvt_pk_bf16_f32 v117, v104, v96
	v_cvt_pk_bf16_f32 v133, v105, v97
	v_cvt_pk_bf16_f32 v167, v106, v98
	v_cvt_pk_bf16_f32 v183, v107, v99
	v_lshlrev_b32_e32 v92, 16, v16
	v_and_b32_e32 v93, 0xffff0000, v16
	v_lshlrev_b32_e32 v94, 16, v17
	v_and_b32_e32 v95, 0xffff0000, v17
	v_mul_f32_e32 v92, 0xbfb8aa3b, v92
	v_mul_f32_e32 v93, 0xbfb8aa3b, v93
	v_mul_f32_e32 v94, 0xbfb8aa3b, v94
	v_mul_f32_e32 v95, 0xbfb8aa3b, v95
	v_exp_f32_e32 v92, v92
	v_exp_f32_e32 v93, v93
	v_exp_f32_e32 v94, v94
	v_exp_f32_e32 v95, v95
	v_add_f32_e32 v92, 1.0, v92
	v_add_f32_e32 v93, 1.0, v93
	v_add_f32_e32 v94, 1.0, v94
	v_add_f32_e32 v95, 1.0, v95
	v_rcp_f32_e32 v92, v92
	v_rcp_f32_e32 v93, v93
	v_rcp_f32_e32 v94, v94
	v_rcp_f32_e32 v95, v95
	v_fma_f32 v96, v72, v92, v68
	v_fma_f32 v97, v73, v93, v69
	v_fma_f32 v98, v74, v94, v70
	v_fma_f32 v99, v75, v95, v71
	v_cmp_gt_f32_e64 s[22:23], s30, v96
	v_cmp_gt_f32_e64 s[24:25], s30, v97
	v_cmp_gt_f32_e64 s[26:27], s30, v98
	v_cmp_gt_f32_e64 s[28:29], s30, v99
	v_cndmask_b32_e64 v92, 0, 32, s[22:23]
	v_cndmask_b32_e64 v93, 0, 32, s[24:25]
	v_cndmask_b32_e64 v94, 0, 32, s[26:27]
	v_cndmask_b32_e64 v95, 0, 32, s[28:29]
	v_ldexp_f32 v92, v96, v92
	v_ldexp_f32 v93, v97, v93
	v_ldexp_f32 v94, v98, v94
	v_ldexp_f32 v95, v99, v95
	v_log_f32_e32 v92, v92
	v_log_f32_e32 v93, v93
	v_log_f32_e32 v94, v94
	v_log_f32_e32 v95, v95
	v_mul_f32_e32 v100, 0x3f317217, v92
	v_mul_f32_e32 v101, 0x3f317217, v93
	v_mul_f32_e32 v102, 0x3f317217, v94
	v_mul_f32_e32 v103, 0x3f317217, v95
	v_fma_f32 v100, v92, s31, -v100
; DEV u16 f2bf(float f) { return (u16)(pack2(f, f) & 0xffffu); }
; DEV float bf2f(u16 h) { return __uint_as_float(((unsigned)h) << 16); }
; DEV float sigmoid_f(float x) { return __builtin_amdgcn_rcpf(1.f + __expf(-x)); }
; DEV void phase_p15(const Params& p, int g) {
;     ...
;         for (int e = 0; e < 8; ++e) {
;           const int jj = j8 * 8 + e;
;           const int j = dir ? 63 - jj : jj;
;           const size_t tok = (size_t)cidx * 64 + j;
;           const float f = lb[cc] + (1.f - lb[cc]) * sigmoid_f(bf2f(xr[st][cc][e]));
;           G[cc] += __logf(f);
;           const float eg = __expf(G[cc]), ig = __expf(-G[cc]);
;           Qp[tok * 512 + c] = f2bf(bf2f(qr[st][cc][e]) * eg);
;           const u16 kk = f2bf((1.f - f) * ig);
;           Kp[tok * 512 + c] = kk;
;           kb[e] = kk;
;         }
	v_fma_f32 v101, v93, s31, -v101
	v_fma_f32 v102, v94, s31, -v102
	v_fma_f32 v103, v95, s31, -v103
	v_fmac_f32_e32 v100, 0x3377d1cf, v92
	v_fmac_f32_e32 v101, 0x3377d1cf, v93
	v_fmac_f32_e32 v102, 0x3377d1cf, v94
	v_fmac_f32_e32 v103, 0x3377d1cf, v95
	v_fmac_f32_e32 v100, 0x3f317217, v92
	v_fmac_f32_e32 v101, 0x3f317217, v93
	v_fmac_f32_e32 v102, 0x3f317217, v94
	v_fmac_f32_e32 v103, 0x3f317217, v95
	v_cmp_lt_f32_e64 vcc, |v92|, s34
	v_cndmask_b32_e32 v92, v92, v100, vcc
	v_cmp_lt_f32_e64 vcc, |v93|, s34
	v_cndmask_b32_e32 v93, v93, v101, vcc
	v_cmp_lt_f32_e64 vcc, |v94|, s34
	v_cndmask_b32_e32 v94, v94, v102, vcc
	v_cmp_lt_f32_e64 vcc, |v95|, s34
	v_cndmask_b32_e32 v95, v95, v103, vcc
	v_cndmask_b32_e64 v100, 0, v213, s[22:23]
	v_cndmask_b32_e64 v101, 0, v213, s[24:25]
	v_cndmask_b32_e64 v102, 0, v213, s[26:27]
	v_cndmask_b32_e64 v103, 0, v213, s[28:29]
	v_sub_f32_e32 v92, v92, v100
	v_sub_f32_e32 v93, v93, v101
	v_sub_f32_e32 v94, v94, v102
	v_sub_f32_e32 v95, v95, v103
	v_add_f32_e32 v64, v64, v92
	v_add_f32_e32 v65, v65, v93
	v_add_f32_e32 v66, v66, v94
	v_add_f32_e32 v67, v67, v95
	v_mul_f32_e32 v92, 0xbfb8aa3b, v64
	v_mul_f32_e32 v93, 0xbfb8aa3b, v65
	v_mul_f32_e32 v94, 0xbfb8aa3b, v66
	v_mul_f32_e32 v95, 0xbfb8aa3b, v67
	v_mul_f32_e32 v100, 0x3fb8aa3b, v64
	v_mul_f32_e32 v101, 0x3fb8aa3b, v65
	v_mul_f32_e32 v102, 0x3fb8aa3b, v66
	v_mul_f32_e32 v103, 0x3fb8aa3b, v67
	v_exp_f32_e32 v92, v92
	v_exp_f32_e32 v93, v93
	v_exp_f32_e32 v94, v94
	v_exp_f32_e32 v95, v95
	v_exp_f32_e32 v100, v100
	v_exp_f32_e32 v101, v101
	v_exp_f32_e32 v102, v102
	v_exp_f32_e32 v103, v103
	v_sub_f32_e32 v96, 1.0, v96
	v_sub_f32_e32 v97, 1.0, v97
	v_sub_f32_e32 v98, 1.0, v98
	v_sub_f32_e32 v99, 1.0, v99
	v_mul_f32_e32 v96, v96, v92
	v_mul_f32_e32 v97, v97, v93
	v_mul_f32_e32 v98, v98, v94
	v_mul_f32_e32 v99, v99, v95
	v_lshlrev_b32_e32 v92, 16, v18
	v_and_b32_e32 v93, 0xffff0000, v18
	v_lshlrev_b32_e32 v94, 16, v19
	v_and_b32_e32 v95, 0xffff0000, v19
	v_mul_f32_e32 v92, v92, v100
	v_mul_f32_e32 v93, v93, v101
	v_mul_f32_e32 v94, v94, v102
	v_mul_f32_e32 v95, v95, v103
	v_cvt_pk_bf16_f32 v108, v92, v93
	v_cvt_pk_bf16_f32 v109, v94, v95
	v_cvt_pk_bf16_f32 v110, v96, v97
	v_cvt_pk_bf16_f32 v111, v98, v99
	global_store_dwordx2 v112, v[108:109], s[2:3]
	global_store_dwordx2 v114, v[110:111], s[2:3]
	s_add_u32 s2, s2, 0x400
	s_addc_u32 s3, s3, 0
	v_mov_b32_e32 v104, v96
	v_mov_b32_e32 v105, v97
	v_mov_b32_e32 v106, v98
	v_mov_b32_e32 v107, v99
	v_lshlrev_b32_e32 v92, 16, v20
	v_and_b32_e32 v93, 0xffff0000, v20
	v_lshlrev_b32_e32 v94, 16, v21
	v_and_b32_e32 v95, 0xffff0000, v21
	v_mul_f32_e32 v92, 0xbfb8aa3b, v92
	v_mul_f32_e32 v93, 0xbfb8aa3b, v93
	v_mul_f32_e32 v94, 0xbfb8aa3b, v94
	v_mul_f32_e32 v95, 0xbfb8aa3b, v95
	v_exp_f32_e32 v92, v92
	v_exp_f32_e32 v93, v93
	v_exp_f32_e32 v94, v94
	v_exp_f32_e32 v95, v95
	v_add_f32_e32 v92, 1.0, v92
	v_add_f32_e32 v93, 1.0, v93
	v_add_f32_e32 v94, 1.0, v94
	v_add_f32_e32 v95, 1.0, v95
	v_rcp_f32_e32 v92, v92
	v_rcp_f32_e32 v93, v93
	v_rcp_f32_e32 v94, v94
	v_rcp_f32_e32 v95, v95
	v_fma_f32 v96, v72, v92, v68
	v_fma_f32 v97, v73, v93, v69
	v_fma_f32 v98, v74, v94, v70
	v_fma_f32 v99, v75, v95, v71
	v_cmp_gt_f32_e64 s[22:23], s30, v96
	v_cmp_gt_f32_e64 s[24:25], s30, v97
	v_cmp_gt_f32_e64 s[26:27], s30, v98
	v_cmp_gt_f32_e64 s[28:29], s30, v99
	v_cndmask_b32_e64 v92, 0, 32, s[22:23]
	v_cndmask_b32_e64 v93, 0, 32, s[24:25]
	v_cndmask_b32_e64 v94, 0, 32, s[26:27]
	v_cndmask_b32_e64 v95, 0, 32, s[28:29]
	v_ldexp_f32 v92, v96, v92
	v_ldexp_f32 v93, v97, v93
	v_ldexp_f32 v94, v98, v94
	v_ldexp_f32 v95, v99, v95
	v_log_f32_e32 v92, v92
	v_log_f32_e32 v93, v93
	v_log_f32_e32 v94, v94
	v_log_f32_e32 v95, v95
	v_mul_f32_e32 v100, 0x3f317217, v92
	v_mul_f32_e32 v101, 0x3f317217, v93
	v_mul_f32_e32 v102, 0x3f317217, v94
	v_mul_f32_e32 v103, 0x3f317217, v95
	v_fma_f32 v100, v92, s31, -v100
	v_fma_f32 v101, v93, s31, -v101
	v_fma_f32 v102, v94, s31, -v102
	v_fma_f32 v103, v95, s31, -v103
	v_fmac_f32_e32 v100, 0x3377d1cf, v92
	v_fmac_f32_e32 v101, 0x3377d1cf, v93
	v_fmac_f32_e32 v102, 0x3377d1cf, v94
	v_fmac_f32_e32 v103, 0x3377d1cf, v95
	v_fmac_f32_e32 v100, 0x3f317217, v92
	v_fmac_f32_e32 v101, 0x3f317217, v93
	v_fmac_f32_e32 v102, 0x3f317217, v94
	v_fmac_f32_e32 v103, 0x3f317217, v95
	v_cmp_lt_f32_e64 vcc, |v92|, s34
	v_cndmask_b32_e32 v92, v92, v100, vcc
	v_cmp_lt_f32_e64 vcc, |v93|, s34
	v_cndmask_b32_e32 v93, v93, v101, vcc
	v_cmp_lt_f32_e64 vcc, |v94|, s34
	v_cndmask_b32_e32 v94, v94, v102, vcc
	v_cmp_lt_f32_e64 vcc, |v95|, s34
	v_cndmask_b32_e32 v95, v95, v103, vcc
	v_cndmask_b32_e64 v100, 0, v213, s[22:23]
	v_cndmask_b32_e64 v101, 0, v213, s[24:25]
	v_cndmask_b32_e64 v102, 0, v213, s[26:27]
	v_cndmask_b32_e64 v103, 0, v213, s[28:29]
	v_sub_f32_e32 v92, v92, v100
	v_sub_f32_e32 v93, v93, v101
	v_sub_f32_e32 v94, v94, v102
	v_sub_f32_e32 v95, v95, v103
	v_add_f32_e32 v64, v64, v92
	v_add_f32_e32 v65, v65, v93
	v_add_f32_e32 v66, v66, v94
	v_add_f32_e32 v67, v67, v95
	v_mul_f32_e32 v92, 0xbfb8aa3b, v64
	v_mul_f32_e32 v93, 0xbfb8aa3b, v65
	v_mul_f32_e32 v94, 0xbfb8aa3b, v66
	v_mul_f32_e32 v95, 0xbfb8aa3b, v67
	v_mul_f32_e32 v100, 0x3fb8aa3b, v64
	v_mul_f32_e32 v101, 0x3fb8aa3b, v65
	v_mul_f32_e32 v102, 0x3fb8aa3b, v66
	v_mul_f32_e32 v103, 0x3fb8aa3b, v67
	v_exp_f32_e32 v92, v92
	v_exp_f32_e32 v93, v93
	v_exp_f32_e32 v94, v94
	v_exp_f32_e32 v95, v95
	v_exp_f32_e32 v100, v100
	v_exp_f32_e32 v101, v101
	v_exp_f32_e32 v102, v102
	v_exp_f32_e32 v103, v103
	v_sub_f32_e32 v96, 1.0, v96
	v_sub_f32_e32 v97, 1.0, v97
	v_sub_f32_e32 v98, 1.0, v98
	v_sub_f32_e32 v99, 1.0, v99
	v_mul_f32_e32 v96, v96, v92
	v_mul_f32_e32 v97, v97, v93
; DEV u16 f2bf(float f) { return (u16)(pack2(f, f) & 0xffffu); }
; DEV float bf2f(u16 h) { return __uint_as_float(((unsigned)h) << 16); }
; DEV float sigmoid_f(float x) { return __builtin_amdgcn_rcpf(1.f + __expf(-x)); }
; DEV void phase_p15(const Params& p, int g) {
;     ...
;         for (int e = 0; e < 8; ++e) {
;           const int jj = j8 * 8 + e;
;           const int j = dir ? 63 - jj : jj;
;           const size_t tok = (size_t)cidx * 64 + j;
;           const float f = lb[cc] + (1.f - lb[cc]) * sigmoid_f(bf2f(xr[st][cc][e]));
;           G[cc] += __logf(f);
;           const float eg = __expf(G[cc]), ig = __expf(-G[cc]);
;           Qp[tok * 512 + c] = f2bf(bf2f(qr[st][cc][e]) * eg);
;           const u16 kk = f2bf((1.f - f) * ig);
;           Kp[tok * 512 + c] = kk;
;           kb[e] = kk;
;         }
;     ...
;         w.x = dir ? (kb[7] | (kb[6] << 16)) : (kb[0] | (kb[1] << 16));
;         w.y = dir ? (kb[5] | (kb[4] << 16)) : (kb[2] | (kb[3] << 16));
;         w.z = dir ? (kb[3] | (kb[2] << 16)) : (kb[4] | (kb[5] << 16));
;         w.w = dir ? (kb[1] | (kb[0] << 16)) : (kb[6] | (kb[7] << 16));
	v_mul_f32_e32 v98, v98, v94
	v_mul_f32_e32 v99, v99, v95
	v_lshlrev_b32_e32 v92, 16, v22
	v_and_b32_e32 v93, 0xffff0000, v22
	v_lshlrev_b32_e32 v94, 16, v23
	v_and_b32_e32 v95, 0xffff0000, v23
	v_mul_f32_e32 v92, v92, v100
	v_mul_f32_e32 v93, v93, v101
	v_mul_f32_e32 v94, v94, v102
	v_mul_f32_e32 v95, v95, v103
	v_cvt_pk_bf16_f32 v108, v92, v93
	v_cvt_pk_bf16_f32 v109, v94, v95
	v_cvt_pk_bf16_f32 v110, v96, v97
	v_cvt_pk_bf16_f32 v111, v98, v99
	global_store_dwordx2 v112, v[108:109], s[2:3]
	global_store_dwordx2 v114, v[110:111], s[2:3]
	s_add_u32 s2, s2, 0x400
	s_addc_u32 s3, s3, 0
	v_cvt_pk_bf16_f32 v118, v104, v96
	v_cvt_pk_bf16_f32 v134, v105, v97
	v_cvt_pk_bf16_f32 v168, v106, v98
	v_cvt_pk_bf16_f32 v184, v107, v99
	v_lshlrev_b32_e32 v92, 16, v24
	v_and_b32_e32 v93, 0xffff0000, v24
	v_lshlrev_b32_e32 v94, 16, v25
	v_and_b32_e32 v95, 0xffff0000, v25
	v_mul_f32_e32 v92, 0xbfb8aa3b, v92
	v_mul_f32_e32 v93, 0xbfb8aa3b, v93
	v_mul_f32_e32 v94, 0xbfb8aa3b, v94
	v_mul_f32_e32 v95, 0xbfb8aa3b, v95
	v_exp_f32_e32 v92, v92
	v_exp_f32_e32 v93, v93
	v_exp_f32_e32 v94, v94
	v_exp_f32_e32 v95, v95
	v_add_f32_e32 v92, 1.0, v92
	v_add_f32_e32 v93, 1.0, v93
	v_add_f32_e32 v94, 1.0, v94
	v_add_f32_e32 v95, 1.0, v95
	v_rcp_f32_e32 v92, v92
	v_rcp_f32_e32 v93, v93
	v_rcp_f32_e32 v94, v94
	v_rcp_f32_e32 v95, v95
	v_fma_f32 v96, v72, v92, v68
	v_fma_f32 v97, v73, v93, v69
	v_fma_f32 v98, v74, v94, v70
	v_fma_f32 v99, v75, v95, v71
	v_cmp_gt_f32_e64 s[22:23], s30, v96
	v_cmp_gt_f32_e64 s[24:25], s30, v97
	v_cmp_gt_f32_e64 s[26:27], s30, v98
	v_cmp_gt_f32_e64 s[28:29], s30, v99
	v_cndmask_b32_e64 v92, 0, 32, s[22:23]
	v_cndmask_b32_e64 v93, 0, 32, s[24:25]
	v_cndmask_b32_e64 v94, 0, 32, s[26:27]
	v_cndmask_b32_e64 v95, 0, 32, s[28:29]
	v_ldexp_f32 v92, v96, v92
	v_ldexp_f32 v93, v97, v93
	v_ldexp_f32 v94, v98, v94
	v_ldexp_f32 v95, v99, v95
	v_log_f32_e32 v92, v92
	v_log_f32_e32 v93, v93
	v_log_f32_e32 v94, v94
	v_log_f32_e32 v95, v95
	v_mul_f32_e32 v100, 0x3f317217, v92
	v_mul_f32_e32 v101, 0x3f317217, v93
	v_mul_f32_e32 v102, 0x3f317217, v94
	v_mul_f32_e32 v103, 0x3f317217, v95
	v_fma_f32 v100, v92, s31, -v100
	v_fma_f32 v101, v93, s31, -v101
	v_fma_f32 v102, v94, s31, -v102
	v_fma_f32 v103, v95, s31, -v103
	v_fmac_f32_e32 v100, 0x3377d1cf, v92
	v_fmac_f32_e32 v101, 0x3377d1cf, v93
	v_fmac_f32_e32 v102, 0x3377d1cf, v94
	v_fmac_f32_e32 v103, 0x3377d1cf, v95
	v_fmac_f32_e32 v100, 0x3f317217, v92
	v_fmac_f32_e32 v101, 0x3f317217, v93
	v_fmac_f32_e32 v102, 0x3f317217, v94
	v_fmac_f32_e32 v103, 0x3f317217, v95
	v_cmp_lt_f32_e64 vcc, |v92|, s34
	v_cndmask_b32_e32 v92, v92, v100, vcc
	v_cmp_lt_f32_e64 vcc, |v93|, s34
	v_cndmask_b32_e32 v93, v93, v101, vcc
	v_cmp_lt_f32_e64 vcc, |v94|, s34
	v_cndmask_b32_e32 v94, v94, v102, vcc
	v_cmp_lt_f32_e64 vcc, |v95|, s34
	v_cndmask_b32_e32 v95, v95, v103, vcc
	v_cndmask_b32_e64 v100, 0, v213, s[22:23]
	v_cndmask_b32_e64 v101, 0, v213, s[24:25]
	v_cndmask_b32_e64 v102, 0, v213, s[26:27]
	v_cndmask_b32_e64 v103, 0, v213, s[28:29]
	v_sub_f32_e32 v92, v92, v100
	v_sub_f32_e32 v93, v93, v101
	v_sub_f32_e32 v94, v94, v102
	v_sub_f32_e32 v95, v95, v103
	v_add_f32_e32 v64, v64, v92
	v_add_f32_e32 v65, v65, v93
	v_add_f32_e32 v66, v66, v94
	v_add_f32_e32 v67, v67, v95
	v_mul_f32_e32 v92, 0xbfb8aa3b, v64
	v_mul_f32_e32 v93, 0xbfb8aa3b, v65
	v_mul_f32_e32 v94, 0xbfb8aa3b, v66
	v_mul_f32_e32 v95, 0xbfb8aa3b, v67
	v_mul_f32_e32 v100, 0x3fb8aa3b, v64
	v_mul_f32_e32 v101, 0x3fb8aa3b, v65
	v_mul_f32_e32 v102, 0x3fb8aa3b, v66
	v_mul_f32_e32 v103, 0x3fb8aa3b, v67
	v_exp_f32_e32 v92, v92
	v_exp_f32_e32 v93, v93
	v_exp_f32_e32 v94, v94
	v_exp_f32_e32 v95, v95
	v_exp_f32_e32 v100, v100
	v_exp_f32_e32 v101, v101
	v_exp_f32_e32 v102, v102
	v_exp_f32_e32 v103, v103
	v_sub_f32_e32 v96, 1.0, v96
	v_sub_f32_e32 v97, 1.0, v97
	v_sub_f32_e32 v98, 1.0, v98
	v_sub_f32_e32 v99, 1.0, v99
	v_mul_f32_e32 v96, v96, v92
	v_mul_f32_e32 v97, v97, v93
	v_mul_f32_e32 v98, v98, v94
	v_mul_f32_e32 v99, v99, v95
	v_lshlrev_b32_e32 v92, 16, v26
	v_and_b32_e32 v93, 0xffff0000, v26
	v_lshlrev_b32_e32 v94, 16, v27
	v_and_b32_e32 v95, 0xffff0000, v27
	v_mul_f32_e32 v92, v92, v100
	v_mul_f32_e32 v93, v93, v101
	v_mul_f32_e32 v94, v94, v102
	v_mul_f32_e32 v95, v95, v103
	v_cvt_pk_bf16_f32 v108, v92, v93
	v_cvt_pk_bf16_f32 v109, v94, v95
	v_cvt_pk_bf16_f32 v110, v96, v97
	v_cvt_pk_bf16_f32 v111, v98, v99
	global_store_dwordx2 v112, v[108:109], s[2:3]
	global_store_dwordx2 v114, v[110:111], s[2:3]
	s_add_u32 s2, s2, 0x400
	s_addc_u32 s3, s3, 0
	v_mov_b32_e32 v104, v96
	v_mov_b32_e32 v105, v97
	v_mov_b32_e32 v106, v98
	v_mov_b32_e32 v107, v99
	v_lshlrev_b32_e32 v92, 16, v28
	v_and_b32_e32 v93, 0xffff0000, v28
	v_lshlrev_b32_e32 v94, 16, v29
	v_and_b32_e32 v95, 0xffff0000, v29
	v_mul_f32_e32 v92, 0xbfb8aa3b, v92
	v_mul_f32_e32 v93, 0xbfb8aa3b, v93
	v_mul_f32_e32 v94, 0xbfb8aa3b, v94
	v_mul_f32_e32 v95, 0xbfb8aa3b, v95
	v_exp_f32_e32 v92, v92
	v_exp_f32_e32 v93, v93
	v_exp_f32_e32 v94, v94
	v_exp_f32_e32 v95, v95
	v_add_f32_e32 v92, 1.0, v92
	v_add_f32_e32 v93, 1.0, v93
	v_add_f32_e32 v94, 1.0, v94
	v_add_f32_e32 v95, 1.0, v95
	v_rcp_f32_e32 v92, v92
	v_rcp_f32_e32 v93, v93
	v_rcp_f32_e32 v94, v94
	v_rcp_f32_e32 v95, v95
	v_fma_f32 v96, v72, v92, v68
	v_fma_f32 v97, v73, v93, v69
	v_fma_f32 v98, v74, v94, v70
	v_fma_f32 v99, v75, v95, v71
	v_cmp_gt_f32_e64 s[22:23], s30, v96
	v_cmp_gt_f32_e64 s[24:25], s30, v97
	v_cmp_gt_f32_e64 s[26:27], s30, v98
	v_cmp_gt_f32_e64 s[28:29], s30, v99
	v_cndmask_b32_e64 v92, 0, 32, s[22:23]
	v_cndmask_b32_e64 v93, 0, 32, s[24:25]
	v_cndmask_b32_e64 v94, 0, 32, s[26:27]
	v_cndmask_b32_e64 v95, 0, 32, s[28:29]
	v_ldexp_f32 v92, v96, v92
; DEV u16 f2bf(float f) { return (u16)(pack2(f, f) & 0xffffu); }
; DEV float bf2f(u16 h) { return __uint_as_float(((unsigned)h) << 16); }
; DEV float sigmoid_f(float x) { return __builtin_amdgcn_rcpf(1.f + __expf(-x)); }
; DEV void phase_p15(const Params& p, int g) {
;     ...
;       if (j8 < 6) { P15_LOAD((j8 + 2) % 3, j8 + 2); }
; #pragma unroll
;       for (int cc = 0; cc < 2; ++cc) {
;         const int c = tid + 256 * cc;
;         unsigned kb[8];
; #pragma unroll
;         for (int e = 0; e < 8; ++e) {
;           const int jj = j8 * 8 + e;
;           const int j = dir ? 63 - jj : jj;
;           const size_t tok = (size_t)cidx * 64 + j;
;           const float f = lb[cc] + (1.f - lb[cc]) * sigmoid_f(bf2f(xr[st][cc][e]));
;           G[cc] += __logf(f);
;           const float eg = __expf(G[cc]), ig = __expf(-G[cc]);
;           Qp[tok * 512 + c] = f2bf(bf2f(qr[st][cc][e]) * eg);
;           const u16 kk = f2bf((1.f - f) * ig);
;           Kp[tok * 512 + c] = kk;
;           kb[e] = kk;
;         }
;     ...
;         w.x = dir ? (kb[7] | (kb[6] << 16)) : (kb[0] | (kb[1] << 16));
;         w.y = dir ? (kb[5] | (kb[4] << 16)) : (kb[2] | (kb[3] << 16));
;         w.z = dir ? (kb[3] | (kb[2] << 16)) : (kb[4] | (kb[5] << 16));
;         w.w = dir ? (kb[1] | (kb[0] << 16)) : (kb[6] | (kb[7] << 16));
	v_ldexp_f32 v93, v97, v93
	v_ldexp_f32 v94, v98, v94
	v_ldexp_f32 v95, v99, v95
	v_log_f32_e32 v92, v92
	v_log_f32_e32 v93, v93
	v_log_f32_e32 v94, v94
	v_log_f32_e32 v95, v95
	v_mul_f32_e32 v100, 0x3f317217, v92
	v_mul_f32_e32 v101, 0x3f317217, v93
	v_mul_f32_e32 v102, 0x3f317217, v94
	v_mul_f32_e32 v103, 0x3f317217, v95
	v_fma_f32 v100, v92, s31, -v100
	v_fma_f32 v101, v93, s31, -v101
	v_fma_f32 v102, v94, s31, -v102
	v_fma_f32 v103, v95, s31, -v103
	v_fmac_f32_e32 v100, 0x3377d1cf, v92
	v_fmac_f32_e32 v101, 0x3377d1cf, v93
	v_fmac_f32_e32 v102, 0x3377d1cf, v94
	v_fmac_f32_e32 v103, 0x3377d1cf, v95
	v_fmac_f32_e32 v100, 0x3f317217, v92
	v_fmac_f32_e32 v101, 0x3f317217, v93
	v_fmac_f32_e32 v102, 0x3f317217, v94
	v_fmac_f32_e32 v103, 0x3f317217, v95
	v_cmp_lt_f32_e64 vcc, |v92|, s34
	v_cndmask_b32_e32 v92, v92, v100, vcc
	v_cmp_lt_f32_e64 vcc, |v93|, s34
	v_cndmask_b32_e32 v93, v93, v101, vcc
	v_cmp_lt_f32_e64 vcc, |v94|, s34
	v_cndmask_b32_e32 v94, v94, v102, vcc
	v_cmp_lt_f32_e64 vcc, |v95|, s34
	v_cndmask_b32_e32 v95, v95, v103, vcc
	v_cndmask_b32_e64 v100, 0, v213, s[22:23]
	v_cndmask_b32_e64 v101, 0, v213, s[24:25]
	v_cndmask_b32_e64 v102, 0, v213, s[26:27]
	v_cndmask_b32_e64 v103, 0, v213, s[28:29]
	v_sub_f32_e32 v92, v92, v100
	v_sub_f32_e32 v93, v93, v101
	v_sub_f32_e32 v94, v94, v102
	v_sub_f32_e32 v95, v95, v103
	v_add_f32_e32 v64, v64, v92
	v_add_f32_e32 v65, v65, v93
	v_add_f32_e32 v66, v66, v94
	v_add_f32_e32 v67, v67, v95
	v_mul_f32_e32 v92, 0xbfb8aa3b, v64
	v_mul_f32_e32 v93, 0xbfb8aa3b, v65
	v_mul_f32_e32 v94, 0xbfb8aa3b, v66
	v_mul_f32_e32 v95, 0xbfb8aa3b, v67
	v_mul_f32_e32 v100, 0x3fb8aa3b, v64
	v_mul_f32_e32 v101, 0x3fb8aa3b, v65
	v_mul_f32_e32 v102, 0x3fb8aa3b, v66
	v_mul_f32_e32 v103, 0x3fb8aa3b, v67
	v_exp_f32_e32 v92, v92
	v_exp_f32_e32 v93, v93
	v_exp_f32_e32 v94, v94
	v_exp_f32_e32 v95, v95
	v_exp_f32_e32 v100, v100
	v_exp_f32_e32 v101, v101
	v_exp_f32_e32 v102, v102
	v_exp_f32_e32 v103, v103
	v_sub_f32_e32 v96, 1.0, v96
	v_sub_f32_e32 v97, 1.0, v97
	v_sub_f32_e32 v98, 1.0, v98
	v_sub_f32_e32 v99, 1.0, v99
	v_mul_f32_e32 v96, v96, v92
	v_mul_f32_e32 v97, v97, v93
	v_mul_f32_e32 v98, v98, v94
	v_mul_f32_e32 v99, v99, v95
	v_lshlrev_b32_e32 v92, 16, v30
	v_and_b32_e32 v93, 0xffff0000, v30
	v_lshlrev_b32_e32 v94, 16, v31
	v_and_b32_e32 v95, 0xffff0000, v31
	v_mul_f32_e32 v92, v92, v100
	v_mul_f32_e32 v93, v93, v101
	v_mul_f32_e32 v94, v94, v102
	v_mul_f32_e32 v95, v95, v103
	v_cvt_pk_bf16_f32 v108, v92, v93
	v_cvt_pk_bf16_f32 v109, v94, v95
	v_cvt_pk_bf16_f32 v110, v96, v97
	v_cvt_pk_bf16_f32 v111, v98, v99
	global_store_dwordx2 v112, v[108:109], s[2:3]
	global_store_dwordx2 v114, v[110:111], s[2:3]
	s_add_u32 s2, s2, 0x400
	s_addc_u32 s3, s3, 0
	v_cvt_pk_bf16_f32 v119, v104, v96
	v_cvt_pk_bf16_f32 v135, v105, v97
	v_cvt_pk_bf16_f32 v169, v106, v98
	v_cvt_pk_bf16_f32 v185, v107, v99
	global_load_dwordx2 v[0:1], v113, s[0:1]
	global_load_dwordx2 v[2:3], v112, s[0:1]
	s_add_u32 s0, s0, 0x1400
	s_addc_u32 s1, s1, 0
	global_load_dwordx2 v[4:5], v113, s[0:1]
	global_load_dwordx2 v[6:7], v112, s[0:1]
	s_add_u32 s0, s0, 0x1400
	s_addc_u32 s1, s1, 0
	global_load_dwordx2 v[8:9], v113, s[0:1]
	global_load_dwordx2 v[10:11], v112, s[0:1]
	s_add_u32 s0, s0, 0x1400
	s_addc_u32 s1, s1, 0
	global_load_dwordx2 v[12:13], v113, s[0:1]
	global_load_dwordx2 v[14:15], v112, s[0:1]
	s_add_u32 s0, s0, 0x1400
	s_addc_u32 s1, s1, 0
	global_load_dwordx2 v[16:17], v113, s[0:1]
	global_load_dwordx2 v[18:19], v112, s[0:1]
	s_add_u32 s0, s0, 0x1400
	s_addc_u32 s1, s1, 0
	global_load_dwordx2 v[20:21], v113, s[0:1]
	global_load_dwordx2 v[22:23], v112, s[0:1]
	s_add_u32 s0, s0, 0x1400
	s_addc_u32 s1, s1, 0
	global_load_dwordx2 v[24:25], v113, s[0:1]
	global_load_dwordx2 v[26:27], v112, s[0:1]
	s_add_u32 s0, s0, 0x1400
	s_addc_u32 s1, s1, 0
	global_load_dwordx2 v[28:29], v113, s[0:1]
	global_load_dwordx2 v[30:31], v112, s[0:1]
	s_add_u32 s0, s0, 0x1400
	s_addc_u32 s1, s1, 0
	s_waitcnt vmcnt(32)
	v_lshlrev_b32_e32 v92, 16, v32
	v_and_b32_e32 v93, 0xffff0000, v32
	v_lshlrev_b32_e32 v94, 16, v33
	v_and_b32_e32 v95, 0xffff0000, v33
	v_mul_f32_e32 v92, 0xbfb8aa3b, v92
	v_mul_f32_e32 v93, 0xbfb8aa3b, v93
	v_mul_f32_e32 v94, 0xbfb8aa3b, v94
	v_mul_f32_e32 v95, 0xbfb8aa3b, v95
	v_exp_f32_e32 v92, v92
	v_exp_f32_e32 v93, v93
	v_exp_f32_e32 v94, v94
	v_exp_f32_e32 v95, v95
	v_add_f32_e32 v92, 1.0, v92
	v_add_f32_e32 v93, 1.0, v93
	v_add_f32_e32 v94, 1.0, v94
	v_add_f32_e32 v95, 1.0, v95
	v_rcp_f32_e32 v92, v92
	v_rcp_f32_e32 v93, v93
	v_rcp_f32_e32 v94, v94
	v_rcp_f32_e32 v95, v95
	v_fma_f32 v96, v72, v92, v68
	v_fma_f32 v97, v73, v93, v69
	v_fma_f32 v98, v74, v94, v70
	v_fma_f32 v99, v75, v95, v71
	v_cmp_gt_f32_e64 s[22:23], s30, v96
	v_cmp_gt_f32_e64 s[24:25], s30, v97
	v_cmp_gt_f32_e64 s[26:27], s30, v98
	v_cmp_gt_f32_e64 s[28:29], s30, v99
	v_cndmask_b32_e64 v92, 0, 32, s[22:23]
	v_cndmask_b32_e64 v93, 0, 32, s[24:25]
	v_cndmask_b32_e64 v94, 0, 32, s[26:27]
	v_cndmask_b32_e64 v95, 0, 32, s[28:29]
	v_ldexp_f32 v92, v96, v92
	v_ldexp_f32 v93, v97, v93
	v_ldexp_f32 v94, v98, v94
	v_ldexp_f32 v95, v99, v95
	v_log_f32_e32 v92, v92
	v_log_f32_e32 v93, v93
	v_log_f32_e32 v94, v94
	v_log_f32_e32 v95, v95
	v_mul_f32_e32 v100, 0x3f317217, v92
	v_mul_f32_e32 v101, 0x3f317217, v93
	v_mul_f32_e32 v102, 0x3f317217, v94
	v_mul_f32_e32 v103, 0x3f317217, v95
	v_fma_f32 v100, v92, s31, -v100
	v_fma_f32 v101, v93, s31, -v101
	v_fma_f32 v102, v94, s31, -v102
	v_fma_f32 v103, v95, s31, -v103
	v_fmac_f32_e32 v100, 0x3377d1cf, v92
	v_fmac_f32_e32 v101, 0x3377d1cf, v93
	v_fmac_f32_e32 v102, 0x3377d1cf, v94
	v_fmac_f32_e32 v103, 0x3377d1cf, v95
	v_fmac_f32_e32 v100, 0x3f317217, v92
; DEV u16 f2bf(float f) { return (u16)(pack2(f, f) & 0xffffu); }
; DEV float bf2f(u16 h) { return __uint_as_float(((unsigned)h) << 16); }
; DEV float sigmoid_f(float x) { return __builtin_amdgcn_rcpf(1.f + __expf(-x)); }
; DEV void phase_p15(const Params& p, int g) {
;     ...
;         for (int e = 0; e < 8; ++e) {
;           const int jj = j8 * 8 + e;
;           const int j = dir ? 63 - jj : jj;
;           const size_t tok = (size_t)cidx * 64 + j;
;           const float f = lb[cc] + (1.f - lb[cc]) * sigmoid_f(bf2f(xr[st][cc][e]));
;           G[cc] += __logf(f);
;           const float eg = __expf(G[cc]), ig = __expf(-G[cc]);
;           Qp[tok * 512 + c] = f2bf(bf2f(qr[st][cc][e]) * eg);
;           const u16 kk = f2bf((1.f - f) * ig);
;           Kp[tok * 512 + c] = kk;
;           kb[e] = kk;
;         }
	v_fmac_f32_e32 v101, 0x3f317217, v93
	v_fmac_f32_e32 v102, 0x3f317217, v94
	v_fmac_f32_e32 v103, 0x3f317217, v95
	v_cmp_lt_f32_e64 vcc, |v92|, s34
	v_cndmask_b32_e32 v92, v92, v100, vcc
	v_cmp_lt_f32_e64 vcc, |v93|, s34
	v_cndmask_b32_e32 v93, v93, v101, vcc
	v_cmp_lt_f32_e64 vcc, |v94|, s34
	v_cndmask_b32_e32 v94, v94, v102, vcc
	v_cmp_lt_f32_e64 vcc, |v95|, s34
	v_cndmask_b32_e32 v95, v95, v103, vcc
	v_cndmask_b32_e64 v100, 0, v213, s[22:23]
	v_cndmask_b32_e64 v101, 0, v213, s[24:25]
	v_cndmask_b32_e64 v102, 0, v213, s[26:27]
	v_cndmask_b32_e64 v103, 0, v213, s[28:29]
	v_sub_f32_e32 v92, v92, v100
	v_sub_f32_e32 v93, v93, v101
	v_sub_f32_e32 v94, v94, v102
	v_sub_f32_e32 v95, v95, v103
	v_add_f32_e32 v64, v64, v92
	v_add_f32_e32 v65, v65, v93
	v_add_f32_e32 v66, v66, v94
	v_add_f32_e32 v67, v67, v95
	v_mul_f32_e32 v92, 0xbfb8aa3b, v64
	v_mul_f32_e32 v93, 0xbfb8aa3b, v65
	v_mul_f32_e32 v94, 0xbfb8aa3b, v66
	v_mul_f32_e32 v95, 0xbfb8aa3b, v67
	v_mul_f32_e32 v100, 0x3fb8aa3b, v64
	v_mul_f32_e32 v101, 0x3fb8aa3b, v65
	v_mul_f32_e32 v102, 0x3fb8aa3b, v66
	v_mul_f32_e32 v103, 0x3fb8aa3b, v67
	v_exp_f32_e32 v92, v92
	v_exp_f32_e32 v93, v93
	v_exp_f32_e32 v94, v94
	v_exp_f32_e32 v95, v95
	v_exp_f32_e32 v100, v100
	v_exp_f32_e32 v101, v101
	v_exp_f32_e32 v102, v102
	v_exp_f32_e32 v103, v103
	v_sub_f32_e32 v96, 1.0, v96
	v_sub_f32_e32 v97, 1.0, v97
	v_sub_f32_e32 v98, 1.0, v98
	v_sub_f32_e32 v99, 1.0, v99
	v_mul_f32_e32 v96, v96, v92
	v_mul_f32_e32 v97, v97, v93
	v_mul_f32_e32 v98, v98, v94
	v_mul_f32_e32 v99, v99, v95
	v_lshlrev_b32_e32 v92, 16, v34
	v_and_b32_e32 v93, 0xffff0000, v34
	v_lshlrev_b32_e32 v94, 16, v35
	v_and_b32_e32 v95, 0xffff0000, v35
	v_mul_f32_e32 v92, v92, v100
	v_mul_f32_e32 v93, v93, v101
	v_mul_f32_e32 v94, v94, v102
	v_mul_f32_e32 v95, v95, v103
	v_cvt_pk_bf16_f32 v108, v92, v93
	v_cvt_pk_bf16_f32 v109, v94, v95
	v_cvt_pk_bf16_f32 v110, v96, v97
	v_cvt_pk_bf16_f32 v111, v98, v99
	global_store_dwordx2 v112, v[108:109], s[2:3]
	global_store_dwordx2 v114, v[110:111], s[2:3]
	s_add_u32 s2, s2, 0x400
	s_addc_u32 s3, s3, 0
	v_mov_b32_e32 v104, v96
	v_mov_b32_e32 v105, v97
	v_mov_b32_e32 v106, v98
	v_mov_b32_e32 v107, v99
	v_lshlrev_b32_e32 v92, 16, v36
	v_and_b32_e32 v93, 0xffff0000, v36
	v_lshlrev_b32_e32 v94, 16, v37
	v_and_b32_e32 v95, 0xffff0000, v37
	v_mul_f32_e32 v92, 0xbfb8aa3b, v92
	v_mul_f32_e32 v93, 0xbfb8aa3b, v93
	v_mul_f32_e32 v94, 0xbfb8aa3b, v94
	v_mul_f32_e32 v95, 0xbfb8aa3b, v95
	v_exp_f32_e32 v92, v92
	v_exp_f32_e32 v93, v93
	v_exp_f32_e32 v94, v94
	v_exp_f32_e32 v95, v95
	v_add_f32_e32 v92, 1.0, v92
	v_add_f32_e32 v93, 1.0, v93
	v_add_f32_e32 v94, 1.0, v94
	v_add_f32_e32 v95, 1.0, v95
	v_rcp_f32_e32 v92, v92
	v_rcp_f32_e32 v93, v93
	v_rcp_f32_e32 v94, v94
	v_rcp_f32_e32 v95, v95
	v_fma_f32 v96, v72, v92, v68
	v_fma_f32 v97, v73, v93, v69
	v_fma_f32 v98, v74, v94, v70
	v_fma_f32 v99, v75, v95, v71
	v_cmp_gt_f32_e64 s[22:23], s30, v96
	v_cmp_gt_f32_e64 s[24:25], s30, v97
	v_cmp_gt_f32_e64 s[26:27], s30, v98
	v_cmp_gt_f32_e64 s[28:29], s30, v99
	v_cndmask_b32_e64 v92, 0, 32, s[22:23]
	v_cndmask_b32_e64 v93, 0, 32, s[24:25]
	v_cndmask_b32_e64 v94, 0, 32, s[26:27]
	v_cndmask_b32_e64 v95, 0, 32, s[28:29]
	v_ldexp_f32 v92, v96, v92
	v_ldexp_f32 v93, v97, v93
	v_ldexp_f32 v94, v98, v94
	v_ldexp_f32 v95, v99, v95
	v_log_f32_e32 v92, v92
	v_log_f32_e32 v93, v93
	v_log_f32_e32 v94, v94
	v_log_f32_e32 v95, v95
	v_mul_f32_e32 v100, 0x3f317217, v92
	v_mul_f32_e32 v101, 0x3f317217, v93
	v_mul_f32_e32 v102, 0x3f317217, v94
	v_mul_f32_e32 v103, 0x3f317217, v95
	v_fma_f32 v100, v92, s31, -v100
	v_fma_f32 v101, v93, s31, -v101
	v_fma_f32 v102, v94, s31, -v102
	v_fma_f32 v103, v95, s31, -v103
	v_fmac_f32_e32 v100, 0x3377d1cf, v92
	v_fmac_f32_e32 v101, 0x3377d1cf, v93
	v_fmac_f32_e32 v102, 0x3377d1cf, v94
	v_fmac_f32_e32 v103, 0x3377d1cf, v95
	v_fmac_f32_e32 v100, 0x3f317217, v92
	v_fmac_f32_e32 v101, 0x3f317217, v93
	v_fmac_f32_e32 v102, 0x3f317217, v94
	v_fmac_f32_e32 v103, 0x3f317217, v95
	v_cmp_lt_f32_e64 vcc, |v92|, s34
	v_cndmask_b32_e32 v92, v92, v100, vcc
	v_cmp_lt_f32_e64 vcc, |v93|, s34
	v_cndmask_b32_e32 v93, v93, v101, vcc
	v_cmp_lt_f32_e64 vcc, |v94|, s34
	v_cndmask_b32_e32 v94, v94, v102, vcc
	v_cmp_lt_f32_e64 vcc, |v95|, s34
	v_cndmask_b32_e32 v95, v95, v103, vcc
	v_cndmask_b32_e64 v100, 0, v213, s[22:23]
	v_cndmask_b32_e64 v101, 0, v213, s[24:25]
	v_cndmask_b32_e64 v102, 0, v213, s[26:27]
	v_cndmask_b32_e64 v103, 0, v213, s[28:29]
	v_sub_f32_e32 v92, v92, v100
	v_sub_f32_e32 v93, v93, v101
	v_sub_f32_e32 v94, v94, v102
	v_sub_f32_e32 v95, v95, v103
	v_add_f32_e32 v64, v64, v92
	v_add_f32_e32 v65, v65, v93
	v_add_f32_e32 v66, v66, v94
	v_add_f32_e32 v67, v67, v95
	v_mul_f32_e32 v92, 0xbfb8aa3b, v64
	v_mul_f32_e32 v93, 0xbfb8aa3b, v65
	v_mul_f32_e32 v94, 0xbfb8aa3b, v66
	v_mul_f32_e32 v95, 0xbfb8aa3b, v67
	v_mul_f32_e32 v100, 0x3fb8aa3b, v64
	v_mul_f32_e32 v101, 0x3fb8aa3b, v65
	v_mul_f32_e32 v102, 0x3fb8aa3b, v66
	v_mul_f32_e32 v103, 0x3fb8aa3b, v67
	v_exp_f32_e32 v92, v92
	v_exp_f32_e32 v93, v93
	v_exp_f32_e32 v94, v94
	v_exp_f32_e32 v95, v95
	v_exp_f32_e32 v100, v100
	v_exp_f32_e32 v101, v101
	v_exp_f32_e32 v102, v102
	v_exp_f32_e32 v103, v103
	v_sub_f32_e32 v96, 1.0, v96
	v_sub_f32_e32 v97, 1.0, v97
	v_sub_f32_e32 v98, 1.0, v98
	v_sub_f32_e32 v99, 1.0, v99
	v_mul_f32_e32 v96, v96, v92
	v_mul_f32_e32 v97, v97, v93
	v_mul_f32_e32 v98, v98, v94
	v_mul_f32_e32 v99, v99, v95
	v_lshlrev_b32_e32 v92, 16, v38
	v_and_b32_e32 v93, 0xffff0000, v38
	v_lshlrev_b32_e32 v94, 16, v39
	v_and_b32_e32 v95, 0xffff0000, v39
	v_mul_f32_e32 v92, v92, v100
	v_mul_f32_e32 v93, v93, v101
	v_mul_f32_e32 v94, v94, v102
; DEV u16 f2bf(float f) { return (u16)(pack2(f, f) & 0xffffu); }
; DEV float bf2f(u16 h) { return __uint_as_float(((unsigned)h) << 16); }
; DEV float sigmoid_f(float x) { return __builtin_amdgcn_rcpf(1.f + __expf(-x)); }
; DEV void phase_p15(const Params& p, int g) {
;     ...
;         for (int e = 0; e < 8; ++e) {
;           const int jj = j8 * 8 + e;
;           const int j = dir ? 63 - jj : jj;
;           const size_t tok = (size_t)cidx * 64 + j;
;           const float f = lb[cc] + (1.f - lb[cc]) * sigmoid_f(bf2f(xr[st][cc][e]));
;           G[cc] += __logf(f);
;           const float eg = __expf(G[cc]), ig = __expf(-G[cc]);
;           Qp[tok * 512 + c] = f2bf(bf2f(qr[st][cc][e]) * eg);
;           const u16 kk = f2bf((1.f - f) * ig);
;           Kp[tok * 512 + c] = kk;
;           kb[e] = kk;
;         }
;     ...
;         w.x = dir ? (kb[7] | (kb[6] << 16)) : (kb[0] | (kb[1] << 16));
;         w.y = dir ? (kb[5] | (kb[4] << 16)) : (kb[2] | (kb[3] << 16));
;         w.z = dir ? (kb[3] | (kb[2] << 16)) : (kb[4] | (kb[5] << 16));
;         w.w = dir ? (kb[1] | (kb[0] << 16)) : (kb[6] | (kb[7] << 16));
	v_mul_f32_e32 v95, v95, v103
	v_cvt_pk_bf16_f32 v108, v92, v93
	v_cvt_pk_bf16_f32 v109, v94, v95
	v_cvt_pk_bf16_f32 v110, v96, v97
	v_cvt_pk_bf16_f32 v111, v98, v99
	global_store_dwordx2 v112, v[108:109], s[2:3]
	global_store_dwordx2 v114, v[110:111], s[2:3]
	s_add_u32 s2, s2, 0x400
	s_addc_u32 s3, s3, 0
	v_cvt_pk_bf16_f32 v120, v104, v96
	v_cvt_pk_bf16_f32 v136, v105, v97
	v_cvt_pk_bf16_f32 v170, v106, v98
	v_cvt_pk_bf16_f32 v186, v107, v99
	v_lshlrev_b32_e32 v92, 16, v40
	v_and_b32_e32 v93, 0xffff0000, v40
	v_lshlrev_b32_e32 v94, 16, v41
	v_and_b32_e32 v95, 0xffff0000, v41
	v_mul_f32_e32 v92, 0xbfb8aa3b, v92
	v_mul_f32_e32 v93, 0xbfb8aa3b, v93
	v_mul_f32_e32 v94, 0xbfb8aa3b, v94
	v_mul_f32_e32 v95, 0xbfb8aa3b, v95
	v_exp_f32_e32 v92, v92
	v_exp_f32_e32 v93, v93
	v_exp_f32_e32 v94, v94
	v_exp_f32_e32 v95, v95
	v_add_f32_e32 v92, 1.0, v92
	v_add_f32_e32 v93, 1.0, v93
	v_add_f32_e32 v94, 1.0, v94
	v_add_f32_e32 v95, 1.0, v95
	v_rcp_f32_e32 v92, v92
	v_rcp_f32_e32 v93, v93
	v_rcp_f32_e32 v94, v94
	v_rcp_f32_e32 v95, v95
	v_fma_f32 v96, v72, v92, v68
	v_fma_f32 v97, v73, v93, v69
	v_fma_f32 v98, v74, v94, v70
	v_fma_f32 v99, v75, v95, v71
	v_cmp_gt_f32_e64 s[22:23], s30, v96
	v_cmp_gt_f32_e64 s[24:25], s30, v97
	v_cmp_gt_f32_e64 s[26:27], s30, v98
	v_cmp_gt_f32_e64 s[28:29], s30, v99
	v_cndmask_b32_e64 v92, 0, 32, s[22:23]
	v_cndmask_b32_e64 v93, 0, 32, s[24:25]
	v_cndmask_b32_e64 v94, 0, 32, s[26:27]
	v_cndmask_b32_e64 v95, 0, 32, s[28:29]
	v_ldexp_f32 v92, v96, v92
	v_ldexp_f32 v93, v97, v93
	v_ldexp_f32 v94, v98, v94
	v_ldexp_f32 v95, v99, v95
	v_log_f32_e32 v92, v92
	v_log_f32_e32 v93, v93
	v_log_f32_e32 v94, v94
	v_log_f32_e32 v95, v95
	v_mul_f32_e32 v100, 0x3f317217, v92
	v_mul_f32_e32 v101, 0x3f317217, v93
	v_mul_f32_e32 v102, 0x3f317217, v94
	v_mul_f32_e32 v103, 0x3f317217, v95
	v_fma_f32 v100, v92, s31, -v100
	v_fma_f32 v101, v93, s31, -v101
	v_fma_f32 v102, v94, s31, -v102
	v_fma_f32 v103, v95, s31, -v103
	v_fmac_f32_e32 v100, 0x3377d1cf, v92
	v_fmac_f32_e32 v101, 0x3377d1cf, v93
	v_fmac_f32_e32 v102, 0x3377d1cf, v94
	v_fmac_f32_e32 v103, 0x3377d1cf, v95
	v_fmac_f32_e32 v100, 0x3f317217, v92
	v_fmac_f32_e32 v101, 0x3f317217, v93
	v_fmac_f32_e32 v102, 0x3f317217, v94
	v_fmac_f32_e32 v103, 0x3f317217, v95
	v_cmp_lt_f32_e64 vcc, |v92|, s34
	v_cndmask_b32_e32 v92, v92, v100, vcc
	v_cmp_lt_f32_e64 vcc, |v93|, s34
	v_cndmask_b32_e32 v93, v93, v101, vcc
	v_cmp_lt_f32_e64 vcc, |v94|, s34
	v_cndmask_b32_e32 v94, v94, v102, vcc
	v_cmp_lt_f32_e64 vcc, |v95|, s34
	v_cndmask_b32_e32 v95, v95, v103, vcc
	v_cndmask_b32_e64 v100, 0, v213, s[22:23]
	v_cndmask_b32_e64 v101, 0, v213, s[24:25]
	v_cndmask_b32_e64 v102, 0, v213, s[26:27]
	v_cndmask_b32_e64 v103, 0, v213, s[28:29]
	v_sub_f32_e32 v92, v92, v100
	v_sub_f32_e32 v93, v93, v101
	v_sub_f32_e32 v94, v94, v102
	v_sub_f32_e32 v95, v95, v103
	v_add_f32_e32 v64, v64, v92
	v_add_f32_e32 v65, v65, v93
	v_add_f32_e32 v66, v66, v94
	v_add_f32_e32 v67, v67, v95
	v_mul_f32_e32 v92, 0xbfb8aa3b, v64
	v_mul_f32_e32 v93, 0xbfb8aa3b, v65
	v_mul_f32_e32 v94, 0xbfb8aa3b, v66
	v_mul_f32_e32 v95, 0xbfb8aa3b, v67
	v_mul_f32_e32 v100, 0x3fb8aa3b, v64
	v_mul_f32_e32 v101, 0x3fb8aa3b, v65
	v_mul_f32_e32 v102, 0x3fb8aa3b, v66
	v_mul_f32_e32 v103, 0x3fb8aa3b, v67
	v_exp_f32_e32 v92, v92
	v_exp_f32_e32 v93, v93
	v_exp_f32_e32 v94, v94
	v_exp_f32_e32 v95, v95
	v_exp_f32_e32 v100, v100
	v_exp_f32_e32 v101, v101
	v_exp_f32_e32 v102, v102
	v_exp_f32_e32 v103, v103
	v_sub_f32_e32 v96, 1.0, v96
	v_sub_f32_e32 v97, 1.0, v97
	v_sub_f32_e32 v98, 1.0, v98
	v_sub_f32_e32 v99, 1.0, v99
	v_mul_f32_e32 v96, v96, v92
	v_mul_f32_e32 v97, v97, v93
	v_mul_f32_e32 v98, v98, v94
	v_mul_f32_e32 v99, v99, v95
	v_lshlrev_b32_e32 v92, 16, v42
	v_and_b32_e32 v93, 0xffff0000, v42
	v_lshlrev_b32_e32 v94, 16, v43
	v_and_b32_e32 v95, 0xffff0000, v43
	v_mul_f32_e32 v92, v92, v100
	v_mul_f32_e32 v93, v93, v101
	v_mul_f32_e32 v94, v94, v102
	v_mul_f32_e32 v95, v95, v103
	v_cvt_pk_bf16_f32 v108, v92, v93
	v_cvt_pk_bf16_f32 v109, v94, v95
	v_cvt_pk_bf16_f32 v110, v96, v97
	v_cvt_pk_bf16_f32 v111, v98, v99
	global_store_dwordx2 v112, v[108:109], s[2:3]
	global_store_dwordx2 v114, v[110:111], s[2:3]
	s_add_u32 s2, s2, 0x400
	s_addc_u32 s3, s3, 0
	v_mov_b32_e32 v104, v96
	v_mov_b32_e32 v105, v97
	v_mov_b32_e32 v106, v98
	v_mov_b32_e32 v107, v99
	v_lshlrev_b32_e32 v92, 16, v44
	v_and_b32_e32 v93, 0xffff0000, v44
	v_lshlrev_b32_e32 v94, 16, v45
	v_and_b32_e32 v95, 0xffff0000, v45
	v_mul_f32_e32 v92, 0xbfb8aa3b, v92
	v_mul_f32_e32 v93, 0xbfb8aa3b, v93
	v_mul_f32_e32 v94, 0xbfb8aa3b, v94
	v_mul_f32_e32 v95, 0xbfb8aa3b, v95
	v_exp_f32_e32 v92, v92
	v_exp_f32_e32 v93, v93
	v_exp_f32_e32 v94, v94
	v_exp_f32_e32 v95, v95
	v_add_f32_e32 v92, 1.0, v92
	v_add_f32_e32 v93, 1.0, v93
	v_add_f32_e32 v94, 1.0, v94
	v_add_f32_e32 v95, 1.0, v95
	v_rcp_f32_e32 v92, v92
	v_rcp_f32_e32 v93, v93
	v_rcp_f32_e32 v94, v94
	v_rcp_f32_e32 v95, v95
	v_fma_f32 v96, v72, v92, v68
	v_fma_f32 v97, v73, v93, v69
	v_fma_f32 v98, v74, v94, v70
	v_fma_f32 v99, v75, v95, v71
	v_cmp_gt_f32_e64 s[22:23], s30, v96
	v_cmp_gt_f32_e64 s[24:25], s30, v97
	v_cmp_gt_f32_e64 s[26:27], s30, v98
	v_cmp_gt_f32_e64 s[28:29], s30, v99
	v_cndmask_b32_e64 v92, 0, 32, s[22:23]
	v_cndmask_b32_e64 v93, 0, 32, s[24:25]
	v_cndmask_b32_e64 v94, 0, 32, s[26:27]
	v_cndmask_b32_e64 v95, 0, 32, s[28:29]
	v_ldexp_f32 v92, v96, v92
	v_ldexp_f32 v93, v97, v93
	v_ldexp_f32 v94, v98, v94
	v_ldexp_f32 v95, v99, v95
	v_log_f32_e32 v92, v92
	v_log_f32_e32 v93, v93
	v_log_f32_e32 v94, v94
	v_log_f32_e32 v95, v95
	v_mul_f32_e32 v100, 0x3f317217, v92
	v_mul_f32_e32 v101, 0x3f317217, v93
	v_mul_f32_e32 v102, 0x3f317217, v94
; DEV u16 f2bf(float f) { return (u16)(pack2(f, f) & 0xffffu); }
; DEV float bf2f(u16 h) { return __uint_as_float(((unsigned)h) << 16); }
; DEV float sigmoid_f(float x) { return __builtin_amdgcn_rcpf(1.f + __expf(-x)); }
; DEV void phase_p15(const Params& p, int g) {
;     ...
;         for (int e = 0; e < 8; ++e) {
;           const int jj = j8 * 8 + e;
;           const int j = dir ? 63 - jj : jj;
;           const size_t tok = (size_t)cidx * 64 + j;
;           const float f = lb[cc] + (1.f - lb[cc]) * sigmoid_f(bf2f(xr[st][cc][e]));
;           G[cc] += __logf(f);
;           const float eg = __expf(G[cc]), ig = __expf(-G[cc]);
;           Qp[tok * 512 + c] = f2bf(bf2f(qr[st][cc][e]) * eg);
;           const u16 kk = f2bf((1.f - f) * ig);
;           Kp[tok * 512 + c] = kk;
;           kb[e] = kk;
;         }
;     ...
;         w.x = dir ? (kb[7] | (kb[6] << 16)) : (kb[0] | (kb[1] << 16));
;         w.y = dir ? (kb[5] | (kb[4] << 16)) : (kb[2] | (kb[3] << 16));
;         w.z = dir ? (kb[3] | (kb[2] << 16)) : (kb[4] | (kb[5] << 16));
;         w.w = dir ? (kb[1] | (kb[0] << 16)) : (kb[6] | (kb[7] << 16));
	v_mul_f32_e32 v103, 0x3f317217, v95
	v_fma_f32 v100, v92, s31, -v100
	v_fma_f32 v101, v93, s31, -v101
	v_fma_f32 v102, v94, s31, -v102
	v_fma_f32 v103, v95, s31, -v103
	v_fmac_f32_e32 v100, 0x3377d1cf, v92
	v_fmac_f32_e32 v101, 0x3377d1cf, v93
	v_fmac_f32_e32 v102, 0x3377d1cf, v94
	v_fmac_f32_e32 v103, 0x3377d1cf, v95
	v_fmac_f32_e32 v100, 0x3f317217, v92
	v_fmac_f32_e32 v101, 0x3f317217, v93
	v_fmac_f32_e32 v102, 0x3f317217, v94
	v_fmac_f32_e32 v103, 0x3f317217, v95
	v_cmp_lt_f32_e64 vcc, |v92|, s34
	v_cndmask_b32_e32 v92, v92, v100, vcc
	v_cmp_lt_f32_e64 vcc, |v93|, s34
	v_cndmask_b32_e32 v93, v93, v101, vcc
	v_cmp_lt_f32_e64 vcc, |v94|, s34
	v_cndmask_b32_e32 v94, v94, v102, vcc
	v_cmp_lt_f32_e64 vcc, |v95|, s34
	v_cndmask_b32_e32 v95, v95, v103, vcc
	v_cndmask_b32_e64 v100, 0, v213, s[22:23]
	v_cndmask_b32_e64 v101, 0, v213, s[24:25]
	v_cndmask_b32_e64 v102, 0, v213, s[26:27]
	v_cndmask_b32_e64 v103, 0, v213, s[28:29]
	v_sub_f32_e32 v92, v92, v100
	v_sub_f32_e32 v93, v93, v101
	v_sub_f32_e32 v94, v94, v102
	v_sub_f32_e32 v95, v95, v103
	v_add_f32_e32 v64, v64, v92
	v_add_f32_e32 v65, v65, v93
	v_add_f32_e32 v66, v66, v94
	v_add_f32_e32 v67, v67, v95
	v_mul_f32_e32 v92, 0xbfb8aa3b, v64
	v_mul_f32_e32 v93, 0xbfb8aa3b, v65
	v_mul_f32_e32 v94, 0xbfb8aa3b, v66
	v_mul_f32_e32 v95, 0xbfb8aa3b, v67
	v_mul_f32_e32 v100, 0x3fb8aa3b, v64
	v_mul_f32_e32 v101, 0x3fb8aa3b, v65
	v_mul_f32_e32 v102, 0x3fb8aa3b, v66
	v_mul_f32_e32 v103, 0x3fb8aa3b, v67
	v_exp_f32_e32 v92, v92
	v_exp_f32_e32 v93, v93
	v_exp_f32_e32 v94, v94
	v_exp_f32_e32 v95, v95
	v_exp_f32_e32 v100, v100
	v_exp_f32_e32 v101, v101
	v_exp_f32_e32 v102, v102
	v_exp_f32_e32 v103, v103
	v_sub_f32_e32 v96, 1.0, v96
	v_sub_f32_e32 v97, 1.0, v97
	v_sub_f32_e32 v98, 1.0, v98
	v_sub_f32_e32 v99, 1.0, v99
	v_mul_f32_e32 v96, v96, v92
	v_mul_f32_e32 v97, v97, v93
	v_mul_f32_e32 v98, v98, v94
	v_mul_f32_e32 v99, v99, v95
	v_lshlrev_b32_e32 v92, 16, v46
	v_and_b32_e32 v93, 0xffff0000, v46
	v_lshlrev_b32_e32 v94, 16, v47
	v_and_b32_e32 v95, 0xffff0000, v47
	v_mul_f32_e32 v92, v92, v100
	v_mul_f32_e32 v93, v93, v101
	v_mul_f32_e32 v94, v94, v102
	v_mul_f32_e32 v95, v95, v103
	v_cvt_pk_bf16_f32 v108, v92, v93
	v_cvt_pk_bf16_f32 v109, v94, v95
	v_cvt_pk_bf16_f32 v110, v96, v97
	v_cvt_pk_bf16_f32 v111, v98, v99
	global_store_dwordx2 v112, v[108:109], s[2:3]
	global_store_dwordx2 v114, v[110:111], s[2:3]
	s_add_u32 s2, s2, 0x400
	s_addc_u32 s3, s3, 0
	v_cvt_pk_bf16_f32 v121, v104, v96
	v_cvt_pk_bf16_f32 v137, v105, v97
	v_cvt_pk_bf16_f32 v171, v106, v98
	v_cvt_pk_bf16_f32 v187, v107, v99
	v_lshlrev_b32_e32 v92, 16, v48
	v_and_b32_e32 v93, 0xffff0000, v48
	v_lshlrev_b32_e32 v94, 16, v49
	v_and_b32_e32 v95, 0xffff0000, v49
	v_mul_f32_e32 v92, 0xbfb8aa3b, v92
	v_mul_f32_e32 v93, 0xbfb8aa3b, v93
	v_mul_f32_e32 v94, 0xbfb8aa3b, v94
	v_mul_f32_e32 v95, 0xbfb8aa3b, v95
	v_exp_f32_e32 v92, v92
	v_exp_f32_e32 v93, v93
	v_exp_f32_e32 v94, v94
	v_exp_f32_e32 v95, v95
	v_add_f32_e32 v92, 1.0, v92
	v_add_f32_e32 v93, 1.0, v93
	v_add_f32_e32 v94, 1.0, v94
	v_add_f32_e32 v95, 1.0, v95
	v_rcp_f32_e32 v92, v92
	v_rcp_f32_e32 v93, v93
	v_rcp_f32_e32 v94, v94
	v_rcp_f32_e32 v95, v95
	v_fma_f32 v96, v72, v92, v68
	v_fma_f32 v97, v73, v93, v69
	v_fma_f32 v98, v74, v94, v70
	v_fma_f32 v99, v75, v95, v71
	v_cmp_gt_f32_e64 s[22:23], s30, v96
	v_cmp_gt_f32_e64 s[24:25], s30, v97
	v_cmp_gt_f32_e64 s[26:27], s30, v98
	v_cmp_gt_f32_e64 s[28:29], s30, v99
	v_cndmask_b32_e64 v92, 0, 32, s[22:23]
	v_cndmask_b32_e64 v93, 0, 32, s[24:25]
	v_cndmask_b32_e64 v94, 0, 32, s[26:27]
	v_cndmask_b32_e64 v95, 0, 32, s[28:29]
	v_ldexp_f32 v92, v96, v92
	v_ldexp_f32 v93, v97, v93
	v_ldexp_f32 v94, v98, v94
	v_ldexp_f32 v95, v99, v95
	v_log_f32_e32 v92, v92
	v_log_f32_e32 v93, v93
	v_log_f32_e32 v94, v94
	v_log_f32_e32 v95, v95
	v_mul_f32_e32 v100, 0x3f317217, v92
	v_mul_f32_e32 v101, 0x3f317217, v93
	v_mul_f32_e32 v102, 0x3f317217, v94
	v_mul_f32_e32 v103, 0x3f317217, v95
	v_fma_f32 v100, v92, s31, -v100
	v_fma_f32 v101, v93, s31, -v101
	v_fma_f32 v102, v94, s31, -v102
	v_fma_f32 v103, v95, s31, -v103
	v_fmac_f32_e32 v100, 0x3377d1cf, v92
	v_fmac_f32_e32 v101, 0x3377d1cf, v93
	v_fmac_f32_e32 v102, 0x3377d1cf, v94
	v_fmac_f32_e32 v103, 0x3377d1cf, v95
	v_fmac_f32_e32 v100, 0x3f317217, v92
	v_fmac_f32_e32 v101, 0x3f317217, v93
	v_fmac_f32_e32 v102, 0x3f317217, v94
	v_fmac_f32_e32 v103, 0x3f317217, v95
	v_cmp_lt_f32_e64 vcc, |v92|, s34
	v_cndmask_b32_e32 v92, v92, v100, vcc
	v_cmp_lt_f32_e64 vcc, |v93|, s34
	v_cndmask_b32_e32 v93, v93, v101, vcc
	v_cmp_lt_f32_e64 vcc, |v94|, s34
	v_cndmask_b32_e32 v94, v94, v102, vcc
	v_cmp_lt_f32_e64 vcc, |v95|, s34
	v_cndmask_b32_e32 v95, v95, v103, vcc
	v_cndmask_b32_e64 v100, 0, v213, s[22:23]
	v_cndmask_b32_e64 v101, 0, v213, s[24:25]
	v_cndmask_b32_e64 v102, 0, v213, s[26:27]
	v_cndmask_b32_e64 v103, 0, v213, s[28:29]
	v_sub_f32_e32 v92, v92, v100
	v_sub_f32_e32 v93, v93, v101
	v_sub_f32_e32 v94, v94, v102
	v_sub_f32_e32 v95, v95, v103
	v_add_f32_e32 v64, v64, v92
	v_add_f32_e32 v65, v65, v93
	v_add_f32_e32 v66, v66, v94
	v_add_f32_e32 v67, v67, v95
	v_mul_f32_e32 v92, 0xbfb8aa3b, v64
	v_mul_f32_e32 v93, 0xbfb8aa3b, v65
	v_mul_f32_e32 v94, 0xbfb8aa3b, v66
	v_mul_f32_e32 v95, 0xbfb8aa3b, v67
	v_mul_f32_e32 v100, 0x3fb8aa3b, v64
	v_mul_f32_e32 v101, 0x3fb8aa3b, v65
	v_mul_f32_e32 v102, 0x3fb8aa3b, v66
	v_mul_f32_e32 v103, 0x3fb8aa3b, v67
	v_exp_f32_e32 v92, v92
	v_exp_f32_e32 v93, v93
	v_exp_f32_e32 v94, v94
	v_exp_f32_e32 v95, v95
	v_exp_f32_e32 v100, v100
	v_exp_f32_e32 v101, v101
	v_exp_f32_e32 v102, v102
	v_exp_f32_e32 v103, v103
	v_sub_f32_e32 v96, 1.0, v96
	v_sub_f32_e32 v97, 1.0, v97
	v_sub_f32_e32 v98, 1.0, v98
; DEV u16 f2bf(float f) { return (u16)(pack2(f, f) & 0xffffu); }
; DEV float bf2f(u16 h) { return __uint_as_float(((unsigned)h) << 16); }
; DEV float sigmoid_f(float x) { return __builtin_amdgcn_rcpf(1.f + __expf(-x)); }
; DEV void phase_p15(const Params& p, int g) {
;     ...
;         for (int e = 0; e < 8; ++e) {
;           const int jj = j8 * 8 + e;
;           const int j = dir ? 63 - jj : jj;
;           const size_t tok = (size_t)cidx * 64 + j;
;           const float f = lb[cc] + (1.f - lb[cc]) * sigmoid_f(bf2f(xr[st][cc][e]));
;           G[cc] += __logf(f);
;           const float eg = __expf(G[cc]), ig = __expf(-G[cc]);
;           Qp[tok * 512 + c] = f2bf(bf2f(qr[st][cc][e]) * eg);
;           const u16 kk = f2bf((1.f - f) * ig);
;           Kp[tok * 512 + c] = kk;
;           kb[e] = kk;
;         }
;     ...
;         w.x = dir ? (kb[7] | (kb[6] << 16)) : (kb[0] | (kb[1] << 16));
;         w.y = dir ? (kb[5] | (kb[4] << 16)) : (kb[2] | (kb[3] << 16));
;         w.z = dir ? (kb[3] | (kb[2] << 16)) : (kb[4] | (kb[5] << 16));
;         w.w = dir ? (kb[1] | (kb[0] << 16)) : (kb[6] | (kb[7] << 16));
	v_sub_f32_e32 v99, 1.0, v99
	v_mul_f32_e32 v96, v96, v92
	v_mul_f32_e32 v97, v97, v93
	v_mul_f32_e32 v98, v98, v94
	v_mul_f32_e32 v99, v99, v95
	v_lshlrev_b32_e32 v92, 16, v50
	v_and_b32_e32 v93, 0xffff0000, v50
	v_lshlrev_b32_e32 v94, 16, v51
	v_and_b32_e32 v95, 0xffff0000, v51
	v_mul_f32_e32 v92, v92, v100
	v_mul_f32_e32 v93, v93, v101
	v_mul_f32_e32 v94, v94, v102
	v_mul_f32_e32 v95, v95, v103
	v_cvt_pk_bf16_f32 v108, v92, v93
	v_cvt_pk_bf16_f32 v109, v94, v95
	v_cvt_pk_bf16_f32 v110, v96, v97
	v_cvt_pk_bf16_f32 v111, v98, v99
	global_store_dwordx2 v112, v[108:109], s[2:3]
	global_store_dwordx2 v114, v[110:111], s[2:3]
	s_add_u32 s2, s2, 0x400
	s_addc_u32 s3, s3, 0
	v_mov_b32_e32 v104, v96
	v_mov_b32_e32 v105, v97
	v_mov_b32_e32 v106, v98
	v_mov_b32_e32 v107, v99
	v_lshlrev_b32_e32 v92, 16, v52
	v_and_b32_e32 v93, 0xffff0000, v52
	v_lshlrev_b32_e32 v94, 16, v53
	v_and_b32_e32 v95, 0xffff0000, v53
	v_mul_f32_e32 v92, 0xbfb8aa3b, v92
	v_mul_f32_e32 v93, 0xbfb8aa3b, v93
	v_mul_f32_e32 v94, 0xbfb8aa3b, v94
	v_mul_f32_e32 v95, 0xbfb8aa3b, v95
	v_exp_f32_e32 v92, v92
	v_exp_f32_e32 v93, v93
	v_exp_f32_e32 v94, v94
	v_exp_f32_e32 v95, v95
	v_add_f32_e32 v92, 1.0, v92
	v_add_f32_e32 v93, 1.0, v93
	v_add_f32_e32 v94, 1.0, v94
	v_add_f32_e32 v95, 1.0, v95
	v_rcp_f32_e32 v92, v92
	v_rcp_f32_e32 v93, v93
	v_rcp_f32_e32 v94, v94
	v_rcp_f32_e32 v95, v95
	v_fma_f32 v96, v72, v92, v68
	v_fma_f32 v97, v73, v93, v69
	v_fma_f32 v98, v74, v94, v70
	v_fma_f32 v99, v75, v95, v71
	v_cmp_gt_f32_e64 s[22:23], s30, v96
	v_cmp_gt_f32_e64 s[24:25], s30, v97
	v_cmp_gt_f32_e64 s[26:27], s30, v98
	v_cmp_gt_f32_e64 s[28:29], s30, v99
	v_cndmask_b32_e64 v92, 0, 32, s[22:23]
	v_cndmask_b32_e64 v93, 0, 32, s[24:25]
	v_cndmask_b32_e64 v94, 0, 32, s[26:27]
	v_cndmask_b32_e64 v95, 0, 32, s[28:29]
	v_ldexp_f32 v92, v96, v92
	v_ldexp_f32 v93, v97, v93
	v_ldexp_f32 v94, v98, v94
	v_ldexp_f32 v95, v99, v95
	v_log_f32_e32 v92, v92
	v_log_f32_e32 v93, v93
	v_log_f32_e32 v94, v94
	v_log_f32_e32 v95, v95
	v_mul_f32_e32 v100, 0x3f317217, v92
	v_mul_f32_e32 v101, 0x3f317217, v93
	v_mul_f32_e32 v102, 0x3f317217, v94
	v_mul_f32_e32 v103, 0x3f317217, v95
	v_fma_f32 v100, v92, s31, -v100
	v_fma_f32 v101, v93, s31, -v101
	v_fma_f32 v102, v94, s31, -v102
	v_fma_f32 v103, v95, s31, -v103
	v_fmac_f32_e32 v100, 0x3377d1cf, v92
	v_fmac_f32_e32 v101, 0x3377d1cf, v93
	v_fmac_f32_e32 v102, 0x3377d1cf, v94
	v_fmac_f32_e32 v103, 0x3377d1cf, v95
	v_fmac_f32_e32 v100, 0x3f317217, v92
	v_fmac_f32_e32 v101, 0x3f317217, v93
	v_fmac_f32_e32 v102, 0x3f317217, v94
	v_fmac_f32_e32 v103, 0x3f317217, v95
	v_cmp_lt_f32_e64 vcc, |v92|, s34
	v_cndmask_b32_e32 v92, v92, v100, vcc
	v_cmp_lt_f32_e64 vcc, |v93|, s34
	v_cndmask_b32_e32 v93, v93, v101, vcc
	v_cmp_lt_f32_e64 vcc, |v94|, s34
	v_cndmask_b32_e32 v94, v94, v102, vcc
	v_cmp_lt_f32_e64 vcc, |v95|, s34
	v_cndmask_b32_e32 v95, v95, v103, vcc
	v_cndmask_b32_e64 v100, 0, v213, s[22:23]
	v_cndmask_b32_e64 v101, 0, v213, s[24:25]
	v_cndmask_b32_e64 v102, 0, v213, s[26:27]
	v_cndmask_b32_e64 v103, 0, v213, s[28:29]
	v_sub_f32_e32 v92, v92, v100
	v_sub_f32_e32 v93, v93, v101
	v_sub_f32_e32 v94, v94, v102
	v_sub_f32_e32 v95, v95, v103
	v_add_f32_e32 v64, v64, v92
	v_add_f32_e32 v65, v65, v93
	v_add_f32_e32 v66, v66, v94
	v_add_f32_e32 v67, v67, v95
	v_mul_f32_e32 v92, 0xbfb8aa3b, v64
	v_mul_f32_e32 v93, 0xbfb8aa3b, v65
	v_mul_f32_e32 v94, 0xbfb8aa3b, v66
	v_mul_f32_e32 v95, 0xbfb8aa3b, v67
	v_mul_f32_e32 v100, 0x3fb8aa3b, v64
	v_mul_f32_e32 v101, 0x3fb8aa3b, v65
	v_mul_f32_e32 v102, 0x3fb8aa3b, v66
	v_mul_f32_e32 v103, 0x3fb8aa3b, v67
	v_exp_f32_e32 v92, v92
	v_exp_f32_e32 v93, v93
	v_exp_f32_e32 v94, v94
	v_exp_f32_e32 v95, v95
	v_exp_f32_e32 v100, v100
	v_exp_f32_e32 v101, v101
	v_exp_f32_e32 v102, v102
	v_exp_f32_e32 v103, v103
	v_sub_f32_e32 v96, 1.0, v96
	v_sub_f32_e32 v97, 1.0, v97
	v_sub_f32_e32 v98, 1.0, v98
	v_sub_f32_e32 v99, 1.0, v99
	v_mul_f32_e32 v96, v96, v92
	v_mul_f32_e32 v97, v97, v93
	v_mul_f32_e32 v98, v98, v94
	v_mul_f32_e32 v99, v99, v95
	v_lshlrev_b32_e32 v92, 16, v54
	v_and_b32_e32 v93, 0xffff0000, v54
	v_lshlrev_b32_e32 v94, 16, v55
	v_and_b32_e32 v95, 0xffff0000, v55
	v_mul_f32_e32 v92, v92, v100
	v_mul_f32_e32 v93, v93, v101
	v_mul_f32_e32 v94, v94, v102
	v_mul_f32_e32 v95, v95, v103
	v_cvt_pk_bf16_f32 v108, v92, v93
	v_cvt_pk_bf16_f32 v109, v94, v95
	v_cvt_pk_bf16_f32 v110, v96, v97
	v_cvt_pk_bf16_f32 v111, v98, v99
	global_store_dwordx2 v112, v[108:109], s[2:3]
	global_store_dwordx2 v114, v[110:111], s[2:3]
	s_add_u32 s2, s2, 0x400
	s_addc_u32 s3, s3, 0
	v_cvt_pk_bf16_f32 v122, v104, v96
	v_cvt_pk_bf16_f32 v138, v105, v97
	v_cvt_pk_bf16_f32 v172, v106, v98
	v_cvt_pk_bf16_f32 v188, v107, v99
	v_lshlrev_b32_e32 v92, 16, v56
	v_and_b32_e32 v93, 0xffff0000, v56
	v_lshlrev_b32_e32 v94, 16, v57
	v_and_b32_e32 v95, 0xffff0000, v57
	v_mul_f32_e32 v92, 0xbfb8aa3b, v92
	v_mul_f32_e32 v93, 0xbfb8aa3b, v93
	v_mul_f32_e32 v94, 0xbfb8aa3b, v94
	v_mul_f32_e32 v95, 0xbfb8aa3b, v95
	v_exp_f32_e32 v92, v92
	v_exp_f32_e32 v93, v93
	v_exp_f32_e32 v94, v94
	v_exp_f32_e32 v95, v95
	v_add_f32_e32 v92, 1.0, v92
	v_add_f32_e32 v93, 1.0, v93
	v_add_f32_e32 v94, 1.0, v94
	v_add_f32_e32 v95, 1.0, v95
	v_rcp_f32_e32 v92, v92
	v_rcp_f32_e32 v93, v93
	v_rcp_f32_e32 v94, v94
	v_rcp_f32_e32 v95, v95
	v_fma_f32 v96, v72, v92, v68
	v_fma_f32 v97, v73, v93, v69
	v_fma_f32 v98, v74, v94, v70
	v_fma_f32 v99, v75, v95, v71
	v_cmp_gt_f32_e64 s[22:23], s30, v96
	v_cmp_gt_f32_e64 s[24:25], s30, v97
	v_cmp_gt_f32_e64 s[26:27], s30, v98
	v_cmp_gt_f32_e64 s[28:29], s30, v99
	v_cndmask_b32_e64 v92, 0, 32, s[22:23]
	v_cndmask_b32_e64 v93, 0, 32, s[24:25]
	v_cndmask_b32_e64 v94, 0, 32, s[26:27]
; DEV u16 f2bf(float f) { return (u16)(pack2(f, f) & 0xffffu); }
; DEV float bf2f(u16 h) { return __uint_as_float(((unsigned)h) << 16); }
; DEV float sigmoid_f(float x) { return __builtin_amdgcn_rcpf(1.f + __expf(-x)); }
; DEV void phase_p15(const Params& p, int g) {
;     ...
;         for (int e = 0; e < 8; ++e) {
;           const int jj = j8 * 8 + e;
;           const int j = dir ? 63 - jj : jj;
;           const size_t tok = (size_t)cidx * 64 + j;
;           const float f = lb[cc] + (1.f - lb[cc]) * sigmoid_f(bf2f(xr[st][cc][e]));
;           G[cc] += __logf(f);
;           const float eg = __expf(G[cc]), ig = __expf(-G[cc]);
;           Qp[tok * 512 + c] = f2bf(bf2f(qr[st][cc][e]) * eg);
;           const u16 kk = f2bf((1.f - f) * ig);
;           Kp[tok * 512 + c] = kk;
;           kb[e] = kk;
;         }
	v_cndmask_b32_e64 v95, 0, 32, s[28:29]
	v_ldexp_f32 v92, v96, v92
	v_ldexp_f32 v93, v97, v93
	v_ldexp_f32 v94, v98, v94
	v_ldexp_f32 v95, v99, v95
	v_log_f32_e32 v92, v92
	v_log_f32_e32 v93, v93
	v_log_f32_e32 v94, v94
	v_log_f32_e32 v95, v95
	v_mul_f32_e32 v100, 0x3f317217, v92
	v_mul_f32_e32 v101, 0x3f317217, v93
	v_mul_f32_e32 v102, 0x3f317217, v94
	v_mul_f32_e32 v103, 0x3f317217, v95
	v_fma_f32 v100, v92, s31, -v100
	v_fma_f32 v101, v93, s31, -v101
	v_fma_f32 v102, v94, s31, -v102
	v_fma_f32 v103, v95, s31, -v103
	v_fmac_f32_e32 v100, 0x3377d1cf, v92
	v_fmac_f32_e32 v101, 0x3377d1cf, v93
	v_fmac_f32_e32 v102, 0x3377d1cf, v94
	v_fmac_f32_e32 v103, 0x3377d1cf, v95
	v_fmac_f32_e32 v100, 0x3f317217, v92
	v_fmac_f32_e32 v101, 0x3f317217, v93
	v_fmac_f32_e32 v102, 0x3f317217, v94
	v_fmac_f32_e32 v103, 0x3f317217, v95
	v_cmp_lt_f32_e64 vcc, |v92|, s34
	v_cndmask_b32_e32 v92, v92, v100, vcc
	v_cmp_lt_f32_e64 vcc, |v93|, s34
	v_cndmask_b32_e32 v93, v93, v101, vcc
	v_cmp_lt_f32_e64 vcc, |v94|, s34
	v_cndmask_b32_e32 v94, v94, v102, vcc
	v_cmp_lt_f32_e64 vcc, |v95|, s34
	v_cndmask_b32_e32 v95, v95, v103, vcc
	v_cndmask_b32_e64 v100, 0, v213, s[22:23]
	v_cndmask_b32_e64 v101, 0, v213, s[24:25]
	v_cndmask_b32_e64 v102, 0, v213, s[26:27]
	v_cndmask_b32_e64 v103, 0, v213, s[28:29]
	v_sub_f32_e32 v92, v92, v100
	v_sub_f32_e32 v93, v93, v101
	v_sub_f32_e32 v94, v94, v102
	v_sub_f32_e32 v95, v95, v103
	v_add_f32_e32 v64, v64, v92
	v_add_f32_e32 v65, v65, v93
	v_add_f32_e32 v66, v66, v94
	v_add_f32_e32 v67, v67, v95
	v_mul_f32_e32 v92, 0xbfb8aa3b, v64
	v_mul_f32_e32 v93, 0xbfb8aa3b, v65
	v_mul_f32_e32 v94, 0xbfb8aa3b, v66
	v_mul_f32_e32 v95, 0xbfb8aa3b, v67
	v_mul_f32_e32 v100, 0x3fb8aa3b, v64
	v_mul_f32_e32 v101, 0x3fb8aa3b, v65
	v_mul_f32_e32 v102, 0x3fb8aa3b, v66
	v_mul_f32_e32 v103, 0x3fb8aa3b, v67
	v_exp_f32_e32 v92, v92
	v_exp_f32_e32 v93, v93
	v_exp_f32_e32 v94, v94
	v_exp_f32_e32 v95, v95
	v_exp_f32_e32 v100, v100
	v_exp_f32_e32 v101, v101
	v_exp_f32_e32 v102, v102
	v_exp_f32_e32 v103, v103
	v_sub_f32_e32 v96, 1.0, v96
	v_sub_f32_e32 v97, 1.0, v97
	v_sub_f32_e32 v98, 1.0, v98
	v_sub_f32_e32 v99, 1.0, v99
	v_mul_f32_e32 v96, v96, v92
	v_mul_f32_e32 v97, v97, v93
	v_mul_f32_e32 v98, v98, v94
	v_mul_f32_e32 v99, v99, v95
	v_lshlrev_b32_e32 v92, 16, v58
	v_and_b32_e32 v93, 0xffff0000, v58
	v_lshlrev_b32_e32 v94, 16, v59
	v_and_b32_e32 v95, 0xffff0000, v59
	v_mul_f32_e32 v92, v92, v100
	v_mul_f32_e32 v93, v93, v101
	v_mul_f32_e32 v94, v94, v102
	v_mul_f32_e32 v95, v95, v103
	v_cvt_pk_bf16_f32 v108, v92, v93
	v_cvt_pk_bf16_f32 v109, v94, v95
	v_cvt_pk_bf16_f32 v110, v96, v97
	v_cvt_pk_bf16_f32 v111, v98, v99
	global_store_dwordx2 v112, v[108:109], s[2:3]
	global_store_dwordx2 v114, v[110:111], s[2:3]
	s_add_u32 s2, s2, 0x400
	s_addc_u32 s3, s3, 0
	v_mov_b32_e32 v104, v96
	v_mov_b32_e32 v105, v97
	v_mov_b32_e32 v106, v98
	v_mov_b32_e32 v107, v99
	v_lshlrev_b32_e32 v92, 16, v60
	v_and_b32_e32 v93, 0xffff0000, v60
	v_lshlrev_b32_e32 v94, 16, v61
	v_and_b32_e32 v95, 0xffff0000, v61
	v_mul_f32_e32 v92, 0xbfb8aa3b, v92
	v_mul_f32_e32 v93, 0xbfb8aa3b, v93
	v_mul_f32_e32 v94, 0xbfb8aa3b, v94
	v_mul_f32_e32 v95, 0xbfb8aa3b, v95
	v_exp_f32_e32 v92, v92
	v_exp_f32_e32 v93, v93
	v_exp_f32_e32 v94, v94
	v_exp_f32_e32 v95, v95
	v_add_f32_e32 v92, 1.0, v92
	v_add_f32_e32 v93, 1.0, v93
	v_add_f32_e32 v94, 1.0, v94
	v_add_f32_e32 v95, 1.0, v95
	v_rcp_f32_e32 v92, v92
	v_rcp_f32_e32 v93, v93
	v_rcp_f32_e32 v94, v94
	v_rcp_f32_e32 v95, v95
	v_fma_f32 v96, v72, v92, v68
	v_fma_f32 v97, v73, v93, v69
	v_fma_f32 v98, v74, v94, v70
	v_fma_f32 v99, v75, v95, v71
	v_cmp_gt_f32_e64 s[22:23], s30, v96
	v_cmp_gt_f32_e64 s[24:25], s30, v97
	v_cmp_gt_f32_e64 s[26:27], s30, v98
	v_cmp_gt_f32_e64 s[28:29], s30, v99
	v_cndmask_b32_e64 v92, 0, 32, s[22:23]
	v_cndmask_b32_e64 v93, 0, 32, s[24:25]
	v_cndmask_b32_e64 v94, 0, 32, s[26:27]
	v_cndmask_b32_e64 v95, 0, 32, s[28:29]
	v_ldexp_f32 v92, v96, v92
	v_ldexp_f32 v93, v97, v93
	v_ldexp_f32 v94, v98, v94
	v_ldexp_f32 v95, v99, v95
	v_log_f32_e32 v92, v92
	v_log_f32_e32 v93, v93
	v_log_f32_e32 v94, v94
	v_log_f32_e32 v95, v95
	v_mul_f32_e32 v100, 0x3f317217, v92
	v_mul_f32_e32 v101, 0x3f317217, v93
	v_mul_f32_e32 v102, 0x3f317217, v94
	v_mul_f32_e32 v103, 0x3f317217, v95
	v_fma_f32 v100, v92, s31, -v100
	v_fma_f32 v101, v93, s31, -v101
	v_fma_f32 v102, v94, s31, -v102
	v_fma_f32 v103, v95, s31, -v103
	v_fmac_f32_e32 v100, 0x3377d1cf, v92
	v_fmac_f32_e32 v101, 0x3377d1cf, v93
	v_fmac_f32_e32 v102, 0x3377d1cf, v94
	v_fmac_f32_e32 v103, 0x3377d1cf, v95
	v_fmac_f32_e32 v100, 0x3f317217, v92
	v_fmac_f32_e32 v101, 0x3f317217, v93
	v_fmac_f32_e32 v102, 0x3f317217, v94
	v_fmac_f32_e32 v103, 0x3f317217, v95
	v_cmp_lt_f32_e64 vcc, |v92|, s34
	v_cndmask_b32_e32 v92, v92, v100, vcc
	v_cmp_lt_f32_e64 vcc, |v93|, s34
	v_cndmask_b32_e32 v93, v93, v101, vcc
	v_cmp_lt_f32_e64 vcc, |v94|, s34
	v_cndmask_b32_e32 v94, v94, v102, vcc
	v_cmp_lt_f32_e64 vcc, |v95|, s34
	v_cndmask_b32_e32 v95, v95, v103, vcc
	v_cndmask_b32_e64 v100, 0, v213, s[22:23]
	v_cndmask_b32_e64 v101, 0, v213, s[24:25]
	v_cndmask_b32_e64 v102, 0, v213, s[26:27]
	v_cndmask_b32_e64 v103, 0, v213, s[28:29]
	v_sub_f32_e32 v92, v92, v100
	v_sub_f32_e32 v93, v93, v101
	v_sub_f32_e32 v94, v94, v102
	v_sub_f32_e32 v95, v95, v103
	v_add_f32_e32 v64, v64, v92
	v_add_f32_e32 v65, v65, v93
	v_add_f32_e32 v66, v66, v94
	v_add_f32_e32 v67, v67, v95
	v_mul_f32_e32 v92, 0xbfb8aa3b, v64
	v_mul_f32_e32 v93, 0xbfb8aa3b, v65
	v_mul_f32_e32 v94, 0xbfb8aa3b, v66
	v_mul_f32_e32 v95, 0xbfb8aa3b, v67
	v_mul_f32_e32 v100, 0x3fb8aa3b, v64
	v_mul_f32_e32 v101, 0x3fb8aa3b, v65
	v_mul_f32_e32 v102, 0x3fb8aa3b, v66
; DEV u16 f2bf(float f) { return (u16)(pack2(f, f) & 0xffffu); }
; DEV float bf2f(u16 h) { return __uint_as_float(((unsigned)h) << 16); }
; DEV float sigmoid_f(float x) { return __builtin_amdgcn_rcpf(1.f + __expf(-x)); }
; DEV void phase_p15(const Params& p, int g) {
;     ...
;     P15_LOAD(0, 0);
;     P15_LOAD(1, 1);
; #pragma unroll
;     for (int j8 = 0; j8 < 8; ++j8) {
;       const int st = j8 % 3;
;       if (j8 < 6) { P15_LOAD((j8 + 2) % 3, j8 + 2); }
;     ...
;         for (int e = 0; e < 8; ++e) {
;           const int jj = j8 * 8 + e;
;           const int j = dir ? 63 - jj : jj;
;           const size_t tok = (size_t)cidx * 64 + j;
;           const float f = lb[cc] + (1.f - lb[cc]) * sigmoid_f(bf2f(xr[st][cc][e]));
;           G[cc] += __logf(f);
;           const float eg = __expf(G[cc]), ig = __expf(-G[cc]);
;           Qp[tok * 512 + c] = f2bf(bf2f(qr[st][cc][e]) * eg);
;           const u16 kk = f2bf((1.f - f) * ig);
;           Kp[tok * 512 + c] = kk;
;           kb[e] = kk;
;         }
	v_mul_f32_e32 v103, 0x3fb8aa3b, v67
	v_exp_f32_e32 v92, v92
	v_exp_f32_e32 v93, v93
	v_exp_f32_e32 v94, v94
	v_exp_f32_e32 v95, v95
	v_exp_f32_e32 v100, v100
	v_exp_f32_e32 v101, v101
	v_exp_f32_e32 v102, v102
	v_exp_f32_e32 v103, v103
	v_sub_f32_e32 v96, 1.0, v96
	v_sub_f32_e32 v97, 1.0, v97
	v_sub_f32_e32 v98, 1.0, v98
	v_sub_f32_e32 v99, 1.0, v99
	v_mul_f32_e32 v96, v96, v92
	v_mul_f32_e32 v97, v97, v93
	v_mul_f32_e32 v98, v98, v94
	v_mul_f32_e32 v99, v99, v95
	v_lshlrev_b32_e32 v92, 16, v62
	v_and_b32_e32 v93, 0xffff0000, v62
	v_lshlrev_b32_e32 v94, 16, v63
	v_and_b32_e32 v95, 0xffff0000, v63
	v_mul_f32_e32 v92, v92, v100
	v_mul_f32_e32 v93, v93, v101
	v_mul_f32_e32 v94, v94, v102
	v_mul_f32_e32 v95, v95, v103
	v_cvt_pk_bf16_f32 v108, v92, v93
	v_cvt_pk_bf16_f32 v109, v94, v95
	v_cvt_pk_bf16_f32 v110, v96, v97
	v_cvt_pk_bf16_f32 v111, v98, v99
	global_store_dwordx2 v112, v[108:109], s[2:3]
	global_store_dwordx2 v114, v[110:111], s[2:3]
	s_add_u32 s2, s2, 0x400
	s_addc_u32 s3, s3, 0
	v_cvt_pk_bf16_f32 v123, v104, v96
	v_cvt_pk_bf16_f32 v139, v105, v97
	v_cvt_pk_bf16_f32 v173, v106, v98
	v_cvt_pk_bf16_f32 v189, v107, v99
	global_load_dwordx2 v[32:33], v113, s[0:1]
	global_load_dwordx2 v[34:35], v112, s[0:1]
	s_add_u32 s0, s0, 0x1400
	s_addc_u32 s1, s1, 0
	global_load_dwordx2 v[36:37], v113, s[0:1]
	global_load_dwordx2 v[38:39], v112, s[0:1]
	s_add_u32 s0, s0, 0x1400
	s_addc_u32 s1, s1, 0
	global_load_dwordx2 v[40:41], v113, s[0:1]
	global_load_dwordx2 v[42:43], v112, s[0:1]
	s_add_u32 s0, s0, 0x1400
	s_addc_u32 s1, s1, 0
	global_load_dwordx2 v[44:45], v113, s[0:1]
	global_load_dwordx2 v[46:47], v112, s[0:1]
	s_add_u32 s0, s0, 0x1400
	s_addc_u32 s1, s1, 0
	global_load_dwordx2 v[48:49], v113, s[0:1]
	global_load_dwordx2 v[50:51], v112, s[0:1]
	s_add_u32 s0, s0, 0x1400
	s_addc_u32 s1, s1, 0
	global_load_dwordx2 v[52:53], v113, s[0:1]
	global_load_dwordx2 v[54:55], v112, s[0:1]
	s_add_u32 s0, s0, 0x1400
	s_addc_u32 s1, s1, 0
	global_load_dwordx2 v[56:57], v113, s[0:1]
	global_load_dwordx2 v[58:59], v112, s[0:1]
	s_add_u32 s0, s0, 0x1400
	s_addc_u32 s1, s1, 0
	global_load_dwordx2 v[60:61], v113, s[0:1]
	global_load_dwordx2 v[62:63], v112, s[0:1]
	s_add_u32 s0, s0, 0x1400
	s_addc_u32 s1, s1, 0
	s_waitcnt vmcnt(32)
	v_lshlrev_b32_e32 v92, 16, v0
	v_and_b32_e32 v93, 0xffff0000, v0
	v_lshlrev_b32_e32 v94, 16, v1
	v_and_b32_e32 v95, 0xffff0000, v1
	v_mul_f32_e32 v92, 0xbfb8aa3b, v92
	v_mul_f32_e32 v93, 0xbfb8aa3b, v93
	v_mul_f32_e32 v94, 0xbfb8aa3b, v94
	v_mul_f32_e32 v95, 0xbfb8aa3b, v95
	v_exp_f32_e32 v92, v92
	v_exp_f32_e32 v93, v93
	v_exp_f32_e32 v94, v94
	v_exp_f32_e32 v95, v95
	v_add_f32_e32 v92, 1.0, v92
	v_add_f32_e32 v93, 1.0, v93
	v_add_f32_e32 v94, 1.0, v94
	v_add_f32_e32 v95, 1.0, v95
	v_rcp_f32_e32 v92, v92
	v_rcp_f32_e32 v93, v93
	v_rcp_f32_e32 v94, v94
	v_rcp_f32_e32 v95, v95
	v_fma_f32 v96, v72, v92, v68
	v_fma_f32 v97, v73, v93, v69
	v_fma_f32 v98, v74, v94, v70
	v_fma_f32 v99, v75, v95, v71
	v_cmp_gt_f32_e64 s[22:23], s30, v96
	v_cmp_gt_f32_e64 s[24:25], s30, v97
	v_cmp_gt_f32_e64 s[26:27], s30, v98
	v_cmp_gt_f32_e64 s[28:29], s30, v99
	v_cndmask_b32_e64 v92, 0, 32, s[22:23]
	v_cndmask_b32_e64 v93, 0, 32, s[24:25]
	v_cndmask_b32_e64 v94, 0, 32, s[26:27]
	v_cndmask_b32_e64 v95, 0, 32, s[28:29]
	v_ldexp_f32 v92, v96, v92
	v_ldexp_f32 v93, v97, v93
	v_ldexp_f32 v94, v98, v94
	v_ldexp_f32 v95, v99, v95
	v_log_f32_e32 v92, v92
	v_log_f32_e32 v93, v93
	v_log_f32_e32 v94, v94
	v_log_f32_e32 v95, v95
	v_mul_f32_e32 v100, 0x3f317217, v92
	v_mul_f32_e32 v101, 0x3f317217, v93
	v_mul_f32_e32 v102, 0x3f317217, v94
	v_mul_f32_e32 v103, 0x3f317217, v95
	v_fma_f32 v100, v92, s31, -v100
	v_fma_f32 v101, v93, s31, -v101
	v_fma_f32 v102, v94, s31, -v102
	v_fma_f32 v103, v95, s31, -v103
	v_fmac_f32_e32 v100, 0x3377d1cf, v92
	v_fmac_f32_e32 v101, 0x3377d1cf, v93
	v_fmac_f32_e32 v102, 0x3377d1cf, v94
	v_fmac_f32_e32 v103, 0x3377d1cf, v95
	v_fmac_f32_e32 v100, 0x3f317217, v92
	v_fmac_f32_e32 v101, 0x3f317217, v93
	v_fmac_f32_e32 v102, 0x3f317217, v94
	v_fmac_f32_e32 v103, 0x3f317217, v95
	v_cmp_lt_f32_e64 vcc, |v92|, s34
	v_cndmask_b32_e32 v92, v92, v100, vcc
	v_cmp_lt_f32_e64 vcc, |v93|, s34
	v_cndmask_b32_e32 v93, v93, v101, vcc
	v_cmp_lt_f32_e64 vcc, |v94|, s34
	v_cndmask_b32_e32 v94, v94, v102, vcc
	v_cmp_lt_f32_e64 vcc, |v95|, s34
	v_cndmask_b32_e32 v95, v95, v103, vcc
	v_cndmask_b32_e64 v100, 0, v213, s[22:23]
	v_cndmask_b32_e64 v101, 0, v213, s[24:25]
	v_cndmask_b32_e64 v102, 0, v213, s[26:27]
	v_cndmask_b32_e64 v103, 0, v213, s[28:29]
	v_sub_f32_e32 v92, v92, v100
	v_sub_f32_e32 v93, v93, v101
	v_sub_f32_e32 v94, v94, v102
	v_sub_f32_e32 v95, v95, v103
	v_add_f32_e32 v64, v64, v92
	v_add_f32_e32 v65, v65, v93
	v_add_f32_e32 v66, v66, v94
	v_add_f32_e32 v67, v67, v95
	v_mul_f32_e32 v92, 0xbfb8aa3b, v64
	v_mul_f32_e32 v93, 0xbfb8aa3b, v65
	v_mul_f32_e32 v94, 0xbfb8aa3b, v66
	v_mul_f32_e32 v95, 0xbfb8aa3b, v67
	v_mul_f32_e32 v100, 0x3fb8aa3b, v64
	v_mul_f32_e32 v101, 0x3fb8aa3b, v65
	v_mul_f32_e32 v102, 0x3fb8aa3b, v66
	v_mul_f32_e32 v103, 0x3fb8aa3b, v67
	v_exp_f32_e32 v92, v92
	v_exp_f32_e32 v93, v93
	v_exp_f32_e32 v94, v94
	v_exp_f32_e32 v95, v95
	v_exp_f32_e32 v100, v100
	v_exp_f32_e32 v101, v101
	v_exp_f32_e32 v102, v102
	v_exp_f32_e32 v103, v103
	v_sub_f32_e32 v96, 1.0, v96
	v_sub_f32_e32 v97, 1.0, v97
	v_sub_f32_e32 v98, 1.0, v98
	v_sub_f32_e32 v99, 1.0, v99
	v_mul_f32_e32 v96, v96, v92
	v_mul_f32_e32 v97, v97, v93
	v_mul_f32_e32 v98, v98, v94
	v_mul_f32_e32 v99, v99, v95
	v_lshlrev_b32_e32 v92, 16, v2
	v_and_b32_e32 v93, 0xffff0000, v2
	v_lshlrev_b32_e32 v94, 16, v3
	v_and_b32_e32 v95, 0xffff0000, v3
	v_mul_f32_e32 v92, v92, v100
; DEV u16 f2bf(float f) { return (u16)(pack2(f, f) & 0xffffu); }
; DEV float bf2f(u16 h) { return __uint_as_float(((unsigned)h) << 16); }
; DEV float sigmoid_f(float x) { return __builtin_amdgcn_rcpf(1.f + __expf(-x)); }
; DEV void phase_p15(const Params& p, int g) {
;     ...
;         for (int e = 0; e < 8; ++e) {
;           const int jj = j8 * 8 + e;
;           const int j = dir ? 63 - jj : jj;
;           const size_t tok = (size_t)cidx * 64 + j;
;           const float f = lb[cc] + (1.f - lb[cc]) * sigmoid_f(bf2f(xr[st][cc][e]));
;           G[cc] += __logf(f);
;           const float eg = __expf(G[cc]), ig = __expf(-G[cc]);
;           Qp[tok * 512 + c] = f2bf(bf2f(qr[st][cc][e]) * eg);
;           const u16 kk = f2bf((1.f - f) * ig);
;           Kp[tok * 512 + c] = kk;
;           kb[e] = kk;
;         }
	v_mul_f32_e32 v93, v93, v101
	v_mul_f32_e32 v94, v94, v102
	v_mul_f32_e32 v95, v95, v103
	v_cvt_pk_bf16_f32 v108, v92, v93
	v_cvt_pk_bf16_f32 v109, v94, v95
	v_cvt_pk_bf16_f32 v110, v96, v97
	v_cvt_pk_bf16_f32 v111, v98, v99
	global_store_dwordx2 v112, v[108:109], s[2:3]
	global_store_dwordx2 v114, v[110:111], s[2:3]
	s_add_u32 s2, s2, 0x400
	s_addc_u32 s3, s3, 0
	v_mov_b32_e32 v104, v96
	v_mov_b32_e32 v105, v97
	v_mov_b32_e32 v106, v98
	v_mov_b32_e32 v107, v99
	v_lshlrev_b32_e32 v92, 16, v4
	v_and_b32_e32 v93, 0xffff0000, v4
	v_lshlrev_b32_e32 v94, 16, v5
	v_and_b32_e32 v95, 0xffff0000, v5
	v_mul_f32_e32 v92, 0xbfb8aa3b, v92
	v_mul_f32_e32 v93, 0xbfb8aa3b, v93
	v_mul_f32_e32 v94, 0xbfb8aa3b, v94
	v_mul_f32_e32 v95, 0xbfb8aa3b, v95
	v_exp_f32_e32 v92, v92
	v_exp_f32_e32 v93, v93
	v_exp_f32_e32 v94, v94
	v_exp_f32_e32 v95, v95
	v_add_f32_e32 v92, 1.0, v92
	v_add_f32_e32 v93, 1.0, v93
	v_add_f32_e32 v94, 1.0, v94
	v_add_f32_e32 v95, 1.0, v95
	v_rcp_f32_e32 v92, v92
	v_rcp_f32_e32 v93, v93
	v_rcp_f32_e32 v94, v94
	v_rcp_f32_e32 v95, v95
	v_fma_f32 v96, v72, v92, v68
	v_fma_f32 v97, v73, v93, v69
	v_fma_f32 v98, v74, v94, v70
	v_fma_f32 v99, v75, v95, v71
	v_cmp_gt_f32_e64 s[22:23], s30, v96
	v_cmp_gt_f32_e64 s[24:25], s30, v97
	v_cmp_gt_f32_e64 s[26:27], s30, v98
	v_cmp_gt_f32_e64 s[28:29], s30, v99
	v_cndmask_b32_e64 v92, 0, 32, s[22:23]
	v_cndmask_b32_e64 v93, 0, 32, s[24:25]
	v_cndmask_b32_e64 v94, 0, 32, s[26:27]
	v_cndmask_b32_e64 v95, 0, 32, s[28:29]
	v_ldexp_f32 v92, v96, v92
	v_ldexp_f32 v93, v97, v93
	v_ldexp_f32 v94, v98, v94
	v_ldexp_f32 v95, v99, v95
	v_log_f32_e32 v92, v92
	v_log_f32_e32 v93, v93
	v_log_f32_e32 v94, v94
	v_log_f32_e32 v95, v95
	v_mul_f32_e32 v100, 0x3f317217, v92
	v_mul_f32_e32 v101, 0x3f317217, v93
	v_mul_f32_e32 v102, 0x3f317217, v94
	v_mul_f32_e32 v103, 0x3f317217, v95
	v_fma_f32 v100, v92, s31, -v100
	v_fma_f32 v101, v93, s31, -v101
	v_fma_f32 v102, v94, s31, -v102
	v_fma_f32 v103, v95, s31, -v103
	v_fmac_f32_e32 v100, 0x3377d1cf, v92
	v_fmac_f32_e32 v101, 0x3377d1cf, v93
	v_fmac_f32_e32 v102, 0x3377d1cf, v94
	v_fmac_f32_e32 v103, 0x3377d1cf, v95
	v_fmac_f32_e32 v100, 0x3f317217, v92
	v_fmac_f32_e32 v101, 0x3f317217, v93
	v_fmac_f32_e32 v102, 0x3f317217, v94
	v_fmac_f32_e32 v103, 0x3f317217, v95
	v_cmp_lt_f32_e64 vcc, |v92|, s34
	v_cndmask_b32_e32 v92, v92, v100, vcc
	v_cmp_lt_f32_e64 vcc, |v93|, s34
	v_cndmask_b32_e32 v93, v93, v101, vcc
	v_cmp_lt_f32_e64 vcc, |v94|, s34
	v_cndmask_b32_e32 v94, v94, v102, vcc
	v_cmp_lt_f32_e64 vcc, |v95|, s34
	v_cndmask_b32_e32 v95, v95, v103, vcc
	v_cndmask_b32_e64 v100, 0, v213, s[22:23]
	v_cndmask_b32_e64 v101, 0, v213, s[24:25]
	v_cndmask_b32_e64 v102, 0, v213, s[26:27]
	v_cndmask_b32_e64 v103, 0, v213, s[28:29]
	v_sub_f32_e32 v92, v92, v100
	v_sub_f32_e32 v93, v93, v101
	v_sub_f32_e32 v94, v94, v102
	v_sub_f32_e32 v95, v95, v103
	v_add_f32_e32 v64, v64, v92
	v_add_f32_e32 v65, v65, v93
	v_add_f32_e32 v66, v66, v94
	v_add_f32_e32 v67, v67, v95
	v_mul_f32_e32 v92, 0xbfb8aa3b, v64
	v_mul_f32_e32 v93, 0xbfb8aa3b, v65
	v_mul_f32_e32 v94, 0xbfb8aa3b, v66
	v_mul_f32_e32 v95, 0xbfb8aa3b, v67
	v_mul_f32_e32 v100, 0x3fb8aa3b, v64
	v_mul_f32_e32 v101, 0x3fb8aa3b, v65
	v_mul_f32_e32 v102, 0x3fb8aa3b, v66
	v_mul_f32_e32 v103, 0x3fb8aa3b, v67
	v_exp_f32_e32 v92, v92
	v_exp_f32_e32 v93, v93
	v_exp_f32_e32 v94, v94
	v_exp_f32_e32 v95, v95
	v_exp_f32_e32 v100, v100
	v_exp_f32_e32 v101, v101
	v_exp_f32_e32 v102, v102
	v_exp_f32_e32 v103, v103
	v_sub_f32_e32 v96, 1.0, v96
	v_sub_f32_e32 v97, 1.0, v97
	v_sub_f32_e32 v98, 1.0, v98
	v_sub_f32_e32 v99, 1.0, v99
	v_mul_f32_e32 v96, v96, v92
	v_mul_f32_e32 v97, v97, v93
	v_mul_f32_e32 v98, v98, v94
	v_mul_f32_e32 v99, v99, v95
	v_lshlrev_b32_e32 v92, 16, v6
	v_and_b32_e32 v93, 0xffff0000, v6
	v_lshlrev_b32_e32 v94, 16, v7
	v_and_b32_e32 v95, 0xffff0000, v7
	v_mul_f32_e32 v92, v92, v100
	v_mul_f32_e32 v93, v93, v101
	v_mul_f32_e32 v94, v94, v102
	v_mul_f32_e32 v95, v95, v103
	v_cvt_pk_bf16_f32 v108, v92, v93
	v_cvt_pk_bf16_f32 v109, v94, v95
	v_cvt_pk_bf16_f32 v110, v96, v97
	v_cvt_pk_bf16_f32 v111, v98, v99
	global_store_dwordx2 v112, v[108:109], s[2:3]
	global_store_dwordx2 v114, v[110:111], s[2:3]
	s_add_u32 s2, s2, 0x400
	s_addc_u32 s3, s3, 0
	v_cvt_pk_bf16_f32 v124, v104, v96
	v_cvt_pk_bf16_f32 v140, v105, v97
	v_cvt_pk_bf16_f32 v174, v106, v98
	v_cvt_pk_bf16_f32 v190, v107, v99
	v_lshlrev_b32_e32 v92, 16, v8
	v_and_b32_e32 v93, 0xffff0000, v8
	v_lshlrev_b32_e32 v94, 16, v9
	v_and_b32_e32 v95, 0xffff0000, v9
	v_mul_f32_e32 v92, 0xbfb8aa3b, v92
	v_mul_f32_e32 v93, 0xbfb8aa3b, v93
	v_mul_f32_e32 v94, 0xbfb8aa3b, v94
	v_mul_f32_e32 v95, 0xbfb8aa3b, v95
	v_exp_f32_e32 v92, v92
	v_exp_f32_e32 v93, v93
	v_exp_f32_e32 v94, v94
	v_exp_f32_e32 v95, v95
	v_add_f32_e32 v92, 1.0, v92
	v_add_f32_e32 v93, 1.0, v93
	v_add_f32_e32 v94, 1.0, v94
	v_add_f32_e32 v95, 1.0, v95
	v_rcp_f32_e32 v92, v92
	v_rcp_f32_e32 v93, v93
	v_rcp_f32_e32 v94, v94
	v_rcp_f32_e32 v95, v95
	v_fma_f32 v96, v72, v92, v68
	v_fma_f32 v97, v73, v93, v69
	v_fma_f32 v98, v74, v94, v70
	v_fma_f32 v99, v75, v95, v71
	v_cmp_gt_f32_e64 s[22:23], s30, v96
	v_cmp_gt_f32_e64 s[24:25], s30, v97
	v_cmp_gt_f32_e64 s[26:27], s30, v98
	v_cmp_gt_f32_e64 s[28:29], s30, v99
	v_cndmask_b32_e64 v92, 0, 32, s[22:23]
	v_cndmask_b32_e64 v93, 0, 32, s[24:25]
	v_cndmask_b32_e64 v94, 0, 32, s[26:27]
	v_cndmask_b32_e64 v95, 0, 32, s[28:29]
	v_ldexp_f32 v92, v96, v92
	v_ldexp_f32 v93, v97, v93
	v_ldexp_f32 v94, v98, v94
	v_ldexp_f32 v95, v99, v95
	v_log_f32_e32 v92, v92
	v_log_f32_e32 v93, v93
	v_log_f32_e32 v94, v94
	v_log_f32_e32 v95, v95
	v_mul_f32_e32 v100, 0x3f317217, v92
	v_mul_f32_e32 v101, 0x3f317217, v93
; DEV u16 f2bf(float f) { return (u16)(pack2(f, f) & 0xffffu); }
; DEV float bf2f(u16 h) { return __uint_as_float(((unsigned)h) << 16); }
; DEV float sigmoid_f(float x) { return __builtin_amdgcn_rcpf(1.f + __expf(-x)); }
; DEV void phase_p15(const Params& p, int g) {
;     ...
;         for (int e = 0; e < 8; ++e) {
;           const int jj = j8 * 8 + e;
;           const int j = dir ? 63 - jj : jj;
;           const size_t tok = (size_t)cidx * 64 + j;
;           const float f = lb[cc] + (1.f - lb[cc]) * sigmoid_f(bf2f(xr[st][cc][e]));
;           G[cc] += __logf(f);
;           const float eg = __expf(G[cc]), ig = __expf(-G[cc]);
;           Qp[tok * 512 + c] = f2bf(bf2f(qr[st][cc][e]) * eg);
;           const u16 kk = f2bf((1.f - f) * ig);
;           Kp[tok * 512 + c] = kk;
;           kb[e] = kk;
;         }
	v_mul_f32_e32 v102, 0x3f317217, v94
	v_mul_f32_e32 v103, 0x3f317217, v95
	v_fma_f32 v100, v92, s31, -v100
	v_fma_f32 v101, v93, s31, -v101
	v_fma_f32 v102, v94, s31, -v102
	v_fma_f32 v103, v95, s31, -v103
	v_fmac_f32_e32 v100, 0x3377d1cf, v92
	v_fmac_f32_e32 v101, 0x3377d1cf, v93
	v_fmac_f32_e32 v102, 0x3377d1cf, v94
	v_fmac_f32_e32 v103, 0x3377d1cf, v95
	v_fmac_f32_e32 v100, 0x3f317217, v92
	v_fmac_f32_e32 v101, 0x3f317217, v93
	v_fmac_f32_e32 v102, 0x3f317217, v94
	v_fmac_f32_e32 v103, 0x3f317217, v95
	v_cmp_lt_f32_e64 vcc, |v92|, s34
	v_cndmask_b32_e32 v92, v92, v100, vcc
	v_cmp_lt_f32_e64 vcc, |v93|, s34
	v_cndmask_b32_e32 v93, v93, v101, vcc
	v_cmp_lt_f32_e64 vcc, |v94|, s34
	v_cndmask_b32_e32 v94, v94, v102, vcc
	v_cmp_lt_f32_e64 vcc, |v95|, s34
	v_cndmask_b32_e32 v95, v95, v103, vcc
	v_cndmask_b32_e64 v100, 0, v213, s[22:23]
	v_cndmask_b32_e64 v101, 0, v213, s[24:25]
	v_cndmask_b32_e64 v102, 0, v213, s[26:27]
	v_cndmask_b32_e64 v103, 0, v213, s[28:29]
	v_sub_f32_e32 v92, v92, v100
	v_sub_f32_e32 v93, v93, v101
	v_sub_f32_e32 v94, v94, v102
	v_sub_f32_e32 v95, v95, v103
	v_add_f32_e32 v64, v64, v92
	v_add_f32_e32 v65, v65, v93
	v_add_f32_e32 v66, v66, v94
	v_add_f32_e32 v67, v67, v95
	v_mul_f32_e32 v92, 0xbfb8aa3b, v64
	v_mul_f32_e32 v93, 0xbfb8aa3b, v65
	v_mul_f32_e32 v94, 0xbfb8aa3b, v66
	v_mul_f32_e32 v95, 0xbfb8aa3b, v67
	v_mul_f32_e32 v100, 0x3fb8aa3b, v64
	v_mul_f32_e32 v101, 0x3fb8aa3b, v65
	v_mul_f32_e32 v102, 0x3fb8aa3b, v66
	v_mul_f32_e32 v103, 0x3fb8aa3b, v67
	v_exp_f32_e32 v92, v92
	v_exp_f32_e32 v93, v93
	v_exp_f32_e32 v94, v94
	v_exp_f32_e32 v95, v95
	v_exp_f32_e32 v100, v100
	v_exp_f32_e32 v101, v101
	v_exp_f32_e32 v102, v102
	v_exp_f32_e32 v103, v103
	v_sub_f32_e32 v96, 1.0, v96
	v_sub_f32_e32 v97, 1.0, v97
	v_sub_f32_e32 v98, 1.0, v98
	v_sub_f32_e32 v99, 1.0, v99
	v_mul_f32_e32 v96, v96, v92
	v_mul_f32_e32 v97, v97, v93
	v_mul_f32_e32 v98, v98, v94
	v_mul_f32_e32 v99, v99, v95
	v_lshlrev_b32_e32 v92, 16, v10
	v_and_b32_e32 v93, 0xffff0000, v10
	v_lshlrev_b32_e32 v94, 16, v11
	v_and_b32_e32 v95, 0xffff0000, v11
	v_mul_f32_e32 v92, v92, v100
	v_mul_f32_e32 v93, v93, v101
	v_mul_f32_e32 v94, v94, v102
	v_mul_f32_e32 v95, v95, v103
	v_cvt_pk_bf16_f32 v108, v92, v93
	v_cvt_pk_bf16_f32 v109, v94, v95
	v_cvt_pk_bf16_f32 v110, v96, v97
	v_cvt_pk_bf16_f32 v111, v98, v99
	global_store_dwordx2 v112, v[108:109], s[2:3]
	global_store_dwordx2 v114, v[110:111], s[2:3]
	s_add_u32 s2, s2, 0x400
	s_addc_u32 s3, s3, 0
	v_mov_b32_e32 v104, v96
	v_mov_b32_e32 v105, v97
	v_mov_b32_e32 v106, v98
	v_mov_b32_e32 v107, v99
	v_lshlrev_b32_e32 v92, 16, v12
	v_and_b32_e32 v93, 0xffff0000, v12
	v_lshlrev_b32_e32 v94, 16, v13
	v_and_b32_e32 v95, 0xffff0000, v13
	v_mul_f32_e32 v92, 0xbfb8aa3b, v92
	v_mul_f32_e32 v93, 0xbfb8aa3b, v93
	v_mul_f32_e32 v94, 0xbfb8aa3b, v94
	v_mul_f32_e32 v95, 0xbfb8aa3b, v95
	v_exp_f32_e32 v92, v92
	v_exp_f32_e32 v93, v93
	v_exp_f32_e32 v94, v94
	v_exp_f32_e32 v95, v95
	v_add_f32_e32 v92, 1.0, v92
	v_add_f32_e32 v93, 1.0, v93
	v_add_f32_e32 v94, 1.0, v94
	v_add_f32_e32 v95, 1.0, v95
	v_rcp_f32_e32 v92, v92
	v_rcp_f32_e32 v93, v93
	v_rcp_f32_e32 v94, v94
	v_rcp_f32_e32 v95, v95
	v_fma_f32 v96, v72, v92, v68
	v_fma_f32 v97, v73, v93, v69
	v_fma_f32 v98, v74, v94, v70
	v_fma_f32 v99, v75, v95, v71
	v_cmp_gt_f32_e64 s[22:23], s30, v96
	v_cmp_gt_f32_e64 s[24:25], s30, v97
	v_cmp_gt_f32_e64 s[26:27], s30, v98
	v_cmp_gt_f32_e64 s[28:29], s30, v99
	v_cndmask_b32_e64 v92, 0, 32, s[22:23]
	v_cndmask_b32_e64 v93, 0, 32, s[24:25]
	v_cndmask_b32_e64 v94, 0, 32, s[26:27]
	v_cndmask_b32_e64 v95, 0, 32, s[28:29]
	v_ldexp_f32 v92, v96, v92
	v_ldexp_f32 v93, v97, v93
	v_ldexp_f32 v94, v98, v94
	v_ldexp_f32 v95, v99, v95
	v_log_f32_e32 v92, v92
	v_log_f32_e32 v93, v93
	v_log_f32_e32 v94, v94
	v_log_f32_e32 v95, v95
	v_mul_f32_e32 v100, 0x3f317217, v92
	v_mul_f32_e32 v101, 0x3f317217, v93
	v_mul_f32_e32 v102, 0x3f317217, v94
	v_mul_f32_e32 v103, 0x3f317217, v95
	v_fma_f32 v100, v92, s31, -v100
	v_fma_f32 v101, v93, s31, -v101
	v_fma_f32 v102, v94, s31, -v102
	v_fma_f32 v103, v95, s31, -v103
	v_fmac_f32_e32 v100, 0x3377d1cf, v92
	v_fmac_f32_e32 v101, 0x3377d1cf, v93
	v_fmac_f32_e32 v102, 0x3377d1cf, v94
	v_fmac_f32_e32 v103, 0x3377d1cf, v95
	v_fmac_f32_e32 v100, 0x3f317217, v92
	v_fmac_f32_e32 v101, 0x3f317217, v93
	v_fmac_f32_e32 v102, 0x3f317217, v94
	v_fmac_f32_e32 v103, 0x3f317217, v95
	v_cmp_lt_f32_e64 vcc, |v92|, s34
	v_cndmask_b32_e32 v92, v92, v100, vcc
	v_cmp_lt_f32_e64 vcc, |v93|, s34
	v_cndmask_b32_e32 v93, v93, v101, vcc
	v_cmp_lt_f32_e64 vcc, |v94|, s34
	v_cndmask_b32_e32 v94, v94, v102, vcc
	v_cmp_lt_f32_e64 vcc, |v95|, s34
	v_cndmask_b32_e32 v95, v95, v103, vcc
	v_cndmask_b32_e64 v100, 0, v213, s[22:23]
	v_cndmask_b32_e64 v101, 0, v213, s[24:25]
	v_cndmask_b32_e64 v102, 0, v213, s[26:27]
	v_cndmask_b32_e64 v103, 0, v213, s[28:29]
	v_sub_f32_e32 v92, v92, v100
	v_sub_f32_e32 v93, v93, v101
	v_sub_f32_e32 v94, v94, v102
	v_sub_f32_e32 v95, v95, v103
	v_add_f32_e32 v64, v64, v92
	v_add_f32_e32 v65, v65, v93
	v_add_f32_e32 v66, v66, v94
	v_add_f32_e32 v67, v67, v95
	v_mul_f32_e32 v92, 0xbfb8aa3b, v64
	v_mul_f32_e32 v93, 0xbfb8aa3b, v65
	v_mul_f32_e32 v94, 0xbfb8aa3b, v66
	v_mul_f32_e32 v95, 0xbfb8aa3b, v67
	v_mul_f32_e32 v100, 0x3fb8aa3b, v64
	v_mul_f32_e32 v101, 0x3fb8aa3b, v65
	v_mul_f32_e32 v102, 0x3fb8aa3b, v66
	v_mul_f32_e32 v103, 0x3fb8aa3b, v67
	v_exp_f32_e32 v92, v92
	v_exp_f32_e32 v93, v93
	v_exp_f32_e32 v94, v94
	v_exp_f32_e32 v95, v95
	v_exp_f32_e32 v100, v100
	v_exp_f32_e32 v101, v101
	v_exp_f32_e32 v102, v102
	v_exp_f32_e32 v103, v103
	v_sub_f32_e32 v96, 1.0, v96
	v_sub_f32_e32 v97, 1.0, v97
	v_sub_f32_e32 v98, 1.0, v98
; DEV u16 f2bf(float f) { return (u16)(pack2(f, f) & 0xffffu); }
; DEV float bf2f(u16 h) { return __uint_as_float(((unsigned)h) << 16); }
; DEV float sigmoid_f(float x) { return __builtin_amdgcn_rcpf(1.f + __expf(-x)); }
; DEV void phase_p15(const Params& p, int g) {
;     ...
;         for (int e = 0; e < 8; ++e) {
;           const int jj = j8 * 8 + e;
;           const int j = dir ? 63 - jj : jj;
;           const size_t tok = (size_t)cidx * 64 + j;
;           const float f = lb[cc] + (1.f - lb[cc]) * sigmoid_f(bf2f(xr[st][cc][e]));
;           G[cc] += __logf(f);
;           const float eg = __expf(G[cc]), ig = __expf(-G[cc]);
;           Qp[tok * 512 + c] = f2bf(bf2f(qr[st][cc][e]) * eg);
;           const u16 kk = f2bf((1.f - f) * ig);
;           Kp[tok * 512 + c] = kk;
;           kb[e] = kk;
;         }
;         const int s0 = dir ? 56 - 8 * j8 : 8 * j8;
;         uint4 w;
;         w.x = dir ? (kb[7] | (kb[6] << 16)) : (kb[0] | (kb[1] << 16));
;         w.y = dir ? (kb[5] | (kb[4] << 16)) : (kb[2] | (kb[3] << 16));
;         w.z = dir ? (kb[3] | (kb[2] << 16)) : (kb[4] | (kb[5] << 16));
;         w.w = dir ? (kb[1] | (kb[0] << 16)) : (kb[6] | (kb[7] << 16));
;         *(uint4*)(KT + (((size_t)cidx * 2 + dir) * 512 + c) * 64 + s0) = w;
	v_sub_f32_e32 v99, 1.0, v99
	v_mul_f32_e32 v96, v96, v92
	v_mul_f32_e32 v97, v97, v93
	v_mul_f32_e32 v98, v98, v94
	v_mul_f32_e32 v99, v99, v95
	v_lshlrev_b32_e32 v92, 16, v14
	v_and_b32_e32 v93, 0xffff0000, v14
	v_lshlrev_b32_e32 v94, 16, v15
	v_and_b32_e32 v95, 0xffff0000, v15
	v_mul_f32_e32 v92, v92, v100
	v_mul_f32_e32 v93, v93, v101
	v_mul_f32_e32 v94, v94, v102
	v_mul_f32_e32 v95, v95, v103
	v_cvt_pk_bf16_f32 v108, v92, v93
	v_cvt_pk_bf16_f32 v109, v94, v95
	v_cvt_pk_bf16_f32 v110, v96, v97
	v_cvt_pk_bf16_f32 v111, v98, v99
	global_store_dwordx2 v112, v[108:109], s[2:3]
	global_store_dwordx2 v114, v[110:111], s[2:3]
	s_add_u32 s2, s2, 0x400
	s_addc_u32 s3, s3, 0
	v_cvt_pk_bf16_f32 v125, v104, v96
	v_cvt_pk_bf16_f32 v141, v105, v97
	v_cvt_pk_bf16_f32 v175, v106, v98
	v_cvt_pk_bf16_f32 v191, v107, v99
	v_lshlrev_b32_e32 v92, 16, v16
	v_and_b32_e32 v93, 0xffff0000, v16
	v_lshlrev_b32_e32 v94, 16, v17
	v_and_b32_e32 v95, 0xffff0000, v17
	v_mul_f32_e32 v92, 0xbfb8aa3b, v92
	v_mul_f32_e32 v93, 0xbfb8aa3b, v93
	v_mul_f32_e32 v94, 0xbfb8aa3b, v94
	v_mul_f32_e32 v95, 0xbfb8aa3b, v95
	v_exp_f32_e32 v92, v92
	v_exp_f32_e32 v93, v93
	v_exp_f32_e32 v94, v94
	v_exp_f32_e32 v95, v95
	v_add_f32_e32 v92, 1.0, v92
	v_add_f32_e32 v93, 1.0, v93
	v_add_f32_e32 v94, 1.0, v94
	v_add_f32_e32 v95, 1.0, v95
	v_rcp_f32_e32 v92, v92
	v_rcp_f32_e32 v93, v93
	v_rcp_f32_e32 v94, v94
	v_rcp_f32_e32 v95, v95
	v_fma_f32 v96, v72, v92, v68
	v_fma_f32 v97, v73, v93, v69
	v_fma_f32 v98, v74, v94, v70
	v_fma_f32 v99, v75, v95, v71
	v_cmp_gt_f32_e64 s[22:23], s30, v96
	v_cmp_gt_f32_e64 s[24:25], s30, v97
	v_cmp_gt_f32_e64 s[26:27], s30, v98
	v_cmp_gt_f32_e64 s[28:29], s30, v99
	v_cndmask_b32_e64 v92, 0, 32, s[22:23]
	v_cndmask_b32_e64 v93, 0, 32, s[24:25]
	v_cndmask_b32_e64 v94, 0, 32, s[26:27]
	v_cndmask_b32_e64 v95, 0, 32, s[28:29]
	v_ldexp_f32 v92, v96, v92
	v_ldexp_f32 v93, v97, v93
	v_ldexp_f32 v94, v98, v94
	v_ldexp_f32 v95, v99, v95
	v_log_f32_e32 v92, v92
	v_log_f32_e32 v93, v93
	v_log_f32_e32 v94, v94
	v_log_f32_e32 v95, v95
	v_mul_f32_e32 v100, 0x3f317217, v92
	v_mul_f32_e32 v101, 0x3f317217, v93
	v_mul_f32_e32 v102, 0x3f317217, v94
	v_mul_f32_e32 v103, 0x3f317217, v95
	v_fma_f32 v100, v92, s31, -v100
	v_fma_f32 v101, v93, s31, -v101
	v_fma_f32 v102, v94, s31, -v102
	v_fma_f32 v103, v95, s31, -v103
	v_fmac_f32_e32 v100, 0x3377d1cf, v92
	v_fmac_f32_e32 v101, 0x3377d1cf, v93
	v_fmac_f32_e32 v102, 0x3377d1cf, v94
	v_fmac_f32_e32 v103, 0x3377d1cf, v95
	v_fmac_f32_e32 v100, 0x3f317217, v92
	v_fmac_f32_e32 v101, 0x3f317217, v93
	v_fmac_f32_e32 v102, 0x3f317217, v94
	v_fmac_f32_e32 v103, 0x3f317217, v95
	v_cmp_lt_f32_e64 vcc, |v92|, s34
	v_cndmask_b32_e32 v92, v92, v100, vcc
	v_cmp_lt_f32_e64 vcc, |v93|, s34
	v_cndmask_b32_e32 v93, v93, v101, vcc
	v_cmp_lt_f32_e64 vcc, |v94|, s34
	v_cndmask_b32_e32 v94, v94, v102, vcc
	v_cmp_lt_f32_e64 vcc, |v95|, s34
	v_cndmask_b32_e32 v95, v95, v103, vcc
	v_cndmask_b32_e64 v100, 0, v213, s[22:23]
	v_cndmask_b32_e64 v101, 0, v213, s[24:25]
	v_cndmask_b32_e64 v102, 0, v213, s[26:27]
	v_cndmask_b32_e64 v103, 0, v213, s[28:29]
	v_sub_f32_e32 v92, v92, v100
	v_sub_f32_e32 v93, v93, v101
	v_sub_f32_e32 v94, v94, v102
	v_sub_f32_e32 v95, v95, v103
	v_add_f32_e32 v64, v64, v92
	v_add_f32_e32 v65, v65, v93
	v_add_f32_e32 v66, v66, v94
	v_add_f32_e32 v67, v67, v95
	v_mul_f32_e32 v92, 0xbfb8aa3b, v64
	v_mul_f32_e32 v93, 0xbfb8aa3b, v65
	v_mul_f32_e32 v94, 0xbfb8aa3b, v66
	v_mul_f32_e32 v95, 0xbfb8aa3b, v67
	v_mul_f32_e32 v100, 0x3fb8aa3b, v64
	v_mul_f32_e32 v101, 0x3fb8aa3b, v65
	v_mul_f32_e32 v102, 0x3fb8aa3b, v66
	v_mul_f32_e32 v103, 0x3fb8aa3b, v67
	v_exp_f32_e32 v92, v92
	v_exp_f32_e32 v93, v93
	v_exp_f32_e32 v94, v94
	v_exp_f32_e32 v95, v95
	v_exp_f32_e32 v100, v100
	v_exp_f32_e32 v101, v101
	v_exp_f32_e32 v102, v102
	v_exp_f32_e32 v103, v103
	v_sub_f32_e32 v96, 1.0, v96
	v_sub_f32_e32 v97, 1.0, v97
	v_sub_f32_e32 v98, 1.0, v98
	v_sub_f32_e32 v99, 1.0, v99
	v_mul_f32_e32 v96, v96, v92
	v_mul_f32_e32 v97, v97, v93
	v_mul_f32_e32 v98, v98, v94
	v_mul_f32_e32 v99, v99, v95
	v_lshlrev_b32_e32 v92, 16, v18
	v_and_b32_e32 v93, 0xffff0000, v18
	v_lshlrev_b32_e32 v94, 16, v19
	v_and_b32_e32 v95, 0xffff0000, v19
	v_mul_f32_e32 v92, v92, v100
	v_mul_f32_e32 v93, v93, v101
	v_mul_f32_e32 v94, v94, v102
	v_mul_f32_e32 v95, v95, v103
	v_cvt_pk_bf16_f32 v108, v92, v93
	v_cvt_pk_bf16_f32 v109, v94, v95
	v_cvt_pk_bf16_f32 v110, v96, v97
	v_cvt_pk_bf16_f32 v111, v98, v99
	global_store_dwordx2 v112, v[108:109], s[2:3]
	global_store_dwordx2 v114, v[110:111], s[2:3]
	s_add_u32 s2, s2, 0x400
	s_addc_u32 s3, s3, 0
	v_mov_b32_e32 v104, v96
	v_mov_b32_e32 v105, v97
	v_mov_b32_e32 v106, v98
	v_mov_b32_e32 v107, v99
	v_lshlrev_b32_e32 v92, 16, v20
	v_and_b32_e32 v93, 0xffff0000, v20
	v_lshlrev_b32_e32 v94, 16, v21
	v_and_b32_e32 v95, 0xffff0000, v21
	v_mul_f32_e32 v92, 0xbfb8aa3b, v92
	v_mul_f32_e32 v93, 0xbfb8aa3b, v93
	v_mul_f32_e32 v94, 0xbfb8aa3b, v94
	v_mul_f32_e32 v95, 0xbfb8aa3b, v95
	v_exp_f32_e32 v92, v92
	v_exp_f32_e32 v93, v93
	v_exp_f32_e32 v94, v94
	v_exp_f32_e32 v95, v95
	v_add_f32_e32 v92, 1.0, v92
	v_add_f32_e32 v93, 1.0, v93
	v_add_f32_e32 v94, 1.0, v94
	v_add_f32_e32 v95, 1.0, v95
	v_rcp_f32_e32 v92, v92
	v_rcp_f32_e32 v93, v93
	v_rcp_f32_e32 v94, v94
	v_rcp_f32_e32 v95, v95
	v_fma_f32 v96, v72, v92, v68
	v_fma_f32 v97, v73, v93, v69
	v_fma_f32 v98, v74, v94, v70
	v_fma_f32 v99, v75, v95, v71
	v_cmp_gt_f32_e64 s[22:23], s30, v96
	v_cmp_gt_f32_e64 s[24:25], s30, v97
	v_cmp_gt_f32_e64 s[26:27], s30, v98
	v_cmp_gt_f32_e64 s[28:29], s30, v99
	v_cndmask_b32_e64 v92, 0, 32, s[22:23]
	v_cndmask_b32_e64 v93, 0, 32, s[24:25]
	v_cndmask_b32_e64 v94, 0, 32, s[26:27]
; DEV u16 f2bf(float f) { return (u16)(pack2(f, f) & 0xffffu); }
; DEV float bf2f(u16 h) { return __uint_as_float(((unsigned)h) << 16); }
; DEV float sigmoid_f(float x) { return __builtin_amdgcn_rcpf(1.f + __expf(-x)); }
; DEV void phase_p15(const Params& p, int g) {
;     ...
;         for (int e = 0; e < 8; ++e) {
;           const int jj = j8 * 8 + e;
;           const int j = dir ? 63 - jj : jj;
;           const size_t tok = (size_t)cidx * 64 + j;
;           const float f = lb[cc] + (1.f - lb[cc]) * sigmoid_f(bf2f(xr[st][cc][e]));
;           G[cc] += __logf(f);
;           const float eg = __expf(G[cc]), ig = __expf(-G[cc]);
;           Qp[tok * 512 + c] = f2bf(bf2f(qr[st][cc][e]) * eg);
;           const u16 kk = f2bf((1.f - f) * ig);
;           Kp[tok * 512 + c] = kk;
;           kb[e] = kk;
;         }
;         const int s0 = dir ? 56 - 8 * j8 : 8 * j8;
;         uint4 w;
;         w.x = dir ? (kb[7] | (kb[6] << 16)) : (kb[0] | (kb[1] << 16));
;         w.y = dir ? (kb[5] | (kb[4] << 16)) : (kb[2] | (kb[3] << 16));
;         w.z = dir ? (kb[3] | (kb[2] << 16)) : (kb[4] | (kb[5] << 16));
;         w.w = dir ? (kb[1] | (kb[0] << 16)) : (kb[6] | (kb[7] << 16));
;         *(uint4*)(KT + (((size_t)cidx * 2 + dir) * 512 + c) * 64 + s0) = w;
	v_cndmask_b32_e64 v95, 0, 32, s[28:29]
	v_ldexp_f32 v92, v96, v92
	v_ldexp_f32 v93, v97, v93
	v_ldexp_f32 v94, v98, v94
	v_ldexp_f32 v95, v99, v95
	v_log_f32_e32 v92, v92
	v_log_f32_e32 v93, v93
	v_log_f32_e32 v94, v94
	v_log_f32_e32 v95, v95
	v_mul_f32_e32 v100, 0x3f317217, v92
	v_mul_f32_e32 v101, 0x3f317217, v93
	v_mul_f32_e32 v102, 0x3f317217, v94
	v_mul_f32_e32 v103, 0x3f317217, v95
	v_fma_f32 v100, v92, s31, -v100
	v_fma_f32 v101, v93, s31, -v101
	v_fma_f32 v102, v94, s31, -v102
	v_fma_f32 v103, v95, s31, -v103
	v_fmac_f32_e32 v100, 0x3377d1cf, v92
	v_fmac_f32_e32 v101, 0x3377d1cf, v93
	v_fmac_f32_e32 v102, 0x3377d1cf, v94
	v_fmac_f32_e32 v103, 0x3377d1cf, v95
	v_fmac_f32_e32 v100, 0x3f317217, v92
	v_fmac_f32_e32 v101, 0x3f317217, v93
	v_fmac_f32_e32 v102, 0x3f317217, v94
	v_fmac_f32_e32 v103, 0x3f317217, v95
	v_cmp_lt_f32_e64 vcc, |v92|, s34
	v_cndmask_b32_e32 v92, v92, v100, vcc
	v_cmp_lt_f32_e64 vcc, |v93|, s34
	v_cndmask_b32_e32 v93, v93, v101, vcc
	v_cmp_lt_f32_e64 vcc, |v94|, s34
	v_cndmask_b32_e32 v94, v94, v102, vcc
	v_cmp_lt_f32_e64 vcc, |v95|, s34
	v_cndmask_b32_e32 v95, v95, v103, vcc
	v_cndmask_b32_e64 v100, 0, v213, s[22:23]
	v_cndmask_b32_e64 v101, 0, v213, s[24:25]
	v_cndmask_b32_e64 v102, 0, v213, s[26:27]
	v_cndmask_b32_e64 v103, 0, v213, s[28:29]
	v_sub_f32_e32 v92, v92, v100
	v_sub_f32_e32 v93, v93, v101
	v_sub_f32_e32 v94, v94, v102
	v_sub_f32_e32 v95, v95, v103
	v_add_f32_e32 v64, v64, v92
	v_add_f32_e32 v65, v65, v93
	v_add_f32_e32 v66, v66, v94
	v_add_f32_e32 v67, v67, v95
	v_mul_f32_e32 v92, 0xbfb8aa3b, v64
	v_mul_f32_e32 v93, 0xbfb8aa3b, v65
	v_mul_f32_e32 v94, 0xbfb8aa3b, v66
	v_mul_f32_e32 v95, 0xbfb8aa3b, v67
	v_mul_f32_e32 v100, 0x3fb8aa3b, v64
	v_mul_f32_e32 v101, 0x3fb8aa3b, v65
	v_mul_f32_e32 v102, 0x3fb8aa3b, v66
	v_mul_f32_e32 v103, 0x3fb8aa3b, v67
	v_exp_f32_e32 v92, v92
	v_exp_f32_e32 v93, v93
	v_exp_f32_e32 v94, v94
	v_exp_f32_e32 v95, v95
	v_exp_f32_e32 v100, v100
	v_exp_f32_e32 v101, v101
	v_exp_f32_e32 v102, v102
	v_exp_f32_e32 v103, v103
	v_sub_f32_e32 v96, 1.0, v96
	v_sub_f32_e32 v97, 1.0, v97
	v_sub_f32_e32 v98, 1.0, v98
	v_sub_f32_e32 v99, 1.0, v99
	v_mul_f32_e32 v96, v96, v92
	v_mul_f32_e32 v97, v97, v93
	v_mul_f32_e32 v98, v98, v94
	v_mul_f32_e32 v99, v99, v95
	v_lshlrev_b32_e32 v92, 16, v22
	v_and_b32_e32 v93, 0xffff0000, v22
	v_lshlrev_b32_e32 v94, 16, v23
	v_and_b32_e32 v95, 0xffff0000, v23
	v_mul_f32_e32 v92, v92, v100
	v_mul_f32_e32 v93, v93, v101
	v_mul_f32_e32 v94, v94, v102
	v_mul_f32_e32 v95, v95, v103
	v_cvt_pk_bf16_f32 v108, v92, v93
	v_cvt_pk_bf16_f32 v109, v94, v95
	v_cvt_pk_bf16_f32 v110, v96, v97
	v_cvt_pk_bf16_f32 v111, v98, v99
	global_store_dwordx2 v112, v[108:109], s[2:3]
	global_store_dwordx2 v114, v[110:111], s[2:3]
	s_add_u32 s2, s2, 0x400
	s_addc_u32 s3, s3, 0
	v_cvt_pk_bf16_f32 v126, v104, v96
	v_cvt_pk_bf16_f32 v142, v105, v97
	v_cvt_pk_bf16_f32 v176, v106, v98
	v_cvt_pk_bf16_f32 v192, v107, v99
	v_lshlrev_b32_e32 v92, 16, v24
	v_and_b32_e32 v93, 0xffff0000, v24
	v_lshlrev_b32_e32 v94, 16, v25
	v_and_b32_e32 v95, 0xffff0000, v25
	v_mul_f32_e32 v92, 0xbfb8aa3b, v92
	v_mul_f32_e32 v93, 0xbfb8aa3b, v93
	v_mul_f32_e32 v94, 0xbfb8aa3b, v94
	v_mul_f32_e32 v95, 0xbfb8aa3b, v95
	v_exp_f32_e32 v92, v92
	v_exp_f32_e32 v93, v93
	v_exp_f32_e32 v94, v94
	v_exp_f32_e32 v95, v95
	v_add_f32_e32 v92, 1.0, v92
	v_add_f32_e32 v93, 1.0, v93
	v_add_f32_e32 v94, 1.0, v94
	v_add_f32_e32 v95, 1.0, v95
	v_rcp_f32_e32 v92, v92
	v_rcp_f32_e32 v93, v93
	v_rcp_f32_e32 v94, v94
	v_rcp_f32_e32 v95, v95
	v_fma_f32 v96, v72, v92, v68
	v_fma_f32 v97, v73, v93, v69
	v_fma_f32 v98, v74, v94, v70
	v_fma_f32 v99, v75, v95, v71
	v_cmp_gt_f32_e64 s[22:23], s30, v96
	v_cmp_gt_f32_e64 s[24:25], s30, v97
	v_cmp_gt_f32_e64 s[26:27], s30, v98
	v_cmp_gt_f32_e64 s[28:29], s30, v99
	v_cndmask_b32_e64 v92, 0, 32, s[22:23]
	v_cndmask_b32_e64 v93, 0, 32, s[24:25]
	v_cndmask_b32_e64 v94, 0, 32, s[26:27]
	v_cndmask_b32_e64 v95, 0, 32, s[28:29]
	v_ldexp_f32 v92, v96, v92
	v_ldexp_f32 v93, v97, v93
	v_ldexp_f32 v94, v98, v94
	v_ldexp_f32 v95, v99, v95
	v_log_f32_e32 v92, v92
	v_log_f32_e32 v93, v93
	v_log_f32_e32 v94, v94
	v_log_f32_e32 v95, v95
	v_mul_f32_e32 v100, 0x3f317217, v92
	v_mul_f32_e32 v101, 0x3f317217, v93
	v_mul_f32_e32 v102, 0x3f317217, v94
	v_mul_f32_e32 v103, 0x3f317217, v95
	v_fma_f32 v100, v92, s31, -v100
	v_fma_f32 v101, v93, s31, -v101
	v_fma_f32 v102, v94, s31, -v102
	v_fma_f32 v103, v95, s31, -v103
	v_fmac_f32_e32 v100, 0x3377d1cf, v92
	v_fmac_f32_e32 v101, 0x3377d1cf, v93
	v_fmac_f32_e32 v102, 0x3377d1cf, v94
	v_fmac_f32_e32 v103, 0x3377d1cf, v95
	v_fmac_f32_e32 v100, 0x3f317217, v92
	v_fmac_f32_e32 v101, 0x3f317217, v93
	v_fmac_f32_e32 v102, 0x3f317217, v94
	v_fmac_f32_e32 v103, 0x3f317217, v95
	v_cmp_lt_f32_e64 vcc, |v92|, s34
	v_cndmask_b32_e32 v92, v92, v100, vcc
	v_cmp_lt_f32_e64 vcc, |v93|, s34
	v_cndmask_b32_e32 v93, v93, v101, vcc
	v_cmp_lt_f32_e64 vcc, |v94|, s34
	v_cndmask_b32_e32 v94, v94, v102, vcc
	v_cmp_lt_f32_e64 vcc, |v95|, s34
	v_cndmask_b32_e32 v95, v95, v103, vcc
	v_cndmask_b32_e64 v100, 0, v213, s[22:23]
	v_cndmask_b32_e64 v101, 0, v213, s[24:25]
	v_cndmask_b32_e64 v102, 0, v213, s[26:27]
	v_cndmask_b32_e64 v103, 0, v213, s[28:29]
	v_sub_f32_e32 v92, v92, v100
	v_sub_f32_e32 v93, v93, v101
	v_sub_f32_e32 v94, v94, v102
	v_sub_f32_e32 v95, v95, v103
	v_add_f32_e32 v64, v64, v92
	v_add_f32_e32 v65, v65, v93
	v_add_f32_e32 v66, v66, v94
	v_add_f32_e32 v67, v67, v95
	v_mul_f32_e32 v92, 0xbfb8aa3b, v64
	v_mul_f32_e32 v93, 0xbfb8aa3b, v65
	v_mul_f32_e32 v94, 0xbfb8aa3b, v66
	v_mul_f32_e32 v95, 0xbfb8aa3b, v67
	v_mul_f32_e32 v100, 0x3fb8aa3b, v64
	v_mul_f32_e32 v101, 0x3fb8aa3b, v65
; DEV u16 f2bf(float f) { return (u16)(pack2(f, f) & 0xffffu); }
; DEV float bf2f(u16 h) { return __uint_as_float(((unsigned)h) << 16); }
; DEV float sigmoid_f(float x) { return __builtin_amdgcn_rcpf(1.f + __expf(-x)); }
; DEV void phase_p15(const Params& p, int g) {
;     ...
;     P15_LOAD(0, 0);
;     P15_LOAD(1, 1);
; #pragma unroll
;     for (int j8 = 0; j8 < 8; ++j8) {
;       const int st = j8 % 3;
;       if (j8 < 6) { P15_LOAD((j8 + 2) % 3, j8 + 2); }
;     ...
;         for (int e = 0; e < 8; ++e) {
;           const int jj = j8 * 8 + e;
;           const int j = dir ? 63 - jj : jj;
;           const size_t tok = (size_t)cidx * 64 + j;
;           const float f = lb[cc] + (1.f - lb[cc]) * sigmoid_f(bf2f(xr[st][cc][e]));
;           G[cc] += __logf(f);
;           const float eg = __expf(G[cc]), ig = __expf(-G[cc]);
;           Qp[tok * 512 + c] = f2bf(bf2f(qr[st][cc][e]) * eg);
;           const u16 kk = f2bf((1.f - f) * ig);
;           Kp[tok * 512 + c] = kk;
;           kb[e] = kk;
;         }
;         const int s0 = dir ? 56 - 8 * j8 : 8 * j8;
;         uint4 w;
;         w.x = dir ? (kb[7] | (kb[6] << 16)) : (kb[0] | (kb[1] << 16));
;         w.y = dir ? (kb[5] | (kb[4] << 16)) : (kb[2] | (kb[3] << 16));
;         w.z = dir ? (kb[3] | (kb[2] << 16)) : (kb[4] | (kb[5] << 16));
;         w.w = dir ? (kb[1] | (kb[0] << 16)) : (kb[6] | (kb[7] << 16));
;         *(uint4*)(KT + (((size_t)cidx * 2 + dir) * 512 + c) * 64 + s0) = w;
	v_mul_f32_e32 v102, 0x3fb8aa3b, v66
	v_mul_f32_e32 v103, 0x3fb8aa3b, v67
	v_exp_f32_e32 v92, v92
	v_exp_f32_e32 v93, v93
	v_exp_f32_e32 v94, v94
	v_exp_f32_e32 v95, v95
	v_exp_f32_e32 v100, v100
	v_exp_f32_e32 v101, v101
	v_exp_f32_e32 v102, v102
	v_exp_f32_e32 v103, v103
	v_sub_f32_e32 v96, 1.0, v96
	v_sub_f32_e32 v97, 1.0, v97
	v_sub_f32_e32 v98, 1.0, v98
	v_sub_f32_e32 v99, 1.0, v99
	v_mul_f32_e32 v96, v96, v92
	v_mul_f32_e32 v97, v97, v93
	v_mul_f32_e32 v98, v98, v94
	v_mul_f32_e32 v99, v99, v95
	v_lshlrev_b32_e32 v92, 16, v26
	v_and_b32_e32 v93, 0xffff0000, v26
	v_lshlrev_b32_e32 v94, 16, v27
	v_and_b32_e32 v95, 0xffff0000, v27
	v_mul_f32_e32 v92, v92, v100
	v_mul_f32_e32 v93, v93, v101
	v_mul_f32_e32 v94, v94, v102
	v_mul_f32_e32 v95, v95, v103
	v_cvt_pk_bf16_f32 v108, v92, v93
	v_cvt_pk_bf16_f32 v109, v94, v95
	v_cvt_pk_bf16_f32 v110, v96, v97
	v_cvt_pk_bf16_f32 v111, v98, v99
	global_store_dwordx2 v112, v[108:109], s[2:3]
	global_store_dwordx2 v114, v[110:111], s[2:3]
	s_add_u32 s2, s2, 0x400
	s_addc_u32 s3, s3, 0
	v_mov_b32_e32 v104, v96
	v_mov_b32_e32 v105, v97
	v_mov_b32_e32 v106, v98
	v_mov_b32_e32 v107, v99
	v_lshlrev_b32_e32 v92, 16, v28
	v_and_b32_e32 v93, 0xffff0000, v28
	v_lshlrev_b32_e32 v94, 16, v29
	v_and_b32_e32 v95, 0xffff0000, v29
	v_mul_f32_e32 v92, 0xbfb8aa3b, v92
	v_mul_f32_e32 v93, 0xbfb8aa3b, v93
	v_mul_f32_e32 v94, 0xbfb8aa3b, v94
	v_mul_f32_e32 v95, 0xbfb8aa3b, v95
	v_exp_f32_e32 v92, v92
	v_exp_f32_e32 v93, v93
	v_exp_f32_e32 v94, v94
	v_exp_f32_e32 v95, v95
	v_add_f32_e32 v92, 1.0, v92
	v_add_f32_e32 v93, 1.0, v93
	v_add_f32_e32 v94, 1.0, v94
	v_add_f32_e32 v95, 1.0, v95
	v_rcp_f32_e32 v92, v92
	v_rcp_f32_e32 v93, v93
	v_rcp_f32_e32 v94, v94
	v_rcp_f32_e32 v95, v95
	v_fma_f32 v96, v72, v92, v68
	v_fma_f32 v97, v73, v93, v69
	v_fma_f32 v98, v74, v94, v70
	v_fma_f32 v99, v75, v95, v71
	v_cmp_gt_f32_e64 s[22:23], s30, v96
	v_cmp_gt_f32_e64 s[24:25], s30, v97
	v_cmp_gt_f32_e64 s[26:27], s30, v98
	v_cmp_gt_f32_e64 s[28:29], s30, v99
	v_cndmask_b32_e64 v92, 0, 32, s[22:23]
	v_cndmask_b32_e64 v93, 0, 32, s[24:25]
	v_cndmask_b32_e64 v94, 0, 32, s[26:27]
	v_cndmask_b32_e64 v95, 0, 32, s[28:29]
	v_ldexp_f32 v92, v96, v92
	v_ldexp_f32 v93, v97, v93
	v_ldexp_f32 v94, v98, v94
	v_ldexp_f32 v95, v99, v95
	v_log_f32_e32 v92, v92
	v_log_f32_e32 v93, v93
	v_log_f32_e32 v94, v94
	v_log_f32_e32 v95, v95
	v_mul_f32_e32 v100, 0x3f317217, v92
	v_mul_f32_e32 v101, 0x3f317217, v93
	v_mul_f32_e32 v102, 0x3f317217, v94
	v_mul_f32_e32 v103, 0x3f317217, v95
	v_fma_f32 v100, v92, s31, -v100
	v_fma_f32 v101, v93, s31, -v101
	v_fma_f32 v102, v94, s31, -v102
	v_fma_f32 v103, v95, s31, -v103
	v_fmac_f32_e32 v100, 0x3377d1cf, v92
	v_fmac_f32_e32 v101, 0x3377d1cf, v93
	v_fmac_f32_e32 v102, 0x3377d1cf, v94
	v_fmac_f32_e32 v103, 0x3377d1cf, v95
	v_fmac_f32_e32 v100, 0x3f317217, v92
	v_fmac_f32_e32 v101, 0x3f317217, v93
	v_fmac_f32_e32 v102, 0x3f317217, v94
	v_fmac_f32_e32 v103, 0x3f317217, v95
	v_cmp_lt_f32_e64 vcc, |v92|, s34
	v_cndmask_b32_e32 v92, v92, v100, vcc
	v_cmp_lt_f32_e64 vcc, |v93|, s34
	v_cndmask_b32_e32 v93, v93, v101, vcc
	v_cmp_lt_f32_e64 vcc, |v94|, s34
	v_cndmask_b32_e32 v94, v94, v102, vcc
	v_cmp_lt_f32_e64 vcc, |v95|, s34
	v_cndmask_b32_e32 v95, v95, v103, vcc
	v_cndmask_b32_e64 v100, 0, v213, s[22:23]
	v_cndmask_b32_e64 v101, 0, v213, s[24:25]
	v_cndmask_b32_e64 v102, 0, v213, s[26:27]
	v_cndmask_b32_e64 v103, 0, v213, s[28:29]
	v_sub_f32_e32 v92, v92, v100
	v_sub_f32_e32 v93, v93, v101
	v_sub_f32_e32 v94, v94, v102
	v_sub_f32_e32 v95, v95, v103
	v_add_f32_e32 v64, v64, v92
	v_add_f32_e32 v65, v65, v93
	v_add_f32_e32 v66, v66, v94
	v_add_f32_e32 v67, v67, v95
	v_mul_f32_e32 v92, 0xbfb8aa3b, v64
	v_mul_f32_e32 v93, 0xbfb8aa3b, v65
	v_mul_f32_e32 v94, 0xbfb8aa3b, v66
	v_mul_f32_e32 v95, 0xbfb8aa3b, v67
	v_mul_f32_e32 v100, 0x3fb8aa3b, v64
	v_mul_f32_e32 v101, 0x3fb8aa3b, v65
	v_mul_f32_e32 v102, 0x3fb8aa3b, v66
	v_mul_f32_e32 v103, 0x3fb8aa3b, v67
	v_exp_f32_e32 v92, v92
	v_exp_f32_e32 v93, v93
	v_exp_f32_e32 v94, v94
	v_exp_f32_e32 v95, v95
	v_exp_f32_e32 v100, v100
	v_exp_f32_e32 v101, v101
	v_exp_f32_e32 v102, v102
	v_exp_f32_e32 v103, v103
	v_sub_f32_e32 v96, 1.0, v96
	v_sub_f32_e32 v97, 1.0, v97
	v_sub_f32_e32 v98, 1.0, v98
	v_sub_f32_e32 v99, 1.0, v99
	v_mul_f32_e32 v96, v96, v92
	v_mul_f32_e32 v97, v97, v93
	v_mul_f32_e32 v98, v98, v94
	v_mul_f32_e32 v99, v99, v95
	v_lshlrev_b32_e32 v92, 16, v30
	v_and_b32_e32 v93, 0xffff0000, v30
	v_lshlrev_b32_e32 v94, 16, v31
	v_and_b32_e32 v95, 0xffff0000, v31
	v_mul_f32_e32 v92, v92, v100
	v_mul_f32_e32 v93, v93, v101
	v_mul_f32_e32 v94, v94, v102
	v_mul_f32_e32 v95, v95, v103
	v_cvt_pk_bf16_f32 v108, v92, v93
	v_cvt_pk_bf16_f32 v109, v94, v95
	v_cvt_pk_bf16_f32 v110, v96, v97
	v_cvt_pk_bf16_f32 v111, v98, v99
	global_store_dwordx2 v112, v[108:109], s[2:3]
	global_store_dwordx2 v114, v[110:111], s[2:3]
	s_add_u32 s2, s2, 0x400
	s_addc_u32 s3, s3, 0
	v_cvt_pk_bf16_f32 v127, v104, v96
	v_cvt_pk_bf16_f32 v143, v105, v97
	v_cvt_pk_bf16_f32 v177, v106, v98
	v_cvt_pk_bf16_f32 v193, v107, v99
	global_load_dwordx2 v[0:1], v113, s[0:1]
	global_load_dwordx2 v[2:3], v112, s[0:1]
	s_add_u32 s0, s0, 0x1400
	s_addc_u32 s1, s1, 0
	global_load_dwordx2 v[4:5], v113, s[0:1]
	global_load_dwordx2 v[6:7], v112, s[0:1]
	s_add_u32 s0, s0, 0x1400
	s_addc_u32 s1, s1, 0
	global_load_dwordx2 v[8:9], v113, s[0:1]
	global_load_dwordx2 v[10:11], v112, s[0:1]
	s_add_u32 s0, s0, 0x1400
	s_addc_u32 s1, s1, 0
	global_load_dwordx2 v[12:13], v113, s[0:1]
	global_load_dwordx2 v[14:15], v112, s[0:1]
	s_add_u32 s0, s0, 0x1400
	s_addc_u32 s1, s1, 0
	global_load_dwordx2 v[16:17], v113, s[0:1]
	global_load_dwordx2 v[18:19], v112, s[0:1]
	s_add_u32 s0, s0, 0x1400
	s_addc_u32 s1, s1, 0
	global_load_dwordx2 v[20:21], v113, s[0:1]
	global_load_dwordx2 v[22:23], v112, s[0:1]
	s_add_u32 s0, s0, 0x1400
	s_addc_u32 s1, s1, 0
	global_load_dwordx2 v[24:25], v113, s[0:1]
	global_load_dwordx2 v[26:27], v112, s[0:1]
	s_add_u32 s0, s0, 0x1400
	s_addc_u32 s1, s1, 0
	global_load_dwordx2 v[28:29], v113, s[0:1]
	global_load_dwordx2 v[30:31], v112, s[0:1]
	s_add_u32 s0, s0, 0x1400
	s_addc_u32 s1, s1, 0
	s_waitcnt vmcnt(32)
; DEV u16 f2bf(float f) { return (u16)(pack2(f, f) & 0xffffu); }
; DEV float bf2f(u16 h) { return __uint_as_float(((unsigned)h) << 16); }
; DEV float sigmoid_f(float x) { return __builtin_amdgcn_rcpf(1.f + __expf(-x)); }
; DEV void phase_p15(const Params& p, int g) {
;     ...
;         for (int e = 0; e < 8; ++e) {
;           const int jj = j8 * 8 + e;
;           const int j = dir ? 63 - jj : jj;
;           const size_t tok = (size_t)cidx * 64 + j;
;           const float f = lb[cc] + (1.f - lb[cc]) * sigmoid_f(bf2f(xr[st][cc][e]));
;           G[cc] += __logf(f);
;           const float eg = __expf(G[cc]), ig = __expf(-G[cc]);
;           Qp[tok * 512 + c] = f2bf(bf2f(qr[st][cc][e]) * eg);
;           const u16 kk = f2bf((1.f - f) * ig);
;           Kp[tok * 512 + c] = kk;
;           kb[e] = kk;
;         }
	v_lshlrev_b32_e32 v92, 16, v32
	v_and_b32_e32 v93, 0xffff0000, v32
	v_lshlrev_b32_e32 v94, 16, v33
	v_and_b32_e32 v95, 0xffff0000, v33
	v_mul_f32_e32 v92, 0xbfb8aa3b, v92
	v_mul_f32_e32 v93, 0xbfb8aa3b, v93
	v_mul_f32_e32 v94, 0xbfb8aa3b, v94
	v_mul_f32_e32 v95, 0xbfb8aa3b, v95
	v_exp_f32_e32 v92, v92
	v_exp_f32_e32 v93, v93
	v_exp_f32_e32 v94, v94
	v_exp_f32_e32 v95, v95
	v_add_f32_e32 v92, 1.0, v92
	v_add_f32_e32 v93, 1.0, v93
	v_add_f32_e32 v94, 1.0, v94
	v_add_f32_e32 v95, 1.0, v95
	v_rcp_f32_e32 v92, v92
	v_rcp_f32_e32 v93, v93
	v_rcp_f32_e32 v94, v94
	v_rcp_f32_e32 v95, v95
	v_fma_f32 v96, v72, v92, v68
	v_fma_f32 v97, v73, v93, v69
	v_fma_f32 v98, v74, v94, v70
	v_fma_f32 v99, v75, v95, v71
	v_cmp_gt_f32_e64 s[22:23], s30, v96
	v_cmp_gt_f32_e64 s[24:25], s30, v97
	v_cmp_gt_f32_e64 s[26:27], s30, v98
	v_cmp_gt_f32_e64 s[28:29], s30, v99
	v_cndmask_b32_e64 v92, 0, 32, s[22:23]
	v_cndmask_b32_e64 v93, 0, 32, s[24:25]
	v_cndmask_b32_e64 v94, 0, 32, s[26:27]
	v_cndmask_b32_e64 v95, 0, 32, s[28:29]
	v_ldexp_f32 v92, v96, v92
	v_ldexp_f32 v93, v97, v93
	v_ldexp_f32 v94, v98, v94
	v_ldexp_f32 v95, v99, v95
	v_log_f32_e32 v92, v92
	v_log_f32_e32 v93, v93
	v_log_f32_e32 v94, v94
	v_log_f32_e32 v95, v95
	v_mul_f32_e32 v100, 0x3f317217, v92
	v_mul_f32_e32 v101, 0x3f317217, v93
	v_mul_f32_e32 v102, 0x3f317217, v94
	v_mul_f32_e32 v103, 0x3f317217, v95
	v_fma_f32 v100, v92, s31, -v100
	v_fma_f32 v101, v93, s31, -v101
	v_fma_f32 v102, v94, s31, -v102
	v_fma_f32 v103, v95, s31, -v103
	v_fmac_f32_e32 v100, 0x3377d1cf, v92
	v_fmac_f32_e32 v101, 0x3377d1cf, v93
	v_fmac_f32_e32 v102, 0x3377d1cf, v94
	v_fmac_f32_e32 v103, 0x3377d1cf, v95
	v_fmac_f32_e32 v100, 0x3f317217, v92
	v_fmac_f32_e32 v101, 0x3f317217, v93
	v_fmac_f32_e32 v102, 0x3f317217, v94
	v_fmac_f32_e32 v103, 0x3f317217, v95
	v_cmp_lt_f32_e64 vcc, |v92|, s34
	v_cndmask_b32_e32 v92, v92, v100, vcc
	v_cmp_lt_f32_e64 vcc, |v93|, s34
	v_cndmask_b32_e32 v93, v93, v101, vcc
	v_cmp_lt_f32_e64 vcc, |v94|, s34
	v_cndmask_b32_e32 v94, v94, v102, vcc
	v_cmp_lt_f32_e64 vcc, |v95|, s34
	v_cndmask_b32_e32 v95, v95, v103, vcc
	v_cndmask_b32_e64 v100, 0, v213, s[22:23]
	v_cndmask_b32_e64 v101, 0, v213, s[24:25]
	v_cndmask_b32_e64 v102, 0, v213, s[26:27]
	v_cndmask_b32_e64 v103, 0, v213, s[28:29]
	v_sub_f32_e32 v92, v92, v100
	v_sub_f32_e32 v93, v93, v101
	v_sub_f32_e32 v94, v94, v102
	v_sub_f32_e32 v95, v95, v103
	v_add_f32_e32 v64, v64, v92
	v_add_f32_e32 v65, v65, v93
	v_add_f32_e32 v66, v66, v94
	v_add_f32_e32 v67, v67, v95
	v_mul_f32_e32 v92, 0xbfb8aa3b, v64
	v_mul_f32_e32 v93, 0xbfb8aa3b, v65
	v_mul_f32_e32 v94, 0xbfb8aa3b, v66
	v_mul_f32_e32 v95, 0xbfb8aa3b, v67
	v_mul_f32_e32 v100, 0x3fb8aa3b, v64
	v_mul_f32_e32 v101, 0x3fb8aa3b, v65
	v_mul_f32_e32 v102, 0x3fb8aa3b, v66
	v_mul_f32_e32 v103, 0x3fb8aa3b, v67
	v_exp_f32_e32 v92, v92
	v_exp_f32_e32 v93, v93
	v_exp_f32_e32 v94, v94
	v_exp_f32_e32 v95, v95
	v_exp_f32_e32 v100, v100
	v_exp_f32_e32 v101, v101
	v_exp_f32_e32 v102, v102
	v_exp_f32_e32 v103, v103
	v_sub_f32_e32 v96, 1.0, v96
	v_sub_f32_e32 v97, 1.0, v97
	v_sub_f32_e32 v98, 1.0, v98
	v_sub_f32_e32 v99, 1.0, v99
	v_mul_f32_e32 v96, v96, v92
	v_mul_f32_e32 v97, v97, v93
	v_mul_f32_e32 v98, v98, v94
	v_mul_f32_e32 v99, v99, v95
	v_lshlrev_b32_e32 v92, 16, v34
	v_and_b32_e32 v93, 0xffff0000, v34
	v_lshlrev_b32_e32 v94, 16, v35
	v_and_b32_e32 v95, 0xffff0000, v35
	v_mul_f32_e32 v92, v92, v100
	v_mul_f32_e32 v93, v93, v101
	v_mul_f32_e32 v94, v94, v102
	v_mul_f32_e32 v95, v95, v103
	v_cvt_pk_bf16_f32 v108, v92, v93
	v_cvt_pk_bf16_f32 v109, v94, v95
	v_cvt_pk_bf16_f32 v110, v96, v97
	v_cvt_pk_bf16_f32 v111, v98, v99
	global_store_dwordx2 v112, v[108:109], s[2:3]
	global_store_dwordx2 v114, v[110:111], s[2:3]
	s_add_u32 s2, s2, 0x400
	s_addc_u32 s3, s3, 0
	v_mov_b32_e32 v104, v96
	v_mov_b32_e32 v105, v97
	v_mov_b32_e32 v106, v98
	v_mov_b32_e32 v107, v99
	v_lshlrev_b32_e32 v92, 16, v36
	v_and_b32_e32 v93, 0xffff0000, v36
	v_lshlrev_b32_e32 v94, 16, v37
	v_and_b32_e32 v95, 0xffff0000, v37
	v_mul_f32_e32 v92, 0xbfb8aa3b, v92
	v_mul_f32_e32 v93, 0xbfb8aa3b, v93
	v_mul_f32_e32 v94, 0xbfb8aa3b, v94
	v_mul_f32_e32 v95, 0xbfb8aa3b, v95
	v_exp_f32_e32 v92, v92
	v_exp_f32_e32 v93, v93
	v_exp_f32_e32 v94, v94
	v_exp_f32_e32 v95, v95
	v_add_f32_e32 v92, 1.0, v92
	v_add_f32_e32 v93, 1.0, v93
	v_add_f32_e32 v94, 1.0, v94
	v_add_f32_e32 v95, 1.0, v95
	v_rcp_f32_e32 v92, v92
	v_rcp_f32_e32 v93, v93
	v_rcp_f32_e32 v94, v94
	v_rcp_f32_e32 v95, v95
	v_fma_f32 v96, v72, v92, v68
	v_fma_f32 v97, v73, v93, v69
	v_fma_f32 v98, v74, v94, v70
	v_fma_f32 v99, v75, v95, v71
	v_cmp_gt_f32_e64 s[22:23], s30, v96
	v_cmp_gt_f32_e64 s[24:25], s30, v97
	v_cmp_gt_f32_e64 s[26:27], s30, v98
	v_cmp_gt_f32_e64 s[28:29], s30, v99
	v_cndmask_b32_e64 v92, 0, 32, s[22:23]
	v_cndmask_b32_e64 v93, 0, 32, s[24:25]
	v_cndmask_b32_e64 v94, 0, 32, s[26:27]
	v_cndmask_b32_e64 v95, 0, 32, s[28:29]
	v_ldexp_f32 v92, v96, v92
	v_ldexp_f32 v93, v97, v93
	v_ldexp_f32 v94, v98, v94
	v_ldexp_f32 v95, v99, v95
	v_log_f32_e32 v92, v92
	v_log_f32_e32 v93, v93
	v_log_f32_e32 v94, v94
	v_log_f32_e32 v95, v95
	v_mul_f32_e32 v100, 0x3f317217, v92
	v_mul_f32_e32 v101, 0x3f317217, v93
	v_mul_f32_e32 v102, 0x3f317217, v94
	v_mul_f32_e32 v103, 0x3f317217, v95
	v_fma_f32 v100, v92, s31, -v100
	v_fma_f32 v101, v93, s31, -v101
	v_fma_f32 v102, v94, s31, -v102
	v_fma_f32 v103, v95, s31, -v103
	v_fmac_f32_e32 v100, 0x3377d1cf, v92
	v_fmac_f32_e32 v101, 0x3377d1cf, v93
	v_fmac_f32_e32 v102, 0x3377d1cf, v94
	v_fmac_f32_e32 v103, 0x3377d1cf, v95
	v_fmac_f32_e32 v100, 0x3f317217, v92
	v_fmac_f32_e32 v101, 0x3f317217, v93
	v_fmac_f32_e32 v102, 0x3f317217, v94
; DEV u16 f2bf(float f) { return (u16)(pack2(f, f) & 0xffffu); }
; DEV float bf2f(u16 h) { return __uint_as_float(((unsigned)h) << 16); }
; DEV float sigmoid_f(float x) { return __builtin_amdgcn_rcpf(1.f + __expf(-x)); }
; DEV void phase_p15(const Params& p, int g) {
;     ...
;         for (int e = 0; e < 8; ++e) {
;           const int jj = j8 * 8 + e;
;           const int j = dir ? 63 - jj : jj;
;           const size_t tok = (size_t)cidx * 64 + j;
;           const float f = lb[cc] + (1.f - lb[cc]) * sigmoid_f(bf2f(xr[st][cc][e]));
;           G[cc] += __logf(f);
;           const float eg = __expf(G[cc]), ig = __expf(-G[cc]);
;           Qp[tok * 512 + c] = f2bf(bf2f(qr[st][cc][e]) * eg);
;           const u16 kk = f2bf((1.f - f) * ig);
;           Kp[tok * 512 + c] = kk;
;           kb[e] = kk;
;         }
;         const int s0 = dir ? 56 - 8 * j8 : 8 * j8;
;         uint4 w;
;         w.x = dir ? (kb[7] | (kb[6] << 16)) : (kb[0] | (kb[1] << 16));
;         w.y = dir ? (kb[5] | (kb[4] << 16)) : (kb[2] | (kb[3] << 16));
;         w.z = dir ? (kb[3] | (kb[2] << 16)) : (kb[4] | (kb[5] << 16));
;         w.w = dir ? (kb[1] | (kb[0] << 16)) : (kb[6] | (kb[7] << 16));
;         *(uint4*)(KT + (((size_t)cidx * 2 + dir) * 512 + c) * 64 + s0) = w;
	v_fmac_f32_e32 v103, 0x3f317217, v95
	v_cmp_lt_f32_e64 vcc, |v92|, s34
	v_cndmask_b32_e32 v92, v92, v100, vcc
	v_cmp_lt_f32_e64 vcc, |v93|, s34
	v_cndmask_b32_e32 v93, v93, v101, vcc
	v_cmp_lt_f32_e64 vcc, |v94|, s34
	v_cndmask_b32_e32 v94, v94, v102, vcc
	v_cmp_lt_f32_e64 vcc, |v95|, s34
	v_cndmask_b32_e32 v95, v95, v103, vcc
	v_cndmask_b32_e64 v100, 0, v213, s[22:23]
	v_cndmask_b32_e64 v101, 0, v213, s[24:25]
	v_cndmask_b32_e64 v102, 0, v213, s[26:27]
	v_cndmask_b32_e64 v103, 0, v213, s[28:29]
	v_sub_f32_e32 v92, v92, v100
	v_sub_f32_e32 v93, v93, v101
	v_sub_f32_e32 v94, v94, v102
	v_sub_f32_e32 v95, v95, v103
	v_add_f32_e32 v64, v64, v92
	v_add_f32_e32 v65, v65, v93
	v_add_f32_e32 v66, v66, v94
	v_add_f32_e32 v67, v67, v95
	v_mul_f32_e32 v92, 0xbfb8aa3b, v64
	v_mul_f32_e32 v93, 0xbfb8aa3b, v65
	v_mul_f32_e32 v94, 0xbfb8aa3b, v66
	v_mul_f32_e32 v95, 0xbfb8aa3b, v67
	v_mul_f32_e32 v100, 0x3fb8aa3b, v64
	v_mul_f32_e32 v101, 0x3fb8aa3b, v65
	v_mul_f32_e32 v102, 0x3fb8aa3b, v66
	v_mul_f32_e32 v103, 0x3fb8aa3b, v67
	v_exp_f32_e32 v92, v92
	v_exp_f32_e32 v93, v93
	v_exp_f32_e32 v94, v94
	v_exp_f32_e32 v95, v95
	v_exp_f32_e32 v100, v100
	v_exp_f32_e32 v101, v101
	v_exp_f32_e32 v102, v102
	v_exp_f32_e32 v103, v103
	v_sub_f32_e32 v96, 1.0, v96
	v_sub_f32_e32 v97, 1.0, v97
	v_sub_f32_e32 v98, 1.0, v98
	v_sub_f32_e32 v99, 1.0, v99
	v_mul_f32_e32 v96, v96, v92
	v_mul_f32_e32 v97, v97, v93
	v_mul_f32_e32 v98, v98, v94
	v_mul_f32_e32 v99, v99, v95
	v_lshlrev_b32_e32 v92, 16, v38
	v_and_b32_e32 v93, 0xffff0000, v38
	v_lshlrev_b32_e32 v94, 16, v39
	v_and_b32_e32 v95, 0xffff0000, v39
	v_mul_f32_e32 v92, v92, v100
	v_mul_f32_e32 v93, v93, v101
	v_mul_f32_e32 v94, v94, v102
	v_mul_f32_e32 v95, v95, v103
	v_cvt_pk_bf16_f32 v108, v92, v93
	v_cvt_pk_bf16_f32 v109, v94, v95
	v_cvt_pk_bf16_f32 v110, v96, v97
	v_cvt_pk_bf16_f32 v111, v98, v99
	global_store_dwordx2 v112, v[108:109], s[2:3]
	global_store_dwordx2 v114, v[110:111], s[2:3]
	s_add_u32 s2, s2, 0x400
	s_addc_u32 s3, s3, 0
	v_cvt_pk_bf16_f32 v128, v104, v96
	v_cvt_pk_bf16_f32 v144, v105, v97
	v_cvt_pk_bf16_f32 v178, v106, v98
	v_cvt_pk_bf16_f32 v194, v107, v99
	v_lshlrev_b32_e32 v92, 16, v40
	v_and_b32_e32 v93, 0xffff0000, v40
	v_lshlrev_b32_e32 v94, 16, v41
	v_and_b32_e32 v95, 0xffff0000, v41
	v_mul_f32_e32 v92, 0xbfb8aa3b, v92
	v_mul_f32_e32 v93, 0xbfb8aa3b, v93
	v_mul_f32_e32 v94, 0xbfb8aa3b, v94
	v_mul_f32_e32 v95, 0xbfb8aa3b, v95
	v_exp_f32_e32 v92, v92
	v_exp_f32_e32 v93, v93
	v_exp_f32_e32 v94, v94
	v_exp_f32_e32 v95, v95
	v_add_f32_e32 v92, 1.0, v92
	v_add_f32_e32 v93, 1.0, v93
	v_add_f32_e32 v94, 1.0, v94
	v_add_f32_e32 v95, 1.0, v95
	v_rcp_f32_e32 v92, v92
	v_rcp_f32_e32 v93, v93
	v_rcp_f32_e32 v94, v94
	v_rcp_f32_e32 v95, v95
	v_fma_f32 v96, v72, v92, v68
	v_fma_f32 v97, v73, v93, v69
	v_fma_f32 v98, v74, v94, v70
	v_fma_f32 v99, v75, v95, v71
	v_cmp_gt_f32_e64 s[22:23], s30, v96
	v_cmp_gt_f32_e64 s[24:25], s30, v97
	v_cmp_gt_f32_e64 s[26:27], s30, v98
	v_cmp_gt_f32_e64 s[28:29], s30, v99
	v_cndmask_b32_e64 v92, 0, 32, s[22:23]
	v_cndmask_b32_e64 v93, 0, 32, s[24:25]
	v_cndmask_b32_e64 v94, 0, 32, s[26:27]
	v_cndmask_b32_e64 v95, 0, 32, s[28:29]
	v_ldexp_f32 v92, v96, v92
	v_ldexp_f32 v93, v97, v93
	v_ldexp_f32 v94, v98, v94
	v_ldexp_f32 v95, v99, v95
	v_log_f32_e32 v92, v92
	v_log_f32_e32 v93, v93
	v_log_f32_e32 v94, v94
	v_log_f32_e32 v95, v95
	v_mul_f32_e32 v100, 0x3f317217, v92
	v_mul_f32_e32 v101, 0x3f317217, v93
	v_mul_f32_e32 v102, 0x3f317217, v94
	v_mul_f32_e32 v103, 0x3f317217, v95
	v_fma_f32 v100, v92, s31, -v100
	v_fma_f32 v101, v93, s31, -v101
	v_fma_f32 v102, v94, s31, -v102
	v_fma_f32 v103, v95, s31, -v103
	v_fmac_f32_e32 v100, 0x3377d1cf, v92
	v_fmac_f32_e32 v101, 0x3377d1cf, v93
	v_fmac_f32_e32 v102, 0x3377d1cf, v94
	v_fmac_f32_e32 v103, 0x3377d1cf, v95
	v_fmac_f32_e32 v100, 0x3f317217, v92
	v_fmac_f32_e32 v101, 0x3f317217, v93
	v_fmac_f32_e32 v102, 0x3f317217, v94
	v_fmac_f32_e32 v103, 0x3f317217, v95
	v_cmp_lt_f32_e64 vcc, |v92|, s34
	v_cndmask_b32_e32 v92, v92, v100, vcc
	v_cmp_lt_f32_e64 vcc, |v93|, s34
	v_cndmask_b32_e32 v93, v93, v101, vcc
	v_cmp_lt_f32_e64 vcc, |v94|, s34
	v_cndmask_b32_e32 v94, v94, v102, vcc
	v_cmp_lt_f32_e64 vcc, |v95|, s34
	v_cndmask_b32_e32 v95, v95, v103, vcc
	v_cndmask_b32_e64 v100, 0, v213, s[22:23]
	v_cndmask_b32_e64 v101, 0, v213, s[24:25]
	v_cndmask_b32_e64 v102, 0, v213, s[26:27]
	v_cndmask_b32_e64 v103, 0, v213, s[28:29]
	v_sub_f32_e32 v92, v92, v100
	v_sub_f32_e32 v93, v93, v101
	v_sub_f32_e32 v94, v94, v102
	v_sub_f32_e32 v95, v95, v103
	v_add_f32_e32 v64, v64, v92
	v_add_f32_e32 v65, v65, v93
	v_add_f32_e32 v66, v66, v94
	v_add_f32_e32 v67, v67, v95
	v_mul_f32_e32 v92, 0xbfb8aa3b, v64
	v_mul_f32_e32 v93, 0xbfb8aa3b, v65
	v_mul_f32_e32 v94, 0xbfb8aa3b, v66
	v_mul_f32_e32 v95, 0xbfb8aa3b, v67
	v_mul_f32_e32 v100, 0x3fb8aa3b, v64
	v_mul_f32_e32 v101, 0x3fb8aa3b, v65
	v_mul_f32_e32 v102, 0x3fb8aa3b, v66
	v_mul_f32_e32 v103, 0x3fb8aa3b, v67
	v_exp_f32_e32 v92, v92
	v_exp_f32_e32 v93, v93
	v_exp_f32_e32 v94, v94
	v_exp_f32_e32 v95, v95
	v_exp_f32_e32 v100, v100
	v_exp_f32_e32 v101, v101
	v_exp_f32_e32 v102, v102
	v_exp_f32_e32 v103, v103
	v_sub_f32_e32 v96, 1.0, v96
	v_sub_f32_e32 v97, 1.0, v97
	v_sub_f32_e32 v98, 1.0, v98
	v_sub_f32_e32 v99, 1.0, v99
	v_mul_f32_e32 v96, v96, v92
	v_mul_f32_e32 v97, v97, v93
	v_mul_f32_e32 v98, v98, v94
	v_mul_f32_e32 v99, v99, v95
	v_lshlrev_b32_e32 v92, 16, v42
	v_and_b32_e32 v93, 0xffff0000, v42
	v_lshlrev_b32_e32 v94, 16, v43
	v_and_b32_e32 v95, 0xffff0000, v43
	v_mul_f32_e32 v92, v92, v100
	v_mul_f32_e32 v93, v93, v101
	v_mul_f32_e32 v94, v94, v102
	v_mul_f32_e32 v95, v95, v103
	v_cvt_pk_bf16_f32 v108, v92, v93
; DEV u16 f2bf(float f) { return (u16)(pack2(f, f) & 0xffffu); }
; DEV float bf2f(u16 h) { return __uint_as_float(((unsigned)h) << 16); }
; DEV float sigmoid_f(float x) { return __builtin_amdgcn_rcpf(1.f + __expf(-x)); }
; DEV void phase_p15(const Params& p, int g) {
;     ...
;         for (int e = 0; e < 8; ++e) {
;           const int jj = j8 * 8 + e;
;           const int j = dir ? 63 - jj : jj;
;           const size_t tok = (size_t)cidx * 64 + j;
;           const float f = lb[cc] + (1.f - lb[cc]) * sigmoid_f(bf2f(xr[st][cc][e]));
;           G[cc] += __logf(f);
;           const float eg = __expf(G[cc]), ig = __expf(-G[cc]);
;           Qp[tok * 512 + c] = f2bf(bf2f(qr[st][cc][e]) * eg);
;           const u16 kk = f2bf((1.f - f) * ig);
;           Kp[tok * 512 + c] = kk;
;           kb[e] = kk;
;         }
;         const int s0 = dir ? 56 - 8 * j8 : 8 * j8;
;         uint4 w;
;         w.x = dir ? (kb[7] | (kb[6] << 16)) : (kb[0] | (kb[1] << 16));
;         w.y = dir ? (kb[5] | (kb[4] << 16)) : (kb[2] | (kb[3] << 16));
;         w.z = dir ? (kb[3] | (kb[2] << 16)) : (kb[4] | (kb[5] << 16));
;         w.w = dir ? (kb[1] | (kb[0] << 16)) : (kb[6] | (kb[7] << 16));
;         *(uint4*)(KT + (((size_t)cidx * 2 + dir) * 512 + c) * 64 + s0) = w;
	v_cvt_pk_bf16_f32 v109, v94, v95
	v_cvt_pk_bf16_f32 v110, v96, v97
	v_cvt_pk_bf16_f32 v111, v98, v99
	global_store_dwordx2 v112, v[108:109], s[2:3]
	global_store_dwordx2 v114, v[110:111], s[2:3]
	s_add_u32 s2, s2, 0x400
	s_addc_u32 s3, s3, 0
	v_mov_b32_e32 v104, v96
	v_mov_b32_e32 v105, v97
	v_mov_b32_e32 v106, v98
	v_mov_b32_e32 v107, v99
	v_lshlrev_b32_e32 v92, 16, v44
	v_and_b32_e32 v93, 0xffff0000, v44
	v_lshlrev_b32_e32 v94, 16, v45
	v_and_b32_e32 v95, 0xffff0000, v45
	v_mul_f32_e32 v92, 0xbfb8aa3b, v92
	v_mul_f32_e32 v93, 0xbfb8aa3b, v93
	v_mul_f32_e32 v94, 0xbfb8aa3b, v94
	v_mul_f32_e32 v95, 0xbfb8aa3b, v95
	v_exp_f32_e32 v92, v92
	v_exp_f32_e32 v93, v93
	v_exp_f32_e32 v94, v94
	v_exp_f32_e32 v95, v95
	v_add_f32_e32 v92, 1.0, v92
	v_add_f32_e32 v93, 1.0, v93
	v_add_f32_e32 v94, 1.0, v94
	v_add_f32_e32 v95, 1.0, v95
	v_rcp_f32_e32 v92, v92
	v_rcp_f32_e32 v93, v93
	v_rcp_f32_e32 v94, v94
	v_rcp_f32_e32 v95, v95
	v_fma_f32 v96, v72, v92, v68
	v_fma_f32 v97, v73, v93, v69
	v_fma_f32 v98, v74, v94, v70
	v_fma_f32 v99, v75, v95, v71
	v_cmp_gt_f32_e64 s[22:23], s30, v96
	v_cmp_gt_f32_e64 s[24:25], s30, v97
	v_cmp_gt_f32_e64 s[26:27], s30, v98
	v_cmp_gt_f32_e64 s[28:29], s30, v99
	v_cndmask_b32_e64 v92, 0, 32, s[22:23]
	v_cndmask_b32_e64 v93, 0, 32, s[24:25]
	v_cndmask_b32_e64 v94, 0, 32, s[26:27]
	v_cndmask_b32_e64 v95, 0, 32, s[28:29]
	v_ldexp_f32 v92, v96, v92
	v_ldexp_f32 v93, v97, v93
	v_ldexp_f32 v94, v98, v94
	v_ldexp_f32 v95, v99, v95
	v_log_f32_e32 v92, v92
	v_log_f32_e32 v93, v93
	v_log_f32_e32 v94, v94
	v_log_f32_e32 v95, v95
	v_mul_f32_e32 v100, 0x3f317217, v92
	v_mul_f32_e32 v101, 0x3f317217, v93
	v_mul_f32_e32 v102, 0x3f317217, v94
	v_mul_f32_e32 v103, 0x3f317217, v95
	v_fma_f32 v100, v92, s31, -v100
	v_fma_f32 v101, v93, s31, -v101
	v_fma_f32 v102, v94, s31, -v102
	v_fma_f32 v103, v95, s31, -v103
	v_fmac_f32_e32 v100, 0x3377d1cf, v92
	v_fmac_f32_e32 v101, 0x3377d1cf, v93
	v_fmac_f32_e32 v102, 0x3377d1cf, v94
	v_fmac_f32_e32 v103, 0x3377d1cf, v95
	v_fmac_f32_e32 v100, 0x3f317217, v92
	v_fmac_f32_e32 v101, 0x3f317217, v93
	v_fmac_f32_e32 v102, 0x3f317217, v94
	v_fmac_f32_e32 v103, 0x3f317217, v95
	v_cmp_lt_f32_e64 vcc, |v92|, s34
	v_cndmask_b32_e32 v92, v92, v100, vcc
	v_cmp_lt_f32_e64 vcc, |v93|, s34
	v_cndmask_b32_e32 v93, v93, v101, vcc
	v_cmp_lt_f32_e64 vcc, |v94|, s34
	v_cndmask_b32_e32 v94, v94, v102, vcc
	v_cmp_lt_f32_e64 vcc, |v95|, s34
	v_cndmask_b32_e32 v95, v95, v103, vcc
	v_cndmask_b32_e64 v100, 0, v213, s[22:23]
	v_cndmask_b32_e64 v101, 0, v213, s[24:25]
	v_cndmask_b32_e64 v102, 0, v213, s[26:27]
	v_cndmask_b32_e64 v103, 0, v213, s[28:29]
	v_sub_f32_e32 v92, v92, v100
	v_sub_f32_e32 v93, v93, v101
	v_sub_f32_e32 v94, v94, v102
	v_sub_f32_e32 v95, v95, v103
	v_add_f32_e32 v64, v64, v92
	v_add_f32_e32 v65, v65, v93
	v_add_f32_e32 v66, v66, v94
	v_add_f32_e32 v67, v67, v95
	v_mul_f32_e32 v92, 0xbfb8aa3b, v64
	v_mul_f32_e32 v93, 0xbfb8aa3b, v65
	v_mul_f32_e32 v94, 0xbfb8aa3b, v66
	v_mul_f32_e32 v95, 0xbfb8aa3b, v67
	v_mul_f32_e32 v100, 0x3fb8aa3b, v64
	v_mul_f32_e32 v101, 0x3fb8aa3b, v65
	v_mul_f32_e32 v102, 0x3fb8aa3b, v66
	v_mul_f32_e32 v103, 0x3fb8aa3b, v67
	v_exp_f32_e32 v92, v92
	v_exp_f32_e32 v93, v93
	v_exp_f32_e32 v94, v94
	v_exp_f32_e32 v95, v95
	v_exp_f32_e32 v100, v100
	v_exp_f32_e32 v101, v101
	v_exp_f32_e32 v102, v102
	v_exp_f32_e32 v103, v103
	v_sub_f32_e32 v96, 1.0, v96
	v_sub_f32_e32 v97, 1.0, v97
	v_sub_f32_e32 v98, 1.0, v98
	v_sub_f32_e32 v99, 1.0, v99
	v_mul_f32_e32 v96, v96, v92
	v_mul_f32_e32 v97, v97, v93
	v_mul_f32_e32 v98, v98, v94
	v_mul_f32_e32 v99, v99, v95
	v_lshlrev_b32_e32 v92, 16, v46
	v_and_b32_e32 v93, 0xffff0000, v46
	v_lshlrev_b32_e32 v94, 16, v47
	v_and_b32_e32 v95, 0xffff0000, v47
	v_mul_f32_e32 v92, v92, v100
	v_mul_f32_e32 v93, v93, v101
	v_mul_f32_e32 v94, v94, v102
	v_mul_f32_e32 v95, v95, v103
	v_cvt_pk_bf16_f32 v108, v92, v93
	v_cvt_pk_bf16_f32 v109, v94, v95
	v_cvt_pk_bf16_f32 v110, v96, v97
	v_cvt_pk_bf16_f32 v111, v98, v99
	global_store_dwordx2 v112, v[108:109], s[2:3]
	global_store_dwordx2 v114, v[110:111], s[2:3]
	s_add_u32 s2, s2, 0x400
	s_addc_u32 s3, s3, 0
	v_cvt_pk_bf16_f32 v129, v104, v96
	v_cvt_pk_bf16_f32 v145, v105, v97
	v_cvt_pk_bf16_f32 v179, v106, v98
	v_cvt_pk_bf16_f32 v195, v107, v99
	v_lshlrev_b32_e32 v92, 16, v48
	v_and_b32_e32 v93, 0xffff0000, v48
	v_lshlrev_b32_e32 v94, 16, v49
	v_and_b32_e32 v95, 0xffff0000, v49
	v_mul_f32_e32 v92, 0xbfb8aa3b, v92
	v_mul_f32_e32 v93, 0xbfb8aa3b, v93
	v_mul_f32_e32 v94, 0xbfb8aa3b, v94
	v_mul_f32_e32 v95, 0xbfb8aa3b, v95
	v_exp_f32_e32 v92, v92
	v_exp_f32_e32 v93, v93
	v_exp_f32_e32 v94, v94
	v_exp_f32_e32 v95, v95
	v_add_f32_e32 v92, 1.0, v92
	v_add_f32_e32 v93, 1.0, v93
	v_add_f32_e32 v94, 1.0, v94
	v_add_f32_e32 v95, 1.0, v95
	v_rcp_f32_e32 v92, v92
	v_rcp_f32_e32 v93, v93
	v_rcp_f32_e32 v94, v94
	v_rcp_f32_e32 v95, v95
	v_fma_f32 v96, v72, v92, v68
	v_fma_f32 v97, v73, v93, v69
	v_fma_f32 v98, v74, v94, v70
	v_fma_f32 v99, v75, v95, v71
	v_cmp_gt_f32_e64 s[22:23], s30, v96
	v_cmp_gt_f32_e64 s[24:25], s30, v97
	v_cmp_gt_f32_e64 s[26:27], s30, v98
	v_cmp_gt_f32_e64 s[28:29], s30, v99
	v_cndmask_b32_e64 v92, 0, 32, s[22:23]
	v_cndmask_b32_e64 v93, 0, 32, s[24:25]
	v_cndmask_b32_e64 v94, 0, 32, s[26:27]
	v_cndmask_b32_e64 v95, 0, 32, s[28:29]
	v_ldexp_f32 v92, v96, v92
	v_ldexp_f32 v93, v97, v93
	v_ldexp_f32 v94, v98, v94
	v_ldexp_f32 v95, v99, v95
	v_log_f32_e32 v92, v92
	v_log_f32_e32 v93, v93
	v_log_f32_e32 v94, v94
	v_log_f32_e32 v95, v95
	v_mul_f32_e32 v100, 0x3f317217, v92
	v_mul_f32_e32 v101, 0x3f317217, v93
	v_mul_f32_e32 v102, 0x3f317217, v94
	v_mul_f32_e32 v103, 0x3f317217, v95
	v_fma_f32 v100, v92, s31, -v100
; DEV u16 f2bf(float f) { return (u16)(pack2(f, f) & 0xffffu); }
; DEV float bf2f(u16 h) { return __uint_as_float(((unsigned)h) << 16); }
; DEV float sigmoid_f(float x) { return __builtin_amdgcn_rcpf(1.f + __expf(-x)); }
; DEV void phase_p15(const Params& p, int g) {
;     ...
;         for (int e = 0; e < 8; ++e) {
;           const int jj = j8 * 8 + e;
;           const int j = dir ? 63 - jj : jj;
;           const size_t tok = (size_t)cidx * 64 + j;
;           const float f = lb[cc] + (1.f - lb[cc]) * sigmoid_f(bf2f(xr[st][cc][e]));
;           G[cc] += __logf(f);
;           const float eg = __expf(G[cc]), ig = __expf(-G[cc]);
;           Qp[tok * 512 + c] = f2bf(bf2f(qr[st][cc][e]) * eg);
;           const u16 kk = f2bf((1.f - f) * ig);
;           Kp[tok * 512 + c] = kk;
;           kb[e] = kk;
;         }
	v_fma_f32 v101, v93, s31, -v101
	v_fma_f32 v102, v94, s31, -v102
	v_fma_f32 v103, v95, s31, -v103
	v_fmac_f32_e32 v100, 0x3377d1cf, v92
	v_fmac_f32_e32 v101, 0x3377d1cf, v93
	v_fmac_f32_e32 v102, 0x3377d1cf, v94
	v_fmac_f32_e32 v103, 0x3377d1cf, v95
	v_fmac_f32_e32 v100, 0x3f317217, v92
	v_fmac_f32_e32 v101, 0x3f317217, v93
	v_fmac_f32_e32 v102, 0x3f317217, v94
	v_fmac_f32_e32 v103, 0x3f317217, v95
	v_cmp_lt_f32_e64 vcc, |v92|, s34
	v_cndmask_b32_e32 v92, v92, v100, vcc
	v_cmp_lt_f32_e64 vcc, |v93|, s34
	v_cndmask_b32_e32 v93, v93, v101, vcc
	v_cmp_lt_f32_e64 vcc, |v94|, s34
	v_cndmask_b32_e32 v94, v94, v102, vcc
	v_cmp_lt_f32_e64 vcc, |v95|, s34
	v_cndmask_b32_e32 v95, v95, v103, vcc
	v_cndmask_b32_e64 v100, 0, v213, s[22:23]
	v_cndmask_b32_e64 v101, 0, v213, s[24:25]
	v_cndmask_b32_e64 v102, 0, v213, s[26:27]
	v_cndmask_b32_e64 v103, 0, v213, s[28:29]
	v_sub_f32_e32 v92, v92, v100
	v_sub_f32_e32 v93, v93, v101
	v_sub_f32_e32 v94, v94, v102
	v_sub_f32_e32 v95, v95, v103
	v_add_f32_e32 v64, v64, v92
	v_add_f32_e32 v65, v65, v93
	v_add_f32_e32 v66, v66, v94
	v_add_f32_e32 v67, v67, v95
	v_mul_f32_e32 v92, 0xbfb8aa3b, v64
	v_mul_f32_e32 v93, 0xbfb8aa3b, v65
	v_mul_f32_e32 v94, 0xbfb8aa3b, v66
	v_mul_f32_e32 v95, 0xbfb8aa3b, v67
	v_mul_f32_e32 v100, 0x3fb8aa3b, v64
	v_mul_f32_e32 v101, 0x3fb8aa3b, v65
	v_mul_f32_e32 v102, 0x3fb8aa3b, v66
	v_mul_f32_e32 v103, 0x3fb8aa3b, v67
	v_exp_f32_e32 v92, v92
	v_exp_f32_e32 v93, v93
	v_exp_f32_e32 v94, v94
	v_exp_f32_e32 v95, v95
	v_exp_f32_e32 v100, v100
	v_exp_f32_e32 v101, v101
	v_exp_f32_e32 v102, v102
	v_exp_f32_e32 v103, v103
	v_sub_f32_e32 v96, 1.0, v96
	v_sub_f32_e32 v97, 1.0, v97
	v_sub_f32_e32 v98, 1.0, v98
	v_sub_f32_e32 v99, 1.0, v99
	v_mul_f32_e32 v96, v96, v92
	v_mul_f32_e32 v97, v97, v93
	v_mul_f32_e32 v98, v98, v94
	v_mul_f32_e32 v99, v99, v95
	v_lshlrev_b32_e32 v92, 16, v50
	v_and_b32_e32 v93, 0xffff0000, v50
	v_lshlrev_b32_e32 v94, 16, v51
	v_and_b32_e32 v95, 0xffff0000, v51
	v_mul_f32_e32 v92, v92, v100
	v_mul_f32_e32 v93, v93, v101
	v_mul_f32_e32 v94, v94, v102
	v_mul_f32_e32 v95, v95, v103
	v_cvt_pk_bf16_f32 v108, v92, v93
	v_cvt_pk_bf16_f32 v109, v94, v95
	v_cvt_pk_bf16_f32 v110, v96, v97
	v_cvt_pk_bf16_f32 v111, v98, v99
	global_store_dwordx2 v112, v[108:109], s[2:3]
	global_store_dwordx2 v114, v[110:111], s[2:3]
	s_add_u32 s2, s2, 0x400
	s_addc_u32 s3, s3, 0
	v_mov_b32_e32 v104, v96
	v_mov_b32_e32 v105, v97
	v_mov_b32_e32 v106, v98
	v_mov_b32_e32 v107, v99
	v_lshlrev_b32_e32 v92, 16, v52
	v_and_b32_e32 v93, 0xffff0000, v52
	v_lshlrev_b32_e32 v94, 16, v53
	v_and_b32_e32 v95, 0xffff0000, v53
	v_mul_f32_e32 v92, 0xbfb8aa3b, v92
	v_mul_f32_e32 v93, 0xbfb8aa3b, v93
	v_mul_f32_e32 v94, 0xbfb8aa3b, v94
	v_mul_f32_e32 v95, 0xbfb8aa3b, v95
	v_exp_f32_e32 v92, v92
	v_exp_f32_e32 v93, v93
	v_exp_f32_e32 v94, v94
	v_exp_f32_e32 v95, v95
	v_add_f32_e32 v92, 1.0, v92
	v_add_f32_e32 v93, 1.0, v93
	v_add_f32_e32 v94, 1.0, v94
	v_add_f32_e32 v95, 1.0, v95
	v_rcp_f32_e32 v92, v92
	v_rcp_f32_e32 v93, v93
	v_rcp_f32_e32 v94, v94
	v_rcp_f32_e32 v95, v95
	v_fma_f32 v96, v72, v92, v68
	v_fma_f32 v97, v73, v93, v69
	v_fma_f32 v98, v74, v94, v70
	v_fma_f32 v99, v75, v95, v71
	v_cmp_gt_f32_e64 s[22:23], s30, v96
	v_cmp_gt_f32_e64 s[24:25], s30, v97
	v_cmp_gt_f32_e64 s[26:27], s30, v98
	v_cmp_gt_f32_e64 s[28:29], s30, v99
	v_cndmask_b32_e64 v92, 0, 32, s[22:23]
	v_cndmask_b32_e64 v93, 0, 32, s[24:25]
	v_cndmask_b32_e64 v94, 0, 32, s[26:27]
	v_cndmask_b32_e64 v95, 0, 32, s[28:29]
	v_ldexp_f32 v92, v96, v92
	v_ldexp_f32 v93, v97, v93
	v_ldexp_f32 v94, v98, v94
	v_ldexp_f32 v95, v99, v95
	v_log_f32_e32 v92, v92
	v_log_f32_e32 v93, v93
	v_log_f32_e32 v94, v94
	v_log_f32_e32 v95, v95
	v_mul_f32_e32 v100, 0x3f317217, v92
	v_mul_f32_e32 v101, 0x3f317217, v93
	v_mul_f32_e32 v102, 0x3f317217, v94
	v_mul_f32_e32 v103, 0x3f317217, v95
	v_fma_f32 v100, v92, s31, -v100
	v_fma_f32 v101, v93, s31, -v101
	v_fma_f32 v102, v94, s31, -v102
	v_fma_f32 v103, v95, s31, -v103
	v_fmac_f32_e32 v100, 0x3377d1cf, v92
	v_fmac_f32_e32 v101, 0x3377d1cf, v93
	v_fmac_f32_e32 v102, 0x3377d1cf, v94
	v_fmac_f32_e32 v103, 0x3377d1cf, v95
	v_fmac_f32_e32 v100, 0x3f317217, v92
	v_fmac_f32_e32 v101, 0x3f317217, v93
	v_fmac_f32_e32 v102, 0x3f317217, v94
	v_fmac_f32_e32 v103, 0x3f317217, v95
	v_cmp_lt_f32_e64 vcc, |v92|, s34
	v_cndmask_b32_e32 v92, v92, v100, vcc
	v_cmp_lt_f32_e64 vcc, |v93|, s34
	v_cndmask_b32_e32 v93, v93, v101, vcc
	v_cmp_lt_f32_e64 vcc, |v94|, s34
	v_cndmask_b32_e32 v94, v94, v102, vcc
	v_cmp_lt_f32_e64 vcc, |v95|, s34
	v_cndmask_b32_e32 v95, v95, v103, vcc
	v_cndmask_b32_e64 v100, 0, v213, s[22:23]
	v_cndmask_b32_e64 v101, 0, v213, s[24:25]
	v_cndmask_b32_e64 v102, 0, v213, s[26:27]
	v_cndmask_b32_e64 v103, 0, v213, s[28:29]
	v_sub_f32_e32 v92, v92, v100
	v_sub_f32_e32 v93, v93, v101
	v_sub_f32_e32 v94, v94, v102
	v_sub_f32_e32 v95, v95, v103
	v_add_f32_e32 v64, v64, v92
	v_add_f32_e32 v65, v65, v93
	v_add_f32_e32 v66, v66, v94
	v_add_f32_e32 v67, v67, v95
	v_mul_f32_e32 v92, 0xbfb8aa3b, v64
	v_mul_f32_e32 v93, 0xbfb8aa3b, v65
	v_mul_f32_e32 v94, 0xbfb8aa3b, v66
	v_mul_f32_e32 v95, 0xbfb8aa3b, v67
	v_mul_f32_e32 v100, 0x3fb8aa3b, v64
	v_mul_f32_e32 v101, 0x3fb8aa3b, v65
	v_mul_f32_e32 v102, 0x3fb8aa3b, v66
	v_mul_f32_e32 v103, 0x3fb8aa3b, v67
	v_exp_f32_e32 v92, v92
	v_exp_f32_e32 v93, v93
	v_exp_f32_e32 v94, v94
	v_exp_f32_e32 v95, v95
	v_exp_f32_e32 v100, v100
	v_exp_f32_e32 v101, v101
	v_exp_f32_e32 v102, v102
	v_exp_f32_e32 v103, v103
	v_sub_f32_e32 v96, 1.0, v96
	v_sub_f32_e32 v97, 1.0, v97
	v_sub_f32_e32 v98, 1.0, v98
	v_sub_f32_e32 v99, 1.0, v99
	v_mul_f32_e32 v96, v96, v92
	v_mul_f32_e32 v97, v97, v93
; DEV u16 f2bf(float f) { return (u16)(pack2(f, f) & 0xffffu); }
; DEV float bf2f(u16 h) { return __uint_as_float(((unsigned)h) << 16); }
; DEV float sigmoid_f(float x) { return __builtin_amdgcn_rcpf(1.f + __expf(-x)); }
; DEV void phase_p15(const Params& p, int g) {
;     ...
;         for (int e = 0; e < 8; ++e) {
;           const int jj = j8 * 8 + e;
;           const int j = dir ? 63 - jj : jj;
;           const size_t tok = (size_t)cidx * 64 + j;
;           const float f = lb[cc] + (1.f - lb[cc]) * sigmoid_f(bf2f(xr[st][cc][e]));
;           G[cc] += __logf(f);
;           const float eg = __expf(G[cc]), ig = __expf(-G[cc]);
;           Qp[tok * 512 + c] = f2bf(bf2f(qr[st][cc][e]) * eg);
;           const u16 kk = f2bf((1.f - f) * ig);
;           Kp[tok * 512 + c] = kk;
;           kb[e] = kk;
;         }
;         const int s0 = dir ? 56 - 8 * j8 : 8 * j8;
;         uint4 w;
;         w.x = dir ? (kb[7] | (kb[6] << 16)) : (kb[0] | (kb[1] << 16));
;         w.y = dir ? (kb[5] | (kb[4] << 16)) : (kb[2] | (kb[3] << 16));
;         w.z = dir ? (kb[3] | (kb[2] << 16)) : (kb[4] | (kb[5] << 16));
;         w.w = dir ? (kb[1] | (kb[0] << 16)) : (kb[6] | (kb[7] << 16));
;         *(uint4*)(KT + (((size_t)cidx * 2 + dir) * 512 + c) * 64 + s0) = w;
	v_mul_f32_e32 v98, v98, v94
	v_mul_f32_e32 v99, v99, v95
	v_lshlrev_b32_e32 v92, 16, v54
	v_and_b32_e32 v93, 0xffff0000, v54
	v_lshlrev_b32_e32 v94, 16, v55
	v_and_b32_e32 v95, 0xffff0000, v55
	v_mul_f32_e32 v92, v92, v100
	v_mul_f32_e32 v93, v93, v101
	v_mul_f32_e32 v94, v94, v102
	v_mul_f32_e32 v95, v95, v103
	v_cvt_pk_bf16_f32 v108, v92, v93
	v_cvt_pk_bf16_f32 v109, v94, v95
	v_cvt_pk_bf16_f32 v110, v96, v97
	v_cvt_pk_bf16_f32 v111, v98, v99
	global_store_dwordx2 v112, v[108:109], s[2:3]
	global_store_dwordx2 v114, v[110:111], s[2:3]
	s_add_u32 s2, s2, 0x400
	s_addc_u32 s3, s3, 0
	v_cvt_pk_bf16_f32 v130, v104, v96
	v_cvt_pk_bf16_f32 v146, v105, v97
	v_cvt_pk_bf16_f32 v180, v106, v98
	v_cvt_pk_bf16_f32 v196, v107, v99
	v_lshlrev_b32_e32 v92, 16, v56
	v_and_b32_e32 v93, 0xffff0000, v56
	v_lshlrev_b32_e32 v94, 16, v57
	v_and_b32_e32 v95, 0xffff0000, v57
	v_mul_f32_e32 v92, 0xbfb8aa3b, v92
	v_mul_f32_e32 v93, 0xbfb8aa3b, v93
	v_mul_f32_e32 v94, 0xbfb8aa3b, v94
	v_mul_f32_e32 v95, 0xbfb8aa3b, v95
	v_exp_f32_e32 v92, v92
	v_exp_f32_e32 v93, v93
	v_exp_f32_e32 v94, v94
	v_exp_f32_e32 v95, v95
	v_add_f32_e32 v92, 1.0, v92
	v_add_f32_e32 v93, 1.0, v93
	v_add_f32_e32 v94, 1.0, v94
	v_add_f32_e32 v95, 1.0, v95
	v_rcp_f32_e32 v92, v92
	v_rcp_f32_e32 v93, v93
	v_rcp_f32_e32 v94, v94
	v_rcp_f32_e32 v95, v95
	v_fma_f32 v96, v72, v92, v68
	v_fma_f32 v97, v73, v93, v69
	v_fma_f32 v98, v74, v94, v70
	v_fma_f32 v99, v75, v95, v71
	v_cmp_gt_f32_e64 s[22:23], s30, v96
	v_cmp_gt_f32_e64 s[24:25], s30, v97
	v_cmp_gt_f32_e64 s[26:27], s30, v98
	v_cmp_gt_f32_e64 s[28:29], s30, v99
	v_cndmask_b32_e64 v92, 0, 32, s[22:23]
	v_cndmask_b32_e64 v93, 0, 32, s[24:25]
	v_cndmask_b32_e64 v94, 0, 32, s[26:27]
	v_cndmask_b32_e64 v95, 0, 32, s[28:29]
	v_ldexp_f32 v92, v96, v92
	v_ldexp_f32 v93, v97, v93
	v_ldexp_f32 v94, v98, v94
	v_ldexp_f32 v95, v99, v95
	v_log_f32_e32 v92, v92
	v_log_f32_e32 v93, v93
	v_log_f32_e32 v94, v94
	v_log_f32_e32 v95, v95
	v_mul_f32_e32 v100, 0x3f317217, v92
	v_mul_f32_e32 v101, 0x3f317217, v93
	v_mul_f32_e32 v102, 0x3f317217, v94
	v_mul_f32_e32 v103, 0x3f317217, v95
	v_fma_f32 v100, v92, s31, -v100
	v_fma_f32 v101, v93, s31, -v101
	v_fma_f32 v102, v94, s31, -v102
	v_fma_f32 v103, v95, s31, -v103
	v_fmac_f32_e32 v100, 0x3377d1cf, v92
	v_fmac_f32_e32 v101, 0x3377d1cf, v93
	v_fmac_f32_e32 v102, 0x3377d1cf, v94
	v_fmac_f32_e32 v103, 0x3377d1cf, v95
	v_fmac_f32_e32 v100, 0x3f317217, v92
	v_fmac_f32_e32 v101, 0x3f317217, v93
	v_fmac_f32_e32 v102, 0x3f317217, v94
	v_fmac_f32_e32 v103, 0x3f317217, v95
	v_cmp_lt_f32_e64 vcc, |v92|, s34
	v_cndmask_b32_e32 v92, v92, v100, vcc
	v_cmp_lt_f32_e64 vcc, |v93|, s34
	v_cndmask_b32_e32 v93, v93, v101, vcc
	v_cmp_lt_f32_e64 vcc, |v94|, s34
	v_cndmask_b32_e32 v94, v94, v102, vcc
	v_cmp_lt_f32_e64 vcc, |v95|, s34
	v_cndmask_b32_e32 v95, v95, v103, vcc
	v_cndmask_b32_e64 v100, 0, v213, s[22:23]
	v_cndmask_b32_e64 v101, 0, v213, s[24:25]
	v_cndmask_b32_e64 v102, 0, v213, s[26:27]
	v_cndmask_b32_e64 v103, 0, v213, s[28:29]
	v_sub_f32_e32 v92, v92, v100
	v_sub_f32_e32 v93, v93, v101
	v_sub_f32_e32 v94, v94, v102
	v_sub_f32_e32 v95, v95, v103
	v_add_f32_e32 v64, v64, v92
	v_add_f32_e32 v65, v65, v93
	v_add_f32_e32 v66, v66, v94
	v_add_f32_e32 v67, v67, v95
	v_mul_f32_e32 v92, 0xbfb8aa3b, v64
	v_mul_f32_e32 v93, 0xbfb8aa3b, v65
	v_mul_f32_e32 v94, 0xbfb8aa3b, v66
	v_mul_f32_e32 v95, 0xbfb8aa3b, v67
	v_mul_f32_e32 v100, 0x3fb8aa3b, v64
	v_mul_f32_e32 v101, 0x3fb8aa3b, v65
	v_mul_f32_e32 v102, 0x3fb8aa3b, v66
	v_mul_f32_e32 v103, 0x3fb8aa3b, v67
	v_exp_f32_e32 v92, v92
	v_exp_f32_e32 v93, v93
	v_exp_f32_e32 v94, v94
	v_exp_f32_e32 v95, v95
	v_exp_f32_e32 v100, v100
	v_exp_f32_e32 v101, v101
	v_exp_f32_e32 v102, v102
	v_exp_f32_e32 v103, v103
	v_sub_f32_e32 v96, 1.0, v96
	v_sub_f32_e32 v97, 1.0, v97
	v_sub_f32_e32 v98, 1.0, v98
	v_sub_f32_e32 v99, 1.0, v99
	v_mul_f32_e32 v96, v96, v92
	v_mul_f32_e32 v97, v97, v93
	v_mul_f32_e32 v98, v98, v94
	v_mul_f32_e32 v99, v99, v95
	v_lshlrev_b32_e32 v92, 16, v58
	v_and_b32_e32 v93, 0xffff0000, v58
	v_lshlrev_b32_e32 v94, 16, v59
	v_and_b32_e32 v95, 0xffff0000, v59
	v_mul_f32_e32 v92, v92, v100
	v_mul_f32_e32 v93, v93, v101
	v_mul_f32_e32 v94, v94, v102
	v_mul_f32_e32 v95, v95, v103
	v_cvt_pk_bf16_f32 v108, v92, v93
	v_cvt_pk_bf16_f32 v109, v94, v95
	v_cvt_pk_bf16_f32 v110, v96, v97
	v_cvt_pk_bf16_f32 v111, v98, v99
	global_store_dwordx2 v112, v[108:109], s[2:3]
	global_store_dwordx2 v114, v[110:111], s[2:3]
	s_add_u32 s2, s2, 0x400
	s_addc_u32 s3, s3, 0
	v_mov_b32_e32 v104, v96
	v_mov_b32_e32 v105, v97
	v_mov_b32_e32 v106, v98
	v_mov_b32_e32 v107, v99
	v_lshlrev_b32_e32 v92, 16, v60
	v_and_b32_e32 v93, 0xffff0000, v60
	v_lshlrev_b32_e32 v94, 16, v61
	v_and_b32_e32 v95, 0xffff0000, v61
	v_mul_f32_e32 v92, 0xbfb8aa3b, v92
	v_mul_f32_e32 v93, 0xbfb8aa3b, v93
	v_mul_f32_e32 v94, 0xbfb8aa3b, v94
	v_mul_f32_e32 v95, 0xbfb8aa3b, v95
	v_exp_f32_e32 v92, v92
	v_exp_f32_e32 v93, v93
	v_exp_f32_e32 v94, v94
	v_exp_f32_e32 v95, v95
	v_add_f32_e32 v92, 1.0, v92
	v_add_f32_e32 v93, 1.0, v93
	v_add_f32_e32 v94, 1.0, v94
	v_add_f32_e32 v95, 1.0, v95
	v_rcp_f32_e32 v92, v92
	v_rcp_f32_e32 v93, v93
	v_rcp_f32_e32 v94, v94
	v_rcp_f32_e32 v95, v95
	v_fma_f32 v96, v72, v92, v68
	v_fma_f32 v97, v73, v93, v69
	v_fma_f32 v98, v74, v94, v70
	v_fma_f32 v99, v75, v95, v71
; DEV u16 f2bf(float f) { return (u16)(pack2(f, f) & 0xffffu); }
; DEV float bf2f(u16 h) { return __uint_as_float(((unsigned)h) << 16); }
; DEV float sigmoid_f(float x) { return __builtin_amdgcn_rcpf(1.f + __expf(-x)); }
; DEV void phase_p15(const Params& p, int g) {
;     ...
;         for (int e = 0; e < 8; ++e) {
;           const int jj = j8 * 8 + e;
;           const int j = dir ? 63 - jj : jj;
;           const size_t tok = (size_t)cidx * 64 + j;
;           const float f = lb[cc] + (1.f - lb[cc]) * sigmoid_f(bf2f(xr[st][cc][e]));
;           G[cc] += __logf(f);
;           const float eg = __expf(G[cc]), ig = __expf(-G[cc]);
;           Qp[tok * 512 + c] = f2bf(bf2f(qr[st][cc][e]) * eg);
;           const u16 kk = f2bf((1.f - f) * ig);
;           Kp[tok * 512 + c] = kk;
;           kb[e] = kk;
;         }
;         const int s0 = dir ? 56 - 8 * j8 : 8 * j8;
;         uint4 w;
;         w.x = dir ? (kb[7] | (kb[6] << 16)) : (kb[0] | (kb[1] << 16));
;         w.y = dir ? (kb[5] | (kb[4] << 16)) : (kb[2] | (kb[3] << 16));
;         w.z = dir ? (kb[3] | (kb[2] << 16)) : (kb[4] | (kb[5] << 16));
;         w.w = dir ? (kb[1] | (kb[0] << 16)) : (kb[6] | (kb[7] << 16));
;         *(uint4*)(KT + (((size_t)cidx * 2 + dir) * 512 + c) * 64 + s0) = w;
	v_cmp_gt_f32_e64 s[22:23], s30, v96
	v_cmp_gt_f32_e64 s[24:25], s30, v97
	v_cmp_gt_f32_e64 s[26:27], s30, v98
	v_cmp_gt_f32_e64 s[28:29], s30, v99
	v_cndmask_b32_e64 v92, 0, 32, s[22:23]
	v_cndmask_b32_e64 v93, 0, 32, s[24:25]
	v_cndmask_b32_e64 v94, 0, 32, s[26:27]
	v_cndmask_b32_e64 v95, 0, 32, s[28:29]
	v_ldexp_f32 v92, v96, v92
	v_ldexp_f32 v93, v97, v93
	v_ldexp_f32 v94, v98, v94
	v_ldexp_f32 v95, v99, v95
	v_log_f32_e32 v92, v92
	v_log_f32_e32 v93, v93
	v_log_f32_e32 v94, v94
	v_log_f32_e32 v95, v95
	v_mul_f32_e32 v100, 0x3f317217, v92
	v_mul_f32_e32 v101, 0x3f317217, v93
	v_mul_f32_e32 v102, 0x3f317217, v94
	v_mul_f32_e32 v103, 0x3f317217, v95
	v_fma_f32 v100, v92, s31, -v100
	v_fma_f32 v101, v93, s31, -v101
	v_fma_f32 v102, v94, s31, -v102
	v_fma_f32 v103, v95, s31, -v103
	v_fmac_f32_e32 v100, 0x3377d1cf, v92
	v_fmac_f32_e32 v101, 0x3377d1cf, v93
	v_fmac_f32_e32 v102, 0x3377d1cf, v94
	v_fmac_f32_e32 v103, 0x3377d1cf, v95
	v_fmac_f32_e32 v100, 0x3f317217, v92
	v_fmac_f32_e32 v101, 0x3f317217, v93
	v_fmac_f32_e32 v102, 0x3f317217, v94
	v_fmac_f32_e32 v103, 0x3f317217, v95
	v_cmp_lt_f32_e64 vcc, |v92|, s34
	v_cndmask_b32_e32 v92, v92, v100, vcc
	v_cmp_lt_f32_e64 vcc, |v93|, s34
	v_cndmask_b32_e32 v93, v93, v101, vcc
	v_cmp_lt_f32_e64 vcc, |v94|, s34
	v_cndmask_b32_e32 v94, v94, v102, vcc
	v_cmp_lt_f32_e64 vcc, |v95|, s34
	v_cndmask_b32_e32 v95, v95, v103, vcc
	v_cndmask_b32_e64 v100, 0, v213, s[22:23]
	v_cndmask_b32_e64 v101, 0, v213, s[24:25]
	v_cndmask_b32_e64 v102, 0, v213, s[26:27]
	v_cndmask_b32_e64 v103, 0, v213, s[28:29]
	v_sub_f32_e32 v92, v92, v100
	v_sub_f32_e32 v93, v93, v101
	v_sub_f32_e32 v94, v94, v102
	v_sub_f32_e32 v95, v95, v103
	v_add_f32_e32 v64, v64, v92
	v_add_f32_e32 v65, v65, v93
	v_add_f32_e32 v66, v66, v94
	v_add_f32_e32 v67, v67, v95
	v_mul_f32_e32 v92, 0xbfb8aa3b, v64
	v_mul_f32_e32 v93, 0xbfb8aa3b, v65
	v_mul_f32_e32 v94, 0xbfb8aa3b, v66
	v_mul_f32_e32 v95, 0xbfb8aa3b, v67
	v_mul_f32_e32 v100, 0x3fb8aa3b, v64
	v_mul_f32_e32 v101, 0x3fb8aa3b, v65
	v_mul_f32_e32 v102, 0x3fb8aa3b, v66
	v_mul_f32_e32 v103, 0x3fb8aa3b, v67
	v_exp_f32_e32 v92, v92
	v_exp_f32_e32 v93, v93
	v_exp_f32_e32 v94, v94
	v_exp_f32_e32 v95, v95
	v_exp_f32_e32 v100, v100
	v_exp_f32_e32 v101, v101
	v_exp_f32_e32 v102, v102
	v_exp_f32_e32 v103, v103
	v_sub_f32_e32 v96, 1.0, v96
	v_sub_f32_e32 v97, 1.0, v97
	v_sub_f32_e32 v98, 1.0, v98
	v_sub_f32_e32 v99, 1.0, v99
	v_mul_f32_e32 v96, v96, v92
	v_mul_f32_e32 v97, v97, v93
	v_mul_f32_e32 v98, v98, v94
	v_mul_f32_e32 v99, v99, v95
	v_lshlrev_b32_e32 v92, 16, v62
	v_and_b32_e32 v93, 0xffff0000, v62
	v_lshlrev_b32_e32 v94, 16, v63
	v_and_b32_e32 v95, 0xffff0000, v63
	v_mul_f32_e32 v92, v92, v100
	v_mul_f32_e32 v93, v93, v101
	v_mul_f32_e32 v94, v94, v102
	v_mul_f32_e32 v95, v95, v103
	v_cvt_pk_bf16_f32 v108, v92, v93
	v_cvt_pk_bf16_f32 v109, v94, v95
	v_cvt_pk_bf16_f32 v110, v96, v97
	v_cvt_pk_bf16_f32 v111, v98, v99
	global_store_dwordx2 v112, v[108:109], s[2:3]
	global_store_dwordx2 v114, v[110:111], s[2:3]
	s_add_u32 s2, s2, 0x400
	s_addc_u32 s3, s3, 0
	v_cvt_pk_bf16_f32 v131, v104, v96
	v_cvt_pk_bf16_f32 v147, v105, v97
	v_cvt_pk_bf16_f32 v181, v106, v98
	v_cvt_pk_bf16_f32 v197, v107, v99
	global_store_dwordx4 v115, v[116:119], s[4:5]
	global_store_dwordx4 v115, v[120:123], s[4:5] offset:16
	global_store_dwordx4 v115, v[124:127], s[4:5] offset:32
	global_store_dwordx4 v115, v[128:131], s[4:5] offset:48
	global_store_dwordx4 v115, v[132:135], s[4:5] offset:128
	global_store_dwordx4 v115, v[136:139], s[4:5] offset:144
	global_store_dwordx4 v115, v[140:143], s[4:5] offset:160
	global_store_dwordx4 v115, v[144:147], s[4:5] offset:176
	global_store_dwordx4 v115, v[166:169], s[4:5] offset:256
	global_store_dwordx4 v115, v[170:173], s[4:5] offset:272
	global_store_dwordx4 v115, v[174:177], s[4:5] offset:288
	global_store_dwordx4 v115, v[178:181], s[4:5] offset:304
	global_store_dwordx4 v115, v[182:185], s[4:5] offset:384
	global_store_dwordx4 v115, v[186:189], s[4:5] offset:400
	global_store_dwordx4 v115, v[190:193], s[4:5] offset:416
	global_store_dwordx4 v115, v[194:197], s[4:5] offset:432
	s_add_u32 s4, s4, 64
	s_addc_u32 s5, s5, 0
	global_load_dwordx2 v[32:33], v113, s[0:1]
	global_load_dwordx2 v[34:35], v112, s[0:1]
	s_add_u32 s0, s0, 0x1400
	s_addc_u32 s1, s1, 0
	global_load_dwordx2 v[36:37], v113, s[0:1]
	global_load_dwordx2 v[38:39], v112, s[0:1]
	s_add_u32 s0, s0, 0x1400
	s_addc_u32 s1, s1, 0
	global_load_dwordx2 v[40:41], v113, s[0:1]
	global_load_dwordx2 v[42:43], v112, s[0:1]
	s_add_u32 s0, s0, 0x1400
	s_addc_u32 s1, s1, 0
	global_load_dwordx2 v[44:45], v113, s[0:1]
	global_load_dwordx2 v[46:47], v112, s[0:1]
	s_add_u32 s0, s0, 0x1400
	s_addc_u32 s1, s1, 0
	global_load_dwordx2 v[48:49], v113, s[0:1]
	global_load_dwordx2 v[50:51], v112, s[0:1]
	s_add_u32 s0, s0, 0x1400
	s_addc_u32 s1, s1, 0
	global_load_dwordx2 v[52:53], v113, s[0:1]
	global_load_dwordx2 v[54:55], v112, s[0:1]
	s_add_u32 s0, s0, 0x1400
	s_addc_u32 s1, s1, 0
	global_load_dwordx2 v[56:57], v113, s[0:1]
	global_load_dwordx2 v[58:59], v112, s[0:1]
	s_add_u32 s0, s0, 0x1400
	s_addc_u32 s1, s1, 0
	global_load_dwordx2 v[60:61], v113, s[0:1]
	global_load_dwordx2 v[62:63], v112, s[0:1]
	s_add_u32 s0, s0, 0x1400
	s_addc_u32 s1, s1, 0
	s_add_u32 s35, s35, 1
	s_cmp_lt_u32 s35, 2
	s_cbranch_scc1 .Lp15_d0_loop
	s_branch .Lp15_done

; DEV u16 f2bf(float f) { return (u16)(pack2(f, f) & 0xffffu); }
; DEV float bf2f(u16 h) { return __uint_as_float(((unsigned)h) << 16); }
; DEV float sigmoid_f(float x) { return __builtin_amdgcn_rcpf(1.f + __expf(-x)); }
; DEV void phase_p15(const Params& p, int g) {
;     ...
;     for (int j8 = 0; j8 < 8; ++j8) {
;       const int st = j8 % 3;
;       if (j8 < 6) { P15_LOAD((j8 + 2) % 3, j8 + 2); }
; #pragma unroll
;       for (int cc = 0; cc < 2; ++cc) {
;         const int c = tid + 256 * cc;
;         unsigned kb[8];
; #pragma unroll
;         for (int e = 0; e < 8; ++e) {
;           const int jj = j8 * 8 + e;
;           const int j = dir ? 63 - jj : jj;
;           const size_t tok = (size_t)cidx * 64 + j;
;           const float f = lb[cc] + (1.f - lb[cc]) * sigmoid_f(bf2f(xr[st][cc][e]));
;           G[cc] += __logf(f);
;           const float eg = __expf(G[cc]), ig = __expf(-G[cc]);
;           Qp[tok * 512 + c] = f2bf(bf2f(qr[st][cc][e]) * eg);
;           const u16 kk = f2bf((1.f - f) * ig);
;           Kp[tok * 512 + c] = kk;
;           kb[e] = kk;
;         }
.Lp15_d1_loop:
	s_waitcnt vmcnt(48)
	v_lshlrev_b32_e32 v92, 16, v0
	v_and_b32_e32 v93, 0xffff0000, v0
	v_lshlrev_b32_e32 v94, 16, v1
	v_and_b32_e32 v95, 0xffff0000, v1
	v_mul_f32_e32 v92, 0xbfb8aa3b, v92
	v_mul_f32_e32 v93, 0xbfb8aa3b, v93
	v_mul_f32_e32 v94, 0xbfb8aa3b, v94
	v_mul_f32_e32 v95, 0xbfb8aa3b, v95
	v_exp_f32_e32 v92, v92
	v_exp_f32_e32 v93, v93
	v_exp_f32_e32 v94, v94
	v_exp_f32_e32 v95, v95
	v_add_f32_e32 v92, 1.0, v92
	v_add_f32_e32 v93, 1.0, v93
	v_add_f32_e32 v94, 1.0, v94
	v_add_f32_e32 v95, 1.0, v95
	v_rcp_f32_e32 v92, v92
	v_rcp_f32_e32 v93, v93
	v_rcp_f32_e32 v94, v94
	v_rcp_f32_e32 v95, v95
	v_fma_f32 v96, v72, v92, v68
	v_fma_f32 v97, v73, v93, v69
	v_fma_f32 v98, v74, v94, v70
	v_fma_f32 v99, v75, v95, v71
	v_cmp_gt_f32_e64 s[22:23], s30, v96
	v_cmp_gt_f32_e64 s[24:25], s30, v97
	v_cmp_gt_f32_e64 s[26:27], s30, v98
	v_cmp_gt_f32_e64 s[28:29], s30, v99
	v_cndmask_b32_e64 v92, 0, 32, s[22:23]
	v_cndmask_b32_e64 v93, 0, 32, s[24:25]
	v_cndmask_b32_e64 v94, 0, 32, s[26:27]
	v_cndmask_b32_e64 v95, 0, 32, s[28:29]
	v_ldexp_f32 v92, v96, v92
	v_ldexp_f32 v93, v97, v93
	v_ldexp_f32 v94, v98, v94
	v_ldexp_f32 v95, v99, v95
	v_log_f32_e32 v92, v92
	v_log_f32_e32 v93, v93
	v_log_f32_e32 v94, v94
	v_log_f32_e32 v95, v95
	v_mul_f32_e32 v100, 0x3f317217, v92
	v_mul_f32_e32 v101, 0x3f317217, v93
	v_mul_f32_e32 v102, 0x3f317217, v94
	v_mul_f32_e32 v103, 0x3f317217, v95
	v_fma_f32 v100, v92, s31, -v100
	v_fma_f32 v101, v93, s31, -v101
	v_fma_f32 v102, v94, s31, -v102
	v_fma_f32 v103, v95, s31, -v103
	v_fmac_f32_e32 v100, 0x3377d1cf, v92
	v_fmac_f32_e32 v101, 0x3377d1cf, v93
	v_fmac_f32_e32 v102, 0x3377d1cf, v94
	v_fmac_f32_e32 v103, 0x3377d1cf, v95
	v_fmac_f32_e32 v100, 0x3f317217, v92
	v_fmac_f32_e32 v101, 0x3f317217, v93
	v_fmac_f32_e32 v102, 0x3f317217, v94
	v_fmac_f32_e32 v103, 0x3f317217, v95
	v_cmp_lt_f32_e64 vcc, |v92|, s34
	v_cndmask_b32_e32 v92, v92, v100, vcc
	v_cmp_lt_f32_e64 vcc, |v93|, s34
	v_cndmask_b32_e32 v93, v93, v101, vcc
	v_cmp_lt_f32_e64 vcc, |v94|, s34
	v_cndmask_b32_e32 v94, v94, v102, vcc
	v_cmp_lt_f32_e64 vcc, |v95|, s34
	v_cndmask_b32_e32 v95, v95, v103, vcc
	v_cndmask_b32_e64 v100, 0, v213, s[22:23]
	v_cndmask_b32_e64 v101, 0, v213, s[24:25]
	v_cndmask_b32_e64 v102, 0, v213, s[26:27]
	v_cndmask_b32_e64 v103, 0, v213, s[28:29]
	v_sub_f32_e32 v92, v92, v100
	v_sub_f32_e32 v93, v93, v101
	v_sub_f32_e32 v94, v94, v102
	v_sub_f32_e32 v95, v95, v103
	v_add_f32_e32 v64, v64, v92
	v_add_f32_e32 v65, v65, v93
	v_add_f32_e32 v66, v66, v94
	v_add_f32_e32 v67, v67, v95
	v_mul_f32_e32 v92, 0xbfb8aa3b, v64
	v_mul_f32_e32 v93, 0xbfb8aa3b, v65
	v_mul_f32_e32 v94, 0xbfb8aa3b, v66
	v_mul_f32_e32 v95, 0xbfb8aa3b, v67
	v_mul_f32_e32 v100, 0x3fb8aa3b, v64
	v_mul_f32_e32 v101, 0x3fb8aa3b, v65
	v_mul_f32_e32 v102, 0x3fb8aa3b, v66
	v_mul_f32_e32 v103, 0x3fb8aa3b, v67
	v_exp_f32_e32 v92, v92
	v_exp_f32_e32 v93, v93
	v_exp_f32_e32 v94, v94
	v_exp_f32_e32 v95, v95
	v_exp_f32_e32 v100, v100
	v_exp_f32_e32 v101, v101
	v_exp_f32_e32 v102, v102
	v_exp_f32_e32 v103, v103
	v_sub_f32_e32 v96, 1.0, v96
	v_sub_f32_e32 v97, 1.0, v97
	v_sub_f32_e32 v98, 1.0, v98
	v_sub_f32_e32 v99, 1.0, v99
	v_mul_f32_e32 v96, v96, v92
	v_mul_f32_e32 v97, v97, v93
	v_mul_f32_e32 v98, v98, v94
	v_mul_f32_e32 v99, v99, v95
	v_lshlrev_b32_e32 v92, 16, v2
	v_and_b32_e32 v93, 0xffff0000, v2
	v_lshlrev_b32_e32 v94, 16, v3
	v_and_b32_e32 v95, 0xffff0000, v3
	v_mul_f32_e32 v92, v92, v100
	v_mul_f32_e32 v93, v93, v101
	v_mul_f32_e32 v94, v94, v102
	v_mul_f32_e32 v95, v95, v103
	v_cvt_pk_bf16_f32 v108, v92, v93
	v_cvt_pk_bf16_f32 v109, v94, v95
	v_cvt_pk_bf16_f32 v110, v96, v97
	v_cvt_pk_bf16_f32 v111, v98, v99
	global_store_dwordx2 v112, v[108:109], s[2:3]
	global_store_dwordx2 v114, v[110:111], s[2:3]
	s_sub_u32 s2, s2, 0x400
	s_subb_u32 s3, s3, 0
	v_mov_b32_e32 v104, v96
	v_mov_b32_e32 v105, v97
	v_mov_b32_e32 v106, v98
	v_mov_b32_e32 v107, v99
	v_lshlrev_b32_e32 v92, 16, v4
	v_and_b32_e32 v93, 0xffff0000, v4
	v_lshlrev_b32_e32 v94, 16, v5
	v_and_b32_e32 v95, 0xffff0000, v5
	v_mul_f32_e32 v92, 0xbfb8aa3b, v92
	v_mul_f32_e32 v93, 0xbfb8aa3b, v93
	v_mul_f32_e32 v94, 0xbfb8aa3b, v94
	v_mul_f32_e32 v95, 0xbfb8aa3b, v95
	v_exp_f32_e32 v92, v92
	v_exp_f32_e32 v93, v93
	v_exp_f32_e32 v94, v94
	v_exp_f32_e32 v95, v95
	v_add_f32_e32 v92, 1.0, v92
	v_add_f32_e32 v93, 1.0, v93
	v_add_f32_e32 v94, 1.0, v94
	v_add_f32_e32 v95, 1.0, v95
	v_rcp_f32_e32 v92, v92
	v_rcp_f32_e32 v93, v93
	v_rcp_f32_e32 v94, v94
	v_rcp_f32_e32 v95, v95
	v_fma_f32 v96, v72, v92, v68
	v_fma_f32 v97, v73, v93, v69
	v_fma_f32 v98, v74, v94, v70
	v_fma_f32 v99, v75, v95, v71
	v_cmp_gt_f32_e64 s[22:23], s30, v96
	v_cmp_gt_f32_e64 s[24:25], s30, v97
	v_cmp_gt_f32_e64 s[26:27], s30, v98
	v_cmp_gt_f32_e64 s[28:29], s30, v99
	v_cndmask_b32_e64 v92, 0, 32, s[22:23]
	v_cndmask_b32_e64 v93, 0, 32, s[24:25]
	v_cndmask_b32_e64 v94, 0, 32, s[26:27]
	v_cndmask_b32_e64 v95, 0, 32, s[28:29]
	v_ldexp_f32 v92, v96, v92
	v_ldexp_f32 v93, v97, v93
	v_ldexp_f32 v94, v98, v94
	v_ldexp_f32 v95, v99, v95
	v_log_f32_e32 v92, v92
	v_log_f32_e32 v93, v93
	v_log_f32_e32 v94, v94
	v_log_f32_e32 v95, v95
	v_mul_f32_e32 v100, 0x3f317217, v92
	v_mul_f32_e32 v101, 0x3f317217, v93
	v_mul_f32_e32 v102, 0x3f317217, v94
	v_mul_f32_e32 v103, 0x3f317217, v95
	v_fma_f32 v100, v92, s31, -v100
	v_fma_f32 v101, v93, s31, -v101
	v_fma_f32 v102, v94, s31, -v102
	v_fma_f32 v103, v95, s31, -v103
	v_fmac_f32_e32 v100, 0x3377d1cf, v92
	v_fmac_f32_e32 v101, 0x3377d1cf, v93
	v_fmac_f32_e32 v102, 0x3377d1cf, v94
	v_fmac_f32_e32 v103, 0x3377d1cf, v95
	v_fmac_f32_e32 v100, 0x3f317217, v92
	v_fmac_f32_e32 v101, 0x3f317217, v93
	v_fmac_f32_e32 v102, 0x3f317217, v94
; DEV u16 f2bf(float f) { return (u16)(pack2(f, f) & 0xffffu); }
; DEV float bf2f(u16 h) { return __uint_as_float(((unsigned)h) << 16); }
; DEV float sigmoid_f(float x) { return __builtin_amdgcn_rcpf(1.f + __expf(-x)); }
; DEV void phase_p15(const Params& p, int g) {
;     ...
;         for (int e = 0; e < 8; ++e) {
;           const int jj = j8 * 8 + e;
;           const int j = dir ? 63 - jj : jj;
;           const size_t tok = (size_t)cidx * 64 + j;
;           const float f = lb[cc] + (1.f - lb[cc]) * sigmoid_f(bf2f(xr[st][cc][e]));
;           G[cc] += __logf(f);
;           const float eg = __expf(G[cc]), ig = __expf(-G[cc]);
;           Qp[tok * 512 + c] = f2bf(bf2f(qr[st][cc][e]) * eg);
;           const u16 kk = f2bf((1.f - f) * ig);
;           Kp[tok * 512 + c] = kk;
;           kb[e] = kk;
;         }
;         const int s0 = dir ? 56 - 8 * j8 : 8 * j8;
;         uint4 w;
;         w.x = dir ? (kb[7] | (kb[6] << 16)) : (kb[0] | (kb[1] << 16));
;         w.y = dir ? (kb[5] | (kb[4] << 16)) : (kb[2] | (kb[3] << 16));
;         w.z = dir ? (kb[3] | (kb[2] << 16)) : (kb[4] | (kb[5] << 16));
;         w.w = dir ? (kb[1] | (kb[0] << 16)) : (kb[6] | (kb[7] << 16));
;         *(uint4*)(KT + (((size_t)cidx * 2 + dir) * 512 + c) * 64 + s0) = w;
	v_fmac_f32_e32 v103, 0x3f317217, v95
	v_cmp_lt_f32_e64 vcc, |v92|, s34
	v_cndmask_b32_e32 v92, v92, v100, vcc
	v_cmp_lt_f32_e64 vcc, |v93|, s34
	v_cndmask_b32_e32 v93, v93, v101, vcc
	v_cmp_lt_f32_e64 vcc, |v94|, s34
	v_cndmask_b32_e32 v94, v94, v102, vcc
	v_cmp_lt_f32_e64 vcc, |v95|, s34
	v_cndmask_b32_e32 v95, v95, v103, vcc
	v_cndmask_b32_e64 v100, 0, v213, s[22:23]
	v_cndmask_b32_e64 v101, 0, v213, s[24:25]
	v_cndmask_b32_e64 v102, 0, v213, s[26:27]
	v_cndmask_b32_e64 v103, 0, v213, s[28:29]
	v_sub_f32_e32 v92, v92, v100
	v_sub_f32_e32 v93, v93, v101
	v_sub_f32_e32 v94, v94, v102
	v_sub_f32_e32 v95, v95, v103
	v_add_f32_e32 v64, v64, v92
	v_add_f32_e32 v65, v65, v93
	v_add_f32_e32 v66, v66, v94
	v_add_f32_e32 v67, v67, v95
	v_mul_f32_e32 v92, 0xbfb8aa3b, v64
	v_mul_f32_e32 v93, 0xbfb8aa3b, v65
	v_mul_f32_e32 v94, 0xbfb8aa3b, v66
	v_mul_f32_e32 v95, 0xbfb8aa3b, v67
	v_mul_f32_e32 v100, 0x3fb8aa3b, v64
	v_mul_f32_e32 v101, 0x3fb8aa3b, v65
	v_mul_f32_e32 v102, 0x3fb8aa3b, v66
	v_mul_f32_e32 v103, 0x3fb8aa3b, v67
	v_exp_f32_e32 v92, v92
	v_exp_f32_e32 v93, v93
	v_exp_f32_e32 v94, v94
	v_exp_f32_e32 v95, v95
	v_exp_f32_e32 v100, v100
	v_exp_f32_e32 v101, v101
	v_exp_f32_e32 v102, v102
	v_exp_f32_e32 v103, v103
	v_sub_f32_e32 v96, 1.0, v96
	v_sub_f32_e32 v97, 1.0, v97
	v_sub_f32_e32 v98, 1.0, v98
	v_sub_f32_e32 v99, 1.0, v99
	v_mul_f32_e32 v96, v96, v92
	v_mul_f32_e32 v97, v97, v93
	v_mul_f32_e32 v98, v98, v94
	v_mul_f32_e32 v99, v99, v95
	v_lshlrev_b32_e32 v92, 16, v6
	v_and_b32_e32 v93, 0xffff0000, v6
	v_lshlrev_b32_e32 v94, 16, v7
	v_and_b32_e32 v95, 0xffff0000, v7
	v_mul_f32_e32 v92, v92, v100
	v_mul_f32_e32 v93, v93, v101
	v_mul_f32_e32 v94, v94, v102
	v_mul_f32_e32 v95, v95, v103
	v_cvt_pk_bf16_f32 v108, v92, v93
	v_cvt_pk_bf16_f32 v109, v94, v95
	v_cvt_pk_bf16_f32 v110, v96, v97
	v_cvt_pk_bf16_f32 v111, v98, v99
	global_store_dwordx2 v112, v[108:109], s[2:3]
	global_store_dwordx2 v114, v[110:111], s[2:3]
	s_sub_u32 s2, s2, 0x400
	s_subb_u32 s3, s3, 0
	v_cvt_pk_bf16_f32 v131, v96, v104
	v_cvt_pk_bf16_f32 v147, v97, v105
	v_cvt_pk_bf16_f32 v181, v98, v106
	v_cvt_pk_bf16_f32 v197, v99, v107
	v_lshlrev_b32_e32 v92, 16, v8
	v_and_b32_e32 v93, 0xffff0000, v8
	v_lshlrev_b32_e32 v94, 16, v9
	v_and_b32_e32 v95, 0xffff0000, v9
	v_mul_f32_e32 v92, 0xbfb8aa3b, v92
	v_mul_f32_e32 v93, 0xbfb8aa3b, v93
	v_mul_f32_e32 v94, 0xbfb8aa3b, v94
	v_mul_f32_e32 v95, 0xbfb8aa3b, v95
	v_exp_f32_e32 v92, v92
	v_exp_f32_e32 v93, v93
	v_exp_f32_e32 v94, v94
	v_exp_f32_e32 v95, v95
	v_add_f32_e32 v92, 1.0, v92
	v_add_f32_e32 v93, 1.0, v93
	v_add_f32_e32 v94, 1.0, v94
	v_add_f32_e32 v95, 1.0, v95
	v_rcp_f32_e32 v92, v92
	v_rcp_f32_e32 v93, v93
	v_rcp_f32_e32 v94, v94
	v_rcp_f32_e32 v95, v95
	v_fma_f32 v96, v72, v92, v68
	v_fma_f32 v97, v73, v93, v69
	v_fma_f32 v98, v74, v94, v70
	v_fma_f32 v99, v75, v95, v71
	v_cmp_gt_f32_e64 s[22:23], s30, v96
	v_cmp_gt_f32_e64 s[24:25], s30, v97
	v_cmp_gt_f32_e64 s[26:27], s30, v98
	v_cmp_gt_f32_e64 s[28:29], s30, v99
	v_cndmask_b32_e64 v92, 0, 32, s[22:23]
	v_cndmask_b32_e64 v93, 0, 32, s[24:25]
	v_cndmask_b32_e64 v94, 0, 32, s[26:27]
	v_cndmask_b32_e64 v95, 0, 32, s[28:29]
	v_ldexp_f32 v92, v96, v92
	v_ldexp_f32 v93, v97, v93
	v_ldexp_f32 v94, v98, v94
	v_ldexp_f32 v95, v99, v95
	v_log_f32_e32 v92, v92
	v_log_f32_e32 v93, v93
	v_log_f32_e32 v94, v94
	v_log_f32_e32 v95, v95
	v_mul_f32_e32 v100, 0x3f317217, v92
	v_mul_f32_e32 v101, 0x3f317217, v93
	v_mul_f32_e32 v102, 0x3f317217, v94
	v_mul_f32_e32 v103, 0x3f317217, v95
	v_fma_f32 v100, v92, s31, -v100
	v_fma_f32 v101, v93, s31, -v101
	v_fma_f32 v102, v94, s31, -v102
	v_fma_f32 v103, v95, s31, -v103
	v_fmac_f32_e32 v100, 0x3377d1cf, v92
	v_fmac_f32_e32 v101, 0x3377d1cf, v93
	v_fmac_f32_e32 v102, 0x3377d1cf, v94
	v_fmac_f32_e32 v103, 0x3377d1cf, v95
	v_fmac_f32_e32 v100, 0x3f317217, v92
	v_fmac_f32_e32 v101, 0x3f317217, v93
	v_fmac_f32_e32 v102, 0x3f317217, v94
	v_fmac_f32_e32 v103, 0x3f317217, v95
	v_cmp_lt_f32_e64 vcc, |v92|, s34
	v_cndmask_b32_e32 v92, v92, v100, vcc
	v_cmp_lt_f32_e64 vcc, |v93|, s34
	v_cndmask_b32_e32 v93, v93, v101, vcc
	v_cmp_lt_f32_e64 vcc, |v94|, s34
	v_cndmask_b32_e32 v94, v94, v102, vcc
	v_cmp_lt_f32_e64 vcc, |v95|, s34
	v_cndmask_b32_e32 v95, v95, v103, vcc
	v_cndmask_b32_e64 v100, 0, v213, s[22:23]
	v_cndmask_b32_e64 v101, 0, v213, s[24:25]
	v_cndmask_b32_e64 v102, 0, v213, s[26:27]
	v_cndmask_b32_e64 v103, 0, v213, s[28:29]
	v_sub_f32_e32 v92, v92, v100
	v_sub_f32_e32 v93, v93, v101
	v_sub_f32_e32 v94, v94, v102
	v_sub_f32_e32 v95, v95, v103
	v_add_f32_e32 v64, v64, v92
	v_add_f32_e32 v65, v65, v93
	v_add_f32_e32 v66, v66, v94
	v_add_f32_e32 v67, v67, v95
	v_mul_f32_e32 v92, 0xbfb8aa3b, v64
	v_mul_f32_e32 v93, 0xbfb8aa3b, v65
	v_mul_f32_e32 v94, 0xbfb8aa3b, v66
	v_mul_f32_e32 v95, 0xbfb8aa3b, v67
	v_mul_f32_e32 v100, 0x3fb8aa3b, v64
	v_mul_f32_e32 v101, 0x3fb8aa3b, v65
	v_mul_f32_e32 v102, 0x3fb8aa3b, v66
	v_mul_f32_e32 v103, 0x3fb8aa3b, v67
	v_exp_f32_e32 v92, v92
	v_exp_f32_e32 v93, v93
	v_exp_f32_e32 v94, v94
	v_exp_f32_e32 v95, v95
	v_exp_f32_e32 v100, v100
	v_exp_f32_e32 v101, v101
	v_exp_f32_e32 v102, v102
	v_exp_f32_e32 v103, v103
	v_sub_f32_e32 v96, 1.0, v96
	v_sub_f32_e32 v97, 1.0, v97
	v_sub_f32_e32 v98, 1.0, v98
	v_sub_f32_e32 v99, 1.0, v99
	v_mul_f32_e32 v96, v96, v92
	v_mul_f32_e32 v97, v97, v93
	v_mul_f32_e32 v98, v98, v94
	v_mul_f32_e32 v99, v99, v95
	v_lshlrev_b32_e32 v92, 16, v10
	v_and_b32_e32 v93, 0xffff0000, v10
	v_lshlrev_b32_e32 v94, 16, v11
	v_and_b32_e32 v95, 0xffff0000, v11
	v_mul_f32_e32 v92, v92, v100
	v_mul_f32_e32 v93, v93, v101
	v_mul_f32_e32 v94, v94, v102
	v_mul_f32_e32 v95, v95, v103
	v_cvt_pk_bf16_f32 v108, v92, v93
; DEV u16 f2bf(float f) { return (u16)(pack2(f, f) & 0xffffu); }
; DEV float bf2f(u16 h) { return __uint_as_float(((unsigned)h) << 16); }
; DEV float sigmoid_f(float x) { return __builtin_amdgcn_rcpf(1.f + __expf(-x)); }
; DEV void phase_p15(const Params& p, int g) {
;     ...
;         for (int e = 0; e < 8; ++e) {
;           const int jj = j8 * 8 + e;
;           const int j = dir ? 63 - jj : jj;
;           const size_t tok = (size_t)cidx * 64 + j;
;           const float f = lb[cc] + (1.f - lb[cc]) * sigmoid_f(bf2f(xr[st][cc][e]));
;           G[cc] += __logf(f);
;           const float eg = __expf(G[cc]), ig = __expf(-G[cc]);
;           Qp[tok * 512 + c] = f2bf(bf2f(qr[st][cc][e]) * eg);
;           const u16 kk = f2bf((1.f - f) * ig);
;           Kp[tok * 512 + c] = kk;
;           kb[e] = kk;
;         }
;         const int s0 = dir ? 56 - 8 * j8 : 8 * j8;
;         uint4 w;
;         w.x = dir ? (kb[7] | (kb[6] << 16)) : (kb[0] | (kb[1] << 16));
;         w.y = dir ? (kb[5] | (kb[4] << 16)) : (kb[2] | (kb[3] << 16));
;         w.z = dir ? (kb[3] | (kb[2] << 16)) : (kb[4] | (kb[5] << 16));
;         w.w = dir ? (kb[1] | (kb[0] << 16)) : (kb[6] | (kb[7] << 16));
;         *(uint4*)(KT + (((size_t)cidx * 2 + dir) * 512 + c) * 64 + s0) = w;
	v_cvt_pk_bf16_f32 v109, v94, v95
	v_cvt_pk_bf16_f32 v110, v96, v97
	v_cvt_pk_bf16_f32 v111, v98, v99
	global_store_dwordx2 v112, v[108:109], s[2:3]
	global_store_dwordx2 v114, v[110:111], s[2:3]
	s_sub_u32 s2, s2, 0x400
	s_subb_u32 s3, s3, 0
	v_mov_b32_e32 v104, v96
	v_mov_b32_e32 v105, v97
	v_mov_b32_e32 v106, v98
	v_mov_b32_e32 v107, v99
	v_lshlrev_b32_e32 v92, 16, v12
	v_and_b32_e32 v93, 0xffff0000, v12
	v_lshlrev_b32_e32 v94, 16, v13
	v_and_b32_e32 v95, 0xffff0000, v13
	v_mul_f32_e32 v92, 0xbfb8aa3b, v92
	v_mul_f32_e32 v93, 0xbfb8aa3b, v93
	v_mul_f32_e32 v94, 0xbfb8aa3b, v94
	v_mul_f32_e32 v95, 0xbfb8aa3b, v95
	v_exp_f32_e32 v92, v92
	v_exp_f32_e32 v93, v93
	v_exp_f32_e32 v94, v94
	v_exp_f32_e32 v95, v95
	v_add_f32_e32 v92, 1.0, v92
	v_add_f32_e32 v93, 1.0, v93
	v_add_f32_e32 v94, 1.0, v94
	v_add_f32_e32 v95, 1.0, v95
	v_rcp_f32_e32 v92, v92
	v_rcp_f32_e32 v93, v93
	v_rcp_f32_e32 v94, v94
	v_rcp_f32_e32 v95, v95
	v_fma_f32 v96, v72, v92, v68
	v_fma_f32 v97, v73, v93, v69
	v_fma_f32 v98, v74, v94, v70
	v_fma_f32 v99, v75, v95, v71
	v_cmp_gt_f32_e64 s[22:23], s30, v96
	v_cmp_gt_f32_e64 s[24:25], s30, v97
	v_cmp_gt_f32_e64 s[26:27], s30, v98
	v_cmp_gt_f32_e64 s[28:29], s30, v99
	v_cndmask_b32_e64 v92, 0, 32, s[22:23]
	v_cndmask_b32_e64 v93, 0, 32, s[24:25]
	v_cndmask_b32_e64 v94, 0, 32, s[26:27]
	v_cndmask_b32_e64 v95, 0, 32, s[28:29]
	v_ldexp_f32 v92, v96, v92
	v_ldexp_f32 v93, v97, v93
	v_ldexp_f32 v94, v98, v94
	v_ldexp_f32 v95, v99, v95
	v_log_f32_e32 v92, v92
	v_log_f32_e32 v93, v93
	v_log_f32_e32 v94, v94
	v_log_f32_e32 v95, v95
	v_mul_f32_e32 v100, 0x3f317217, v92
	v_mul_f32_e32 v101, 0x3f317217, v93
	v_mul_f32_e32 v102, 0x3f317217, v94
	v_mul_f32_e32 v103, 0x3f317217, v95
	v_fma_f32 v100, v92, s31, -v100
	v_fma_f32 v101, v93, s31, -v101
	v_fma_f32 v102, v94, s31, -v102
	v_fma_f32 v103, v95, s31, -v103
	v_fmac_f32_e32 v100, 0x3377d1cf, v92
	v_fmac_f32_e32 v101, 0x3377d1cf, v93
	v_fmac_f32_e32 v102, 0x3377d1cf, v94
	v_fmac_f32_e32 v103, 0x3377d1cf, v95
	v_fmac_f32_e32 v100, 0x3f317217, v92
	v_fmac_f32_e32 v101, 0x3f317217, v93
	v_fmac_f32_e32 v102, 0x3f317217, v94
	v_fmac_f32_e32 v103, 0x3f317217, v95
	v_cmp_lt_f32_e64 vcc, |v92|, s34
	v_cndmask_b32_e32 v92, v92, v100, vcc
	v_cmp_lt_f32_e64 vcc, |v93|, s34
	v_cndmask_b32_e32 v93, v93, v101, vcc
	v_cmp_lt_f32_e64 vcc, |v94|, s34
	v_cndmask_b32_e32 v94, v94, v102, vcc
	v_cmp_lt_f32_e64 vcc, |v95|, s34
	v_cndmask_b32_e32 v95, v95, v103, vcc
	v_cndmask_b32_e64 v100, 0, v213, s[22:23]
	v_cndmask_b32_e64 v101, 0, v213, s[24:25]
	v_cndmask_b32_e64 v102, 0, v213, s[26:27]
	v_cndmask_b32_e64 v103, 0, v213, s[28:29]
	v_sub_f32_e32 v92, v92, v100
	v_sub_f32_e32 v93, v93, v101
	v_sub_f32_e32 v94, v94, v102
	v_sub_f32_e32 v95, v95, v103
	v_add_f32_e32 v64, v64, v92
	v_add_f32_e32 v65, v65, v93
	v_add_f32_e32 v66, v66, v94
	v_add_f32_e32 v67, v67, v95
	v_mul_f32_e32 v92, 0xbfb8aa3b, v64
	v_mul_f32_e32 v93, 0xbfb8aa3b, v65
	v_mul_f32_e32 v94, 0xbfb8aa3b, v66
	v_mul_f32_e32 v95, 0xbfb8aa3b, v67
	v_mul_f32_e32 v100, 0x3fb8aa3b, v64
	v_mul_f32_e32 v101, 0x3fb8aa3b, v65
	v_mul_f32_e32 v102, 0x3fb8aa3b, v66
	v_mul_f32_e32 v103, 0x3fb8aa3b, v67
	v_exp_f32_e32 v92, v92
	v_exp_f32_e32 v93, v93
	v_exp_f32_e32 v94, v94
	v_exp_f32_e32 v95, v95
	v_exp_f32_e32 v100, v100
	v_exp_f32_e32 v101, v101
	v_exp_f32_e32 v102, v102
	v_exp_f32_e32 v103, v103
	v_sub_f32_e32 v96, 1.0, v96
	v_sub_f32_e32 v97, 1.0, v97
	v_sub_f32_e32 v98, 1.0, v98
	v_sub_f32_e32 v99, 1.0, v99
	v_mul_f32_e32 v96, v96, v92
	v_mul_f32_e32 v97, v97, v93
	v_mul_f32_e32 v98, v98, v94
	v_mul_f32_e32 v99, v99, v95
	v_lshlrev_b32_e32 v92, 16, v14
	v_and_b32_e32 v93, 0xffff0000, v14
	v_lshlrev_b32_e32 v94, 16, v15
	v_and_b32_e32 v95, 0xffff0000, v15
	v_mul_f32_e32 v92, v92, v100
	v_mul_f32_e32 v93, v93, v101
	v_mul_f32_e32 v94, v94, v102
	v_mul_f32_e32 v95, v95, v103
	v_cvt_pk_bf16_f32 v108, v92, v93
	v_cvt_pk_bf16_f32 v109, v94, v95
	v_cvt_pk_bf16_f32 v110, v96, v97
	v_cvt_pk_bf16_f32 v111, v98, v99
	global_store_dwordx2 v112, v[108:109], s[2:3]
	global_store_dwordx2 v114, v[110:111], s[2:3]
	s_sub_u32 s2, s2, 0x400
	s_subb_u32 s3, s3, 0
	v_cvt_pk_bf16_f32 v130, v96, v104
	v_cvt_pk_bf16_f32 v146, v97, v105
	v_cvt_pk_bf16_f32 v180, v98, v106
	v_cvt_pk_bf16_f32 v196, v99, v107
	v_lshlrev_b32_e32 v92, 16, v16
	v_and_b32_e32 v93, 0xffff0000, v16
	v_lshlrev_b32_e32 v94, 16, v17
	v_and_b32_e32 v95, 0xffff0000, v17
	v_mul_f32_e32 v92, 0xbfb8aa3b, v92
	v_mul_f32_e32 v93, 0xbfb8aa3b, v93
	v_mul_f32_e32 v94, 0xbfb8aa3b, v94
	v_mul_f32_e32 v95, 0xbfb8aa3b, v95
	v_exp_f32_e32 v92, v92
	v_exp_f32_e32 v93, v93
	v_exp_f32_e32 v94, v94
	v_exp_f32_e32 v95, v95
	v_add_f32_e32 v92, 1.0, v92
	v_add_f32_e32 v93, 1.0, v93
	v_add_f32_e32 v94, 1.0, v94
	v_add_f32_e32 v95, 1.0, v95
	v_rcp_f32_e32 v92, v92
	v_rcp_f32_e32 v93, v93
	v_rcp_f32_e32 v94, v94
	v_rcp_f32_e32 v95, v95
	v_fma_f32 v96, v72, v92, v68
	v_fma_f32 v97, v73, v93, v69
	v_fma_f32 v98, v74, v94, v70
	v_fma_f32 v99, v75, v95, v71
	v_cmp_gt_f32_e64 s[22:23], s30, v96
	v_cmp_gt_f32_e64 s[24:25], s30, v97
	v_cmp_gt_f32_e64 s[26:27], s30, v98
	v_cmp_gt_f32_e64 s[28:29], s30, v99
	v_cndmask_b32_e64 v92, 0, 32, s[22:23]
	v_cndmask_b32_e64 v93, 0, 32, s[24:25]
	v_cndmask_b32_e64 v94, 0, 32, s[26:27]
	v_cndmask_b32_e64 v95, 0, 32, s[28:29]
	v_ldexp_f32 v92, v96, v92
	v_ldexp_f32 v93, v97, v93
	v_ldexp_f32 v94, v98, v94
	v_ldexp_f32 v95, v99, v95
	v_log_f32_e32 v92, v92
	v_log_f32_e32 v93, v93
	v_log_f32_e32 v94, v94
	v_log_f32_e32 v95, v95
	v_mul_f32_e32 v100, 0x3f317217, v92
	v_mul_f32_e32 v101, 0x3f317217, v93
	v_mul_f32_e32 v102, 0x3f317217, v94
	v_mul_f32_e32 v103, 0x3f317217, v95
	v_fma_f32 v100, v92, s31, -v100
; DEV u16 f2bf(float f) { return (u16)(pack2(f, f) & 0xffffu); }
; DEV float bf2f(u16 h) { return __uint_as_float(((unsigned)h) << 16); }
; DEV float sigmoid_f(float x) { return __builtin_amdgcn_rcpf(1.f + __expf(-x)); }
; DEV void phase_p15(const Params& p, int g) {
;     ...
;         for (int e = 0; e < 8; ++e) {
;           const int jj = j8 * 8 + e;
;           const int j = dir ? 63 - jj : jj;
;           const size_t tok = (size_t)cidx * 64 + j;
;           const float f = lb[cc] + (1.f - lb[cc]) * sigmoid_f(bf2f(xr[st][cc][e]));
;           G[cc] += __logf(f);
;           const float eg = __expf(G[cc]), ig = __expf(-G[cc]);
;           Qp[tok * 512 + c] = f2bf(bf2f(qr[st][cc][e]) * eg);
;           const u16 kk = f2bf((1.f - f) * ig);
;           Kp[tok * 512 + c] = kk;
;           kb[e] = kk;
;         }
	v_fma_f32 v101, v93, s31, -v101
	v_fma_f32 v102, v94, s31, -v102
	v_fma_f32 v103, v95, s31, -v103
	v_fmac_f32_e32 v100, 0x3377d1cf, v92
	v_fmac_f32_e32 v101, 0x3377d1cf, v93
	v_fmac_f32_e32 v102, 0x3377d1cf, v94
	v_fmac_f32_e32 v103, 0x3377d1cf, v95
	v_fmac_f32_e32 v100, 0x3f317217, v92
	v_fmac_f32_e32 v101, 0x3f317217, v93
	v_fmac_f32_e32 v102, 0x3f317217, v94
	v_fmac_f32_e32 v103, 0x3f317217, v95
	v_cmp_lt_f32_e64 vcc, |v92|, s34
	v_cndmask_b32_e32 v92, v92, v100, vcc
	v_cmp_lt_f32_e64 vcc, |v93|, s34
	v_cndmask_b32_e32 v93, v93, v101, vcc
	v_cmp_lt_f32_e64 vcc, |v94|, s34
	v_cndmask_b32_e32 v94, v94, v102, vcc
	v_cmp_lt_f32_e64 vcc, |v95|, s34
	v_cndmask_b32_e32 v95, v95, v103, vcc
	v_cndmask_b32_e64 v100, 0, v213, s[22:23]
	v_cndmask_b32_e64 v101, 0, v213, s[24:25]
	v_cndmask_b32_e64 v102, 0, v213, s[26:27]
	v_cndmask_b32_e64 v103, 0, v213, s[28:29]
	v_sub_f32_e32 v92, v92, v100
	v_sub_f32_e32 v93, v93, v101
	v_sub_f32_e32 v94, v94, v102
	v_sub_f32_e32 v95, v95, v103
	v_add_f32_e32 v64, v64, v92
	v_add_f32_e32 v65, v65, v93
	v_add_f32_e32 v66, v66, v94
	v_add_f32_e32 v67, v67, v95
	v_mul_f32_e32 v92, 0xbfb8aa3b, v64
	v_mul_f32_e32 v93, 0xbfb8aa3b, v65
	v_mul_f32_e32 v94, 0xbfb8aa3b, v66
	v_mul_f32_e32 v95, 0xbfb8aa3b, v67
	v_mul_f32_e32 v100, 0x3fb8aa3b, v64
	v_mul_f32_e32 v101, 0x3fb8aa3b, v65
	v_mul_f32_e32 v102, 0x3fb8aa3b, v66
	v_mul_f32_e32 v103, 0x3fb8aa3b, v67
	v_exp_f32_e32 v92, v92
	v_exp_f32_e32 v93, v93
	v_exp_f32_e32 v94, v94
	v_exp_f32_e32 v95, v95
	v_exp_f32_e32 v100, v100
	v_exp_f32_e32 v101, v101
	v_exp_f32_e32 v102, v102
	v_exp_f32_e32 v103, v103
	v_sub_f32_e32 v96, 1.0, v96
	v_sub_f32_e32 v97, 1.0, v97
	v_sub_f32_e32 v98, 1.0, v98
	v_sub_f32_e32 v99, 1.0, v99
	v_mul_f32_e32 v96, v96, v92
	v_mul_f32_e32 v97, v97, v93
	v_mul_f32_e32 v98, v98, v94
	v_mul_f32_e32 v99, v99, v95
	v_lshlrev_b32_e32 v92, 16, v18
	v_and_b32_e32 v93, 0xffff0000, v18
	v_lshlrev_b32_e32 v94, 16, v19
	v_and_b32_e32 v95, 0xffff0000, v19
	v_mul_f32_e32 v92, v92, v100
	v_mul_f32_e32 v93, v93, v101
	v_mul_f32_e32 v94, v94, v102
	v_mul_f32_e32 v95, v95, v103
	v_cvt_pk_bf16_f32 v108, v92, v93
	v_cvt_pk_bf16_f32 v109, v94, v95
	v_cvt_pk_bf16_f32 v110, v96, v97
	v_cvt_pk_bf16_f32 v111, v98, v99
	global_store_dwordx2 v112, v[108:109], s[2:3]
	global_store_dwordx2 v114, v[110:111], s[2:3]
	s_sub_u32 s2, s2, 0x400
	s_subb_u32 s3, s3, 0
	v_mov_b32_e32 v104, v96
	v_mov_b32_e32 v105, v97
	v_mov_b32_e32 v106, v98
	v_mov_b32_e32 v107, v99
	v_lshlrev_b32_e32 v92, 16, v20
	v_and_b32_e32 v93, 0xffff0000, v20
	v_lshlrev_b32_e32 v94, 16, v21
	v_and_b32_e32 v95, 0xffff0000, v21
	v_mul_f32_e32 v92, 0xbfb8aa3b, v92
	v_mul_f32_e32 v93, 0xbfb8aa3b, v93
	v_mul_f32_e32 v94, 0xbfb8aa3b, v94
	v_mul_f32_e32 v95, 0xbfb8aa3b, v95
	v_exp_f32_e32 v92, v92
	v_exp_f32_e32 v93, v93
	v_exp_f32_e32 v94, v94
	v_exp_f32_e32 v95, v95
	v_add_f32_e32 v92, 1.0, v92
	v_add_f32_e32 v93, 1.0, v93
	v_add_f32_e32 v94, 1.0, v94
	v_add_f32_e32 v95, 1.0, v95
	v_rcp_f32_e32 v92, v92
	v_rcp_f32_e32 v93, v93
	v_rcp_f32_e32 v94, v94
	v_rcp_f32_e32 v95, v95
	v_fma_f32 v96, v72, v92, v68
	v_fma_f32 v97, v73, v93, v69
	v_fma_f32 v98, v74, v94, v70
	v_fma_f32 v99, v75, v95, v71
	v_cmp_gt_f32_e64 s[22:23], s30, v96
	v_cmp_gt_f32_e64 s[24:25], s30, v97
	v_cmp_gt_f32_e64 s[26:27], s30, v98
	v_cmp_gt_f32_e64 s[28:29], s30, v99
	v_cndmask_b32_e64 v92, 0, 32, s[22:23]
	v_cndmask_b32_e64 v93, 0, 32, s[24:25]
	v_cndmask_b32_e64 v94, 0, 32, s[26:27]
	v_cndmask_b32_e64 v95, 0, 32, s[28:29]
	v_ldexp_f32 v92, v96, v92
	v_ldexp_f32 v93, v97, v93
	v_ldexp_f32 v94, v98, v94
	v_ldexp_f32 v95, v99, v95
	v_log_f32_e32 v92, v92
	v_log_f32_e32 v93, v93
	v_log_f32_e32 v94, v94
	v_log_f32_e32 v95, v95
	v_mul_f32_e32 v100, 0x3f317217, v92
	v_mul_f32_e32 v101, 0x3f317217, v93
	v_mul_f32_e32 v102, 0x3f317217, v94
	v_mul_f32_e32 v103, 0x3f317217, v95
	v_fma_f32 v100, v92, s31, -v100
	v_fma_f32 v101, v93, s31, -v101
	v_fma_f32 v102, v94, s31, -v102
	v_fma_f32 v103, v95, s31, -v103
	v_fmac_f32_e32 v100, 0x3377d1cf, v92
	v_fmac_f32_e32 v101, 0x3377d1cf, v93
	v_fmac_f32_e32 v102, 0x3377d1cf, v94
	v_fmac_f32_e32 v103, 0x3377d1cf, v95
	v_fmac_f32_e32 v100, 0x3f317217, v92
	v_fmac_f32_e32 v101, 0x3f317217, v93
	v_fmac_f32_e32 v102, 0x3f317217, v94
	v_fmac_f32_e32 v103, 0x3f317217, v95
	v_cmp_lt_f32_e64 vcc, |v92|, s34
	v_cndmask_b32_e32 v92, v92, v100, vcc
	v_cmp_lt_f32_e64 vcc, |v93|, s34
	v_cndmask_b32_e32 v93, v93, v101, vcc
	v_cmp_lt_f32_e64 vcc, |v94|, s34
	v_cndmask_b32_e32 v94, v94, v102, vcc
	v_cmp_lt_f32_e64 vcc, |v95|, s34
	v_cndmask_b32_e32 v95, v95, v103, vcc
	v_cndmask_b32_e64 v100, 0, v213, s[22:23]
	v_cndmask_b32_e64 v101, 0, v213, s[24:25]
	v_cndmask_b32_e64 v102, 0, v213, s[26:27]
	v_cndmask_b32_e64 v103, 0, v213, s[28:29]
	v_sub_f32_e32 v92, v92, v100
	v_sub_f32_e32 v93, v93, v101
	v_sub_f32_e32 v94, v94, v102
	v_sub_f32_e32 v95, v95, v103
	v_add_f32_e32 v64, v64, v92
	v_add_f32_e32 v65, v65, v93
	v_add_f32_e32 v66, v66, v94
	v_add_f32_e32 v67, v67, v95
	v_mul_f32_e32 v92, 0xbfb8aa3b, v64
	v_mul_f32_e32 v93, 0xbfb8aa3b, v65
	v_mul_f32_e32 v94, 0xbfb8aa3b, v66
	v_mul_f32_e32 v95, 0xbfb8aa3b, v67
	v_mul_f32_e32 v100, 0x3fb8aa3b, v64
	v_mul_f32_e32 v101, 0x3fb8aa3b, v65
	v_mul_f32_e32 v102, 0x3fb8aa3b, v66
	v_mul_f32_e32 v103, 0x3fb8aa3b, v67
	v_exp_f32_e32 v92, v92
	v_exp_f32_e32 v93, v93
	v_exp_f32_e32 v94, v94
	v_exp_f32_e32 v95, v95
	v_exp_f32_e32 v100, v100
	v_exp_f32_e32 v101, v101
	v_exp_f32_e32 v102, v102
	v_exp_f32_e32 v103, v103
	v_sub_f32_e32 v96, 1.0, v96
	v_sub_f32_e32 v97, 1.0, v97
	v_sub_f32_e32 v98, 1.0, v98
	v_sub_f32_e32 v99, 1.0, v99
	v_mul_f32_e32 v96, v96, v92
	v_mul_f32_e32 v97, v97, v93
; DEV u16 f2bf(float f) { return (u16)(pack2(f, f) & 0xffffu); }
; DEV float bf2f(u16 h) { return __uint_as_float(((unsigned)h) << 16); }
; DEV float sigmoid_f(float x) { return __builtin_amdgcn_rcpf(1.f + __expf(-x)); }
; DEV void phase_p15(const Params& p, int g) {
;     ...
;         for (int e = 0; e < 8; ++e) {
;           const int jj = j8 * 8 + e;
;           const int j = dir ? 63 - jj : jj;
;           const size_t tok = (size_t)cidx * 64 + j;
;           const float f = lb[cc] + (1.f - lb[cc]) * sigmoid_f(bf2f(xr[st][cc][e]));
;           G[cc] += __logf(f);
;           const float eg = __expf(G[cc]), ig = __expf(-G[cc]);
;           Qp[tok * 512 + c] = f2bf(bf2f(qr[st][cc][e]) * eg);
;           const u16 kk = f2bf((1.f - f) * ig);
;           Kp[tok * 512 + c] = kk;
;           kb[e] = kk;
;         }
;         const int s0 = dir ? 56 - 8 * j8 : 8 * j8;
;         uint4 w;
;         w.x = dir ? (kb[7] | (kb[6] << 16)) : (kb[0] | (kb[1] << 16));
;         w.y = dir ? (kb[5] | (kb[4] << 16)) : (kb[2] | (kb[3] << 16));
;         w.z = dir ? (kb[3] | (kb[2] << 16)) : (kb[4] | (kb[5] << 16));
;         w.w = dir ? (kb[1] | (kb[0] << 16)) : (kb[6] | (kb[7] << 16));
;         *(uint4*)(KT + (((size_t)cidx * 2 + dir) * 512 + c) * 64 + s0) = w;
	v_mul_f32_e32 v98, v98, v94
	v_mul_f32_e32 v99, v99, v95
	v_lshlrev_b32_e32 v92, 16, v22
	v_and_b32_e32 v93, 0xffff0000, v22
	v_lshlrev_b32_e32 v94, 16, v23
	v_and_b32_e32 v95, 0xffff0000, v23
	v_mul_f32_e32 v92, v92, v100
	v_mul_f32_e32 v93, v93, v101
	v_mul_f32_e32 v94, v94, v102
	v_mul_f32_e32 v95, v95, v103
	v_cvt_pk_bf16_f32 v108, v92, v93
	v_cvt_pk_bf16_f32 v109, v94, v95
	v_cvt_pk_bf16_f32 v110, v96, v97
	v_cvt_pk_bf16_f32 v111, v98, v99
	global_store_dwordx2 v112, v[108:109], s[2:3]
	global_store_dwordx2 v114, v[110:111], s[2:3]
	s_sub_u32 s2, s2, 0x400
	s_subb_u32 s3, s3, 0
	v_cvt_pk_bf16_f32 v129, v96, v104
	v_cvt_pk_bf16_f32 v145, v97, v105
	v_cvt_pk_bf16_f32 v179, v98, v106
	v_cvt_pk_bf16_f32 v195, v99, v107
	v_lshlrev_b32_e32 v92, 16, v24
	v_and_b32_e32 v93, 0xffff0000, v24
	v_lshlrev_b32_e32 v94, 16, v25
	v_and_b32_e32 v95, 0xffff0000, v25
	v_mul_f32_e32 v92, 0xbfb8aa3b, v92
	v_mul_f32_e32 v93, 0xbfb8aa3b, v93
	v_mul_f32_e32 v94, 0xbfb8aa3b, v94
	v_mul_f32_e32 v95, 0xbfb8aa3b, v95
	v_exp_f32_e32 v92, v92
	v_exp_f32_e32 v93, v93
	v_exp_f32_e32 v94, v94
	v_exp_f32_e32 v95, v95
	v_add_f32_e32 v92, 1.0, v92
	v_add_f32_e32 v93, 1.0, v93
	v_add_f32_e32 v94, 1.0, v94
	v_add_f32_e32 v95, 1.0, v95
	v_rcp_f32_e32 v92, v92
	v_rcp_f32_e32 v93, v93
	v_rcp_f32_e32 v94, v94
	v_rcp_f32_e32 v95, v95
	v_fma_f32 v96, v72, v92, v68
	v_fma_f32 v97, v73, v93, v69
	v_fma_f32 v98, v74, v94, v70
	v_fma_f32 v99, v75, v95, v71
	v_cmp_gt_f32_e64 s[22:23], s30, v96
	v_cmp_gt_f32_e64 s[24:25], s30, v97
	v_cmp_gt_f32_e64 s[26:27], s30, v98
	v_cmp_gt_f32_e64 s[28:29], s30, v99
	v_cndmask_b32_e64 v92, 0, 32, s[22:23]
	v_cndmask_b32_e64 v93, 0, 32, s[24:25]
	v_cndmask_b32_e64 v94, 0, 32, s[26:27]
	v_cndmask_b32_e64 v95, 0, 32, s[28:29]
	v_ldexp_f32 v92, v96, v92
	v_ldexp_f32 v93, v97, v93
	v_ldexp_f32 v94, v98, v94
	v_ldexp_f32 v95, v99, v95
	v_log_f32_e32 v92, v92
	v_log_f32_e32 v93, v93
	v_log_f32_e32 v94, v94
	v_log_f32_e32 v95, v95
	v_mul_f32_e32 v100, 0x3f317217, v92
	v_mul_f32_e32 v101, 0x3f317217, v93
	v_mul_f32_e32 v102, 0x3f317217, v94
	v_mul_f32_e32 v103, 0x3f317217, v95
	v_fma_f32 v100, v92, s31, -v100
	v_fma_f32 v101, v93, s31, -v101
	v_fma_f32 v102, v94, s31, -v102
	v_fma_f32 v103, v95, s31, -v103
	v_fmac_f32_e32 v100, 0x3377d1cf, v92
	v_fmac_f32_e32 v101, 0x3377d1cf, v93
	v_fmac_f32_e32 v102, 0x3377d1cf, v94
	v_fmac_f32_e32 v103, 0x3377d1cf, v95
	v_fmac_f32_e32 v100, 0x3f317217, v92
	v_fmac_f32_e32 v101, 0x3f317217, v93
	v_fmac_f32_e32 v102, 0x3f317217, v94
	v_fmac_f32_e32 v103, 0x3f317217, v95
	v_cmp_lt_f32_e64 vcc, |v92|, s34
	v_cndmask_b32_e32 v92, v92, v100, vcc
	v_cmp_lt_f32_e64 vcc, |v93|, s34
	v_cndmask_b32_e32 v93, v93, v101, vcc
	v_cmp_lt_f32_e64 vcc, |v94|, s34
	v_cndmask_b32_e32 v94, v94, v102, vcc
	v_cmp_lt_f32_e64 vcc, |v95|, s34
	v_cndmask_b32_e32 v95, v95, v103, vcc
	v_cndmask_b32_e64 v100, 0, v213, s[22:23]
	v_cndmask_b32_e64 v101, 0, v213, s[24:25]
	v_cndmask_b32_e64 v102, 0, v213, s[26:27]
	v_cndmask_b32_e64 v103, 0, v213, s[28:29]
	v_sub_f32_e32 v92, v92, v100
	v_sub_f32_e32 v93, v93, v101
	v_sub_f32_e32 v94, v94, v102
	v_sub_f32_e32 v95, v95, v103
	v_add_f32_e32 v64, v64, v92
	v_add_f32_e32 v65, v65, v93
	v_add_f32_e32 v66, v66, v94
	v_add_f32_e32 v67, v67, v95
	v_mul_f32_e32 v92, 0xbfb8aa3b, v64
	v_mul_f32_e32 v93, 0xbfb8aa3b, v65
	v_mul_f32_e32 v94, 0xbfb8aa3b, v66
	v_mul_f32_e32 v95, 0xbfb8aa3b, v67
	v_mul_f32_e32 v100, 0x3fb8aa3b, v64
	v_mul_f32_e32 v101, 0x3fb8aa3b, v65
	v_mul_f32_e32 v102, 0x3fb8aa3b, v66
	v_mul_f32_e32 v103, 0x3fb8aa3b, v67
	v_exp_f32_e32 v92, v92
	v_exp_f32_e32 v93, v93
	v_exp_f32_e32 v94, v94
	v_exp_f32_e32 v95, v95
	v_exp_f32_e32 v100, v100
	v_exp_f32_e32 v101, v101
	v_exp_f32_e32 v102, v102
	v_exp_f32_e32 v103, v103
	v_sub_f32_e32 v96, 1.0, v96
	v_sub_f32_e32 v97, 1.0, v97
	v_sub_f32_e32 v98, 1.0, v98
	v_sub_f32_e32 v99, 1.0, v99
	v_mul_f32_e32 v96, v96, v92
	v_mul_f32_e32 v97, v97, v93
	v_mul_f32_e32 v98, v98, v94
	v_mul_f32_e32 v99, v99, v95
	v_lshlrev_b32_e32 v92, 16, v26
	v_and_b32_e32 v93, 0xffff0000, v26
	v_lshlrev_b32_e32 v94, 16, v27
	v_and_b32_e32 v95, 0xffff0000, v27
	v_mul_f32_e32 v92, v92, v100
	v_mul_f32_e32 v93, v93, v101
	v_mul_f32_e32 v94, v94, v102
	v_mul_f32_e32 v95, v95, v103
	v_cvt_pk_bf16_f32 v108, v92, v93
	v_cvt_pk_bf16_f32 v109, v94, v95
	v_cvt_pk_bf16_f32 v110, v96, v97
	v_cvt_pk_bf16_f32 v111, v98, v99
	global_store_dwordx2 v112, v[108:109], s[2:3]
	global_store_dwordx2 v114, v[110:111], s[2:3]
	s_sub_u32 s2, s2, 0x400
	s_subb_u32 s3, s3, 0
	v_mov_b32_e32 v104, v96
	v_mov_b32_e32 v105, v97
	v_mov_b32_e32 v106, v98
	v_mov_b32_e32 v107, v99
	v_lshlrev_b32_e32 v92, 16, v28
	v_and_b32_e32 v93, 0xffff0000, v28
	v_lshlrev_b32_e32 v94, 16, v29
	v_and_b32_e32 v95, 0xffff0000, v29
	v_mul_f32_e32 v92, 0xbfb8aa3b, v92
	v_mul_f32_e32 v93, 0xbfb8aa3b, v93
	v_mul_f32_e32 v94, 0xbfb8aa3b, v94
	v_mul_f32_e32 v95, 0xbfb8aa3b, v95
	v_exp_f32_e32 v92, v92
	v_exp_f32_e32 v93, v93
	v_exp_f32_e32 v94, v94
	v_exp_f32_e32 v95, v95
	v_add_f32_e32 v92, 1.0, v92
	v_add_f32_e32 v93, 1.0, v93
	v_add_f32_e32 v94, 1.0, v94
	v_add_f32_e32 v95, 1.0, v95
	v_rcp_f32_e32 v92, v92
	v_rcp_f32_e32 v93, v93
	v_rcp_f32_e32 v94, v94
	v_rcp_f32_e32 v95, v95
	v_fma_f32 v96, v72, v92, v68
	v_fma_f32 v97, v73, v93, v69
	v_fma_f32 v98, v74, v94, v70
	v_fma_f32 v99, v75, v95, v71
	v_cmp_gt_f32_e64 s[22:23], s30, v96
	v_cmp_gt_f32_e64 s[24:25], s30, v97
	v_cmp_gt_f32_e64 s[26:27], s30, v98
	v_cmp_gt_f32_e64 s[28:29], s30, v99
	v_cndmask_b32_e64 v92, 0, 32, s[22:23]
	v_cndmask_b32_e64 v93, 0, 32, s[24:25]
	v_cndmask_b32_e64 v94, 0, 32, s[26:27]
	v_cndmask_b32_e64 v95, 0, 32, s[28:29]
	v_ldexp_f32 v92, v96, v92
; DEV u16 f2bf(float f) { return (u16)(pack2(f, f) & 0xffffu); }
; DEV float bf2f(u16 h) { return __uint_as_float(((unsigned)h) << 16); }
; DEV float sigmoid_f(float x) { return __builtin_amdgcn_rcpf(1.f + __expf(-x)); }
; DEV void phase_p15(const Params& p, int g) {
;     ...
;     P15_LOAD(0, 0);
;     P15_LOAD(1, 1);
; #pragma unroll
;     for (int j8 = 0; j8 < 8; ++j8) {
;       const int st = j8 % 3;
;       if (j8 < 6) { P15_LOAD((j8 + 2) % 3, j8 + 2); }
;     ...
;         for (int e = 0; e < 8; ++e) {
;           const int jj = j8 * 8 + e;
;           const int j = dir ? 63 - jj : jj;
;           const size_t tok = (size_t)cidx * 64 + j;
;           const float f = lb[cc] + (1.f - lb[cc]) * sigmoid_f(bf2f(xr[st][cc][e]));
;           G[cc] += __logf(f);
;           const float eg = __expf(G[cc]), ig = __expf(-G[cc]);
;           Qp[tok * 512 + c] = f2bf(bf2f(qr[st][cc][e]) * eg);
;           const u16 kk = f2bf((1.f - f) * ig);
;           Kp[tok * 512 + c] = kk;
;           kb[e] = kk;
;         }
	v_ldexp_f32 v93, v97, v93
	v_ldexp_f32 v94, v98, v94
	v_ldexp_f32 v95, v99, v95
	v_log_f32_e32 v92, v92
	v_log_f32_e32 v93, v93
	v_log_f32_e32 v94, v94
	v_log_f32_e32 v95, v95
	v_mul_f32_e32 v100, 0x3f317217, v92
	v_mul_f32_e32 v101, 0x3f317217, v93
	v_mul_f32_e32 v102, 0x3f317217, v94
	v_mul_f32_e32 v103, 0x3f317217, v95
	v_fma_f32 v100, v92, s31, -v100
	v_fma_f32 v101, v93, s31, -v101
	v_fma_f32 v102, v94, s31, -v102
	v_fma_f32 v103, v95, s31, -v103
	v_fmac_f32_e32 v100, 0x3377d1cf, v92
	v_fmac_f32_e32 v101, 0x3377d1cf, v93
	v_fmac_f32_e32 v102, 0x3377d1cf, v94
	v_fmac_f32_e32 v103, 0x3377d1cf, v95
	v_fmac_f32_e32 v100, 0x3f317217, v92
	v_fmac_f32_e32 v101, 0x3f317217, v93
	v_fmac_f32_e32 v102, 0x3f317217, v94
	v_fmac_f32_e32 v103, 0x3f317217, v95
	v_cmp_lt_f32_e64 vcc, |v92|, s34
	v_cndmask_b32_e32 v92, v92, v100, vcc
	v_cmp_lt_f32_e64 vcc, |v93|, s34
	v_cndmask_b32_e32 v93, v93, v101, vcc
	v_cmp_lt_f32_e64 vcc, |v94|, s34
	v_cndmask_b32_e32 v94, v94, v102, vcc
	v_cmp_lt_f32_e64 vcc, |v95|, s34
	v_cndmask_b32_e32 v95, v95, v103, vcc
	v_cndmask_b32_e64 v100, 0, v213, s[22:23]
	v_cndmask_b32_e64 v101, 0, v213, s[24:25]
	v_cndmask_b32_e64 v102, 0, v213, s[26:27]
	v_cndmask_b32_e64 v103, 0, v213, s[28:29]
	v_sub_f32_e32 v92, v92, v100
	v_sub_f32_e32 v93, v93, v101
	v_sub_f32_e32 v94, v94, v102
	v_sub_f32_e32 v95, v95, v103
	v_add_f32_e32 v64, v64, v92
	v_add_f32_e32 v65, v65, v93
	v_add_f32_e32 v66, v66, v94
	v_add_f32_e32 v67, v67, v95
	v_mul_f32_e32 v92, 0xbfb8aa3b, v64
	v_mul_f32_e32 v93, 0xbfb8aa3b, v65
	v_mul_f32_e32 v94, 0xbfb8aa3b, v66
	v_mul_f32_e32 v95, 0xbfb8aa3b, v67
	v_mul_f32_e32 v100, 0x3fb8aa3b, v64
	v_mul_f32_e32 v101, 0x3fb8aa3b, v65
	v_mul_f32_e32 v102, 0x3fb8aa3b, v66
	v_mul_f32_e32 v103, 0x3fb8aa3b, v67
	v_exp_f32_e32 v92, v92
	v_exp_f32_e32 v93, v93
	v_exp_f32_e32 v94, v94
	v_exp_f32_e32 v95, v95
	v_exp_f32_e32 v100, v100
	v_exp_f32_e32 v101, v101
	v_exp_f32_e32 v102, v102
	v_exp_f32_e32 v103, v103
	v_sub_f32_e32 v96, 1.0, v96
	v_sub_f32_e32 v97, 1.0, v97
	v_sub_f32_e32 v98, 1.0, v98
	v_sub_f32_e32 v99, 1.0, v99
	v_mul_f32_e32 v96, v96, v92
	v_mul_f32_e32 v97, v97, v93
	v_mul_f32_e32 v98, v98, v94
	v_mul_f32_e32 v99, v99, v95
	v_lshlrev_b32_e32 v92, 16, v30
	v_and_b32_e32 v93, 0xffff0000, v30
	v_lshlrev_b32_e32 v94, 16, v31
	v_and_b32_e32 v95, 0xffff0000, v31
	v_mul_f32_e32 v92, v92, v100
	v_mul_f32_e32 v93, v93, v101
	v_mul_f32_e32 v94, v94, v102
	v_mul_f32_e32 v95, v95, v103
	v_cvt_pk_bf16_f32 v108, v92, v93
	v_cvt_pk_bf16_f32 v109, v94, v95
	v_cvt_pk_bf16_f32 v110, v96, v97
	v_cvt_pk_bf16_f32 v111, v98, v99
	global_store_dwordx2 v112, v[108:109], s[2:3]
	global_store_dwordx2 v114, v[110:111], s[2:3]
	s_sub_u32 s2, s2, 0x400
	s_subb_u32 s3, s3, 0
	v_cvt_pk_bf16_f32 v128, v96, v104
	v_cvt_pk_bf16_f32 v144, v97, v105
	v_cvt_pk_bf16_f32 v178, v98, v106
	v_cvt_pk_bf16_f32 v194, v99, v107
	global_load_dwordx2 v[0:1], v113, s[0:1]
	global_load_dwordx2 v[2:3], v112, s[0:1]
	s_sub_u32 s0, s0, 0x1400
	s_subb_u32 s1, s1, 0
	global_load_dwordx2 v[4:5], v113, s[0:1]
	global_load_dwordx2 v[6:7], v112, s[0:1]
	s_sub_u32 s0, s0, 0x1400
	s_subb_u32 s1, s1, 0
	global_load_dwordx2 v[8:9], v113, s[0:1]
	global_load_dwordx2 v[10:11], v112, s[0:1]
	s_sub_u32 s0, s0, 0x1400
	s_subb_u32 s1, s1, 0
	global_load_dwordx2 v[12:13], v113, s[0:1]
	global_load_dwordx2 v[14:15], v112, s[0:1]
	s_sub_u32 s0, s0, 0x1400
	s_subb_u32 s1, s1, 0
	global_load_dwordx2 v[16:17], v113, s[0:1]
	global_load_dwordx2 v[18:19], v112, s[0:1]
	s_sub_u32 s0, s0, 0x1400
	s_subb_u32 s1, s1, 0
	global_load_dwordx2 v[20:21], v113, s[0:1]
	global_load_dwordx2 v[22:23], v112, s[0:1]
	s_sub_u32 s0, s0, 0x1400
	s_subb_u32 s1, s1, 0
	global_load_dwordx2 v[24:25], v113, s[0:1]
	global_load_dwordx2 v[26:27], v112, s[0:1]
	s_sub_u32 s0, s0, 0x1400
	s_subb_u32 s1, s1, 0
	global_load_dwordx2 v[28:29], v113, s[0:1]
	global_load_dwordx2 v[30:31], v112, s[0:1]
	s_sub_u32 s0, s0, 0x1400
	s_subb_u32 s1, s1, 0
	s_waitcnt vmcnt(32)
	v_lshlrev_b32_e32 v92, 16, v32
	v_and_b32_e32 v93, 0xffff0000, v32
	v_lshlrev_b32_e32 v94, 16, v33
	v_and_b32_e32 v95, 0xffff0000, v33
	v_mul_f32_e32 v92, 0xbfb8aa3b, v92
	v_mul_f32_e32 v93, 0xbfb8aa3b, v93
	v_mul_f32_e32 v94, 0xbfb8aa3b, v94
	v_mul_f32_e32 v95, 0xbfb8aa3b, v95
	v_exp_f32_e32 v92, v92
	v_exp_f32_e32 v93, v93
	v_exp_f32_e32 v94, v94
	v_exp_f32_e32 v95, v95
	v_add_f32_e32 v92, 1.0, v92
	v_add_f32_e32 v93, 1.0, v93
	v_add_f32_e32 v94, 1.0, v94
	v_add_f32_e32 v95, 1.0, v95
	v_rcp_f32_e32 v92, v92
	v_rcp_f32_e32 v93, v93
	v_rcp_f32_e32 v94, v94
	v_rcp_f32_e32 v95, v95
	v_fma_f32 v96, v72, v92, v68
	v_fma_f32 v97, v73, v93, v69
	v_fma_f32 v98, v74, v94, v70
	v_fma_f32 v99, v75, v95, v71
	v_cmp_gt_f32_e64 s[22:23], s30, v96
	v_cmp_gt_f32_e64 s[24:25], s30, v97
	v_cmp_gt_f32_e64 s[26:27], s30, v98
	v_cmp_gt_f32_e64 s[28:29], s30, v99
	v_cndmask_b32_e64 v92, 0, 32, s[22:23]
	v_cndmask_b32_e64 v93, 0, 32, s[24:25]
	v_cndmask_b32_e64 v94, 0, 32, s[26:27]
	v_cndmask_b32_e64 v95, 0, 32, s[28:29]
	v_ldexp_f32 v92, v96, v92
	v_ldexp_f32 v93, v97, v93
	v_ldexp_f32 v94, v98, v94
	v_ldexp_f32 v95, v99, v95
	v_log_f32_e32 v92, v92
	v_log_f32_e32 v93, v93
	v_log_f32_e32 v94, v94
	v_log_f32_e32 v95, v95
	v_mul_f32_e32 v100, 0x3f317217, v92
	v_mul_f32_e32 v101, 0x3f317217, v93
	v_mul_f32_e32 v102, 0x3f317217, v94
	v_mul_f32_e32 v103, 0x3f317217, v95
	v_fma_f32 v100, v92, s31, -v100
	v_fma_f32 v101, v93, s31, -v101
	v_fma_f32 v102, v94, s31, -v102
	v_fma_f32 v103, v95, s31, -v103
	v_fmac_f32_e32 v100, 0x3377d1cf, v92
	v_fmac_f32_e32 v101, 0x3377d1cf, v93
	v_fmac_f32_e32 v102, 0x3377d1cf, v94
	v_fmac_f32_e32 v103, 0x3377d1cf, v95
	v_fmac_f32_e32 v100, 0x3f317217, v92
; DEV u16 f2bf(float f) { return (u16)(pack2(f, f) & 0xffffu); }
; DEV float bf2f(u16 h) { return __uint_as_float(((unsigned)h) << 16); }
; DEV float sigmoid_f(float x) { return __builtin_amdgcn_rcpf(1.f + __expf(-x)); }
; DEV void phase_p15(const Params& p, int g) {
;     ...
;         for (int e = 0; e < 8; ++e) {
;           const int jj = j8 * 8 + e;
;           const int j = dir ? 63 - jj : jj;
;           const size_t tok = (size_t)cidx * 64 + j;
;           const float f = lb[cc] + (1.f - lb[cc]) * sigmoid_f(bf2f(xr[st][cc][e]));
;           G[cc] += __logf(f);
;           const float eg = __expf(G[cc]), ig = __expf(-G[cc]);
;           Qp[tok * 512 + c] = f2bf(bf2f(qr[st][cc][e]) * eg);
;           const u16 kk = f2bf((1.f - f) * ig);
;           Kp[tok * 512 + c] = kk;
;           kb[e] = kk;
;         }
	v_fmac_f32_e32 v101, 0x3f317217, v93
	v_fmac_f32_e32 v102, 0x3f317217, v94
	v_fmac_f32_e32 v103, 0x3f317217, v95
	v_cmp_lt_f32_e64 vcc, |v92|, s34
	v_cndmask_b32_e32 v92, v92, v100, vcc
	v_cmp_lt_f32_e64 vcc, |v93|, s34
	v_cndmask_b32_e32 v93, v93, v101, vcc
	v_cmp_lt_f32_e64 vcc, |v94|, s34
	v_cndmask_b32_e32 v94, v94, v102, vcc
	v_cmp_lt_f32_e64 vcc, |v95|, s34
	v_cndmask_b32_e32 v95, v95, v103, vcc
	v_cndmask_b32_e64 v100, 0, v213, s[22:23]
	v_cndmask_b32_e64 v101, 0, v213, s[24:25]
	v_cndmask_b32_e64 v102, 0, v213, s[26:27]
	v_cndmask_b32_e64 v103, 0, v213, s[28:29]
	v_sub_f32_e32 v92, v92, v100
	v_sub_f32_e32 v93, v93, v101
	v_sub_f32_e32 v94, v94, v102
	v_sub_f32_e32 v95, v95, v103
	v_add_f32_e32 v64, v64, v92
	v_add_f32_e32 v65, v65, v93
	v_add_f32_e32 v66, v66, v94
	v_add_f32_e32 v67, v67, v95
	v_mul_f32_e32 v92, 0xbfb8aa3b, v64
	v_mul_f32_e32 v93, 0xbfb8aa3b, v65
	v_mul_f32_e32 v94, 0xbfb8aa3b, v66
	v_mul_f32_e32 v95, 0xbfb8aa3b, v67
	v_mul_f32_e32 v100, 0x3fb8aa3b, v64
	v_mul_f32_e32 v101, 0x3fb8aa3b, v65
	v_mul_f32_e32 v102, 0x3fb8aa3b, v66
	v_mul_f32_e32 v103, 0x3fb8aa3b, v67
	v_exp_f32_e32 v92, v92
	v_exp_f32_e32 v93, v93
	v_exp_f32_e32 v94, v94
	v_exp_f32_e32 v95, v95
	v_exp_f32_e32 v100, v100
	v_exp_f32_e32 v101, v101
	v_exp_f32_e32 v102, v102
	v_exp_f32_e32 v103, v103
	v_sub_f32_e32 v96, 1.0, v96
	v_sub_f32_e32 v97, 1.0, v97
	v_sub_f32_e32 v98, 1.0, v98
	v_sub_f32_e32 v99, 1.0, v99
	v_mul_f32_e32 v96, v96, v92
	v_mul_f32_e32 v97, v97, v93
	v_mul_f32_e32 v98, v98, v94
	v_mul_f32_e32 v99, v99, v95
	v_lshlrev_b32_e32 v92, 16, v34
	v_and_b32_e32 v93, 0xffff0000, v34
	v_lshlrev_b32_e32 v94, 16, v35
	v_and_b32_e32 v95, 0xffff0000, v35
	v_mul_f32_e32 v92, v92, v100
	v_mul_f32_e32 v93, v93, v101
	v_mul_f32_e32 v94, v94, v102
	v_mul_f32_e32 v95, v95, v103
	v_cvt_pk_bf16_f32 v108, v92, v93
	v_cvt_pk_bf16_f32 v109, v94, v95
	v_cvt_pk_bf16_f32 v110, v96, v97
	v_cvt_pk_bf16_f32 v111, v98, v99
	global_store_dwordx2 v112, v[108:109], s[2:3]
	global_store_dwordx2 v114, v[110:111], s[2:3]
	s_sub_u32 s2, s2, 0x400
	s_subb_u32 s3, s3, 0
	v_mov_b32_e32 v104, v96
	v_mov_b32_e32 v105, v97
	v_mov_b32_e32 v106, v98
	v_mov_b32_e32 v107, v99
	v_lshlrev_b32_e32 v92, 16, v36
	v_and_b32_e32 v93, 0xffff0000, v36
	v_lshlrev_b32_e32 v94, 16, v37
	v_and_b32_e32 v95, 0xffff0000, v37
	v_mul_f32_e32 v92, 0xbfb8aa3b, v92
	v_mul_f32_e32 v93, 0xbfb8aa3b, v93
	v_mul_f32_e32 v94, 0xbfb8aa3b, v94
	v_mul_f32_e32 v95, 0xbfb8aa3b, v95
	v_exp_f32_e32 v92, v92
	v_exp_f32_e32 v93, v93
	v_exp_f32_e32 v94, v94
	v_exp_f32_e32 v95, v95
	v_add_f32_e32 v92, 1.0, v92
	v_add_f32_e32 v93, 1.0, v93
	v_add_f32_e32 v94, 1.0, v94
	v_add_f32_e32 v95, 1.0, v95
	v_rcp_f32_e32 v92, v92
	v_rcp_f32_e32 v93, v93
	v_rcp_f32_e32 v94, v94
	v_rcp_f32_e32 v95, v95
	v_fma_f32 v96, v72, v92, v68
	v_fma_f32 v97, v73, v93, v69
	v_fma_f32 v98, v74, v94, v70
	v_fma_f32 v99, v75, v95, v71
	v_cmp_gt_f32_e64 s[22:23], s30, v96
	v_cmp_gt_f32_e64 s[24:25], s30, v97
	v_cmp_gt_f32_e64 s[26:27], s30, v98
	v_cmp_gt_f32_e64 s[28:29], s30, v99
	v_cndmask_b32_e64 v92, 0, 32, s[22:23]
	v_cndmask_b32_e64 v93, 0, 32, s[24:25]
	v_cndmask_b32_e64 v94, 0, 32, s[26:27]
	v_cndmask_b32_e64 v95, 0, 32, s[28:29]
	v_ldexp_f32 v92, v96, v92
	v_ldexp_f32 v93, v97, v93
	v_ldexp_f32 v94, v98, v94
	v_ldexp_f32 v95, v99, v95
	v_log_f32_e32 v92, v92
	v_log_f32_e32 v93, v93
	v_log_f32_e32 v94, v94
	v_log_f32_e32 v95, v95
	v_mul_f32_e32 v100, 0x3f317217, v92
	v_mul_f32_e32 v101, 0x3f317217, v93
	v_mul_f32_e32 v102, 0x3f317217, v94
	v_mul_f32_e32 v103, 0x3f317217, v95
	v_fma_f32 v100, v92, s31, -v100
	v_fma_f32 v101, v93, s31, -v101
	v_fma_f32 v102, v94, s31, -v102
	v_fma_f32 v103, v95, s31, -v103
	v_fmac_f32_e32 v100, 0x3377d1cf, v92
	v_fmac_f32_e32 v101, 0x3377d1cf, v93
	v_fmac_f32_e32 v102, 0x3377d1cf, v94
	v_fmac_f32_e32 v103, 0x3377d1cf, v95
	v_fmac_f32_e32 v100, 0x3f317217, v92
	v_fmac_f32_e32 v101, 0x3f317217, v93
	v_fmac_f32_e32 v102, 0x3f317217, v94
	v_fmac_f32_e32 v103, 0x3f317217, v95
	v_cmp_lt_f32_e64 vcc, |v92|, s34
	v_cndmask_b32_e32 v92, v92, v100, vcc
	v_cmp_lt_f32_e64 vcc, |v93|, s34
	v_cndmask_b32_e32 v93, v93, v101, vcc
	v_cmp_lt_f32_e64 vcc, |v94|, s34
	v_cndmask_b32_e32 v94, v94, v102, vcc
	v_cmp_lt_f32_e64 vcc, |v95|, s34
	v_cndmask_b32_e32 v95, v95, v103, vcc
	v_cndmask_b32_e64 v100, 0, v213, s[22:23]
	v_cndmask_b32_e64 v101, 0, v213, s[24:25]
	v_cndmask_b32_e64 v102, 0, v213, s[26:27]
	v_cndmask_b32_e64 v103, 0, v213, s[28:29]
	v_sub_f32_e32 v92, v92, v100
	v_sub_f32_e32 v93, v93, v101
	v_sub_f32_e32 v94, v94, v102
	v_sub_f32_e32 v95, v95, v103
	v_add_f32_e32 v64, v64, v92
	v_add_f32_e32 v65, v65, v93
	v_add_f32_e32 v66, v66, v94
	v_add_f32_e32 v67, v67, v95
	v_mul_f32_e32 v92, 0xbfb8aa3b, v64
	v_mul_f32_e32 v93, 0xbfb8aa3b, v65
	v_mul_f32_e32 v94, 0xbfb8aa3b, v66
	v_mul_f32_e32 v95, 0xbfb8aa3b, v67
	v_mul_f32_e32 v100, 0x3fb8aa3b, v64
	v_mul_f32_e32 v101, 0x3fb8aa3b, v65
	v_mul_f32_e32 v102, 0x3fb8aa3b, v66
	v_mul_f32_e32 v103, 0x3fb8aa3b, v67
	v_exp_f32_e32 v92, v92
	v_exp_f32_e32 v93, v93
	v_exp_f32_e32 v94, v94
	v_exp_f32_e32 v95, v95
	v_exp_f32_e32 v100, v100
	v_exp_f32_e32 v101, v101
	v_exp_f32_e32 v102, v102
	v_exp_f32_e32 v103, v103
	v_sub_f32_e32 v96, 1.0, v96
	v_sub_f32_e32 v97, 1.0, v97
	v_sub_f32_e32 v98, 1.0, v98
	v_sub_f32_e32 v99, 1.0, v99
	v_mul_f32_e32 v96, v96, v92
	v_mul_f32_e32 v97, v97, v93
	v_mul_f32_e32 v98, v98, v94
	v_mul_f32_e32 v99, v99, v95
	v_lshlrev_b32_e32 v92, 16, v38
	v_and_b32_e32 v93, 0xffff0000, v38
	v_lshlrev_b32_e32 v94, 16, v39
	v_and_b32_e32 v95, 0xffff0000, v39
	v_mul_f32_e32 v92, v92, v100
	v_mul_f32_e32 v93, v93, v101
	v_mul_f32_e32 v94, v94, v102
; DEV u16 f2bf(float f) { return (u16)(pack2(f, f) & 0xffffu); }
; DEV float bf2f(u16 h) { return __uint_as_float(((unsigned)h) << 16); }
; DEV float sigmoid_f(float x) { return __builtin_amdgcn_rcpf(1.f + __expf(-x)); }
; DEV void phase_p15(const Params& p, int g) {
;     ...
;         for (int e = 0; e < 8; ++e) {
;           const int jj = j8 * 8 + e;
;           const int j = dir ? 63 - jj : jj;
;           const size_t tok = (size_t)cidx * 64 + j;
;           const float f = lb[cc] + (1.f - lb[cc]) * sigmoid_f(bf2f(xr[st][cc][e]));
;           G[cc] += __logf(f);
;           const float eg = __expf(G[cc]), ig = __expf(-G[cc]);
;           Qp[tok * 512 + c] = f2bf(bf2f(qr[st][cc][e]) * eg);
;           const u16 kk = f2bf((1.f - f) * ig);
;           Kp[tok * 512 + c] = kk;
;           kb[e] = kk;
;         }
;         const int s0 = dir ? 56 - 8 * j8 : 8 * j8;
;         uint4 w;
;         w.x = dir ? (kb[7] | (kb[6] << 16)) : (kb[0] | (kb[1] << 16));
;         w.y = dir ? (kb[5] | (kb[4] << 16)) : (kb[2] | (kb[3] << 16));
;         w.z = dir ? (kb[3] | (kb[2] << 16)) : (kb[4] | (kb[5] << 16));
;         w.w = dir ? (kb[1] | (kb[0] << 16)) : (kb[6] | (kb[7] << 16));
;         *(uint4*)(KT + (((size_t)cidx * 2 + dir) * 512 + c) * 64 + s0) = w;
	v_mul_f32_e32 v95, v95, v103
	v_cvt_pk_bf16_f32 v108, v92, v93
	v_cvt_pk_bf16_f32 v109, v94, v95
	v_cvt_pk_bf16_f32 v110, v96, v97
	v_cvt_pk_bf16_f32 v111, v98, v99
	global_store_dwordx2 v112, v[108:109], s[2:3]
	global_store_dwordx2 v114, v[110:111], s[2:3]
	s_sub_u32 s2, s2, 0x400
	s_subb_u32 s3, s3, 0
	v_cvt_pk_bf16_f32 v127, v96, v104
	v_cvt_pk_bf16_f32 v143, v97, v105
	v_cvt_pk_bf16_f32 v177, v98, v106
	v_cvt_pk_bf16_f32 v193, v99, v107
	v_lshlrev_b32_e32 v92, 16, v40
	v_and_b32_e32 v93, 0xffff0000, v40
	v_lshlrev_b32_e32 v94, 16, v41
	v_and_b32_e32 v95, 0xffff0000, v41
	v_mul_f32_e32 v92, 0xbfb8aa3b, v92
	v_mul_f32_e32 v93, 0xbfb8aa3b, v93
	v_mul_f32_e32 v94, 0xbfb8aa3b, v94
	v_mul_f32_e32 v95, 0xbfb8aa3b, v95
	v_exp_f32_e32 v92, v92
	v_exp_f32_e32 v93, v93
	v_exp_f32_e32 v94, v94
	v_exp_f32_e32 v95, v95
	v_add_f32_e32 v92, 1.0, v92
	v_add_f32_e32 v93, 1.0, v93
	v_add_f32_e32 v94, 1.0, v94
	v_add_f32_e32 v95, 1.0, v95
	v_rcp_f32_e32 v92, v92
	v_rcp_f32_e32 v93, v93
	v_rcp_f32_e32 v94, v94
	v_rcp_f32_e32 v95, v95
	v_fma_f32 v96, v72, v92, v68
	v_fma_f32 v97, v73, v93, v69
	v_fma_f32 v98, v74, v94, v70
	v_fma_f32 v99, v75, v95, v71
	v_cmp_gt_f32_e64 s[22:23], s30, v96
	v_cmp_gt_f32_e64 s[24:25], s30, v97
	v_cmp_gt_f32_e64 s[26:27], s30, v98
	v_cmp_gt_f32_e64 s[28:29], s30, v99
	v_cndmask_b32_e64 v92, 0, 32, s[22:23]
	v_cndmask_b32_e64 v93, 0, 32, s[24:25]
	v_cndmask_b32_e64 v94, 0, 32, s[26:27]
	v_cndmask_b32_e64 v95, 0, 32, s[28:29]
	v_ldexp_f32 v92, v96, v92
	v_ldexp_f32 v93, v97, v93
	v_ldexp_f32 v94, v98, v94
	v_ldexp_f32 v95, v99, v95
	v_log_f32_e32 v92, v92
	v_log_f32_e32 v93, v93
	v_log_f32_e32 v94, v94
	v_log_f32_e32 v95, v95
	v_mul_f32_e32 v100, 0x3f317217, v92
	v_mul_f32_e32 v101, 0x3f317217, v93
	v_mul_f32_e32 v102, 0x3f317217, v94
	v_mul_f32_e32 v103, 0x3f317217, v95
	v_fma_f32 v100, v92, s31, -v100
	v_fma_f32 v101, v93, s31, -v101
	v_fma_f32 v102, v94, s31, -v102
	v_fma_f32 v103, v95, s31, -v103
	v_fmac_f32_e32 v100, 0x3377d1cf, v92
	v_fmac_f32_e32 v101, 0x3377d1cf, v93
	v_fmac_f32_e32 v102, 0x3377d1cf, v94
	v_fmac_f32_e32 v103, 0x3377d1cf, v95
	v_fmac_f32_e32 v100, 0x3f317217, v92
	v_fmac_f32_e32 v101, 0x3f317217, v93
	v_fmac_f32_e32 v102, 0x3f317217, v94
	v_fmac_f32_e32 v103, 0x3f317217, v95
	v_cmp_lt_f32_e64 vcc, |v92|, s34
	v_cndmask_b32_e32 v92, v92, v100, vcc
	v_cmp_lt_f32_e64 vcc, |v93|, s34
	v_cndmask_b32_e32 v93, v93, v101, vcc
	v_cmp_lt_f32_e64 vcc, |v94|, s34
	v_cndmask_b32_e32 v94, v94, v102, vcc
	v_cmp_lt_f32_e64 vcc, |v95|, s34
	v_cndmask_b32_e32 v95, v95, v103, vcc
	v_cndmask_b32_e64 v100, 0, v213, s[22:23]
	v_cndmask_b32_e64 v101, 0, v213, s[24:25]
	v_cndmask_b32_e64 v102, 0, v213, s[26:27]
	v_cndmask_b32_e64 v103, 0, v213, s[28:29]
	v_sub_f32_e32 v92, v92, v100
	v_sub_f32_e32 v93, v93, v101
	v_sub_f32_e32 v94, v94, v102
	v_sub_f32_e32 v95, v95, v103
	v_add_f32_e32 v64, v64, v92
	v_add_f32_e32 v65, v65, v93
	v_add_f32_e32 v66, v66, v94
	v_add_f32_e32 v67, v67, v95
	v_mul_f32_e32 v92, 0xbfb8aa3b, v64
	v_mul_f32_e32 v93, 0xbfb8aa3b, v65
	v_mul_f32_e32 v94, 0xbfb8aa3b, v66
	v_mul_f32_e32 v95, 0xbfb8aa3b, v67
	v_mul_f32_e32 v100, 0x3fb8aa3b, v64
	v_mul_f32_e32 v101, 0x3fb8aa3b, v65
	v_mul_f32_e32 v102, 0x3fb8aa3b, v66
	v_mul_f32_e32 v103, 0x3fb8aa3b, v67
	v_exp_f32_e32 v92, v92
	v_exp_f32_e32 v93, v93
	v_exp_f32_e32 v94, v94
	v_exp_f32_e32 v95, v95
	v_exp_f32_e32 v100, v100
	v_exp_f32_e32 v101, v101
	v_exp_f32_e32 v102, v102
	v_exp_f32_e32 v103, v103
	v_sub_f32_e32 v96, 1.0, v96
	v_sub_f32_e32 v97, 1.0, v97
	v_sub_f32_e32 v98, 1.0, v98
	v_sub_f32_e32 v99, 1.0, v99
	v_mul_f32_e32 v96, v96, v92
	v_mul_f32_e32 v97, v97, v93
	v_mul_f32_e32 v98, v98, v94
	v_mul_f32_e32 v99, v99, v95
	v_lshlrev_b32_e32 v92, 16, v42
	v_and_b32_e32 v93, 0xffff0000, v42
	v_lshlrev_b32_e32 v94, 16, v43
	v_and_b32_e32 v95, 0xffff0000, v43
	v_mul_f32_e32 v92, v92, v100
	v_mul_f32_e32 v93, v93, v101
	v_mul_f32_e32 v94, v94, v102
	v_mul_f32_e32 v95, v95, v103
	v_cvt_pk_bf16_f32 v108, v92, v93
	v_cvt_pk_bf16_f32 v109, v94, v95
	v_cvt_pk_bf16_f32 v110, v96, v97
	v_cvt_pk_bf16_f32 v111, v98, v99
	global_store_dwordx2 v112, v[108:109], s[2:3]
	global_store_dwordx2 v114, v[110:111], s[2:3]
	s_sub_u32 s2, s2, 0x400
	s_subb_u32 s3, s3, 0
	v_mov_b32_e32 v104, v96
	v_mov_b32_e32 v105, v97
	v_mov_b32_e32 v106, v98
	v_mov_b32_e32 v107, v99
	v_lshlrev_b32_e32 v92, 16, v44
	v_and_b32_e32 v93, 0xffff0000, v44
	v_lshlrev_b32_e32 v94, 16, v45
	v_and_b32_e32 v95, 0xffff0000, v45
	v_mul_f32_e32 v92, 0xbfb8aa3b, v92
	v_mul_f32_e32 v93, 0xbfb8aa3b, v93
	v_mul_f32_e32 v94, 0xbfb8aa3b, v94
	v_mul_f32_e32 v95, 0xbfb8aa3b, v95
	v_exp_f32_e32 v92, v92
	v_exp_f32_e32 v93, v93
	v_exp_f32_e32 v94, v94
	v_exp_f32_e32 v95, v95
	v_add_f32_e32 v92, 1.0, v92
	v_add_f32_e32 v93, 1.0, v93
	v_add_f32_e32 v94, 1.0, v94
	v_add_f32_e32 v95, 1.0, v95
	v_rcp_f32_e32 v92, v92
	v_rcp_f32_e32 v93, v93
	v_rcp_f32_e32 v94, v94
	v_rcp_f32_e32 v95, v95
	v_fma_f32 v96, v72, v92, v68
	v_fma_f32 v97, v73, v93, v69
	v_fma_f32 v98, v74, v94, v70
	v_fma_f32 v99, v75, v95, v71
	v_cmp_gt_f32_e64 s[22:23], s30, v96
	v_cmp_gt_f32_e64 s[24:25], s30, v97
	v_cmp_gt_f32_e64 s[26:27], s30, v98
	v_cmp_gt_f32_e64 s[28:29], s30, v99
	v_cndmask_b32_e64 v92, 0, 32, s[22:23]
	v_cndmask_b32_e64 v93, 0, 32, s[24:25]
	v_cndmask_b32_e64 v94, 0, 32, s[26:27]
	v_cndmask_b32_e64 v95, 0, 32, s[28:29]
	v_ldexp_f32 v92, v96, v92
	v_ldexp_f32 v93, v97, v93
	v_ldexp_f32 v94, v98, v94
	v_ldexp_f32 v95, v99, v95
	v_log_f32_e32 v92, v92
	v_log_f32_e32 v93, v93
	v_log_f32_e32 v94, v94
	v_log_f32_e32 v95, v95
	v_mul_f32_e32 v100, 0x3f317217, v92
	v_mul_f32_e32 v101, 0x3f317217, v93
	v_mul_f32_e32 v102, 0x3f317217, v94
; DEV u16 f2bf(float f) { return (u16)(pack2(f, f) & 0xffffu); }
; DEV float bf2f(u16 h) { return __uint_as_float(((unsigned)h) << 16); }
; DEV float sigmoid_f(float x) { return __builtin_amdgcn_rcpf(1.f + __expf(-x)); }
; DEV void phase_p15(const Params& p, int g) {
;     ...
;         for (int e = 0; e < 8; ++e) {
;           const int jj = j8 * 8 + e;
;           const int j = dir ? 63 - jj : jj;
;           const size_t tok = (size_t)cidx * 64 + j;
;           const float f = lb[cc] + (1.f - lb[cc]) * sigmoid_f(bf2f(xr[st][cc][e]));
;           G[cc] += __logf(f);
;           const float eg = __expf(G[cc]), ig = __expf(-G[cc]);
;           Qp[tok * 512 + c] = f2bf(bf2f(qr[st][cc][e]) * eg);
;           const u16 kk = f2bf((1.f - f) * ig);
;           Kp[tok * 512 + c] = kk;
;           kb[e] = kk;
;         }
;         const int s0 = dir ? 56 - 8 * j8 : 8 * j8;
;         uint4 w;
;         w.x = dir ? (kb[7] | (kb[6] << 16)) : (kb[0] | (kb[1] << 16));
;         w.y = dir ? (kb[5] | (kb[4] << 16)) : (kb[2] | (kb[3] << 16));
;         w.z = dir ? (kb[3] | (kb[2] << 16)) : (kb[4] | (kb[5] << 16));
;         w.w = dir ? (kb[1] | (kb[0] << 16)) : (kb[6] | (kb[7] << 16));
;         *(uint4*)(KT + (((size_t)cidx * 2 + dir) * 512 + c) * 64 + s0) = w;
	v_mul_f32_e32 v103, 0x3f317217, v95
	v_fma_f32 v100, v92, s31, -v100
	v_fma_f32 v101, v93, s31, -v101
	v_fma_f32 v102, v94, s31, -v102
	v_fma_f32 v103, v95, s31, -v103
	v_fmac_f32_e32 v100, 0x3377d1cf, v92
	v_fmac_f32_e32 v101, 0x3377d1cf, v93
	v_fmac_f32_e32 v102, 0x3377d1cf, v94
	v_fmac_f32_e32 v103, 0x3377d1cf, v95
	v_fmac_f32_e32 v100, 0x3f317217, v92
	v_fmac_f32_e32 v101, 0x3f317217, v93
	v_fmac_f32_e32 v102, 0x3f317217, v94
	v_fmac_f32_e32 v103, 0x3f317217, v95
	v_cmp_lt_f32_e64 vcc, |v92|, s34
	v_cndmask_b32_e32 v92, v92, v100, vcc
	v_cmp_lt_f32_e64 vcc, |v93|, s34
	v_cndmask_b32_e32 v93, v93, v101, vcc
	v_cmp_lt_f32_e64 vcc, |v94|, s34
	v_cndmask_b32_e32 v94, v94, v102, vcc
	v_cmp_lt_f32_e64 vcc, |v95|, s34
	v_cndmask_b32_e32 v95, v95, v103, vcc
	v_cndmask_b32_e64 v100, 0, v213, s[22:23]
	v_cndmask_b32_e64 v101, 0, v213, s[24:25]
	v_cndmask_b32_e64 v102, 0, v213, s[26:27]
	v_cndmask_b32_e64 v103, 0, v213, s[28:29]
	v_sub_f32_e32 v92, v92, v100
	v_sub_f32_e32 v93, v93, v101
	v_sub_f32_e32 v94, v94, v102
	v_sub_f32_e32 v95, v95, v103
	v_add_f32_e32 v64, v64, v92
	v_add_f32_e32 v65, v65, v93
	v_add_f32_e32 v66, v66, v94
	v_add_f32_e32 v67, v67, v95
	v_mul_f32_e32 v92, 0xbfb8aa3b, v64
	v_mul_f32_e32 v93, 0xbfb8aa3b, v65
	v_mul_f32_e32 v94, 0xbfb8aa3b, v66
	v_mul_f32_e32 v95, 0xbfb8aa3b, v67
	v_mul_f32_e32 v100, 0x3fb8aa3b, v64
	v_mul_f32_e32 v101, 0x3fb8aa3b, v65
	v_mul_f32_e32 v102, 0x3fb8aa3b, v66
	v_mul_f32_e32 v103, 0x3fb8aa3b, v67
	v_exp_f32_e32 v92, v92
	v_exp_f32_e32 v93, v93
	v_exp_f32_e32 v94, v94
	v_exp_f32_e32 v95, v95
	v_exp_f32_e32 v100, v100
	v_exp_f32_e32 v101, v101
	v_exp_f32_e32 v102, v102
	v_exp_f32_e32 v103, v103
	v_sub_f32_e32 v96, 1.0, v96
	v_sub_f32_e32 v97, 1.0, v97
	v_sub_f32_e32 v98, 1.0, v98
	v_sub_f32_e32 v99, 1.0, v99
	v_mul_f32_e32 v96, v96, v92
	v_mul_f32_e32 v97, v97, v93
	v_mul_f32_e32 v98, v98, v94
	v_mul_f32_e32 v99, v99, v95
	v_lshlrev_b32_e32 v92, 16, v46
	v_and_b32_e32 v93, 0xffff0000, v46
	v_lshlrev_b32_e32 v94, 16, v47
	v_and_b32_e32 v95, 0xffff0000, v47
	v_mul_f32_e32 v92, v92, v100
	v_mul_f32_e32 v93, v93, v101
	v_mul_f32_e32 v94, v94, v102
	v_mul_f32_e32 v95, v95, v103
	v_cvt_pk_bf16_f32 v108, v92, v93
	v_cvt_pk_bf16_f32 v109, v94, v95
	v_cvt_pk_bf16_f32 v110, v96, v97
	v_cvt_pk_bf16_f32 v111, v98, v99
	global_store_dwordx2 v112, v[108:109], s[2:3]
	global_store_dwordx2 v114, v[110:111], s[2:3]
	s_sub_u32 s2, s2, 0x400
	s_subb_u32 s3, s3, 0
	v_cvt_pk_bf16_f32 v126, v96, v104
	v_cvt_pk_bf16_f32 v142, v97, v105
	v_cvt_pk_bf16_f32 v176, v98, v106
	v_cvt_pk_bf16_f32 v192, v99, v107
	v_lshlrev_b32_e32 v92, 16, v48
	v_and_b32_e32 v93, 0xffff0000, v48
	v_lshlrev_b32_e32 v94, 16, v49
	v_and_b32_e32 v95, 0xffff0000, v49
	v_mul_f32_e32 v92, 0xbfb8aa3b, v92
	v_mul_f32_e32 v93, 0xbfb8aa3b, v93
	v_mul_f32_e32 v94, 0xbfb8aa3b, v94
	v_mul_f32_e32 v95, 0xbfb8aa3b, v95
	v_exp_f32_e32 v92, v92
	v_exp_f32_e32 v93, v93
	v_exp_f32_e32 v94, v94
	v_exp_f32_e32 v95, v95
	v_add_f32_e32 v92, 1.0, v92
	v_add_f32_e32 v93, 1.0, v93
	v_add_f32_e32 v94, 1.0, v94
	v_add_f32_e32 v95, 1.0, v95
	v_rcp_f32_e32 v92, v92
	v_rcp_f32_e32 v93, v93
	v_rcp_f32_e32 v94, v94
	v_rcp_f32_e32 v95, v95
	v_fma_f32 v96, v72, v92, v68
	v_fma_f32 v97, v73, v93, v69
	v_fma_f32 v98, v74, v94, v70
	v_fma_f32 v99, v75, v95, v71
	v_cmp_gt_f32_e64 s[22:23], s30, v96
	v_cmp_gt_f32_e64 s[24:25], s30, v97
	v_cmp_gt_f32_e64 s[26:27], s30, v98
	v_cmp_gt_f32_e64 s[28:29], s30, v99
	v_cndmask_b32_e64 v92, 0, 32, s[22:23]
	v_cndmask_b32_e64 v93, 0, 32, s[24:25]
	v_cndmask_b32_e64 v94, 0, 32, s[26:27]
	v_cndmask_b32_e64 v95, 0, 32, s[28:29]
	v_ldexp_f32 v92, v96, v92
	v_ldexp_f32 v93, v97, v93
	v_ldexp_f32 v94, v98, v94
	v_ldexp_f32 v95, v99, v95
	v_log_f32_e32 v92, v92
	v_log_f32_e32 v93, v93
	v_log_f32_e32 v94, v94
	v_log_f32_e32 v95, v95
	v_mul_f32_e32 v100, 0x3f317217, v92
	v_mul_f32_e32 v101, 0x3f317217, v93
	v_mul_f32_e32 v102, 0x3f317217, v94
	v_mul_f32_e32 v103, 0x3f317217, v95
	v_fma_f32 v100, v92, s31, -v100
	v_fma_f32 v101, v93, s31, -v101
	v_fma_f32 v102, v94, s31, -v102
	v_fma_f32 v103, v95, s31, -v103
	v_fmac_f32_e32 v100, 0x3377d1cf, v92
	v_fmac_f32_e32 v101, 0x3377d1cf, v93
	v_fmac_f32_e32 v102, 0x3377d1cf, v94
	v_fmac_f32_e32 v103, 0x3377d1cf, v95
	v_fmac_f32_e32 v100, 0x3f317217, v92
	v_fmac_f32_e32 v101, 0x3f317217, v93
	v_fmac_f32_e32 v102, 0x3f317217, v94
	v_fmac_f32_e32 v103, 0x3f317217, v95
	v_cmp_lt_f32_e64 vcc, |v92|, s34
	v_cndmask_b32_e32 v92, v92, v100, vcc
	v_cmp_lt_f32_e64 vcc, |v93|, s34
	v_cndmask_b32_e32 v93, v93, v101, vcc
	v_cmp_lt_f32_e64 vcc, |v94|, s34
	v_cndmask_b32_e32 v94, v94, v102, vcc
	v_cmp_lt_f32_e64 vcc, |v95|, s34
	v_cndmask_b32_e32 v95, v95, v103, vcc
	v_cndmask_b32_e64 v100, 0, v213, s[22:23]
	v_cndmask_b32_e64 v101, 0, v213, s[24:25]
	v_cndmask_b32_e64 v102, 0, v213, s[26:27]
	v_cndmask_b32_e64 v103, 0, v213, s[28:29]
	v_sub_f32_e32 v92, v92, v100
	v_sub_f32_e32 v93, v93, v101
	v_sub_f32_e32 v94, v94, v102
	v_sub_f32_e32 v95, v95, v103
	v_add_f32_e32 v64, v64, v92
	v_add_f32_e32 v65, v65, v93
	v_add_f32_e32 v66, v66, v94
	v_add_f32_e32 v67, v67, v95
	v_mul_f32_e32 v92, 0xbfb8aa3b, v64
	v_mul_f32_e32 v93, 0xbfb8aa3b, v65
	v_mul_f32_e32 v94, 0xbfb8aa3b, v66
	v_mul_f32_e32 v95, 0xbfb8aa3b, v67
	v_mul_f32_e32 v100, 0x3fb8aa3b, v64
	v_mul_f32_e32 v101, 0x3fb8aa3b, v65
	v_mul_f32_e32 v102, 0x3fb8aa3b, v66
	v_mul_f32_e32 v103, 0x3fb8aa3b, v67
	v_exp_f32_e32 v92, v92
	v_exp_f32_e32 v93, v93
	v_exp_f32_e32 v94, v94
	v_exp_f32_e32 v95, v95
	v_exp_f32_e32 v100, v100
	v_exp_f32_e32 v101, v101
	v_exp_f32_e32 v102, v102
	v_exp_f32_e32 v103, v103
	v_sub_f32_e32 v96, 1.0, v96
	v_sub_f32_e32 v97, 1.0, v97
	v_sub_f32_e32 v98, 1.0, v98
; DEV u16 f2bf(float f) { return (u16)(pack2(f, f) & 0xffffu); }
; DEV float bf2f(u16 h) { return __uint_as_float(((unsigned)h) << 16); }
; DEV float sigmoid_f(float x) { return __builtin_amdgcn_rcpf(1.f + __expf(-x)); }
; DEV void phase_p15(const Params& p, int g) {
;     ...
;     for (int j8 = 0; j8 < 8; ++j8) {
;       const int st = j8 % 3;
;       if (j8 < 6) { P15_LOAD((j8 + 2) % 3, j8 + 2); }
; #pragma unroll
;       for (int cc = 0; cc < 2; ++cc) {
;         const int c = tid + 256 * cc;
;         unsigned kb[8];
; #pragma unroll
;         for (int e = 0; e < 8; ++e) {
;           const int jj = j8 * 8 + e;
;           const int j = dir ? 63 - jj : jj;
;           const size_t tok = (size_t)cidx * 64 + j;
;           const float f = lb[cc] + (1.f - lb[cc]) * sigmoid_f(bf2f(xr[st][cc][e]));
;           G[cc] += __logf(f);
;           const float eg = __expf(G[cc]), ig = __expf(-G[cc]);
;           Qp[tok * 512 + c] = f2bf(bf2f(qr[st][cc][e]) * eg);
;           const u16 kk = f2bf((1.f - f) * ig);
;           Kp[tok * 512 + c] = kk;
;           kb[e] = kk;
;         }
;         const int s0 = dir ? 56 - 8 * j8 : 8 * j8;
;         uint4 w;
;         w.x = dir ? (kb[7] | (kb[6] << 16)) : (kb[0] | (kb[1] << 16));
;         w.y = dir ? (kb[5] | (kb[4] << 16)) : (kb[2] | (kb[3] << 16));
;         w.z = dir ? (kb[3] | (kb[2] << 16)) : (kb[4] | (kb[5] << 16));
;         w.w = dir ? (kb[1] | (kb[0] << 16)) : (kb[6] | (kb[7] << 16));
;         *(uint4*)(KT + (((size_t)cidx * 2 + dir) * 512 + c) * 64 + s0) = w;
;       }
	v_sub_f32_e32 v99, 1.0, v99
	v_mul_f32_e32 v96, v96, v92
	v_mul_f32_e32 v97, v97, v93
	v_mul_f32_e32 v98, v98, v94
	v_mul_f32_e32 v99, v99, v95
	v_lshlrev_b32_e32 v92, 16, v50
	v_and_b32_e32 v93, 0xffff0000, v50
	v_lshlrev_b32_e32 v94, 16, v51
	v_and_b32_e32 v95, 0xffff0000, v51
	v_mul_f32_e32 v92, v92, v100
	v_mul_f32_e32 v93, v93, v101
	v_mul_f32_e32 v94, v94, v102
	v_mul_f32_e32 v95, v95, v103
	v_cvt_pk_bf16_f32 v108, v92, v93
	v_cvt_pk_bf16_f32 v109, v94, v95
	v_cvt_pk_bf16_f32 v110, v96, v97
	v_cvt_pk_bf16_f32 v111, v98, v99
	global_store_dwordx2 v112, v[108:109], s[2:3]
	global_store_dwordx2 v114, v[110:111], s[2:3]
	s_sub_u32 s2, s2, 0x400
	s_subb_u32 s3, s3, 0
	v_mov_b32_e32 v104, v96
	v_mov_b32_e32 v105, v97
	v_mov_b32_e32 v106, v98
	v_mov_b32_e32 v107, v99
	v_lshlrev_b32_e32 v92, 16, v52
	v_and_b32_e32 v93, 0xffff0000, v52
	v_lshlrev_b32_e32 v94, 16, v53
	v_and_b32_e32 v95, 0xffff0000, v53
	v_mul_f32_e32 v92, 0xbfb8aa3b, v92
	v_mul_f32_e32 v93, 0xbfb8aa3b, v93
	v_mul_f32_e32 v94, 0xbfb8aa3b, v94
	v_mul_f32_e32 v95, 0xbfb8aa3b, v95
	v_exp_f32_e32 v92, v92
	v_exp_f32_e32 v93, v93
	v_exp_f32_e32 v94, v94
	v_exp_f32_e32 v95, v95
	v_add_f32_e32 v92, 1.0, v92
	v_add_f32_e32 v93, 1.0, v93
	v_add_f32_e32 v94, 1.0, v94
	v_add_f32_e32 v95, 1.0, v95
	v_rcp_f32_e32 v92, v92
	v_rcp_f32_e32 v93, v93
	v_rcp_f32_e32 v94, v94
	v_rcp_f32_e32 v95, v95
	v_fma_f32 v96, v72, v92, v68
	v_fma_f32 v97, v73, v93, v69
	v_fma_f32 v98, v74, v94, v70
	v_fma_f32 v99, v75, v95, v71
	v_cmp_gt_f32_e64 s[22:23], s30, v96
	v_cmp_gt_f32_e64 s[24:25], s30, v97
	v_cmp_gt_f32_e64 s[26:27], s30, v98
	v_cmp_gt_f32_e64 s[28:29], s30, v99
	v_cndmask_b32_e64 v92, 0, 32, s[22:23]
	v_cndmask_b32_e64 v93, 0, 32, s[24:25]
	v_cndmask_b32_e64 v94, 0, 32, s[26:27]
	v_cndmask_b32_e64 v95, 0, 32, s[28:29]
	v_ldexp_f32 v92, v96, v92
	v_ldexp_f32 v93, v97, v93
	v_ldexp_f32 v94, v98, v94
	v_ldexp_f32 v95, v99, v95
	v_log_f32_e32 v92, v92
	v_log_f32_e32 v93, v93
	v_log_f32_e32 v94, v94
	v_log_f32_e32 v95, v95
	v_mul_f32_e32 v100, 0x3f317217, v92
	v_mul_f32_e32 v101, 0x3f317217, v93
	v_mul_f32_e32 v102, 0x3f317217, v94
	v_mul_f32_e32 v103, 0x3f317217, v95
	v_fma_f32 v100, v92, s31, -v100
	v_fma_f32 v101, v93, s31, -v101
	v_fma_f32 v102, v94, s31, -v102
	v_fma_f32 v103, v95, s31, -v103
	v_fmac_f32_e32 v100, 0x3377d1cf, v92
	v_fmac_f32_e32 v101, 0x3377d1cf, v93
	v_fmac_f32_e32 v102, 0x3377d1cf, v94
	v_fmac_f32_e32 v103, 0x3377d1cf, v95
	v_fmac_f32_e32 v100, 0x3f317217, v92
	v_fmac_f32_e32 v101, 0x3f317217, v93
	v_fmac_f32_e32 v102, 0x3f317217, v94
	v_fmac_f32_e32 v103, 0x3f317217, v95
	v_cmp_lt_f32_e64 vcc, |v92|, s34
	v_cndmask_b32_e32 v92, v92, v100, vcc
	v_cmp_lt_f32_e64 vcc, |v93|, s34
	v_cndmask_b32_e32 v93, v93, v101, vcc
	v_cmp_lt_f32_e64 vcc, |v94|, s34
	v_cndmask_b32_e32 v94, v94, v102, vcc
	v_cmp_lt_f32_e64 vcc, |v95|, s34
	v_cndmask_b32_e32 v95, v95, v103, vcc
	v_cndmask_b32_e64 v100, 0, v213, s[22:23]
	v_cndmask_b32_e64 v101, 0, v213, s[24:25]
	v_cndmask_b32_e64 v102, 0, v213, s[26:27]
	v_cndmask_b32_e64 v103, 0, v213, s[28:29]
	v_sub_f32_e32 v92, v92, v100
	v_sub_f32_e32 v93, v93, v101
	v_sub_f32_e32 v94, v94, v102
	v_sub_f32_e32 v95, v95, v103
	v_add_f32_e32 v64, v64, v92
	v_add_f32_e32 v65, v65, v93
	v_add_f32_e32 v66, v66, v94
	v_add_f32_e32 v67, v67, v95
	v_mul_f32_e32 v92, 0xbfb8aa3b, v64
	v_mul_f32_e32 v93, 0xbfb8aa3b, v65
	v_mul_f32_e32 v94, 0xbfb8aa3b, v66
	v_mul_f32_e32 v95, 0xbfb8aa3b, v67
	v_mul_f32_e32 v100, 0x3fb8aa3b, v64
	v_mul_f32_e32 v101, 0x3fb8aa3b, v65
	v_mul_f32_e32 v102, 0x3fb8aa3b, v66
	v_mul_f32_e32 v103, 0x3fb8aa3b, v67
	v_exp_f32_e32 v92, v92
	v_exp_f32_e32 v93, v93
	v_exp_f32_e32 v94, v94
	v_exp_f32_e32 v95, v95
	v_exp_f32_e32 v100, v100
	v_exp_f32_e32 v101, v101
	v_exp_f32_e32 v102, v102
	v_exp_f32_e32 v103, v103
	v_sub_f32_e32 v96, 1.0, v96
	v_sub_f32_e32 v97, 1.0, v97
	v_sub_f32_e32 v98, 1.0, v98
	v_sub_f32_e32 v99, 1.0, v99
	v_mul_f32_e32 v96, v96, v92
	v_mul_f32_e32 v97, v97, v93
	v_mul_f32_e32 v98, v98, v94
	v_mul_f32_e32 v99, v99, v95
	v_lshlrev_b32_e32 v92, 16, v54
	v_and_b32_e32 v93, 0xffff0000, v54
	v_lshlrev_b32_e32 v94, 16, v55
	v_and_b32_e32 v95, 0xffff0000, v55
	v_mul_f32_e32 v92, v92, v100
	v_mul_f32_e32 v93, v93, v101
	v_mul_f32_e32 v94, v94, v102
	v_mul_f32_e32 v95, v95, v103
	v_cvt_pk_bf16_f32 v108, v92, v93
	v_cvt_pk_bf16_f32 v109, v94, v95
	v_cvt_pk_bf16_f32 v110, v96, v97
	v_cvt_pk_bf16_f32 v111, v98, v99
	global_store_dwordx2 v112, v[108:109], s[2:3]
	global_store_dwordx2 v114, v[110:111], s[2:3]
	s_sub_u32 s2, s2, 0x400
	s_subb_u32 s3, s3, 0
	v_cvt_pk_bf16_f32 v125, v96, v104
	v_cvt_pk_bf16_f32 v141, v97, v105
	v_cvt_pk_bf16_f32 v175, v98, v106
	v_cvt_pk_bf16_f32 v191, v99, v107
	v_lshlrev_b32_e32 v92, 16, v56
	v_and_b32_e32 v93, 0xffff0000, v56
	v_lshlrev_b32_e32 v94, 16, v57
	v_and_b32_e32 v95, 0xffff0000, v57
	v_mul_f32_e32 v92, 0xbfb8aa3b, v92
	v_mul_f32_e32 v93, 0xbfb8aa3b, v93
	v_mul_f32_e32 v94, 0xbfb8aa3b, v94
	v_mul_f32_e32 v95, 0xbfb8aa3b, v95
	v_exp_f32_e32 v92, v92
	v_exp_f32_e32 v93, v93
	v_exp_f32_e32 v94, v94
	v_exp_f32_e32 v95, v95
	v_add_f32_e32 v92, 1.0, v92
	v_add_f32_e32 v93, 1.0, v93
	v_add_f32_e32 v94, 1.0, v94
	v_add_f32_e32 v95, 1.0, v95
	v_rcp_f32_e32 v92, v92
	v_rcp_f32_e32 v93, v93
	v_rcp_f32_e32 v94, v94
	v_rcp_f32_e32 v95, v95
	v_fma_f32 v96, v72, v92, v68
	v_fma_f32 v97, v73, v93, v69
	v_fma_f32 v98, v74, v94, v70
	v_fma_f32 v99, v75, v95, v71
	v_cmp_gt_f32_e64 s[22:23], s30, v96
	v_cmp_gt_f32_e64 s[24:25], s30, v97
	v_cmp_gt_f32_e64 s[26:27], s30, v98
	v_cmp_gt_f32_e64 s[28:29], s30, v99
	v_cndmask_b32_e64 v92, 0, 32, s[22:23]
	v_cndmask_b32_e64 v93, 0, 32, s[24:25]
	v_cndmask_b32_e64 v94, 0, 32, s[26:27]
; DEV u16 f2bf(float f) { return (u16)(pack2(f, f) & 0xffffu); }
; DEV float bf2f(u16 h) { return __uint_as_float(((unsigned)h) << 16); }
; DEV float sigmoid_f(float x) { return __builtin_amdgcn_rcpf(1.f + __expf(-x)); }
; DEV void phase_p15(const Params& p, int g) {
;     ...
;     for (int j8 = 0; j8 < 8; ++j8) {
;       const int st = j8 % 3;
;       if (j8 < 6) { P15_LOAD((j8 + 2) % 3, j8 + 2); }
; #pragma unroll
;       for (int cc = 0; cc < 2; ++cc) {
;         const int c = tid + 256 * cc;
;         unsigned kb[8];
; #pragma unroll
;         for (int e = 0; e < 8; ++e) {
;           const int jj = j8 * 8 + e;
;           const int j = dir ? 63 - jj : jj;
;           const size_t tok = (size_t)cidx * 64 + j;
;           const float f = lb[cc] + (1.f - lb[cc]) * sigmoid_f(bf2f(xr[st][cc][e]));
;           G[cc] += __logf(f);
;           const float eg = __expf(G[cc]), ig = __expf(-G[cc]);
;           Qp[tok * 512 + c] = f2bf(bf2f(qr[st][cc][e]) * eg);
;           const u16 kk = f2bf((1.f - f) * ig);
;           Kp[tok * 512 + c] = kk;
;           kb[e] = kk;
;         }
;         const int s0 = dir ? 56 - 8 * j8 : 8 * j8;
;         uint4 w;
;         w.x = dir ? (kb[7] | (kb[6] << 16)) : (kb[0] | (kb[1] << 16));
;         w.y = dir ? (kb[5] | (kb[4] << 16)) : (kb[2] | (kb[3] << 16));
;         w.z = dir ? (kb[3] | (kb[2] << 16)) : (kb[4] | (kb[5] << 16));
;         w.w = dir ? (kb[1] | (kb[0] << 16)) : (kb[6] | (kb[7] << 16));
;         *(uint4*)(KT + (((size_t)cidx * 2 + dir) * 512 + c) * 64 + s0) = w;
;       }
	v_cndmask_b32_e64 v95, 0, 32, s[28:29]
	v_ldexp_f32 v92, v96, v92
	v_ldexp_f32 v93, v97, v93
	v_ldexp_f32 v94, v98, v94
	v_ldexp_f32 v95, v99, v95
	v_log_f32_e32 v92, v92
	v_log_f32_e32 v93, v93
	v_log_f32_e32 v94, v94
	v_log_f32_e32 v95, v95
	v_mul_f32_e32 v100, 0x3f317217, v92
	v_mul_f32_e32 v101, 0x3f317217, v93
	v_mul_f32_e32 v102, 0x3f317217, v94
	v_mul_f32_e32 v103, 0x3f317217, v95
	v_fma_f32 v100, v92, s31, -v100
	v_fma_f32 v101, v93, s31, -v101
	v_fma_f32 v102, v94, s31, -v102
	v_fma_f32 v103, v95, s31, -v103
	v_fmac_f32_e32 v100, 0x3377d1cf, v92
	v_fmac_f32_e32 v101, 0x3377d1cf, v93
	v_fmac_f32_e32 v102, 0x3377d1cf, v94
	v_fmac_f32_e32 v103, 0x3377d1cf, v95
	v_fmac_f32_e32 v100, 0x3f317217, v92
	v_fmac_f32_e32 v101, 0x3f317217, v93
	v_fmac_f32_e32 v102, 0x3f317217, v94
	v_fmac_f32_e32 v103, 0x3f317217, v95
	v_cmp_lt_f32_e64 vcc, |v92|, s34
	v_cndmask_b32_e32 v92, v92, v100, vcc
	v_cmp_lt_f32_e64 vcc, |v93|, s34
	v_cndmask_b32_e32 v93, v93, v101, vcc
	v_cmp_lt_f32_e64 vcc, |v94|, s34
	v_cndmask_b32_e32 v94, v94, v102, vcc
	v_cmp_lt_f32_e64 vcc, |v95|, s34
	v_cndmask_b32_e32 v95, v95, v103, vcc
	v_cndmask_b32_e64 v100, 0, v213, s[22:23]
	v_cndmask_b32_e64 v101, 0, v213, s[24:25]
	v_cndmask_b32_e64 v102, 0, v213, s[26:27]
	v_cndmask_b32_e64 v103, 0, v213, s[28:29]
	v_sub_f32_e32 v92, v92, v100
	v_sub_f32_e32 v93, v93, v101
	v_sub_f32_e32 v94, v94, v102
	v_sub_f32_e32 v95, v95, v103
	v_add_f32_e32 v64, v64, v92
	v_add_f32_e32 v65, v65, v93
	v_add_f32_e32 v66, v66, v94
	v_add_f32_e32 v67, v67, v95
	v_mul_f32_e32 v92, 0xbfb8aa3b, v64
	v_mul_f32_e32 v93, 0xbfb8aa3b, v65
	v_mul_f32_e32 v94, 0xbfb8aa3b, v66
	v_mul_f32_e32 v95, 0xbfb8aa3b, v67
	v_mul_f32_e32 v100, 0x3fb8aa3b, v64
	v_mul_f32_e32 v101, 0x3fb8aa3b, v65
	v_mul_f32_e32 v102, 0x3fb8aa3b, v66
	v_mul_f32_e32 v103, 0x3fb8aa3b, v67
	v_exp_f32_e32 v92, v92
	v_exp_f32_e32 v93, v93
	v_exp_f32_e32 v94, v94
	v_exp_f32_e32 v95, v95
	v_exp_f32_e32 v100, v100
	v_exp_f32_e32 v101, v101
	v_exp_f32_e32 v102, v102
	v_exp_f32_e32 v103, v103
	v_sub_f32_e32 v96, 1.0, v96
	v_sub_f32_e32 v97, 1.0, v97
	v_sub_f32_e32 v98, 1.0, v98
	v_sub_f32_e32 v99, 1.0, v99
	v_mul_f32_e32 v96, v96, v92
	v_mul_f32_e32 v97, v97, v93
	v_mul_f32_e32 v98, v98, v94
	v_mul_f32_e32 v99, v99, v95
	v_lshlrev_b32_e32 v92, 16, v58
	v_and_b32_e32 v93, 0xffff0000, v58
	v_lshlrev_b32_e32 v94, 16, v59
	v_and_b32_e32 v95, 0xffff0000, v59
	v_mul_f32_e32 v92, v92, v100
	v_mul_f32_e32 v93, v93, v101
	v_mul_f32_e32 v94, v94, v102
	v_mul_f32_e32 v95, v95, v103
	v_cvt_pk_bf16_f32 v108, v92, v93
	v_cvt_pk_bf16_f32 v109, v94, v95
	v_cvt_pk_bf16_f32 v110, v96, v97
	v_cvt_pk_bf16_f32 v111, v98, v99
	global_store_dwordx2 v112, v[108:109], s[2:3]
	global_store_dwordx2 v114, v[110:111], s[2:3]
	s_sub_u32 s2, s2, 0x400
	s_subb_u32 s3, s3, 0
	v_mov_b32_e32 v104, v96
	v_mov_b32_e32 v105, v97
	v_mov_b32_e32 v106, v98
	v_mov_b32_e32 v107, v99
	v_lshlrev_b32_e32 v92, 16, v60
	v_and_b32_e32 v93, 0xffff0000, v60
	v_lshlrev_b32_e32 v94, 16, v61
	v_and_b32_e32 v95, 0xffff0000, v61
	v_mul_f32_e32 v92, 0xbfb8aa3b, v92
	v_mul_f32_e32 v93, 0xbfb8aa3b, v93
	v_mul_f32_e32 v94, 0xbfb8aa3b, v94
	v_mul_f32_e32 v95, 0xbfb8aa3b, v95
	v_exp_f32_e32 v92, v92
	v_exp_f32_e32 v93, v93
	v_exp_f32_e32 v94, v94
	v_exp_f32_e32 v95, v95
	v_add_f32_e32 v92, 1.0, v92
	v_add_f32_e32 v93, 1.0, v93
	v_add_f32_e32 v94, 1.0, v94
	v_add_f32_e32 v95, 1.0, v95
	v_rcp_f32_e32 v92, v92
	v_rcp_f32_e32 v93, v93
	v_rcp_f32_e32 v94, v94
	v_rcp_f32_e32 v95, v95
	v_fma_f32 v96, v72, v92, v68
	v_fma_f32 v97, v73, v93, v69
	v_fma_f32 v98, v74, v94, v70
	v_fma_f32 v99, v75, v95, v71
	v_cmp_gt_f32_e64 s[22:23], s30, v96
	v_cmp_gt_f32_e64 s[24:25], s30, v97
	v_cmp_gt_f32_e64 s[26:27], s30, v98
	v_cmp_gt_f32_e64 s[28:29], s30, v99
	v_cndmask_b32_e64 v92, 0, 32, s[22:23]
	v_cndmask_b32_e64 v93, 0, 32, s[24:25]
	v_cndmask_b32_e64 v94, 0, 32, s[26:27]
	v_cndmask_b32_e64 v95, 0, 32, s[28:29]
	v_ldexp_f32 v92, v96, v92
	v_ldexp_f32 v93, v97, v93
	v_ldexp_f32 v94, v98, v94
	v_ldexp_f32 v95, v99, v95
	v_log_f32_e32 v92, v92
	v_log_f32_e32 v93, v93
	v_log_f32_e32 v94, v94
	v_log_f32_e32 v95, v95
	v_mul_f32_e32 v100, 0x3f317217, v92
	v_mul_f32_e32 v101, 0x3f317217, v93
	v_mul_f32_e32 v102, 0x3f317217, v94
	v_mul_f32_e32 v103, 0x3f317217, v95
	v_fma_f32 v100, v92, s31, -v100
	v_fma_f32 v101, v93, s31, -v101
	v_fma_f32 v102, v94, s31, -v102
	v_fma_f32 v103, v95, s31, -v103
	v_fmac_f32_e32 v100, 0x3377d1cf, v92
	v_fmac_f32_e32 v101, 0x3377d1cf, v93
	v_fmac_f32_e32 v102, 0x3377d1cf, v94
	v_fmac_f32_e32 v103, 0x3377d1cf, v95
	v_fmac_f32_e32 v100, 0x3f317217, v92
	v_fmac_f32_e32 v101, 0x3f317217, v93
	v_fmac_f32_e32 v102, 0x3f317217, v94
	v_fmac_f32_e32 v103, 0x3f317217, v95
	v_cmp_lt_f32_e64 vcc, |v92|, s34
	v_cndmask_b32_e32 v92, v92, v100, vcc
	v_cmp_lt_f32_e64 vcc, |v93|, s34
	v_cndmask_b32_e32 v93, v93, v101, vcc
	v_cmp_lt_f32_e64 vcc, |v94|, s34
	v_cndmask_b32_e32 v94, v94, v102, vcc
	v_cmp_lt_f32_e64 vcc, |v95|, s34
	v_cndmask_b32_e32 v95, v95, v103, vcc
	v_cndmask_b32_e64 v100, 0, v213, s[22:23]
	v_cndmask_b32_e64 v101, 0, v213, s[24:25]
	v_cndmask_b32_e64 v102, 0, v213, s[26:27]
	v_cndmask_b32_e64 v103, 0, v213, s[28:29]
	v_sub_f32_e32 v92, v92, v100
	v_sub_f32_e32 v93, v93, v101
	v_sub_f32_e32 v94, v94, v102
	v_sub_f32_e32 v95, v95, v103
	v_add_f32_e32 v64, v64, v92
	v_add_f32_e32 v65, v65, v93
	v_add_f32_e32 v66, v66, v94
	v_add_f32_e32 v67, v67, v95
	v_mul_f32_e32 v92, 0xbfb8aa3b, v64
	v_mul_f32_e32 v93, 0xbfb8aa3b, v65
	v_mul_f32_e32 v94, 0xbfb8aa3b, v66
	v_mul_f32_e32 v95, 0xbfb8aa3b, v67
	v_mul_f32_e32 v100, 0x3fb8aa3b, v64
	v_mul_f32_e32 v101, 0x3fb8aa3b, v65
	v_mul_f32_e32 v102, 0x3fb8aa3b, v66
; DEV u16 f2bf(float f) { return (u16)(pack2(f, f) & 0xffffu); }
; DEV float bf2f(u16 h) { return __uint_as_float(((unsigned)h) << 16); }
; DEV float sigmoid_f(float x) { return __builtin_amdgcn_rcpf(1.f + __expf(-x)); }
; DEV void phase_p15(const Params& p, int g) {
;     ...
;     P15_LOAD(0, 0);
;     P15_LOAD(1, 1);
; #pragma unroll
;     for (int j8 = 0; j8 < 8; ++j8) {
;       const int st = j8 % 3;
;       if (j8 < 6) { P15_LOAD((j8 + 2) % 3, j8 + 2); }
; #pragma unroll
;       for (int cc = 0; cc < 2; ++cc) {
;         const int c = tid + 256 * cc;
;         unsigned kb[8];
; #pragma unroll
;         for (int e = 0; e < 8; ++e) {
;           const int jj = j8 * 8 + e;
;           const int j = dir ? 63 - jj : jj;
;           const size_t tok = (size_t)cidx * 64 + j;
;           const float f = lb[cc] + (1.f - lb[cc]) * sigmoid_f(bf2f(xr[st][cc][e]));
;           G[cc] += __logf(f);
;           const float eg = __expf(G[cc]), ig = __expf(-G[cc]);
;           Qp[tok * 512 + c] = f2bf(bf2f(qr[st][cc][e]) * eg);
;           const u16 kk = f2bf((1.f - f) * ig);
;           Kp[tok * 512 + c] = kk;
;           kb[e] = kk;
;         }
;         const int s0 = dir ? 56 - 8 * j8 : 8 * j8;
;         uint4 w;
;         w.x = dir ? (kb[7] | (kb[6] << 16)) : (kb[0] | (kb[1] << 16));
;         w.y = dir ? (kb[5] | (kb[4] << 16)) : (kb[2] | (kb[3] << 16));
;         w.z = dir ? (kb[3] | (kb[2] << 16)) : (kb[4] | (kb[5] << 16));
;         w.w = dir ? (kb[1] | (kb[0] << 16)) : (kb[6] | (kb[7] << 16));
;         *(uint4*)(KT + (((size_t)cidx * 2 + dir) * 512 + c) * 64 + s0) = w;
;       }
	v_mul_f32_e32 v103, 0x3fb8aa3b, v67
	v_exp_f32_e32 v92, v92
	v_exp_f32_e32 v93, v93
	v_exp_f32_e32 v94, v94
	v_exp_f32_e32 v95, v95
	v_exp_f32_e32 v100, v100
	v_exp_f32_e32 v101, v101
	v_exp_f32_e32 v102, v102
	v_exp_f32_e32 v103, v103
	v_sub_f32_e32 v96, 1.0, v96
	v_sub_f32_e32 v97, 1.0, v97
	v_sub_f32_e32 v98, 1.0, v98
	v_sub_f32_e32 v99, 1.0, v99
	v_mul_f32_e32 v96, v96, v92
	v_mul_f32_e32 v97, v97, v93
	v_mul_f32_e32 v98, v98, v94
	v_mul_f32_e32 v99, v99, v95
	v_lshlrev_b32_e32 v92, 16, v62
	v_and_b32_e32 v93, 0xffff0000, v62
	v_lshlrev_b32_e32 v94, 16, v63
	v_and_b32_e32 v95, 0xffff0000, v63
	v_mul_f32_e32 v92, v92, v100
	v_mul_f32_e32 v93, v93, v101
	v_mul_f32_e32 v94, v94, v102
	v_mul_f32_e32 v95, v95, v103
	v_cvt_pk_bf16_f32 v108, v92, v93
	v_cvt_pk_bf16_f32 v109, v94, v95
	v_cvt_pk_bf16_f32 v110, v96, v97
	v_cvt_pk_bf16_f32 v111, v98, v99
	global_store_dwordx2 v112, v[108:109], s[2:3]
	global_store_dwordx2 v114, v[110:111], s[2:3]
	s_sub_u32 s2, s2, 0x400
	s_subb_u32 s3, s3, 0
	v_cvt_pk_bf16_f32 v124, v96, v104
	v_cvt_pk_bf16_f32 v140, v97, v105
	v_cvt_pk_bf16_f32 v174, v98, v106
	v_cvt_pk_bf16_f32 v190, v99, v107
	global_load_dwordx2 v[32:33], v113, s[0:1]
	global_load_dwordx2 v[34:35], v112, s[0:1]
	s_sub_u32 s0, s0, 0x1400
	s_subb_u32 s1, s1, 0
	global_load_dwordx2 v[36:37], v113, s[0:1]
	global_load_dwordx2 v[38:39], v112, s[0:1]
	s_sub_u32 s0, s0, 0x1400
	s_subb_u32 s1, s1, 0
	global_load_dwordx2 v[40:41], v113, s[0:1]
	global_load_dwordx2 v[42:43], v112, s[0:1]
	s_sub_u32 s0, s0, 0x1400
	s_subb_u32 s1, s1, 0
	global_load_dwordx2 v[44:45], v113, s[0:1]
	global_load_dwordx2 v[46:47], v112, s[0:1]
	s_sub_u32 s0, s0, 0x1400
	s_subb_u32 s1, s1, 0
	global_load_dwordx2 v[48:49], v113, s[0:1]
	global_load_dwordx2 v[50:51], v112, s[0:1]
	s_sub_u32 s0, s0, 0x1400
	s_subb_u32 s1, s1, 0
	global_load_dwordx2 v[52:53], v113, s[0:1]
	global_load_dwordx2 v[54:55], v112, s[0:1]
	s_sub_u32 s0, s0, 0x1400
	s_subb_u32 s1, s1, 0
	global_load_dwordx2 v[56:57], v113, s[0:1]
	global_load_dwordx2 v[58:59], v112, s[0:1]
	s_sub_u32 s0, s0, 0x1400
	s_subb_u32 s1, s1, 0
	global_load_dwordx2 v[60:61], v113, s[0:1]
	global_load_dwordx2 v[62:63], v112, s[0:1]
	s_sub_u32 s0, s0, 0x1400
	s_subb_u32 s1, s1, 0
	s_waitcnt vmcnt(32)
	v_lshlrev_b32_e32 v92, 16, v0
	v_and_b32_e32 v93, 0xffff0000, v0
	v_lshlrev_b32_e32 v94, 16, v1
	v_and_b32_e32 v95, 0xffff0000, v1
	v_mul_f32_e32 v92, 0xbfb8aa3b, v92
	v_mul_f32_e32 v93, 0xbfb8aa3b, v93
	v_mul_f32_e32 v94, 0xbfb8aa3b, v94
	v_mul_f32_e32 v95, 0xbfb8aa3b, v95
	v_exp_f32_e32 v92, v92
	v_exp_f32_e32 v93, v93
	v_exp_f32_e32 v94, v94
	v_exp_f32_e32 v95, v95
	v_add_f32_e32 v92, 1.0, v92
	v_add_f32_e32 v93, 1.0, v93
	v_add_f32_e32 v94, 1.0, v94
	v_add_f32_e32 v95, 1.0, v95
	v_rcp_f32_e32 v92, v92
	v_rcp_f32_e32 v93, v93
	v_rcp_f32_e32 v94, v94
	v_rcp_f32_e32 v95, v95
	v_fma_f32 v96, v72, v92, v68
	v_fma_f32 v97, v73, v93, v69
	v_fma_f32 v98, v74, v94, v70
	v_fma_f32 v99, v75, v95, v71
	v_cmp_gt_f32_e64 s[22:23], s30, v96
	v_cmp_gt_f32_e64 s[24:25], s30, v97
	v_cmp_gt_f32_e64 s[26:27], s30, v98
	v_cmp_gt_f32_e64 s[28:29], s30, v99
	v_cndmask_b32_e64 v92, 0, 32, s[22:23]
	v_cndmask_b32_e64 v93, 0, 32, s[24:25]
	v_cndmask_b32_e64 v94, 0, 32, s[26:27]
	v_cndmask_b32_e64 v95, 0, 32, s[28:29]
	v_ldexp_f32 v92, v96, v92
	v_ldexp_f32 v93, v97, v93
	v_ldexp_f32 v94, v98, v94
	v_ldexp_f32 v95, v99, v95
	v_log_f32_e32 v92, v92
	v_log_f32_e32 v93, v93
	v_log_f32_e32 v94, v94
	v_log_f32_e32 v95, v95
	v_mul_f32_e32 v100, 0x3f317217, v92
	v_mul_f32_e32 v101, 0x3f317217, v93
	v_mul_f32_e32 v102, 0x3f317217, v94
	v_mul_f32_e32 v103, 0x3f317217, v95
	v_fma_f32 v100, v92, s31, -v100
	v_fma_f32 v101, v93, s31, -v101
	v_fma_f32 v102, v94, s31, -v102
	v_fma_f32 v103, v95, s31, -v103
	v_fmac_f32_e32 v100, 0x3377d1cf, v92
	v_fmac_f32_e32 v101, 0x3377d1cf, v93
	v_fmac_f32_e32 v102, 0x3377d1cf, v94
	v_fmac_f32_e32 v103, 0x3377d1cf, v95
	v_fmac_f32_e32 v100, 0x3f317217, v92
	v_fmac_f32_e32 v101, 0x3f317217, v93
	v_fmac_f32_e32 v102, 0x3f317217, v94
	v_fmac_f32_e32 v103, 0x3f317217, v95
	v_cmp_lt_f32_e64 vcc, |v92|, s34
	v_cndmask_b32_e32 v92, v92, v100, vcc
	v_cmp_lt_f32_e64 vcc, |v93|, s34
	v_cndmask_b32_e32 v93, v93, v101, vcc
	v_cmp_lt_f32_e64 vcc, |v94|, s34
	v_cndmask_b32_e32 v94, v94, v102, vcc
	v_cmp_lt_f32_e64 vcc, |v95|, s34
	v_cndmask_b32_e32 v95, v95, v103, vcc
	v_cndmask_b32_e64 v100, 0, v213, s[22:23]
	v_cndmask_b32_e64 v101, 0, v213, s[24:25]
	v_cndmask_b32_e64 v102, 0, v213, s[26:27]
	v_cndmask_b32_e64 v103, 0, v213, s[28:29]
	v_sub_f32_e32 v92, v92, v100
	v_sub_f32_e32 v93, v93, v101
	v_sub_f32_e32 v94, v94, v102
	v_sub_f32_e32 v95, v95, v103
	v_add_f32_e32 v64, v64, v92
	v_add_f32_e32 v65, v65, v93
	v_add_f32_e32 v66, v66, v94
	v_add_f32_e32 v67, v67, v95
	v_mul_f32_e32 v92, 0xbfb8aa3b, v64
	v_mul_f32_e32 v93, 0xbfb8aa3b, v65
	v_mul_f32_e32 v94, 0xbfb8aa3b, v66
	v_mul_f32_e32 v95, 0xbfb8aa3b, v67
	v_mul_f32_e32 v100, 0x3fb8aa3b, v64
	v_mul_f32_e32 v101, 0x3fb8aa3b, v65
	v_mul_f32_e32 v102, 0x3fb8aa3b, v66
	v_mul_f32_e32 v103, 0x3fb8aa3b, v67
	v_exp_f32_e32 v92, v92
	v_exp_f32_e32 v93, v93
	v_exp_f32_e32 v94, v94
	v_exp_f32_e32 v95, v95
	v_exp_f32_e32 v100, v100
	v_exp_f32_e32 v101, v101
	v_exp_f32_e32 v102, v102
	v_exp_f32_e32 v103, v103
	v_sub_f32_e32 v96, 1.0, v96
	v_sub_f32_e32 v97, 1.0, v97
	v_sub_f32_e32 v98, 1.0, v98
	v_sub_f32_e32 v99, 1.0, v99
	v_mul_f32_e32 v96, v96, v92
	v_mul_f32_e32 v97, v97, v93
	v_mul_f32_e32 v98, v98, v94
	v_mul_f32_e32 v99, v99, v95
	v_lshlrev_b32_e32 v92, 16, v2
	v_and_b32_e32 v93, 0xffff0000, v2
	v_lshlrev_b32_e32 v94, 16, v3
	v_and_b32_e32 v95, 0xffff0000, v3
	v_mul_f32_e32 v92, v92, v100
; DEV u16 f2bf(float f) { return (u16)(pack2(f, f) & 0xffffu); }
; DEV float bf2f(u16 h) { return __uint_as_float(((unsigned)h) << 16); }
; DEV float sigmoid_f(float x) { return __builtin_amdgcn_rcpf(1.f + __expf(-x)); }
; DEV void phase_p15(const Params& p, int g) {
;     ...
;     for (int j8 = 0; j8 < 8; ++j8) {
;       const int st = j8 % 3;
;       if (j8 < 6) { P15_LOAD((j8 + 2) % 3, j8 + 2); }
; #pragma unroll
;       for (int cc = 0; cc < 2; ++cc) {
;         const int c = tid + 256 * cc;
;         unsigned kb[8];
; #pragma unroll
;         for (int e = 0; e < 8; ++e) {
;           const int jj = j8 * 8 + e;
;           const int j = dir ? 63 - jj : jj;
;           const size_t tok = (size_t)cidx * 64 + j;
;           const float f = lb[cc] + (1.f - lb[cc]) * sigmoid_f(bf2f(xr[st][cc][e]));
;           G[cc] += __logf(f);
;           const float eg = __expf(G[cc]), ig = __expf(-G[cc]);
;           Qp[tok * 512 + c] = f2bf(bf2f(qr[st][cc][e]) * eg);
;           const u16 kk = f2bf((1.f - f) * ig);
;           Kp[tok * 512 + c] = kk;
;           kb[e] = kk;
;         }
;         const int s0 = dir ? 56 - 8 * j8 : 8 * j8;
;         uint4 w;
;         w.x = dir ? (kb[7] | (kb[6] << 16)) : (kb[0] | (kb[1] << 16));
;         w.y = dir ? (kb[5] | (kb[4] << 16)) : (kb[2] | (kb[3] << 16));
;         w.z = dir ? (kb[3] | (kb[2] << 16)) : (kb[4] | (kb[5] << 16));
;         w.w = dir ? (kb[1] | (kb[0] << 16)) : (kb[6] | (kb[7] << 16));
;         *(uint4*)(KT + (((size_t)cidx * 2 + dir) * 512 + c) * 64 + s0) = w;
;       }
	v_mul_f32_e32 v93, v93, v101
	v_mul_f32_e32 v94, v94, v102
	v_mul_f32_e32 v95, v95, v103
	v_cvt_pk_bf16_f32 v108, v92, v93
	v_cvt_pk_bf16_f32 v109, v94, v95
	v_cvt_pk_bf16_f32 v110, v96, v97
	v_cvt_pk_bf16_f32 v111, v98, v99
	global_store_dwordx2 v112, v[108:109], s[2:3]
	global_store_dwordx2 v114, v[110:111], s[2:3]
	s_sub_u32 s2, s2, 0x400
	s_subb_u32 s3, s3, 0
	v_mov_b32_e32 v104, v96
	v_mov_b32_e32 v105, v97
	v_mov_b32_e32 v106, v98
	v_mov_b32_e32 v107, v99
	v_lshlrev_b32_e32 v92, 16, v4
	v_and_b32_e32 v93, 0xffff0000, v4
	v_lshlrev_b32_e32 v94, 16, v5
	v_and_b32_e32 v95, 0xffff0000, v5
	v_mul_f32_e32 v92, 0xbfb8aa3b, v92
	v_mul_f32_e32 v93, 0xbfb8aa3b, v93
	v_mul_f32_e32 v94, 0xbfb8aa3b, v94
	v_mul_f32_e32 v95, 0xbfb8aa3b, v95
	v_exp_f32_e32 v92, v92
	v_exp_f32_e32 v93, v93
	v_exp_f32_e32 v94, v94
	v_exp_f32_e32 v95, v95
	v_add_f32_e32 v92, 1.0, v92
	v_add_f32_e32 v93, 1.0, v93
	v_add_f32_e32 v94, 1.0, v94
	v_add_f32_e32 v95, 1.0, v95
	v_rcp_f32_e32 v92, v92
	v_rcp_f32_e32 v93, v93
	v_rcp_f32_e32 v94, v94
	v_rcp_f32_e32 v95, v95
	v_fma_f32 v96, v72, v92, v68
	v_fma_f32 v97, v73, v93, v69
	v_fma_f32 v98, v74, v94, v70
	v_fma_f32 v99, v75, v95, v71
	v_cmp_gt_f32_e64 s[22:23], s30, v96
	v_cmp_gt_f32_e64 s[24:25], s30, v97
	v_cmp_gt_f32_e64 s[26:27], s30, v98
	v_cmp_gt_f32_e64 s[28:29], s30, v99
	v_cndmask_b32_e64 v92, 0, 32, s[22:23]
	v_cndmask_b32_e64 v93, 0, 32, s[24:25]
	v_cndmask_b32_e64 v94, 0, 32, s[26:27]
	v_cndmask_b32_e64 v95, 0, 32, s[28:29]
	v_ldexp_f32 v92, v96, v92
	v_ldexp_f32 v93, v97, v93
	v_ldexp_f32 v94, v98, v94
	v_ldexp_f32 v95, v99, v95
	v_log_f32_e32 v92, v92
	v_log_f32_e32 v93, v93
	v_log_f32_e32 v94, v94
	v_log_f32_e32 v95, v95
	v_mul_f32_e32 v100, 0x3f317217, v92
	v_mul_f32_e32 v101, 0x3f317217, v93
	v_mul_f32_e32 v102, 0x3f317217, v94
	v_mul_f32_e32 v103, 0x3f317217, v95
	v_fma_f32 v100, v92, s31, -v100
	v_fma_f32 v101, v93, s31, -v101
	v_fma_f32 v102, v94, s31, -v102
	v_fma_f32 v103, v95, s31, -v103
	v_fmac_f32_e32 v100, 0x3377d1cf, v92
	v_fmac_f32_e32 v101, 0x3377d1cf, v93
	v_fmac_f32_e32 v102, 0x3377d1cf, v94
	v_fmac_f32_e32 v103, 0x3377d1cf, v95
	v_fmac_f32_e32 v100, 0x3f317217, v92
	v_fmac_f32_e32 v101, 0x3f317217, v93
	v_fmac_f32_e32 v102, 0x3f317217, v94
	v_fmac_f32_e32 v103, 0x3f317217, v95
	v_cmp_lt_f32_e64 vcc, |v92|, s34
	v_cndmask_b32_e32 v92, v92, v100, vcc
	v_cmp_lt_f32_e64 vcc, |v93|, s34
	v_cndmask_b32_e32 v93, v93, v101, vcc
	v_cmp_lt_f32_e64 vcc, |v94|, s34
	v_cndmask_b32_e32 v94, v94, v102, vcc
	v_cmp_lt_f32_e64 vcc, |v95|, s34
	v_cndmask_b32_e32 v95, v95, v103, vcc
	v_cndmask_b32_e64 v100, 0, v213, s[22:23]
	v_cndmask_b32_e64 v101, 0, v213, s[24:25]
	v_cndmask_b32_e64 v102, 0, v213, s[26:27]
	v_cndmask_b32_e64 v103, 0, v213, s[28:29]
	v_sub_f32_e32 v92, v92, v100
	v_sub_f32_e32 v93, v93, v101
	v_sub_f32_e32 v94, v94, v102
	v_sub_f32_e32 v95, v95, v103
	v_add_f32_e32 v64, v64, v92
	v_add_f32_e32 v65, v65, v93
	v_add_f32_e32 v66, v66, v94
	v_add_f32_e32 v67, v67, v95
	v_mul_f32_e32 v92, 0xbfb8aa3b, v64
	v_mul_f32_e32 v93, 0xbfb8aa3b, v65
	v_mul_f32_e32 v94, 0xbfb8aa3b, v66
	v_mul_f32_e32 v95, 0xbfb8aa3b, v67
	v_mul_f32_e32 v100, 0x3fb8aa3b, v64
	v_mul_f32_e32 v101, 0x3fb8aa3b, v65
	v_mul_f32_e32 v102, 0x3fb8aa3b, v66
	v_mul_f32_e32 v103, 0x3fb8aa3b, v67
	v_exp_f32_e32 v92, v92
	v_exp_f32_e32 v93, v93
	v_exp_f32_e32 v94, v94
	v_exp_f32_e32 v95, v95
	v_exp_f32_e32 v100, v100
	v_exp_f32_e32 v101, v101
	v_exp_f32_e32 v102, v102
	v_exp_f32_e32 v103, v103
	v_sub_f32_e32 v96, 1.0, v96
	v_sub_f32_e32 v97, 1.0, v97
	v_sub_f32_e32 v98, 1.0, v98
	v_sub_f32_e32 v99, 1.0, v99
	v_mul_f32_e32 v96, v96, v92
	v_mul_f32_e32 v97, v97, v93
	v_mul_f32_e32 v98, v98, v94
	v_mul_f32_e32 v99, v99, v95
	v_lshlrev_b32_e32 v92, 16, v6
	v_and_b32_e32 v93, 0xffff0000, v6
	v_lshlrev_b32_e32 v94, 16, v7
	v_and_b32_e32 v95, 0xffff0000, v7
	v_mul_f32_e32 v92, v92, v100
	v_mul_f32_e32 v93, v93, v101
	v_mul_f32_e32 v94, v94, v102
	v_mul_f32_e32 v95, v95, v103
	v_cvt_pk_bf16_f32 v108, v92, v93
	v_cvt_pk_bf16_f32 v109, v94, v95
	v_cvt_pk_bf16_f32 v110, v96, v97
	v_cvt_pk_bf16_f32 v111, v98, v99
	global_store_dwordx2 v112, v[108:109], s[2:3]
	global_store_dwordx2 v114, v[110:111], s[2:3]
	s_sub_u32 s2, s2, 0x400
	s_subb_u32 s3, s3, 0
	v_cvt_pk_bf16_f32 v123, v96, v104
	v_cvt_pk_bf16_f32 v139, v97, v105
	v_cvt_pk_bf16_f32 v173, v98, v106
	v_cvt_pk_bf16_f32 v189, v99, v107
	v_lshlrev_b32_e32 v92, 16, v8
	v_and_b32_e32 v93, 0xffff0000, v8
	v_lshlrev_b32_e32 v94, 16, v9
	v_and_b32_e32 v95, 0xffff0000, v9
	v_mul_f32_e32 v92, 0xbfb8aa3b, v92
	v_mul_f32_e32 v93, 0xbfb8aa3b, v93
	v_mul_f32_e32 v94, 0xbfb8aa3b, v94
	v_mul_f32_e32 v95, 0xbfb8aa3b, v95
	v_exp_f32_e32 v92, v92
	v_exp_f32_e32 v93, v93
	v_exp_f32_e32 v94, v94
	v_exp_f32_e32 v95, v95
	v_add_f32_e32 v92, 1.0, v92
	v_add_f32_e32 v93, 1.0, v93
	v_add_f32_e32 v94, 1.0, v94
	v_add_f32_e32 v95, 1.0, v95
	v_rcp_f32_e32 v92, v92
	v_rcp_f32_e32 v93, v93
	v_rcp_f32_e32 v94, v94
	v_rcp_f32_e32 v95, v95
	v_fma_f32 v96, v72, v92, v68
	v_fma_f32 v97, v73, v93, v69
	v_fma_f32 v98, v74, v94, v70
	v_fma_f32 v99, v75, v95, v71
	v_cmp_gt_f32_e64 s[22:23], s30, v96
	v_cmp_gt_f32_e64 s[24:25], s30, v97
	v_cmp_gt_f32_e64 s[26:27], s30, v98
	v_cmp_gt_f32_e64 s[28:29], s30, v99
	v_cndmask_b32_e64 v92, 0, 32, s[22:23]
	v_cndmask_b32_e64 v93, 0, 32, s[24:25]
	v_cndmask_b32_e64 v94, 0, 32, s[26:27]
	v_cndmask_b32_e64 v95, 0, 32, s[28:29]
	v_ldexp_f32 v92, v96, v92
	v_ldexp_f32 v93, v97, v93
	v_ldexp_f32 v94, v98, v94
	v_ldexp_f32 v95, v99, v95
	v_log_f32_e32 v92, v92
	v_log_f32_e32 v93, v93
	v_log_f32_e32 v94, v94
	v_log_f32_e32 v95, v95
	v_mul_f32_e32 v100, 0x3f317217, v92
	v_mul_f32_e32 v101, 0x3f317217, v93
; DEV u16 f2bf(float f) { return (u16)(pack2(f, f) & 0xffffu); }
; DEV float bf2f(u16 h) { return __uint_as_float(((unsigned)h) << 16); }
; DEV float sigmoid_f(float x) { return __builtin_amdgcn_rcpf(1.f + __expf(-x)); }
; DEV void phase_p15(const Params& p, int g) {
;     ...
;     for (int j8 = 0; j8 < 8; ++j8) {
;       const int st = j8 % 3;
;       if (j8 < 6) { P15_LOAD((j8 + 2) % 3, j8 + 2); }
; #pragma unroll
;       for (int cc = 0; cc < 2; ++cc) {
;         const int c = tid + 256 * cc;
;         unsigned kb[8];
; #pragma unroll
;         for (int e = 0; e < 8; ++e) {
;           const int jj = j8 * 8 + e;
;           const int j = dir ? 63 - jj : jj;
;           const size_t tok = (size_t)cidx * 64 + j;
;           const float f = lb[cc] + (1.f - lb[cc]) * sigmoid_f(bf2f(xr[st][cc][e]));
;           G[cc] += __logf(f);
;           const float eg = __expf(G[cc]), ig = __expf(-G[cc]);
;           Qp[tok * 512 + c] = f2bf(bf2f(qr[st][cc][e]) * eg);
;           const u16 kk = f2bf((1.f - f) * ig);
;           Kp[tok * 512 + c] = kk;
;           kb[e] = kk;
;         }
;         const int s0 = dir ? 56 - 8 * j8 : 8 * j8;
;         uint4 w;
;         w.x = dir ? (kb[7] | (kb[6] << 16)) : (kb[0] | (kb[1] << 16));
;         w.y = dir ? (kb[5] | (kb[4] << 16)) : (kb[2] | (kb[3] << 16));
;         w.z = dir ? (kb[3] | (kb[2] << 16)) : (kb[4] | (kb[5] << 16));
;         w.w = dir ? (kb[1] | (kb[0] << 16)) : (kb[6] | (kb[7] << 16));
;         *(uint4*)(KT + (((size_t)cidx * 2 + dir) * 512 + c) * 64 + s0) = w;
;       }
	v_mul_f32_e32 v102, 0x3f317217, v94
	v_mul_f32_e32 v103, 0x3f317217, v95
	v_fma_f32 v100, v92, s31, -v100
	v_fma_f32 v101, v93, s31, -v101
	v_fma_f32 v102, v94, s31, -v102
	v_fma_f32 v103, v95, s31, -v103
	v_fmac_f32_e32 v100, 0x3377d1cf, v92
	v_fmac_f32_e32 v101, 0x3377d1cf, v93
	v_fmac_f32_e32 v102, 0x3377d1cf, v94
	v_fmac_f32_e32 v103, 0x3377d1cf, v95
	v_fmac_f32_e32 v100, 0x3f317217, v92
	v_fmac_f32_e32 v101, 0x3f317217, v93
	v_fmac_f32_e32 v102, 0x3f317217, v94
	v_fmac_f32_e32 v103, 0x3f317217, v95
	v_cmp_lt_f32_e64 vcc, |v92|, s34
	v_cndmask_b32_e32 v92, v92, v100, vcc
	v_cmp_lt_f32_e64 vcc, |v93|, s34
	v_cndmask_b32_e32 v93, v93, v101, vcc
	v_cmp_lt_f32_e64 vcc, |v94|, s34
	v_cndmask_b32_e32 v94, v94, v102, vcc
	v_cmp_lt_f32_e64 vcc, |v95|, s34
	v_cndmask_b32_e32 v95, v95, v103, vcc
	v_cndmask_b32_e64 v100, 0, v213, s[22:23]
	v_cndmask_b32_e64 v101, 0, v213, s[24:25]
	v_cndmask_b32_e64 v102, 0, v213, s[26:27]
	v_cndmask_b32_e64 v103, 0, v213, s[28:29]
	v_sub_f32_e32 v92, v92, v100
	v_sub_f32_e32 v93, v93, v101
	v_sub_f32_e32 v94, v94, v102
	v_sub_f32_e32 v95, v95, v103
	v_add_f32_e32 v64, v64, v92
	v_add_f32_e32 v65, v65, v93
	v_add_f32_e32 v66, v66, v94
	v_add_f32_e32 v67, v67, v95
	v_mul_f32_e32 v92, 0xbfb8aa3b, v64
	v_mul_f32_e32 v93, 0xbfb8aa3b, v65
	v_mul_f32_e32 v94, 0xbfb8aa3b, v66
	v_mul_f32_e32 v95, 0xbfb8aa3b, v67
	v_mul_f32_e32 v100, 0x3fb8aa3b, v64
	v_mul_f32_e32 v101, 0x3fb8aa3b, v65
	v_mul_f32_e32 v102, 0x3fb8aa3b, v66
	v_mul_f32_e32 v103, 0x3fb8aa3b, v67
	v_exp_f32_e32 v92, v92
	v_exp_f32_e32 v93, v93
	v_exp_f32_e32 v94, v94
	v_exp_f32_e32 v95, v95
	v_exp_f32_e32 v100, v100
	v_exp_f32_e32 v101, v101
	v_exp_f32_e32 v102, v102
	v_exp_f32_e32 v103, v103
	v_sub_f32_e32 v96, 1.0, v96
	v_sub_f32_e32 v97, 1.0, v97
	v_sub_f32_e32 v98, 1.0, v98
	v_sub_f32_e32 v99, 1.0, v99
	v_mul_f32_e32 v96, v96, v92
	v_mul_f32_e32 v97, v97, v93
	v_mul_f32_e32 v98, v98, v94
	v_mul_f32_e32 v99, v99, v95
	v_lshlrev_b32_e32 v92, 16, v10
	v_and_b32_e32 v93, 0xffff0000, v10
	v_lshlrev_b32_e32 v94, 16, v11
	v_and_b32_e32 v95, 0xffff0000, v11
	v_mul_f32_e32 v92, v92, v100
	v_mul_f32_e32 v93, v93, v101
	v_mul_f32_e32 v94, v94, v102
	v_mul_f32_e32 v95, v95, v103
	v_cvt_pk_bf16_f32 v108, v92, v93
	v_cvt_pk_bf16_f32 v109, v94, v95
	v_cvt_pk_bf16_f32 v110, v96, v97
	v_cvt_pk_bf16_f32 v111, v98, v99
	global_store_dwordx2 v112, v[108:109], s[2:3]
	global_store_dwordx2 v114, v[110:111], s[2:3]
	s_sub_u32 s2, s2, 0x400
	s_subb_u32 s3, s3, 0
	v_mov_b32_e32 v104, v96
	v_mov_b32_e32 v105, v97
	v_mov_b32_e32 v106, v98
	v_mov_b32_e32 v107, v99
	v_lshlrev_b32_e32 v92, 16, v12
	v_and_b32_e32 v93, 0xffff0000, v12
	v_lshlrev_b32_e32 v94, 16, v13
	v_and_b32_e32 v95, 0xffff0000, v13
	v_mul_f32_e32 v92, 0xbfb8aa3b, v92
	v_mul_f32_e32 v93, 0xbfb8aa3b, v93
	v_mul_f32_e32 v94, 0xbfb8aa3b, v94
	v_mul_f32_e32 v95, 0xbfb8aa3b, v95
	v_exp_f32_e32 v92, v92
	v_exp_f32_e32 v93, v93
	v_exp_f32_e32 v94, v94
	v_exp_f32_e32 v95, v95
	v_add_f32_e32 v92, 1.0, v92
	v_add_f32_e32 v93, 1.0, v93
	v_add_f32_e32 v94, 1.0, v94
	v_add_f32_e32 v95, 1.0, v95
	v_rcp_f32_e32 v92, v92
	v_rcp_f32_e32 v93, v93
	v_rcp_f32_e32 v94, v94
	v_rcp_f32_e32 v95, v95
	v_fma_f32 v96, v72, v92, v68
	v_fma_f32 v97, v73, v93, v69
	v_fma_f32 v98, v74, v94, v70
	v_fma_f32 v99, v75, v95, v71
	v_cmp_gt_f32_e64 s[22:23], s30, v96
	v_cmp_gt_f32_e64 s[24:25], s30, v97
	v_cmp_gt_f32_e64 s[26:27], s30, v98
	v_cmp_gt_f32_e64 s[28:29], s30, v99
	v_cndmask_b32_e64 v92, 0, 32, s[22:23]
	v_cndmask_b32_e64 v93, 0, 32, s[24:25]
	v_cndmask_b32_e64 v94, 0, 32, s[26:27]
	v_cndmask_b32_e64 v95, 0, 32, s[28:29]
	v_ldexp_f32 v92, v96, v92
	v_ldexp_f32 v93, v97, v93
	v_ldexp_f32 v94, v98, v94
	v_ldexp_f32 v95, v99, v95
	v_log_f32_e32 v92, v92
	v_log_f32_e32 v93, v93
	v_log_f32_e32 v94, v94
	v_log_f32_e32 v95, v95
	v_mul_f32_e32 v100, 0x3f317217, v92
	v_mul_f32_e32 v101, 0x3f317217, v93
	v_mul_f32_e32 v102, 0x3f317217, v94
	v_mul_f32_e32 v103, 0x3f317217, v95
	v_fma_f32 v100, v92, s31, -v100
	v_fma_f32 v101, v93, s31, -v101
	v_fma_f32 v102, v94, s31, -v102
	v_fma_f32 v103, v95, s31, -v103
	v_fmac_f32_e32 v100, 0x3377d1cf, v92
	v_fmac_f32_e32 v101, 0x3377d1cf, v93
	v_fmac_f32_e32 v102, 0x3377d1cf, v94
	v_fmac_f32_e32 v103, 0x3377d1cf, v95
	v_fmac_f32_e32 v100, 0x3f317217, v92
	v_fmac_f32_e32 v101, 0x3f317217, v93
	v_fmac_f32_e32 v102, 0x3f317217, v94
	v_fmac_f32_e32 v103, 0x3f317217, v95
	v_cmp_lt_f32_e64 vcc, |v92|, s34
	v_cndmask_b32_e32 v92, v92, v100, vcc
	v_cmp_lt_f32_e64 vcc, |v93|, s34
	v_cndmask_b32_e32 v93, v93, v101, vcc
	v_cmp_lt_f32_e64 vcc, |v94|, s34
	v_cndmask_b32_e32 v94, v94, v102, vcc
	v_cmp_lt_f32_e64 vcc, |v95|, s34
	v_cndmask_b32_e32 v95, v95, v103, vcc
	v_cndmask_b32_e64 v100, 0, v213, s[22:23]
	v_cndmask_b32_e64 v101, 0, v213, s[24:25]
	v_cndmask_b32_e64 v102, 0, v213, s[26:27]
	v_cndmask_b32_e64 v103, 0, v213, s[28:29]
	v_sub_f32_e32 v92, v92, v100
	v_sub_f32_e32 v93, v93, v101
	v_sub_f32_e32 v94, v94, v102
	v_sub_f32_e32 v95, v95, v103
	v_add_f32_e32 v64, v64, v92
	v_add_f32_e32 v65, v65, v93
	v_add_f32_e32 v66, v66, v94
	v_add_f32_e32 v67, v67, v95
	v_mul_f32_e32 v92, 0xbfb8aa3b, v64
	v_mul_f32_e32 v93, 0xbfb8aa3b, v65
	v_mul_f32_e32 v94, 0xbfb8aa3b, v66
	v_mul_f32_e32 v95, 0xbfb8aa3b, v67
	v_mul_f32_e32 v100, 0x3fb8aa3b, v64
	v_mul_f32_e32 v101, 0x3fb8aa3b, v65
	v_mul_f32_e32 v102, 0x3fb8aa3b, v66
	v_mul_f32_e32 v103, 0x3fb8aa3b, v67
	v_exp_f32_e32 v92, v92
	v_exp_f32_e32 v93, v93
	v_exp_f32_e32 v94, v94
	v_exp_f32_e32 v95, v95
	v_exp_f32_e32 v100, v100
	v_exp_f32_e32 v101, v101
	v_exp_f32_e32 v102, v102
	v_exp_f32_e32 v103, v103
	v_sub_f32_e32 v96, 1.0, v96
	v_sub_f32_e32 v97, 1.0, v97
	v_sub_f32_e32 v98, 1.0, v98
; DEV u16 f2bf(float f) { return (u16)(pack2(f, f) & 0xffffu); }
; DEV float bf2f(u16 h) { return __uint_as_float(((unsigned)h) << 16); }
; DEV float sigmoid_f(float x) { return __builtin_amdgcn_rcpf(1.f + __expf(-x)); }
; DEV void phase_p15(const Params& p, int g) {
;     ...
;     for (int j8 = 0; j8 < 8; ++j8) {
;       const int st = j8 % 3;
;       if (j8 < 6) { P15_LOAD((j8 + 2) % 3, j8 + 2); }
; #pragma unroll
;       for (int cc = 0; cc < 2; ++cc) {
;         const int c = tid + 256 * cc;
;         unsigned kb[8];
; #pragma unroll
;         for (int e = 0; e < 8; ++e) {
;           const int jj = j8 * 8 + e;
;           const int j = dir ? 63 - jj : jj;
;           const size_t tok = (size_t)cidx * 64 + j;
;           const float f = lb[cc] + (1.f - lb[cc]) * sigmoid_f(bf2f(xr[st][cc][e]));
;           G[cc] += __logf(f);
;           const float eg = __expf(G[cc]), ig = __expf(-G[cc]);
;           Qp[tok * 512 + c] = f2bf(bf2f(qr[st][cc][e]) * eg);
;           const u16 kk = f2bf((1.f - f) * ig);
;           Kp[tok * 512 + c] = kk;
;           kb[e] = kk;
;         }
;         const int s0 = dir ? 56 - 8 * j8 : 8 * j8;
;         uint4 w;
;         w.x = dir ? (kb[7] | (kb[6] << 16)) : (kb[0] | (kb[1] << 16));
;         w.y = dir ? (kb[5] | (kb[4] << 16)) : (kb[2] | (kb[3] << 16));
;         w.z = dir ? (kb[3] | (kb[2] << 16)) : (kb[4] | (kb[5] << 16));
;         w.w = dir ? (kb[1] | (kb[0] << 16)) : (kb[6] | (kb[7] << 16));
;         *(uint4*)(KT + (((size_t)cidx * 2 + dir) * 512 + c) * 64 + s0) = w;
;       }
	v_sub_f32_e32 v99, 1.0, v99
	v_mul_f32_e32 v96, v96, v92
	v_mul_f32_e32 v97, v97, v93
	v_mul_f32_e32 v98, v98, v94
	v_mul_f32_e32 v99, v99, v95
	v_lshlrev_b32_e32 v92, 16, v14
	v_and_b32_e32 v93, 0xffff0000, v14
	v_lshlrev_b32_e32 v94, 16, v15
	v_and_b32_e32 v95, 0xffff0000, v15
	v_mul_f32_e32 v92, v92, v100
	v_mul_f32_e32 v93, v93, v101
	v_mul_f32_e32 v94, v94, v102
	v_mul_f32_e32 v95, v95, v103
	v_cvt_pk_bf16_f32 v108, v92, v93
	v_cvt_pk_bf16_f32 v109, v94, v95
	v_cvt_pk_bf16_f32 v110, v96, v97
	v_cvt_pk_bf16_f32 v111, v98, v99
	global_store_dwordx2 v112, v[108:109], s[2:3]
	global_store_dwordx2 v114, v[110:111], s[2:3]
	s_sub_u32 s2, s2, 0x400
	s_subb_u32 s3, s3, 0
	v_cvt_pk_bf16_f32 v122, v96, v104
	v_cvt_pk_bf16_f32 v138, v97, v105
	v_cvt_pk_bf16_f32 v172, v98, v106
	v_cvt_pk_bf16_f32 v188, v99, v107
	v_lshlrev_b32_e32 v92, 16, v16
	v_and_b32_e32 v93, 0xffff0000, v16
	v_lshlrev_b32_e32 v94, 16, v17
	v_and_b32_e32 v95, 0xffff0000, v17
	v_mul_f32_e32 v92, 0xbfb8aa3b, v92
	v_mul_f32_e32 v93, 0xbfb8aa3b, v93
	v_mul_f32_e32 v94, 0xbfb8aa3b, v94
	v_mul_f32_e32 v95, 0xbfb8aa3b, v95
	v_exp_f32_e32 v92, v92
	v_exp_f32_e32 v93, v93
	v_exp_f32_e32 v94, v94
	v_exp_f32_e32 v95, v95
	v_add_f32_e32 v92, 1.0, v92
	v_add_f32_e32 v93, 1.0, v93
	v_add_f32_e32 v94, 1.0, v94
	v_add_f32_e32 v95, 1.0, v95
	v_rcp_f32_e32 v92, v92
	v_rcp_f32_e32 v93, v93
	v_rcp_f32_e32 v94, v94
	v_rcp_f32_e32 v95, v95
	v_fma_f32 v96, v72, v92, v68
	v_fma_f32 v97, v73, v93, v69
	v_fma_f32 v98, v74, v94, v70
	v_fma_f32 v99, v75, v95, v71
	v_cmp_gt_f32_e64 s[22:23], s30, v96
	v_cmp_gt_f32_e64 s[24:25], s30, v97
	v_cmp_gt_f32_e64 s[26:27], s30, v98
	v_cmp_gt_f32_e64 s[28:29], s30, v99
	v_cndmask_b32_e64 v92, 0, 32, s[22:23]
	v_cndmask_b32_e64 v93, 0, 32, s[24:25]
	v_cndmask_b32_e64 v94, 0, 32, s[26:27]
	v_cndmask_b32_e64 v95, 0, 32, s[28:29]
	v_ldexp_f32 v92, v96, v92
	v_ldexp_f32 v93, v97, v93
	v_ldexp_f32 v94, v98, v94
	v_ldexp_f32 v95, v99, v95
	v_log_f32_e32 v92, v92
	v_log_f32_e32 v93, v93
	v_log_f32_e32 v94, v94
	v_log_f32_e32 v95, v95
	v_mul_f32_e32 v100, 0x3f317217, v92
	v_mul_f32_e32 v101, 0x3f317217, v93
	v_mul_f32_e32 v102, 0x3f317217, v94
	v_mul_f32_e32 v103, 0x3f317217, v95
	v_fma_f32 v100, v92, s31, -v100
	v_fma_f32 v101, v93, s31, -v101
	v_fma_f32 v102, v94, s31, -v102
	v_fma_f32 v103, v95, s31, -v103
	v_fmac_f32_e32 v100, 0x3377d1cf, v92
	v_fmac_f32_e32 v101, 0x3377d1cf, v93
	v_fmac_f32_e32 v102, 0x3377d1cf, v94
	v_fmac_f32_e32 v103, 0x3377d1cf, v95
	v_fmac_f32_e32 v100, 0x3f317217, v92
	v_fmac_f32_e32 v101, 0x3f317217, v93
	v_fmac_f32_e32 v102, 0x3f317217, v94
	v_fmac_f32_e32 v103, 0x3f317217, v95
	v_cmp_lt_f32_e64 vcc, |v92|, s34
	v_cndmask_b32_e32 v92, v92, v100, vcc
	v_cmp_lt_f32_e64 vcc, |v93|, s34
	v_cndmask_b32_e32 v93, v93, v101, vcc
	v_cmp_lt_f32_e64 vcc, |v94|, s34
	v_cndmask_b32_e32 v94, v94, v102, vcc
	v_cmp_lt_f32_e64 vcc, |v95|, s34
	v_cndmask_b32_e32 v95, v95, v103, vcc
	v_cndmask_b32_e64 v100, 0, v213, s[22:23]
	v_cndmask_b32_e64 v101, 0, v213, s[24:25]
	v_cndmask_b32_e64 v102, 0, v213, s[26:27]
	v_cndmask_b32_e64 v103, 0, v213, s[28:29]
	v_sub_f32_e32 v92, v92, v100
	v_sub_f32_e32 v93, v93, v101
	v_sub_f32_e32 v94, v94, v102
	v_sub_f32_e32 v95, v95, v103
	v_add_f32_e32 v64, v64, v92
	v_add_f32_e32 v65, v65, v93
	v_add_f32_e32 v66, v66, v94
	v_add_f32_e32 v67, v67, v95
	v_mul_f32_e32 v92, 0xbfb8aa3b, v64
	v_mul_f32_e32 v93, 0xbfb8aa3b, v65
	v_mul_f32_e32 v94, 0xbfb8aa3b, v66
	v_mul_f32_e32 v95, 0xbfb8aa3b, v67
	v_mul_f32_e32 v100, 0x3fb8aa3b, v64
	v_mul_f32_e32 v101, 0x3fb8aa3b, v65
	v_mul_f32_e32 v102, 0x3fb8aa3b, v66
	v_mul_f32_e32 v103, 0x3fb8aa3b, v67
	v_exp_f32_e32 v92, v92
	v_exp_f32_e32 v93, v93
	v_exp_f32_e32 v94, v94
	v_exp_f32_e32 v95, v95
	v_exp_f32_e32 v100, v100
	v_exp_f32_e32 v101, v101
	v_exp_f32_e32 v102, v102
	v_exp_f32_e32 v103, v103
	v_sub_f32_e32 v96, 1.0, v96
	v_sub_f32_e32 v97, 1.0, v97
	v_sub_f32_e32 v98, 1.0, v98
	v_sub_f32_e32 v99, 1.0, v99
	v_mul_f32_e32 v96, v96, v92
	v_mul_f32_e32 v97, v97, v93
	v_mul_f32_e32 v98, v98, v94
	v_mul_f32_e32 v99, v99, v95
	v_lshlrev_b32_e32 v92, 16, v18
	v_and_b32_e32 v93, 0xffff0000, v18
	v_lshlrev_b32_e32 v94, 16, v19
	v_and_b32_e32 v95, 0xffff0000, v19
	v_mul_f32_e32 v92, v92, v100
	v_mul_f32_e32 v93, v93, v101
	v_mul_f32_e32 v94, v94, v102
	v_mul_f32_e32 v95, v95, v103
	v_cvt_pk_bf16_f32 v108, v92, v93
	v_cvt_pk_bf16_f32 v109, v94, v95
	v_cvt_pk_bf16_f32 v110, v96, v97
	v_cvt_pk_bf16_f32 v111, v98, v99
	global_store_dwordx2 v112, v[108:109], s[2:3]
	global_store_dwordx2 v114, v[110:111], s[2:3]
	s_sub_u32 s2, s2, 0x400
	s_subb_u32 s3, s3, 0
	v_mov_b32_e32 v104, v96
	v_mov_b32_e32 v105, v97
	v_mov_b32_e32 v106, v98
	v_mov_b32_e32 v107, v99
	v_lshlrev_b32_e32 v92, 16, v20
	v_and_b32_e32 v93, 0xffff0000, v20
	v_lshlrev_b32_e32 v94, 16, v21
	v_and_b32_e32 v95, 0xffff0000, v21
	v_mul_f32_e32 v92, 0xbfb8aa3b, v92
	v_mul_f32_e32 v93, 0xbfb8aa3b, v93
	v_mul_f32_e32 v94, 0xbfb8aa3b, v94
	v_mul_f32_e32 v95, 0xbfb8aa3b, v95
	v_exp_f32_e32 v92, v92
	v_exp_f32_e32 v93, v93
	v_exp_f32_e32 v94, v94
	v_exp_f32_e32 v95, v95
	v_add_f32_e32 v92, 1.0, v92
	v_add_f32_e32 v93, 1.0, v93
	v_add_f32_e32 v94, 1.0, v94
	v_add_f32_e32 v95, 1.0, v95
	v_rcp_f32_e32 v92, v92
	v_rcp_f32_e32 v93, v93
	v_rcp_f32_e32 v94, v94
	v_rcp_f32_e32 v95, v95
	v_fma_f32 v96, v72, v92, v68
	v_fma_f32 v97, v73, v93, v69
	v_fma_f32 v98, v74, v94, v70
	v_fma_f32 v99, v75, v95, v71
	v_cmp_gt_f32_e64 s[22:23], s30, v96
	v_cmp_gt_f32_e64 s[24:25], s30, v97
	v_cmp_gt_f32_e64 s[26:27], s30, v98
	v_cmp_gt_f32_e64 s[28:29], s30, v99
	v_cndmask_b32_e64 v92, 0, 32, s[22:23]
	v_cndmask_b32_e64 v93, 0, 32, s[24:25]
	v_cndmask_b32_e64 v94, 0, 32, s[26:27]
; DEV u16 f2bf(float f) { return (u16)(pack2(f, f) & 0xffffu); }
; DEV float bf2f(u16 h) { return __uint_as_float(((unsigned)h) << 16); }
; DEV float sigmoid_f(float x) { return __builtin_amdgcn_rcpf(1.f + __expf(-x)); }
; DEV void phase_p15(const Params& p, int g) {
;     ...
;     for (int j8 = 0; j8 < 8; ++j8) {
;       const int st = j8 % 3;
;       if (j8 < 6) { P15_LOAD((j8 + 2) % 3, j8 + 2); }
; #pragma unroll
;       for (int cc = 0; cc < 2; ++cc) {
;         const int c = tid + 256 * cc;
;         unsigned kb[8];
; #pragma unroll
;         for (int e = 0; e < 8; ++e) {
;           const int jj = j8 * 8 + e;
;           const int j = dir ? 63 - jj : jj;
;           const size_t tok = (size_t)cidx * 64 + j;
;           const float f = lb[cc] + (1.f - lb[cc]) * sigmoid_f(bf2f(xr[st][cc][e]));
;           G[cc] += __logf(f);
;           const float eg = __expf(G[cc]), ig = __expf(-G[cc]);
;           Qp[tok * 512 + c] = f2bf(bf2f(qr[st][cc][e]) * eg);
;           const u16 kk = f2bf((1.f - f) * ig);
;           Kp[tok * 512 + c] = kk;
;           kb[e] = kk;
;         }
;         const int s0 = dir ? 56 - 8 * j8 : 8 * j8;
;         uint4 w;
;         w.x = dir ? (kb[7] | (kb[6] << 16)) : (kb[0] | (kb[1] << 16));
;         w.y = dir ? (kb[5] | (kb[4] << 16)) : (kb[2] | (kb[3] << 16));
;         w.z = dir ? (kb[3] | (kb[2] << 16)) : (kb[4] | (kb[5] << 16));
;         w.w = dir ? (kb[1] | (kb[0] << 16)) : (kb[6] | (kb[7] << 16));
;         *(uint4*)(KT + (((size_t)cidx * 2 + dir) * 512 + c) * 64 + s0) = w;
;       }
	v_cndmask_b32_e64 v95, 0, 32, s[28:29]
	v_ldexp_f32 v92, v96, v92
	v_ldexp_f32 v93, v97, v93
	v_ldexp_f32 v94, v98, v94
	v_ldexp_f32 v95, v99, v95
	v_log_f32_e32 v92, v92
	v_log_f32_e32 v93, v93
	v_log_f32_e32 v94, v94
	v_log_f32_e32 v95, v95
	v_mul_f32_e32 v100, 0x3f317217, v92
	v_mul_f32_e32 v101, 0x3f317217, v93
	v_mul_f32_e32 v102, 0x3f317217, v94
	v_mul_f32_e32 v103, 0x3f317217, v95
	v_fma_f32 v100, v92, s31, -v100
	v_fma_f32 v101, v93, s31, -v101
	v_fma_f32 v102, v94, s31, -v102
	v_fma_f32 v103, v95, s31, -v103
	v_fmac_f32_e32 v100, 0x3377d1cf, v92
	v_fmac_f32_e32 v101, 0x3377d1cf, v93
	v_fmac_f32_e32 v102, 0x3377d1cf, v94
	v_fmac_f32_e32 v103, 0x3377d1cf, v95
	v_fmac_f32_e32 v100, 0x3f317217, v92
	v_fmac_f32_e32 v101, 0x3f317217, v93
	v_fmac_f32_e32 v102, 0x3f317217, v94
	v_fmac_f32_e32 v103, 0x3f317217, v95
	v_cmp_lt_f32_e64 vcc, |v92|, s34
	v_cndmask_b32_e32 v92, v92, v100, vcc
	v_cmp_lt_f32_e64 vcc, |v93|, s34
	v_cndmask_b32_e32 v93, v93, v101, vcc
	v_cmp_lt_f32_e64 vcc, |v94|, s34
	v_cndmask_b32_e32 v94, v94, v102, vcc
	v_cmp_lt_f32_e64 vcc, |v95|, s34
	v_cndmask_b32_e32 v95, v95, v103, vcc
	v_cndmask_b32_e64 v100, 0, v213, s[22:23]
	v_cndmask_b32_e64 v101, 0, v213, s[24:25]
	v_cndmask_b32_e64 v102, 0, v213, s[26:27]
	v_cndmask_b32_e64 v103, 0, v213, s[28:29]
	v_sub_f32_e32 v92, v92, v100
	v_sub_f32_e32 v93, v93, v101
	v_sub_f32_e32 v94, v94, v102
	v_sub_f32_e32 v95, v95, v103
	v_add_f32_e32 v64, v64, v92
	v_add_f32_e32 v65, v65, v93
	v_add_f32_e32 v66, v66, v94
	v_add_f32_e32 v67, v67, v95
	v_mul_f32_e32 v92, 0xbfb8aa3b, v64
	v_mul_f32_e32 v93, 0xbfb8aa3b, v65
	v_mul_f32_e32 v94, 0xbfb8aa3b, v66
	v_mul_f32_e32 v95, 0xbfb8aa3b, v67
	v_mul_f32_e32 v100, 0x3fb8aa3b, v64
	v_mul_f32_e32 v101, 0x3fb8aa3b, v65
	v_mul_f32_e32 v102, 0x3fb8aa3b, v66
	v_mul_f32_e32 v103, 0x3fb8aa3b, v67
	v_exp_f32_e32 v92, v92
	v_exp_f32_e32 v93, v93
	v_exp_f32_e32 v94, v94
	v_exp_f32_e32 v95, v95
	v_exp_f32_e32 v100, v100
	v_exp_f32_e32 v101, v101
	v_exp_f32_e32 v102, v102
	v_exp_f32_e32 v103, v103
	v_sub_f32_e32 v96, 1.0, v96
	v_sub_f32_e32 v97, 1.0, v97
	v_sub_f32_e32 v98, 1.0, v98
	v_sub_f32_e32 v99, 1.0, v99
	v_mul_f32_e32 v96, v96, v92
	v_mul_f32_e32 v97, v97, v93
	v_mul_f32_e32 v98, v98, v94
	v_mul_f32_e32 v99, v99, v95
	v_lshlrev_b32_e32 v92, 16, v22
	v_and_b32_e32 v93, 0xffff0000, v22
	v_lshlrev_b32_e32 v94, 16, v23
	v_and_b32_e32 v95, 0xffff0000, v23
	v_mul_f32_e32 v92, v92, v100
	v_mul_f32_e32 v93, v93, v101
	v_mul_f32_e32 v94, v94, v102
	v_mul_f32_e32 v95, v95, v103
	v_cvt_pk_bf16_f32 v108, v92, v93
	v_cvt_pk_bf16_f32 v109, v94, v95
	v_cvt_pk_bf16_f32 v110, v96, v97
	v_cvt_pk_bf16_f32 v111, v98, v99
	global_store_dwordx2 v112, v[108:109], s[2:3]
	global_store_dwordx2 v114, v[110:111], s[2:3]
	s_sub_u32 s2, s2, 0x400
	s_subb_u32 s3, s3, 0
	v_cvt_pk_bf16_f32 v121, v96, v104
	v_cvt_pk_bf16_f32 v137, v97, v105
	v_cvt_pk_bf16_f32 v171, v98, v106
	v_cvt_pk_bf16_f32 v187, v99, v107
	v_lshlrev_b32_e32 v92, 16, v24
	v_and_b32_e32 v93, 0xffff0000, v24
	v_lshlrev_b32_e32 v94, 16, v25
	v_and_b32_e32 v95, 0xffff0000, v25
	v_mul_f32_e32 v92, 0xbfb8aa3b, v92
	v_mul_f32_e32 v93, 0xbfb8aa3b, v93
	v_mul_f32_e32 v94, 0xbfb8aa3b, v94
	v_mul_f32_e32 v95, 0xbfb8aa3b, v95
	v_exp_f32_e32 v92, v92
	v_exp_f32_e32 v93, v93
	v_exp_f32_e32 v94, v94
	v_exp_f32_e32 v95, v95
	v_add_f32_e32 v92, 1.0, v92
	v_add_f32_e32 v93, 1.0, v93
	v_add_f32_e32 v94, 1.0, v94
	v_add_f32_e32 v95, 1.0, v95
	v_rcp_f32_e32 v92, v92
	v_rcp_f32_e32 v93, v93
	v_rcp_f32_e32 v94, v94
	v_rcp_f32_e32 v95, v95
	v_fma_f32 v96, v72, v92, v68
	v_fma_f32 v97, v73, v93, v69
	v_fma_f32 v98, v74, v94, v70
	v_fma_f32 v99, v75, v95, v71
	v_cmp_gt_f32_e64 s[22:23], s30, v96
	v_cmp_gt_f32_e64 s[24:25], s30, v97
	v_cmp_gt_f32_e64 s[26:27], s30, v98
	v_cmp_gt_f32_e64 s[28:29], s30, v99
	v_cndmask_b32_e64 v92, 0, 32, s[22:23]
	v_cndmask_b32_e64 v93, 0, 32, s[24:25]
	v_cndmask_b32_e64 v94, 0, 32, s[26:27]
	v_cndmask_b32_e64 v95, 0, 32, s[28:29]
	v_ldexp_f32 v92, v96, v92
	v_ldexp_f32 v93, v97, v93
	v_ldexp_f32 v94, v98, v94
	v_ldexp_f32 v95, v99, v95
	v_log_f32_e32 v92, v92
	v_log_f32_e32 v93, v93
	v_log_f32_e32 v94, v94
	v_log_f32_e32 v95, v95
	v_mul_f32_e32 v100, 0x3f317217, v92
	v_mul_f32_e32 v101, 0x3f317217, v93
	v_mul_f32_e32 v102, 0x3f317217, v94
	v_mul_f32_e32 v103, 0x3f317217, v95
	v_fma_f32 v100, v92, s31, -v100
	v_fma_f32 v101, v93, s31, -v101
	v_fma_f32 v102, v94, s31, -v102
	v_fma_f32 v103, v95, s31, -v103
	v_fmac_f32_e32 v100, 0x3377d1cf, v92
	v_fmac_f32_e32 v101, 0x3377d1cf, v93
	v_fmac_f32_e32 v102, 0x3377d1cf, v94
	v_fmac_f32_e32 v103, 0x3377d1cf, v95
	v_fmac_f32_e32 v100, 0x3f317217, v92
	v_fmac_f32_e32 v101, 0x3f317217, v93
	v_fmac_f32_e32 v102, 0x3f317217, v94
	v_fmac_f32_e32 v103, 0x3f317217, v95
	v_cmp_lt_f32_e64 vcc, |v92|, s34
	v_cndmask_b32_e32 v92, v92, v100, vcc
	v_cmp_lt_f32_e64 vcc, |v93|, s34
	v_cndmask_b32_e32 v93, v93, v101, vcc
	v_cmp_lt_f32_e64 vcc, |v94|, s34
	v_cndmask_b32_e32 v94, v94, v102, vcc
	v_cmp_lt_f32_e64 vcc, |v95|, s34
	v_cndmask_b32_e32 v95, v95, v103, vcc
	v_cndmask_b32_e64 v100, 0, v213, s[22:23]
	v_cndmask_b32_e64 v101, 0, v213, s[24:25]
	v_cndmask_b32_e64 v102, 0, v213, s[26:27]
	v_cndmask_b32_e64 v103, 0, v213, s[28:29]
	v_sub_f32_e32 v92, v92, v100
	v_sub_f32_e32 v93, v93, v101
	v_sub_f32_e32 v94, v94, v102
	v_sub_f32_e32 v95, v95, v103
	v_add_f32_e32 v64, v64, v92
	v_add_f32_e32 v65, v65, v93
	v_add_f32_e32 v66, v66, v94
	v_add_f32_e32 v67, v67, v95
	v_mul_f32_e32 v92, 0xbfb8aa3b, v64
	v_mul_f32_e32 v93, 0xbfb8aa3b, v65
	v_mul_f32_e32 v94, 0xbfb8aa3b, v66
	v_mul_f32_e32 v95, 0xbfb8aa3b, v67
	v_mul_f32_e32 v100, 0x3fb8aa3b, v64
	v_mul_f32_e32 v101, 0x3fb8aa3b, v65
; DEV u16 f2bf(float f) { return (u16)(pack2(f, f) & 0xffffu); }
; DEV float bf2f(u16 h) { return __uint_as_float(((unsigned)h) << 16); }
; DEV float sigmoid_f(float x) { return __builtin_amdgcn_rcpf(1.f + __expf(-x)); }
; DEV void phase_p15(const Params& p, int g) {
;     ...
;     P15_LOAD(0, 0);
;     P15_LOAD(1, 1);
; #pragma unroll
;     for (int j8 = 0; j8 < 8; ++j8) {
;       const int st = j8 % 3;
;       if (j8 < 6) { P15_LOAD((j8 + 2) % 3, j8 + 2); }
; #pragma unroll
;       for (int cc = 0; cc < 2; ++cc) {
;         const int c = tid + 256 * cc;
;         unsigned kb[8];
; #pragma unroll
;         for (int e = 0; e < 8; ++e) {
;           const int jj = j8 * 8 + e;
;           const int j = dir ? 63 - jj : jj;
;           const size_t tok = (size_t)cidx * 64 + j;
;           const float f = lb[cc] + (1.f - lb[cc]) * sigmoid_f(bf2f(xr[st][cc][e]));
;           G[cc] += __logf(f);
;           const float eg = __expf(G[cc]), ig = __expf(-G[cc]);
;           Qp[tok * 512 + c] = f2bf(bf2f(qr[st][cc][e]) * eg);
;           const u16 kk = f2bf((1.f - f) * ig);
;           Kp[tok * 512 + c] = kk;
;           kb[e] = kk;
;         }
;         const int s0 = dir ? 56 - 8 * j8 : 8 * j8;
;         uint4 w;
;         w.x = dir ? (kb[7] | (kb[6] << 16)) : (kb[0] | (kb[1] << 16));
;         w.y = dir ? (kb[5] | (kb[4] << 16)) : (kb[2] | (kb[3] << 16));
;         w.z = dir ? (kb[3] | (kb[2] << 16)) : (kb[4] | (kb[5] << 16));
;         w.w = dir ? (kb[1] | (kb[0] << 16)) : (kb[6] | (kb[7] << 16));
;         *(uint4*)(KT + (((size_t)cidx * 2 + dir) * 512 + c) * 64 + s0) = w;
;       }
	v_mul_f32_e32 v102, 0x3fb8aa3b, v66
	v_mul_f32_e32 v103, 0x3fb8aa3b, v67
	v_exp_f32_e32 v92, v92
	v_exp_f32_e32 v93, v93
	v_exp_f32_e32 v94, v94
	v_exp_f32_e32 v95, v95
	v_exp_f32_e32 v100, v100
	v_exp_f32_e32 v101, v101
	v_exp_f32_e32 v102, v102
	v_exp_f32_e32 v103, v103
	v_sub_f32_e32 v96, 1.0, v96
	v_sub_f32_e32 v97, 1.0, v97
	v_sub_f32_e32 v98, 1.0, v98
	v_sub_f32_e32 v99, 1.0, v99
	v_mul_f32_e32 v96, v96, v92
	v_mul_f32_e32 v97, v97, v93
	v_mul_f32_e32 v98, v98, v94
	v_mul_f32_e32 v99, v99, v95
	v_lshlrev_b32_e32 v92, 16, v26
	v_and_b32_e32 v93, 0xffff0000, v26
	v_lshlrev_b32_e32 v94, 16, v27
	v_and_b32_e32 v95, 0xffff0000, v27
	v_mul_f32_e32 v92, v92, v100
	v_mul_f32_e32 v93, v93, v101
	v_mul_f32_e32 v94, v94, v102
	v_mul_f32_e32 v95, v95, v103
	v_cvt_pk_bf16_f32 v108, v92, v93
	v_cvt_pk_bf16_f32 v109, v94, v95
	v_cvt_pk_bf16_f32 v110, v96, v97
	v_cvt_pk_bf16_f32 v111, v98, v99
	global_store_dwordx2 v112, v[108:109], s[2:3]
	global_store_dwordx2 v114, v[110:111], s[2:3]
	s_sub_u32 s2, s2, 0x400
	s_subb_u32 s3, s3, 0
	v_mov_b32_e32 v104, v96
	v_mov_b32_e32 v105, v97
	v_mov_b32_e32 v106, v98
	v_mov_b32_e32 v107, v99
	v_lshlrev_b32_e32 v92, 16, v28
	v_and_b32_e32 v93, 0xffff0000, v28
	v_lshlrev_b32_e32 v94, 16, v29
	v_and_b32_e32 v95, 0xffff0000, v29
	v_mul_f32_e32 v92, 0xbfb8aa3b, v92
	v_mul_f32_e32 v93, 0xbfb8aa3b, v93
	v_mul_f32_e32 v94, 0xbfb8aa3b, v94
	v_mul_f32_e32 v95, 0xbfb8aa3b, v95
	v_exp_f32_e32 v92, v92
	v_exp_f32_e32 v93, v93
	v_exp_f32_e32 v94, v94
	v_exp_f32_e32 v95, v95
	v_add_f32_e32 v92, 1.0, v92
	v_add_f32_e32 v93, 1.0, v93
	v_add_f32_e32 v94, 1.0, v94
	v_add_f32_e32 v95, 1.0, v95
	v_rcp_f32_e32 v92, v92
	v_rcp_f32_e32 v93, v93
	v_rcp_f32_e32 v94, v94
	v_rcp_f32_e32 v95, v95
	v_fma_f32 v96, v72, v92, v68
	v_fma_f32 v97, v73, v93, v69
	v_fma_f32 v98, v74, v94, v70
	v_fma_f32 v99, v75, v95, v71
	v_cmp_gt_f32_e64 s[22:23], s30, v96
	v_cmp_gt_f32_e64 s[24:25], s30, v97
	v_cmp_gt_f32_e64 s[26:27], s30, v98
	v_cmp_gt_f32_e64 s[28:29], s30, v99
	v_cndmask_b32_e64 v92, 0, 32, s[22:23]
	v_cndmask_b32_e64 v93, 0, 32, s[24:25]
	v_cndmask_b32_e64 v94, 0, 32, s[26:27]
	v_cndmask_b32_e64 v95, 0, 32, s[28:29]
	v_ldexp_f32 v92, v96, v92
	v_ldexp_f32 v93, v97, v93
	v_ldexp_f32 v94, v98, v94
	v_ldexp_f32 v95, v99, v95
	v_log_f32_e32 v92, v92
	v_log_f32_e32 v93, v93
	v_log_f32_e32 v94, v94
	v_log_f32_e32 v95, v95
	v_mul_f32_e32 v100, 0x3f317217, v92
	v_mul_f32_e32 v101, 0x3f317217, v93
	v_mul_f32_e32 v102, 0x3f317217, v94
	v_mul_f32_e32 v103, 0x3f317217, v95
	v_fma_f32 v100, v92, s31, -v100
	v_fma_f32 v101, v93, s31, -v101
	v_fma_f32 v102, v94, s31, -v102
	v_fma_f32 v103, v95, s31, -v103
	v_fmac_f32_e32 v100, 0x3377d1cf, v92
	v_fmac_f32_e32 v101, 0x3377d1cf, v93
	v_fmac_f32_e32 v102, 0x3377d1cf, v94
	v_fmac_f32_e32 v103, 0x3377d1cf, v95
	v_fmac_f32_e32 v100, 0x3f317217, v92
	v_fmac_f32_e32 v101, 0x3f317217, v93
	v_fmac_f32_e32 v102, 0x3f317217, v94
	v_fmac_f32_e32 v103, 0x3f317217, v95
	v_cmp_lt_f32_e64 vcc, |v92|, s34
	v_cndmask_b32_e32 v92, v92, v100, vcc
	v_cmp_lt_f32_e64 vcc, |v93|, s34
	v_cndmask_b32_e32 v93, v93, v101, vcc
	v_cmp_lt_f32_e64 vcc, |v94|, s34
	v_cndmask_b32_e32 v94, v94, v102, vcc
	v_cmp_lt_f32_e64 vcc, |v95|, s34
	v_cndmask_b32_e32 v95, v95, v103, vcc
	v_cndmask_b32_e64 v100, 0, v213, s[22:23]
	v_cndmask_b32_e64 v101, 0, v213, s[24:25]
	v_cndmask_b32_e64 v102, 0, v213, s[26:27]
	v_cndmask_b32_e64 v103, 0, v213, s[28:29]
	v_sub_f32_e32 v92, v92, v100
	v_sub_f32_e32 v93, v93, v101
	v_sub_f32_e32 v94, v94, v102
	v_sub_f32_e32 v95, v95, v103
	v_add_f32_e32 v64, v64, v92
	v_add_f32_e32 v65, v65, v93
	v_add_f32_e32 v66, v66, v94
	v_add_f32_e32 v67, v67, v95
	v_mul_f32_e32 v92, 0xbfb8aa3b, v64
	v_mul_f32_e32 v93, 0xbfb8aa3b, v65
	v_mul_f32_e32 v94, 0xbfb8aa3b, v66
	v_mul_f32_e32 v95, 0xbfb8aa3b, v67
	v_mul_f32_e32 v100, 0x3fb8aa3b, v64
	v_mul_f32_e32 v101, 0x3fb8aa3b, v65
	v_mul_f32_e32 v102, 0x3fb8aa3b, v66
	v_mul_f32_e32 v103, 0x3fb8aa3b, v67
	v_exp_f32_e32 v92, v92
	v_exp_f32_e32 v93, v93
	v_exp_f32_e32 v94, v94
	v_exp_f32_e32 v95, v95
	v_exp_f32_e32 v100, v100
	v_exp_f32_e32 v101, v101
	v_exp_f32_e32 v102, v102
	v_exp_f32_e32 v103, v103
	v_sub_f32_e32 v96, 1.0, v96
	v_sub_f32_e32 v97, 1.0, v97
	v_sub_f32_e32 v98, 1.0, v98
	v_sub_f32_e32 v99, 1.0, v99
	v_mul_f32_e32 v96, v96, v92
	v_mul_f32_e32 v97, v97, v93
	v_mul_f32_e32 v98, v98, v94
	v_mul_f32_e32 v99, v99, v95
	v_lshlrev_b32_e32 v92, 16, v30
	v_and_b32_e32 v93, 0xffff0000, v30
	v_lshlrev_b32_e32 v94, 16, v31
	v_and_b32_e32 v95, 0xffff0000, v31
	v_mul_f32_e32 v92, v92, v100
	v_mul_f32_e32 v93, v93, v101
	v_mul_f32_e32 v94, v94, v102
	v_mul_f32_e32 v95, v95, v103
	v_cvt_pk_bf16_f32 v108, v92, v93
	v_cvt_pk_bf16_f32 v109, v94, v95
	v_cvt_pk_bf16_f32 v110, v96, v97
	v_cvt_pk_bf16_f32 v111, v98, v99
	global_store_dwordx2 v112, v[108:109], s[2:3]
	global_store_dwordx2 v114, v[110:111], s[2:3]
	s_sub_u32 s2, s2, 0x400
	s_subb_u32 s3, s3, 0
	v_cvt_pk_bf16_f32 v120, v96, v104
	v_cvt_pk_bf16_f32 v136, v97, v105
	v_cvt_pk_bf16_f32 v170, v98, v106
	v_cvt_pk_bf16_f32 v186, v99, v107
	global_load_dwordx2 v[0:1], v113, s[0:1]
	global_load_dwordx2 v[2:3], v112, s[0:1]
	s_sub_u32 s0, s0, 0x1400
	s_subb_u32 s1, s1, 0
	global_load_dwordx2 v[4:5], v113, s[0:1]
	global_load_dwordx2 v[6:7], v112, s[0:1]
	s_sub_u32 s0, s0, 0x1400
	s_subb_u32 s1, s1, 0
	global_load_dwordx2 v[8:9], v113, s[0:1]
	global_load_dwordx2 v[10:11], v112, s[0:1]
	s_sub_u32 s0, s0, 0x1400
	s_subb_u32 s1, s1, 0
	global_load_dwordx2 v[12:13], v113, s[0:1]
	global_load_dwordx2 v[14:15], v112, s[0:1]
	s_sub_u32 s0, s0, 0x1400
	s_subb_u32 s1, s1, 0
	global_load_dwordx2 v[16:17], v113, s[0:1]
	global_load_dwordx2 v[18:19], v112, s[0:1]
	s_sub_u32 s0, s0, 0x1400
	s_subb_u32 s1, s1, 0
	global_load_dwordx2 v[20:21], v113, s[0:1]
	global_load_dwordx2 v[22:23], v112, s[0:1]
	s_sub_u32 s0, s0, 0x1400
	s_subb_u32 s1, s1, 0
	global_load_dwordx2 v[24:25], v113, s[0:1]
	global_load_dwordx2 v[26:27], v112, s[0:1]
	s_sub_u32 s0, s0, 0x1400
	s_subb_u32 s1, s1, 0
	global_load_dwordx2 v[28:29], v113, s[0:1]
	global_load_dwordx2 v[30:31], v112, s[0:1]
	s_sub_u32 s0, s0, 0x1400
	s_subb_u32 s1, s1, 0
	s_waitcnt vmcnt(32)
; DEV u16 f2bf(float f) { return (u16)(pack2(f, f) & 0xffffu); }
; DEV float bf2f(u16 h) { return __uint_as_float(((unsigned)h) << 16); }
; DEV float sigmoid_f(float x) { return __builtin_amdgcn_rcpf(1.f + __expf(-x)); }
; DEV void phase_p15(const Params& p, int g) {
;     ...
;     for (int j8 = 0; j8 < 8; ++j8) {
;       const int st = j8 % 3;
;       if (j8 < 6) { P15_LOAD((j8 + 2) % 3, j8 + 2); }
; #pragma unroll
;       for (int cc = 0; cc < 2; ++cc) {
;         const int c = tid + 256 * cc;
;         unsigned kb[8];
; #pragma unroll
;         for (int e = 0; e < 8; ++e) {
;           const int jj = j8 * 8 + e;
;           const int j = dir ? 63 - jj : jj;
;           const size_t tok = (size_t)cidx * 64 + j;
;           const float f = lb[cc] + (1.f - lb[cc]) * sigmoid_f(bf2f(xr[st][cc][e]));
;           G[cc] += __logf(f);
;           const float eg = __expf(G[cc]), ig = __expf(-G[cc]);
;           Qp[tok * 512 + c] = f2bf(bf2f(qr[st][cc][e]) * eg);
;           const u16 kk = f2bf((1.f - f) * ig);
;           Kp[tok * 512 + c] = kk;
;           kb[e] = kk;
;         }
;         const int s0 = dir ? 56 - 8 * j8 : 8 * j8;
;         uint4 w;
;         w.x = dir ? (kb[7] | (kb[6] << 16)) : (kb[0] | (kb[1] << 16));
;         w.y = dir ? (kb[5] | (kb[4] << 16)) : (kb[2] | (kb[3] << 16));
;         w.z = dir ? (kb[3] | (kb[2] << 16)) : (kb[4] | (kb[5] << 16));
;         w.w = dir ? (kb[1] | (kb[0] << 16)) : (kb[6] | (kb[7] << 16));
;         *(uint4*)(KT + (((size_t)cidx * 2 + dir) * 512 + c) * 64 + s0) = w;
;       }
	v_lshlrev_b32_e32 v92, 16, v32
	v_and_b32_e32 v93, 0xffff0000, v32
	v_lshlrev_b32_e32 v94, 16, v33
	v_and_b32_e32 v95, 0xffff0000, v33
	v_mul_f32_e32 v92, 0xbfb8aa3b, v92
	v_mul_f32_e32 v93, 0xbfb8aa3b, v93
	v_mul_f32_e32 v94, 0xbfb8aa3b, v94
	v_mul_f32_e32 v95, 0xbfb8aa3b, v95
	v_exp_f32_e32 v92, v92
	v_exp_f32_e32 v93, v93
	v_exp_f32_e32 v94, v94
	v_exp_f32_e32 v95, v95
	v_add_f32_e32 v92, 1.0, v92
	v_add_f32_e32 v93, 1.0, v93
	v_add_f32_e32 v94, 1.0, v94
	v_add_f32_e32 v95, 1.0, v95
	v_rcp_f32_e32 v92, v92
	v_rcp_f32_e32 v93, v93
	v_rcp_f32_e32 v94, v94
	v_rcp_f32_e32 v95, v95
	v_fma_f32 v96, v72, v92, v68
	v_fma_f32 v97, v73, v93, v69
	v_fma_f32 v98, v74, v94, v70
	v_fma_f32 v99, v75, v95, v71
	v_cmp_gt_f32_e64 s[22:23], s30, v96
	v_cmp_gt_f32_e64 s[24:25], s30, v97
	v_cmp_gt_f32_e64 s[26:27], s30, v98
	v_cmp_gt_f32_e64 s[28:29], s30, v99
	v_cndmask_b32_e64 v92, 0, 32, s[22:23]
	v_cndmask_b32_e64 v93, 0, 32, s[24:25]
	v_cndmask_b32_e64 v94, 0, 32, s[26:27]
	v_cndmask_b32_e64 v95, 0, 32, s[28:29]
	v_ldexp_f32 v92, v96, v92
	v_ldexp_f32 v93, v97, v93
	v_ldexp_f32 v94, v98, v94
	v_ldexp_f32 v95, v99, v95
	v_log_f32_e32 v92, v92
	v_log_f32_e32 v93, v93
	v_log_f32_e32 v94, v94
	v_log_f32_e32 v95, v95
	v_mul_f32_e32 v100, 0x3f317217, v92
	v_mul_f32_e32 v101, 0x3f317217, v93
	v_mul_f32_e32 v102, 0x3f317217, v94
	v_mul_f32_e32 v103, 0x3f317217, v95
	v_fma_f32 v100, v92, s31, -v100
	v_fma_f32 v101, v93, s31, -v101
	v_fma_f32 v102, v94, s31, -v102
	v_fma_f32 v103, v95, s31, -v103
	v_fmac_f32_e32 v100, 0x3377d1cf, v92
	v_fmac_f32_e32 v101, 0x3377d1cf, v93
	v_fmac_f32_e32 v102, 0x3377d1cf, v94
	v_fmac_f32_e32 v103, 0x3377d1cf, v95
	v_fmac_f32_e32 v100, 0x3f317217, v92
	v_fmac_f32_e32 v101, 0x3f317217, v93
	v_fmac_f32_e32 v102, 0x3f317217, v94
	v_fmac_f32_e32 v103, 0x3f317217, v95
	v_cmp_lt_f32_e64 vcc, |v92|, s34
	v_cndmask_b32_e32 v92, v92, v100, vcc
	v_cmp_lt_f32_e64 vcc, |v93|, s34
	v_cndmask_b32_e32 v93, v93, v101, vcc
	v_cmp_lt_f32_e64 vcc, |v94|, s34
	v_cndmask_b32_e32 v94, v94, v102, vcc
	v_cmp_lt_f32_e64 vcc, |v95|, s34
	v_cndmask_b32_e32 v95, v95, v103, vcc
	v_cndmask_b32_e64 v100, 0, v213, s[22:23]
	v_cndmask_b32_e64 v101, 0, v213, s[24:25]
	v_cndmask_b32_e64 v102, 0, v213, s[26:27]
	v_cndmask_b32_e64 v103, 0, v213, s[28:29]
	v_sub_f32_e32 v92, v92, v100
	v_sub_f32_e32 v93, v93, v101
	v_sub_f32_e32 v94, v94, v102
	v_sub_f32_e32 v95, v95, v103
	v_add_f32_e32 v64, v64, v92
	v_add_f32_e32 v65, v65, v93
	v_add_f32_e32 v66, v66, v94
	v_add_f32_e32 v67, v67, v95
	v_mul_f32_e32 v92, 0xbfb8aa3b, v64
	v_mul_f32_e32 v93, 0xbfb8aa3b, v65
	v_mul_f32_e32 v94, 0xbfb8aa3b, v66
	v_mul_f32_e32 v95, 0xbfb8aa3b, v67
	v_mul_f32_e32 v100, 0x3fb8aa3b, v64
	v_mul_f32_e32 v101, 0x3fb8aa3b, v65
	v_mul_f32_e32 v102, 0x3fb8aa3b, v66
	v_mul_f32_e32 v103, 0x3fb8aa3b, v67
	v_exp_f32_e32 v92, v92
	v_exp_f32_e32 v93, v93
	v_exp_f32_e32 v94, v94
	v_exp_f32_e32 v95, v95
	v_exp_f32_e32 v100, v100
	v_exp_f32_e32 v101, v101
	v_exp_f32_e32 v102, v102
	v_exp_f32_e32 v103, v103
	v_sub_f32_e32 v96, 1.0, v96
	v_sub_f32_e32 v97, 1.0, v97
	v_sub_f32_e32 v98, 1.0, v98
	v_sub_f32_e32 v99, 1.0, v99
	v_mul_f32_e32 v96, v96, v92
	v_mul_f32_e32 v97, v97, v93
	v_mul_f32_e32 v98, v98, v94
	v_mul_f32_e32 v99, v99, v95
	v_lshlrev_b32_e32 v92, 16, v34
	v_and_b32_e32 v93, 0xffff0000, v34
	v_lshlrev_b32_e32 v94, 16, v35
	v_and_b32_e32 v95, 0xffff0000, v35
	v_mul_f32_e32 v92, v92, v100
	v_mul_f32_e32 v93, v93, v101
	v_mul_f32_e32 v94, v94, v102
	v_mul_f32_e32 v95, v95, v103
	v_cvt_pk_bf16_f32 v108, v92, v93
	v_cvt_pk_bf16_f32 v109, v94, v95
	v_cvt_pk_bf16_f32 v110, v96, v97
	v_cvt_pk_bf16_f32 v111, v98, v99
	global_store_dwordx2 v112, v[108:109], s[2:3]
	global_store_dwordx2 v114, v[110:111], s[2:3]
	s_sub_u32 s2, s2, 0x400
	s_subb_u32 s3, s3, 0
	v_mov_b32_e32 v104, v96
	v_mov_b32_e32 v105, v97
	v_mov_b32_e32 v106, v98
	v_mov_b32_e32 v107, v99
	v_lshlrev_b32_e32 v92, 16, v36
	v_and_b32_e32 v93, 0xffff0000, v36
	v_lshlrev_b32_e32 v94, 16, v37
	v_and_b32_e32 v95, 0xffff0000, v37
	v_mul_f32_e32 v92, 0xbfb8aa3b, v92
	v_mul_f32_e32 v93, 0xbfb8aa3b, v93
	v_mul_f32_e32 v94, 0xbfb8aa3b, v94
	v_mul_f32_e32 v95, 0xbfb8aa3b, v95
	v_exp_f32_e32 v92, v92
	v_exp_f32_e32 v93, v93
	v_exp_f32_e32 v94, v94
	v_exp_f32_e32 v95, v95
	v_add_f32_e32 v92, 1.0, v92
	v_add_f32_e32 v93, 1.0, v93
	v_add_f32_e32 v94, 1.0, v94
	v_add_f32_e32 v95, 1.0, v95
	v_rcp_f32_e32 v92, v92
	v_rcp_f32_e32 v93, v93
	v_rcp_f32_e32 v94, v94
	v_rcp_f32_e32 v95, v95
	v_fma_f32 v96, v72, v92, v68
	v_fma_f32 v97, v73, v93, v69
	v_fma_f32 v98, v74, v94, v70
	v_fma_f32 v99, v75, v95, v71
	v_cmp_gt_f32_e64 s[22:23], s30, v96
	v_cmp_gt_f32_e64 s[24:25], s30, v97
	v_cmp_gt_f32_e64 s[26:27], s30, v98
	v_cmp_gt_f32_e64 s[28:29], s30, v99
	v_cndmask_b32_e64 v92, 0, 32, s[22:23]
	v_cndmask_b32_e64 v93, 0, 32, s[24:25]
	v_cndmask_b32_e64 v94, 0, 32, s[26:27]
	v_cndmask_b32_e64 v95, 0, 32, s[28:29]
	v_ldexp_f32 v92, v96, v92
	v_ldexp_f32 v93, v97, v93
	v_ldexp_f32 v94, v98, v94
	v_ldexp_f32 v95, v99, v95
	v_log_f32_e32 v92, v92
	v_log_f32_e32 v93, v93
	v_log_f32_e32 v94, v94
	v_log_f32_e32 v95, v95
	v_mul_f32_e32 v100, 0x3f317217, v92
	v_mul_f32_e32 v101, 0x3f317217, v93
	v_mul_f32_e32 v102, 0x3f317217, v94
	v_mul_f32_e32 v103, 0x3f317217, v95
	v_fma_f32 v100, v92, s31, -v100
	v_fma_f32 v101, v93, s31, -v101
	v_fma_f32 v102, v94, s31, -v102
	v_fma_f32 v103, v95, s31, -v103
	v_fmac_f32_e32 v100, 0x3377d1cf, v92
	v_fmac_f32_e32 v101, 0x3377d1cf, v93
	v_fmac_f32_e32 v102, 0x3377d1cf, v94
	v_fmac_f32_e32 v103, 0x3377d1cf, v95
	v_fmac_f32_e32 v100, 0x3f317217, v92
	v_fmac_f32_e32 v101, 0x3f317217, v93
	v_fmac_f32_e32 v102, 0x3f317217, v94
; DEV u16 f2bf(float f) { return (u16)(pack2(f, f) & 0xffffu); }
; DEV float bf2f(u16 h) { return __uint_as_float(((unsigned)h) << 16); }
; DEV float sigmoid_f(float x) { return __builtin_amdgcn_rcpf(1.f + __expf(-x)); }
; DEV void phase_p15(const Params& p, int g) {
;     ...
;     for (int j8 = 0; j8 < 8; ++j8) {
;       const int st = j8 % 3;
;       if (j8 < 6) { P15_LOAD((j8 + 2) % 3, j8 + 2); }
; #pragma unroll
;       for (int cc = 0; cc < 2; ++cc) {
;         const int c = tid + 256 * cc;
;         unsigned kb[8];
; #pragma unroll
;         for (int e = 0; e < 8; ++e) {
;           const int jj = j8 * 8 + e;
;           const int j = dir ? 63 - jj : jj;
;           const size_t tok = (size_t)cidx * 64 + j;
;           const float f = lb[cc] + (1.f - lb[cc]) * sigmoid_f(bf2f(xr[st][cc][e]));
;           G[cc] += __logf(f);
;           const float eg = __expf(G[cc]), ig = __expf(-G[cc]);
;           Qp[tok * 512 + c] = f2bf(bf2f(qr[st][cc][e]) * eg);
;           const u16 kk = f2bf((1.f - f) * ig);
;           Kp[tok * 512 + c] = kk;
;           kb[e] = kk;
;         }
;         const int s0 = dir ? 56 - 8 * j8 : 8 * j8;
;         uint4 w;
;         w.x = dir ? (kb[7] | (kb[6] << 16)) : (kb[0] | (kb[1] << 16));
;         w.y = dir ? (kb[5] | (kb[4] << 16)) : (kb[2] | (kb[3] << 16));
;         w.z = dir ? (kb[3] | (kb[2] << 16)) : (kb[4] | (kb[5] << 16));
;         w.w = dir ? (kb[1] | (kb[0] << 16)) : (kb[6] | (kb[7] << 16));
;         *(uint4*)(KT + (((size_t)cidx * 2 + dir) * 512 + c) * 64 + s0) = w;
;       }
	v_fmac_f32_e32 v103, 0x3f317217, v95
	v_cmp_lt_f32_e64 vcc, |v92|, s34
	v_cndmask_b32_e32 v92, v92, v100, vcc
	v_cmp_lt_f32_e64 vcc, |v93|, s34
	v_cndmask_b32_e32 v93, v93, v101, vcc
	v_cmp_lt_f32_e64 vcc, |v94|, s34
	v_cndmask_b32_e32 v94, v94, v102, vcc
	v_cmp_lt_f32_e64 vcc, |v95|, s34
	v_cndmask_b32_e32 v95, v95, v103, vcc
	v_cndmask_b32_e64 v100, 0, v213, s[22:23]
	v_cndmask_b32_e64 v101, 0, v213, s[24:25]
	v_cndmask_b32_e64 v102, 0, v213, s[26:27]
	v_cndmask_b32_e64 v103, 0, v213, s[28:29]
	v_sub_f32_e32 v92, v92, v100
	v_sub_f32_e32 v93, v93, v101
	v_sub_f32_e32 v94, v94, v102
	v_sub_f32_e32 v95, v95, v103
	v_add_f32_e32 v64, v64, v92
	v_add_f32_e32 v65, v65, v93
	v_add_f32_e32 v66, v66, v94
	v_add_f32_e32 v67, v67, v95
	v_mul_f32_e32 v92, 0xbfb8aa3b, v64
	v_mul_f32_e32 v93, 0xbfb8aa3b, v65
	v_mul_f32_e32 v94, 0xbfb8aa3b, v66
	v_mul_f32_e32 v95, 0xbfb8aa3b, v67
	v_mul_f32_e32 v100, 0x3fb8aa3b, v64
	v_mul_f32_e32 v101, 0x3fb8aa3b, v65
	v_mul_f32_e32 v102, 0x3fb8aa3b, v66
	v_mul_f32_e32 v103, 0x3fb8aa3b, v67
	v_exp_f32_e32 v92, v92
	v_exp_f32_e32 v93, v93
	v_exp_f32_e32 v94, v94
	v_exp_f32_e32 v95, v95
	v_exp_f32_e32 v100, v100
	v_exp_f32_e32 v101, v101
	v_exp_f32_e32 v102, v102
	v_exp_f32_e32 v103, v103
	v_sub_f32_e32 v96, 1.0, v96
	v_sub_f32_e32 v97, 1.0, v97
	v_sub_f32_e32 v98, 1.0, v98
	v_sub_f32_e32 v99, 1.0, v99
	v_mul_f32_e32 v96, v96, v92
	v_mul_f32_e32 v97, v97, v93
	v_mul_f32_e32 v98, v98, v94
	v_mul_f32_e32 v99, v99, v95
	v_lshlrev_b32_e32 v92, 16, v38
	v_and_b32_e32 v93, 0xffff0000, v38
	v_lshlrev_b32_e32 v94, 16, v39
	v_and_b32_e32 v95, 0xffff0000, v39
	v_mul_f32_e32 v92, v92, v100
	v_mul_f32_e32 v93, v93, v101
	v_mul_f32_e32 v94, v94, v102
	v_mul_f32_e32 v95, v95, v103
	v_cvt_pk_bf16_f32 v108, v92, v93
	v_cvt_pk_bf16_f32 v109, v94, v95
	v_cvt_pk_bf16_f32 v110, v96, v97
	v_cvt_pk_bf16_f32 v111, v98, v99
	global_store_dwordx2 v112, v[108:109], s[2:3]
	global_store_dwordx2 v114, v[110:111], s[2:3]
	s_sub_u32 s2, s2, 0x400
	s_subb_u32 s3, s3, 0
	v_cvt_pk_bf16_f32 v119, v96, v104
	v_cvt_pk_bf16_f32 v135, v97, v105
	v_cvt_pk_bf16_f32 v169, v98, v106
	v_cvt_pk_bf16_f32 v185, v99, v107
	v_lshlrev_b32_e32 v92, 16, v40
	v_and_b32_e32 v93, 0xffff0000, v40
	v_lshlrev_b32_e32 v94, 16, v41
	v_and_b32_e32 v95, 0xffff0000, v41
	v_mul_f32_e32 v92, 0xbfb8aa3b, v92
	v_mul_f32_e32 v93, 0xbfb8aa3b, v93
	v_mul_f32_e32 v94, 0xbfb8aa3b, v94
	v_mul_f32_e32 v95, 0xbfb8aa3b, v95
	v_exp_f32_e32 v92, v92
	v_exp_f32_e32 v93, v93
	v_exp_f32_e32 v94, v94
	v_exp_f32_e32 v95, v95
	v_add_f32_e32 v92, 1.0, v92
	v_add_f32_e32 v93, 1.0, v93
	v_add_f32_e32 v94, 1.0, v94
	v_add_f32_e32 v95, 1.0, v95
	v_rcp_f32_e32 v92, v92
	v_rcp_f32_e32 v93, v93
	v_rcp_f32_e32 v94, v94
	v_rcp_f32_e32 v95, v95
	v_fma_f32 v96, v72, v92, v68
	v_fma_f32 v97, v73, v93, v69
	v_fma_f32 v98, v74, v94, v70
	v_fma_f32 v99, v75, v95, v71
	v_cmp_gt_f32_e64 s[22:23], s30, v96
	v_cmp_gt_f32_e64 s[24:25], s30, v97
	v_cmp_gt_f32_e64 s[26:27], s30, v98
	v_cmp_gt_f32_e64 s[28:29], s30, v99
	v_cndmask_b32_e64 v92, 0, 32, s[22:23]
	v_cndmask_b32_e64 v93, 0, 32, s[24:25]
	v_cndmask_b32_e64 v94, 0, 32, s[26:27]
	v_cndmask_b32_e64 v95, 0, 32, s[28:29]
	v_ldexp_f32 v92, v96, v92
	v_ldexp_f32 v93, v97, v93
	v_ldexp_f32 v94, v98, v94
	v_ldexp_f32 v95, v99, v95
	v_log_f32_e32 v92, v92
	v_log_f32_e32 v93, v93
	v_log_f32_e32 v94, v94
	v_log_f32_e32 v95, v95
	v_mul_f32_e32 v100, 0x3f317217, v92
	v_mul_f32_e32 v101, 0x3f317217, v93
	v_mul_f32_e32 v102, 0x3f317217, v94
	v_mul_f32_e32 v103, 0x3f317217, v95
	v_fma_f32 v100, v92, s31, -v100
	v_fma_f32 v101, v93, s31, -v101
	v_fma_f32 v102, v94, s31, -v102
	v_fma_f32 v103, v95, s31, -v103
	v_fmac_f32_e32 v100, 0x3377d1cf, v92
	v_fmac_f32_e32 v101, 0x3377d1cf, v93
	v_fmac_f32_e32 v102, 0x3377d1cf, v94
	v_fmac_f32_e32 v103, 0x3377d1cf, v95
	v_fmac_f32_e32 v100, 0x3f317217, v92
	v_fmac_f32_e32 v101, 0x3f317217, v93
	v_fmac_f32_e32 v102, 0x3f317217, v94
	v_fmac_f32_e32 v103, 0x3f317217, v95
	v_cmp_lt_f32_e64 vcc, |v92|, s34
	v_cndmask_b32_e32 v92, v92, v100, vcc
	v_cmp_lt_f32_e64 vcc, |v93|, s34
	v_cndmask_b32_e32 v93, v93, v101, vcc
	v_cmp_lt_f32_e64 vcc, |v94|, s34
	v_cndmask_b32_e32 v94, v94, v102, vcc
	v_cmp_lt_f32_e64 vcc, |v95|, s34
	v_cndmask_b32_e32 v95, v95, v103, vcc
	v_cndmask_b32_e64 v100, 0, v213, s[22:23]
	v_cndmask_b32_e64 v101, 0, v213, s[24:25]
	v_cndmask_b32_e64 v102, 0, v213, s[26:27]
	v_cndmask_b32_e64 v103, 0, v213, s[28:29]
	v_sub_f32_e32 v92, v92, v100
	v_sub_f32_e32 v93, v93, v101
	v_sub_f32_e32 v94, v94, v102
	v_sub_f32_e32 v95, v95, v103
	v_add_f32_e32 v64, v64, v92
	v_add_f32_e32 v65, v65, v93
	v_add_f32_e32 v66, v66, v94
	v_add_f32_e32 v67, v67, v95
	v_mul_f32_e32 v92, 0xbfb8aa3b, v64
	v_mul_f32_e32 v93, 0xbfb8aa3b, v65
	v_mul_f32_e32 v94, 0xbfb8aa3b, v66
	v_mul_f32_e32 v95, 0xbfb8aa3b, v67
	v_mul_f32_e32 v100, 0x3fb8aa3b, v64
	v_mul_f32_e32 v101, 0x3fb8aa3b, v65
	v_mul_f32_e32 v102, 0x3fb8aa3b, v66
	v_mul_f32_e32 v103, 0x3fb8aa3b, v67
	v_exp_f32_e32 v92, v92
	v_exp_f32_e32 v93, v93
	v_exp_f32_e32 v94, v94
	v_exp_f32_e32 v95, v95
	v_exp_f32_e32 v100, v100
	v_exp_f32_e32 v101, v101
	v_exp_f32_e32 v102, v102
	v_exp_f32_e32 v103, v103
	v_sub_f32_e32 v96, 1.0, v96
	v_sub_f32_e32 v97, 1.0, v97
	v_sub_f32_e32 v98, 1.0, v98
	v_sub_f32_e32 v99, 1.0, v99
	v_mul_f32_e32 v96, v96, v92
	v_mul_f32_e32 v97, v97, v93
	v_mul_f32_e32 v98, v98, v94
	v_mul_f32_e32 v99, v99, v95
	v_lshlrev_b32_e32 v92, 16, v42
	v_and_b32_e32 v93, 0xffff0000, v42
	v_lshlrev_b32_e32 v94, 16, v43
	v_and_b32_e32 v95, 0xffff0000, v43
	v_mul_f32_e32 v92, v92, v100
	v_mul_f32_e32 v93, v93, v101
	v_mul_f32_e32 v94, v94, v102
	v_mul_f32_e32 v95, v95, v103
	v_cvt_pk_bf16_f32 v108, v92, v93
; DEV u16 f2bf(float f) { return (u16)(pack2(f, f) & 0xffffu); }
; DEV float bf2f(u16 h) { return __uint_as_float(((unsigned)h) << 16); }
; DEV float sigmoid_f(float x) { return __builtin_amdgcn_rcpf(1.f + __expf(-x)); }
; DEV void phase_p15(const Params& p, int g) {
;     ...
;     for (int j8 = 0; j8 < 8; ++j8) {
;       const int st = j8 % 3;
;       if (j8 < 6) { P15_LOAD((j8 + 2) % 3, j8 + 2); }
; #pragma unroll
;       for (int cc = 0; cc < 2; ++cc) {
;         const int c = tid + 256 * cc;
;         unsigned kb[8];
; #pragma unroll
;         for (int e = 0; e < 8; ++e) {
;           const int jj = j8 * 8 + e;
;           const int j = dir ? 63 - jj : jj;
;           const size_t tok = (size_t)cidx * 64 + j;
;           const float f = lb[cc] + (1.f - lb[cc]) * sigmoid_f(bf2f(xr[st][cc][e]));
;           G[cc] += __logf(f);
;           const float eg = __expf(G[cc]), ig = __expf(-G[cc]);
;           Qp[tok * 512 + c] = f2bf(bf2f(qr[st][cc][e]) * eg);
;           const u16 kk = f2bf((1.f - f) * ig);
;           Kp[tok * 512 + c] = kk;
;           kb[e] = kk;
;         }
;         const int s0 = dir ? 56 - 8 * j8 : 8 * j8;
;         uint4 w;
;         w.x = dir ? (kb[7] | (kb[6] << 16)) : (kb[0] | (kb[1] << 16));
;         w.y = dir ? (kb[5] | (kb[4] << 16)) : (kb[2] | (kb[3] << 16));
;         w.z = dir ? (kb[3] | (kb[2] << 16)) : (kb[4] | (kb[5] << 16));
;         w.w = dir ? (kb[1] | (kb[0] << 16)) : (kb[6] | (kb[7] << 16));
;         *(uint4*)(KT + (((size_t)cidx * 2 + dir) * 512 + c) * 64 + s0) = w;
;       }
	v_cvt_pk_bf16_f32 v109, v94, v95
	v_cvt_pk_bf16_f32 v110, v96, v97
	v_cvt_pk_bf16_f32 v111, v98, v99
	global_store_dwordx2 v112, v[108:109], s[2:3]
	global_store_dwordx2 v114, v[110:111], s[2:3]
	s_sub_u32 s2, s2, 0x400
	s_subb_u32 s3, s3, 0
	v_mov_b32_e32 v104, v96
	v_mov_b32_e32 v105, v97
	v_mov_b32_e32 v106, v98
	v_mov_b32_e32 v107, v99
	v_lshlrev_b32_e32 v92, 16, v44
	v_and_b32_e32 v93, 0xffff0000, v44
	v_lshlrev_b32_e32 v94, 16, v45
	v_and_b32_e32 v95, 0xffff0000, v45
	v_mul_f32_e32 v92, 0xbfb8aa3b, v92
	v_mul_f32_e32 v93, 0xbfb8aa3b, v93
	v_mul_f32_e32 v94, 0xbfb8aa3b, v94
	v_mul_f32_e32 v95, 0xbfb8aa3b, v95
	v_exp_f32_e32 v92, v92
	v_exp_f32_e32 v93, v93
	v_exp_f32_e32 v94, v94
	v_exp_f32_e32 v95, v95
	v_add_f32_e32 v92, 1.0, v92
	v_add_f32_e32 v93, 1.0, v93
	v_add_f32_e32 v94, 1.0, v94
	v_add_f32_e32 v95, 1.0, v95
	v_rcp_f32_e32 v92, v92
	v_rcp_f32_e32 v93, v93
	v_rcp_f32_e32 v94, v94
	v_rcp_f32_e32 v95, v95
	v_fma_f32 v96, v72, v92, v68
	v_fma_f32 v97, v73, v93, v69
	v_fma_f32 v98, v74, v94, v70
	v_fma_f32 v99, v75, v95, v71
	v_cmp_gt_f32_e64 s[22:23], s30, v96
	v_cmp_gt_f32_e64 s[24:25], s30, v97
	v_cmp_gt_f32_e64 s[26:27], s30, v98
	v_cmp_gt_f32_e64 s[28:29], s30, v99
	v_cndmask_b32_e64 v92, 0, 32, s[22:23]
	v_cndmask_b32_e64 v93, 0, 32, s[24:25]
	v_cndmask_b32_e64 v94, 0, 32, s[26:27]
	v_cndmask_b32_e64 v95, 0, 32, s[28:29]
	v_ldexp_f32 v92, v96, v92
	v_ldexp_f32 v93, v97, v93
	v_ldexp_f32 v94, v98, v94
	v_ldexp_f32 v95, v99, v95
	v_log_f32_e32 v92, v92
	v_log_f32_e32 v93, v93
	v_log_f32_e32 v94, v94
	v_log_f32_e32 v95, v95
	v_mul_f32_e32 v100, 0x3f317217, v92
	v_mul_f32_e32 v101, 0x3f317217, v93
	v_mul_f32_e32 v102, 0x3f317217, v94
	v_mul_f32_e32 v103, 0x3f317217, v95
	v_fma_f32 v100, v92, s31, -v100
	v_fma_f32 v101, v93, s31, -v101
	v_fma_f32 v102, v94, s31, -v102
	v_fma_f32 v103, v95, s31, -v103
	v_fmac_f32_e32 v100, 0x3377d1cf, v92
	v_fmac_f32_e32 v101, 0x3377d1cf, v93
	v_fmac_f32_e32 v102, 0x3377d1cf, v94
	v_fmac_f32_e32 v103, 0x3377d1cf, v95
	v_fmac_f32_e32 v100, 0x3f317217, v92
	v_fmac_f32_e32 v101, 0x3f317217, v93
	v_fmac_f32_e32 v102, 0x3f317217, v94
	v_fmac_f32_e32 v103, 0x3f317217, v95
	v_cmp_lt_f32_e64 vcc, |v92|, s34
	v_cndmask_b32_e32 v92, v92, v100, vcc
	v_cmp_lt_f32_e64 vcc, |v93|, s34
	v_cndmask_b32_e32 v93, v93, v101, vcc
	v_cmp_lt_f32_e64 vcc, |v94|, s34
	v_cndmask_b32_e32 v94, v94, v102, vcc
	v_cmp_lt_f32_e64 vcc, |v95|, s34
	v_cndmask_b32_e32 v95, v95, v103, vcc
	v_cndmask_b32_e64 v100, 0, v213, s[22:23]
	v_cndmask_b32_e64 v101, 0, v213, s[24:25]
	v_cndmask_b32_e64 v102, 0, v213, s[26:27]
	v_cndmask_b32_e64 v103, 0, v213, s[28:29]
	v_sub_f32_e32 v92, v92, v100
	v_sub_f32_e32 v93, v93, v101
	v_sub_f32_e32 v94, v94, v102
	v_sub_f32_e32 v95, v95, v103
	v_add_f32_e32 v64, v64, v92
	v_add_f32_e32 v65, v65, v93
	v_add_f32_e32 v66, v66, v94
	v_add_f32_e32 v67, v67, v95
	v_mul_f32_e32 v92, 0xbfb8aa3b, v64
	v_mul_f32_e32 v93, 0xbfb8aa3b, v65
	v_mul_f32_e32 v94, 0xbfb8aa3b, v66
	v_mul_f32_e32 v95, 0xbfb8aa3b, v67
	v_mul_f32_e32 v100, 0x3fb8aa3b, v64
	v_mul_f32_e32 v101, 0x3fb8aa3b, v65
	v_mul_f32_e32 v102, 0x3fb8aa3b, v66
	v_mul_f32_e32 v103, 0x3fb8aa3b, v67
	v_exp_f32_e32 v92, v92
	v_exp_f32_e32 v93, v93
	v_exp_f32_e32 v94, v94
	v_exp_f32_e32 v95, v95
	v_exp_f32_e32 v100, v100
	v_exp_f32_e32 v101, v101
	v_exp_f32_e32 v102, v102
	v_exp_f32_e32 v103, v103
	v_sub_f32_e32 v96, 1.0, v96
	v_sub_f32_e32 v97, 1.0, v97
	v_sub_f32_e32 v98, 1.0, v98
	v_sub_f32_e32 v99, 1.0, v99
	v_mul_f32_e32 v96, v96, v92
	v_mul_f32_e32 v97, v97, v93
	v_mul_f32_e32 v98, v98, v94
	v_mul_f32_e32 v99, v99, v95
	v_lshlrev_b32_e32 v92, 16, v46
	v_and_b32_e32 v93, 0xffff0000, v46
	v_lshlrev_b32_e32 v94, 16, v47
	v_and_b32_e32 v95, 0xffff0000, v47
	v_mul_f32_e32 v92, v92, v100
	v_mul_f32_e32 v93, v93, v101
	v_mul_f32_e32 v94, v94, v102
	v_mul_f32_e32 v95, v95, v103
	v_cvt_pk_bf16_f32 v108, v92, v93
	v_cvt_pk_bf16_f32 v109, v94, v95
	v_cvt_pk_bf16_f32 v110, v96, v97
	v_cvt_pk_bf16_f32 v111, v98, v99
	global_store_dwordx2 v112, v[108:109], s[2:3]
	global_store_dwordx2 v114, v[110:111], s[2:3]
	s_sub_u32 s2, s2, 0x400
	s_subb_u32 s3, s3, 0
	v_cvt_pk_bf16_f32 v118, v96, v104
	v_cvt_pk_bf16_f32 v134, v97, v105
	v_cvt_pk_bf16_f32 v168, v98, v106
	v_cvt_pk_bf16_f32 v184, v99, v107
	v_lshlrev_b32_e32 v92, 16, v48
	v_and_b32_e32 v93, 0xffff0000, v48
	v_lshlrev_b32_e32 v94, 16, v49
	v_and_b32_e32 v95, 0xffff0000, v49
	v_mul_f32_e32 v92, 0xbfb8aa3b, v92
	v_mul_f32_e32 v93, 0xbfb8aa3b, v93
	v_mul_f32_e32 v94, 0xbfb8aa3b, v94
	v_mul_f32_e32 v95, 0xbfb8aa3b, v95
	v_exp_f32_e32 v92, v92
	v_exp_f32_e32 v93, v93
	v_exp_f32_e32 v94, v94
	v_exp_f32_e32 v95, v95
	v_add_f32_e32 v92, 1.0, v92
	v_add_f32_e32 v93, 1.0, v93
	v_add_f32_e32 v94, 1.0, v94
	v_add_f32_e32 v95, 1.0, v95
	v_rcp_f32_e32 v92, v92
	v_rcp_f32_e32 v93, v93
	v_rcp_f32_e32 v94, v94
	v_rcp_f32_e32 v95, v95
	v_fma_f32 v96, v72, v92, v68
	v_fma_f32 v97, v73, v93, v69
	v_fma_f32 v98, v74, v94, v70
	v_fma_f32 v99, v75, v95, v71
	v_cmp_gt_f32_e64 s[22:23], s30, v96
	v_cmp_gt_f32_e64 s[24:25], s30, v97
	v_cmp_gt_f32_e64 s[26:27], s30, v98
	v_cmp_gt_f32_e64 s[28:29], s30, v99
	v_cndmask_b32_e64 v92, 0, 32, s[22:23]
	v_cndmask_b32_e64 v93, 0, 32, s[24:25]
	v_cndmask_b32_e64 v94, 0, 32, s[26:27]
	v_cndmask_b32_e64 v95, 0, 32, s[28:29]
	v_ldexp_f32 v92, v96, v92
	v_ldexp_f32 v93, v97, v93
	v_ldexp_f32 v94, v98, v94
	v_ldexp_f32 v95, v99, v95
	v_log_f32_e32 v92, v92
	v_log_f32_e32 v93, v93
	v_log_f32_e32 v94, v94
	v_log_f32_e32 v95, v95
	v_mul_f32_e32 v100, 0x3f317217, v92
	v_mul_f32_e32 v101, 0x3f317217, v93
	v_mul_f32_e32 v102, 0x3f317217, v94
	v_mul_f32_e32 v103, 0x3f317217, v95
	v_fma_f32 v100, v92, s31, -v100
; DEV u16 f2bf(float f) { return (u16)(pack2(f, f) & 0xffffu); }
; DEV float bf2f(u16 h) { return __uint_as_float(((unsigned)h) << 16); }
; DEV float sigmoid_f(float x) { return __builtin_amdgcn_rcpf(1.f + __expf(-x)); }
; DEV void phase_p15(const Params& p, int g) {
;     ...
;     for (int j8 = 0; j8 < 8; ++j8) {
;       const int st = j8 % 3;
;       if (j8 < 6) { P15_LOAD((j8 + 2) % 3, j8 + 2); }
; #pragma unroll
;       for (int cc = 0; cc < 2; ++cc) {
;         const int c = tid + 256 * cc;
;         unsigned kb[8];
; #pragma unroll
;         for (int e = 0; e < 8; ++e) {
;           const int jj = j8 * 8 + e;
;           const int j = dir ? 63 - jj : jj;
;           const size_t tok = (size_t)cidx * 64 + j;
;           const float f = lb[cc] + (1.f - lb[cc]) * sigmoid_f(bf2f(xr[st][cc][e]));
;           G[cc] += __logf(f);
;           const float eg = __expf(G[cc]), ig = __expf(-G[cc]);
;           Qp[tok * 512 + c] = f2bf(bf2f(qr[st][cc][e]) * eg);
;           const u16 kk = f2bf((1.f - f) * ig);
;           Kp[tok * 512 + c] = kk;
;           kb[e] = kk;
;         }
;         const int s0 = dir ? 56 - 8 * j8 : 8 * j8;
;         uint4 w;
;         w.x = dir ? (kb[7] | (kb[6] << 16)) : (kb[0] | (kb[1] << 16));
;         w.y = dir ? (kb[5] | (kb[4] << 16)) : (kb[2] | (kb[3] << 16));
;         w.z = dir ? (kb[3] | (kb[2] << 16)) : (kb[4] | (kb[5] << 16));
;         w.w = dir ? (kb[1] | (kb[0] << 16)) : (kb[6] | (kb[7] << 16));
;         *(uint4*)(KT + (((size_t)cidx * 2 + dir) * 512 + c) * 64 + s0) = w;
;       }
	v_fma_f32 v101, v93, s31, -v101
	v_fma_f32 v102, v94, s31, -v102
	v_fma_f32 v103, v95, s31, -v103
	v_fmac_f32_e32 v100, 0x3377d1cf, v92
	v_fmac_f32_e32 v101, 0x3377d1cf, v93
	v_fmac_f32_e32 v102, 0x3377d1cf, v94
	v_fmac_f32_e32 v103, 0x3377d1cf, v95
	v_fmac_f32_e32 v100, 0x3f317217, v92
	v_fmac_f32_e32 v101, 0x3f317217, v93
	v_fmac_f32_e32 v102, 0x3f317217, v94
	v_fmac_f32_e32 v103, 0x3f317217, v95
	v_cmp_lt_f32_e64 vcc, |v92|, s34
	v_cndmask_b32_e32 v92, v92, v100, vcc
	v_cmp_lt_f32_e64 vcc, |v93|, s34
	v_cndmask_b32_e32 v93, v93, v101, vcc
	v_cmp_lt_f32_e64 vcc, |v94|, s34
	v_cndmask_b32_e32 v94, v94, v102, vcc
	v_cmp_lt_f32_e64 vcc, |v95|, s34
	v_cndmask_b32_e32 v95, v95, v103, vcc
	v_cndmask_b32_e64 v100, 0, v213, s[22:23]
	v_cndmask_b32_e64 v101, 0, v213, s[24:25]
	v_cndmask_b32_e64 v102, 0, v213, s[26:27]
	v_cndmask_b32_e64 v103, 0, v213, s[28:29]
	v_sub_f32_e32 v92, v92, v100
	v_sub_f32_e32 v93, v93, v101
	v_sub_f32_e32 v94, v94, v102
	v_sub_f32_e32 v95, v95, v103
	v_add_f32_e32 v64, v64, v92
	v_add_f32_e32 v65, v65, v93
	v_add_f32_e32 v66, v66, v94
	v_add_f32_e32 v67, v67, v95
	v_mul_f32_e32 v92, 0xbfb8aa3b, v64
	v_mul_f32_e32 v93, 0xbfb8aa3b, v65
	v_mul_f32_e32 v94, 0xbfb8aa3b, v66
	v_mul_f32_e32 v95, 0xbfb8aa3b, v67
	v_mul_f32_e32 v100, 0x3fb8aa3b, v64
	v_mul_f32_e32 v101, 0x3fb8aa3b, v65
	v_mul_f32_e32 v102, 0x3fb8aa3b, v66
	v_mul_f32_e32 v103, 0x3fb8aa3b, v67
	v_exp_f32_e32 v92, v92
	v_exp_f32_e32 v93, v93
	v_exp_f32_e32 v94, v94
	v_exp_f32_e32 v95, v95
	v_exp_f32_e32 v100, v100
	v_exp_f32_e32 v101, v101
	v_exp_f32_e32 v102, v102
	v_exp_f32_e32 v103, v103
	v_sub_f32_e32 v96, 1.0, v96
	v_sub_f32_e32 v97, 1.0, v97
	v_sub_f32_e32 v98, 1.0, v98
	v_sub_f32_e32 v99, 1.0, v99
	v_mul_f32_e32 v96, v96, v92
	v_mul_f32_e32 v97, v97, v93
	v_mul_f32_e32 v98, v98, v94
	v_mul_f32_e32 v99, v99, v95
	v_lshlrev_b32_e32 v92, 16, v50
	v_and_b32_e32 v93, 0xffff0000, v50
	v_lshlrev_b32_e32 v94, 16, v51
	v_and_b32_e32 v95, 0xffff0000, v51
	v_mul_f32_e32 v92, v92, v100
	v_mul_f32_e32 v93, v93, v101
	v_mul_f32_e32 v94, v94, v102
	v_mul_f32_e32 v95, v95, v103
	v_cvt_pk_bf16_f32 v108, v92, v93
	v_cvt_pk_bf16_f32 v109, v94, v95
	v_cvt_pk_bf16_f32 v110, v96, v97
	v_cvt_pk_bf16_f32 v111, v98, v99
	global_store_dwordx2 v112, v[108:109], s[2:3]
	global_store_dwordx2 v114, v[110:111], s[2:3]
	s_sub_u32 s2, s2, 0x400
	s_subb_u32 s3, s3, 0
	v_mov_b32_e32 v104, v96
	v_mov_b32_e32 v105, v97
	v_mov_b32_e32 v106, v98
	v_mov_b32_e32 v107, v99
	v_lshlrev_b32_e32 v92, 16, v52
	v_and_b32_e32 v93, 0xffff0000, v52
	v_lshlrev_b32_e32 v94, 16, v53
	v_and_b32_e32 v95, 0xffff0000, v53
	v_mul_f32_e32 v92, 0xbfb8aa3b, v92
	v_mul_f32_e32 v93, 0xbfb8aa3b, v93
	v_mul_f32_e32 v94, 0xbfb8aa3b, v94
	v_mul_f32_e32 v95, 0xbfb8aa3b, v95
	v_exp_f32_e32 v92, v92
	v_exp_f32_e32 v93, v93
	v_exp_f32_e32 v94, v94
	v_exp_f32_e32 v95, v95
	v_add_f32_e32 v92, 1.0, v92
	v_add_f32_e32 v93, 1.0, v93
	v_add_f32_e32 v94, 1.0, v94
	v_add_f32_e32 v95, 1.0, v95
	v_rcp_f32_e32 v92, v92
	v_rcp_f32_e32 v93, v93
	v_rcp_f32_e32 v94, v94
	v_rcp_f32_e32 v95, v95
	v_fma_f32 v96, v72, v92, v68
	v_fma_f32 v97, v73, v93, v69
	v_fma_f32 v98, v74, v94, v70
	v_fma_f32 v99, v75, v95, v71
	v_cmp_gt_f32_e64 s[22:23], s30, v96
	v_cmp_gt_f32_e64 s[24:25], s30, v97
	v_cmp_gt_f32_e64 s[26:27], s30, v98
	v_cmp_gt_f32_e64 s[28:29], s30, v99
	v_cndmask_b32_e64 v92, 0, 32, s[22:23]
	v_cndmask_b32_e64 v93, 0, 32, s[24:25]
	v_cndmask_b32_e64 v94, 0, 32, s[26:27]
	v_cndmask_b32_e64 v95, 0, 32, s[28:29]
	v_ldexp_f32 v92, v96, v92
	v_ldexp_f32 v93, v97, v93
	v_ldexp_f32 v94, v98, v94
	v_ldexp_f32 v95, v99, v95
	v_log_f32_e32 v92, v92
	v_log_f32_e32 v93, v93
	v_log_f32_e32 v94, v94
	v_log_f32_e32 v95, v95
	v_mul_f32_e32 v100, 0x3f317217, v92
	v_mul_f32_e32 v101, 0x3f317217, v93
	v_mul_f32_e32 v102, 0x3f317217, v94
	v_mul_f32_e32 v103, 0x3f317217, v95
	v_fma_f32 v100, v92, s31, -v100
	v_fma_f32 v101, v93, s31, -v101
	v_fma_f32 v102, v94, s31, -v102
	v_fma_f32 v103, v95, s31, -v103
	v_fmac_f32_e32 v100, 0x3377d1cf, v92
	v_fmac_f32_e32 v101, 0x3377d1cf, v93
	v_fmac_f32_e32 v102, 0x3377d1cf, v94
	v_fmac_f32_e32 v103, 0x3377d1cf, v95
	v_fmac_f32_e32 v100, 0x3f317217, v92
	v_fmac_f32_e32 v101, 0x3f317217, v93
	v_fmac_f32_e32 v102, 0x3f317217, v94
	v_fmac_f32_e32 v103, 0x3f317217, v95
	v_cmp_lt_f32_e64 vcc, |v92|, s34
	v_cndmask_b32_e32 v92, v92, v100, vcc
	v_cmp_lt_f32_e64 vcc, |v93|, s34
	v_cndmask_b32_e32 v93, v93, v101, vcc
	v_cmp_lt_f32_e64 vcc, |v94|, s34
	v_cndmask_b32_e32 v94, v94, v102, vcc
	v_cmp_lt_f32_e64 vcc, |v95|, s34
	v_cndmask_b32_e32 v95, v95, v103, vcc
	v_cndmask_b32_e64 v100, 0, v213, s[22:23]
	v_cndmask_b32_e64 v101, 0, v213, s[24:25]
	v_cndmask_b32_e64 v102, 0, v213, s[26:27]
	v_cndmask_b32_e64 v103, 0, v213, s[28:29]
	v_sub_f32_e32 v92, v92, v100
	v_sub_f32_e32 v93, v93, v101
	v_sub_f32_e32 v94, v94, v102
	v_sub_f32_e32 v95, v95, v103
	v_add_f32_e32 v64, v64, v92
	v_add_f32_e32 v65, v65, v93
	v_add_f32_e32 v66, v66, v94
	v_add_f32_e32 v67, v67, v95
	v_mul_f32_e32 v92, 0xbfb8aa3b, v64
	v_mul_f32_e32 v93, 0xbfb8aa3b, v65
	v_mul_f32_e32 v94, 0xbfb8aa3b, v66
	v_mul_f32_e32 v95, 0xbfb8aa3b, v67
	v_mul_f32_e32 v100, 0x3fb8aa3b, v64
	v_mul_f32_e32 v101, 0x3fb8aa3b, v65
	v_mul_f32_e32 v102, 0x3fb8aa3b, v66
	v_mul_f32_e32 v103, 0x3fb8aa3b, v67
	v_exp_f32_e32 v92, v92
	v_exp_f32_e32 v93, v93
	v_exp_f32_e32 v94, v94
	v_exp_f32_e32 v95, v95
	v_exp_f32_e32 v100, v100
	v_exp_f32_e32 v101, v101
	v_exp_f32_e32 v102, v102
	v_exp_f32_e32 v103, v103
	v_sub_f32_e32 v96, 1.0, v96
	v_sub_f32_e32 v97, 1.0, v97
	v_sub_f32_e32 v98, 1.0, v98
	v_sub_f32_e32 v99, 1.0, v99
	v_mul_f32_e32 v96, v96, v92
	v_mul_f32_e32 v97, v97, v93
; DEV u16 f2bf(float f) { return (u16)(pack2(f, f) & 0xffffu); }
; DEV float bf2f(u16 h) { return __uint_as_float(((unsigned)h) << 16); }
; DEV float sigmoid_f(float x) { return __builtin_amdgcn_rcpf(1.f + __expf(-x)); }
; DEV void phase_p15(const Params& p, int g) {
;     ...
;     for (int j8 = 0; j8 < 8; ++j8) {
;       const int st = j8 % 3;
;       if (j8 < 6) { P15_LOAD((j8 + 2) % 3, j8 + 2); }
; #pragma unroll
;       for (int cc = 0; cc < 2; ++cc) {
;         const int c = tid + 256 * cc;
;         unsigned kb[8];
; #pragma unroll
;         for (int e = 0; e < 8; ++e) {
;           const int jj = j8 * 8 + e;
;           const int j = dir ? 63 - jj : jj;
;           const size_t tok = (size_t)cidx * 64 + j;
;           const float f = lb[cc] + (1.f - lb[cc]) * sigmoid_f(bf2f(xr[st][cc][e]));
;           G[cc] += __logf(f);
;           const float eg = __expf(G[cc]), ig = __expf(-G[cc]);
;           Qp[tok * 512 + c] = f2bf(bf2f(qr[st][cc][e]) * eg);
;           const u16 kk = f2bf((1.f - f) * ig);
;           Kp[tok * 512 + c] = kk;
;           kb[e] = kk;
;         }
;         const int s0 = dir ? 56 - 8 * j8 : 8 * j8;
;         uint4 w;
;         w.x = dir ? (kb[7] | (kb[6] << 16)) : (kb[0] | (kb[1] << 16));
;         w.y = dir ? (kb[5] | (kb[4] << 16)) : (kb[2] | (kb[3] << 16));
;         w.z = dir ? (kb[3] | (kb[2] << 16)) : (kb[4] | (kb[5] << 16));
;         w.w = dir ? (kb[1] | (kb[0] << 16)) : (kb[6] | (kb[7] << 16));
;         *(uint4*)(KT + (((size_t)cidx * 2 + dir) * 512 + c) * 64 + s0) = w;
;       }
	v_mul_f32_e32 v98, v98, v94
	v_mul_f32_e32 v99, v99, v95
	v_lshlrev_b32_e32 v92, 16, v54
	v_and_b32_e32 v93, 0xffff0000, v54
	v_lshlrev_b32_e32 v94, 16, v55
	v_and_b32_e32 v95, 0xffff0000, v55
	v_mul_f32_e32 v92, v92, v100
	v_mul_f32_e32 v93, v93, v101
	v_mul_f32_e32 v94, v94, v102
	v_mul_f32_e32 v95, v95, v103
	v_cvt_pk_bf16_f32 v108, v92, v93
	v_cvt_pk_bf16_f32 v109, v94, v95
	v_cvt_pk_bf16_f32 v110, v96, v97
	v_cvt_pk_bf16_f32 v111, v98, v99
	global_store_dwordx2 v112, v[108:109], s[2:3]
	global_store_dwordx2 v114, v[110:111], s[2:3]
	s_sub_u32 s2, s2, 0x400
	s_subb_u32 s3, s3, 0
	v_cvt_pk_bf16_f32 v117, v96, v104
	v_cvt_pk_bf16_f32 v133, v97, v105
	v_cvt_pk_bf16_f32 v167, v98, v106
	v_cvt_pk_bf16_f32 v183, v99, v107
	v_lshlrev_b32_e32 v92, 16, v56
	v_and_b32_e32 v93, 0xffff0000, v56
	v_lshlrev_b32_e32 v94, 16, v57
	v_and_b32_e32 v95, 0xffff0000, v57
	v_mul_f32_e32 v92, 0xbfb8aa3b, v92
	v_mul_f32_e32 v93, 0xbfb8aa3b, v93
	v_mul_f32_e32 v94, 0xbfb8aa3b, v94
	v_mul_f32_e32 v95, 0xbfb8aa3b, v95
	v_exp_f32_e32 v92, v92
	v_exp_f32_e32 v93, v93
	v_exp_f32_e32 v94, v94
	v_exp_f32_e32 v95, v95
	v_add_f32_e32 v92, 1.0, v92
	v_add_f32_e32 v93, 1.0, v93
	v_add_f32_e32 v94, 1.0, v94
	v_add_f32_e32 v95, 1.0, v95
	v_rcp_f32_e32 v92, v92
	v_rcp_f32_e32 v93, v93
	v_rcp_f32_e32 v94, v94
	v_rcp_f32_e32 v95, v95
	v_fma_f32 v96, v72, v92, v68
	v_fma_f32 v97, v73, v93, v69
	v_fma_f32 v98, v74, v94, v70
	v_fma_f32 v99, v75, v95, v71
	v_cmp_gt_f32_e64 s[22:23], s30, v96
	v_cmp_gt_f32_e64 s[24:25], s30, v97
	v_cmp_gt_f32_e64 s[26:27], s30, v98
	v_cmp_gt_f32_e64 s[28:29], s30, v99
	v_cndmask_b32_e64 v92, 0, 32, s[22:23]
	v_cndmask_b32_e64 v93, 0, 32, s[24:25]
	v_cndmask_b32_e64 v94, 0, 32, s[26:27]
	v_cndmask_b32_e64 v95, 0, 32, s[28:29]
	v_ldexp_f32 v92, v96, v92
	v_ldexp_f32 v93, v97, v93
	v_ldexp_f32 v94, v98, v94
	v_ldexp_f32 v95, v99, v95
	v_log_f32_e32 v92, v92
	v_log_f32_e32 v93, v93
	v_log_f32_e32 v94, v94
	v_log_f32_e32 v95, v95
	v_mul_f32_e32 v100, 0x3f317217, v92
	v_mul_f32_e32 v101, 0x3f317217, v93
	v_mul_f32_e32 v102, 0x3f317217, v94
	v_mul_f32_e32 v103, 0x3f317217, v95
	v_fma_f32 v100, v92, s31, -v100
	v_fma_f32 v101, v93, s31, -v101
	v_fma_f32 v102, v94, s31, -v102
	v_fma_f32 v103, v95, s31, -v103
	v_fmac_f32_e32 v100, 0x3377d1cf, v92
	v_fmac_f32_e32 v101, 0x3377d1cf, v93
	v_fmac_f32_e32 v102, 0x3377d1cf, v94
	v_fmac_f32_e32 v103, 0x3377d1cf, v95
	v_fmac_f32_e32 v100, 0x3f317217, v92
	v_fmac_f32_e32 v101, 0x3f317217, v93
	v_fmac_f32_e32 v102, 0x3f317217, v94
	v_fmac_f32_e32 v103, 0x3f317217, v95
	v_cmp_lt_f32_e64 vcc, |v92|, s34
	v_cndmask_b32_e32 v92, v92, v100, vcc
	v_cmp_lt_f32_e64 vcc, |v93|, s34
	v_cndmask_b32_e32 v93, v93, v101, vcc
	v_cmp_lt_f32_e64 vcc, |v94|, s34
	v_cndmask_b32_e32 v94, v94, v102, vcc
	v_cmp_lt_f32_e64 vcc, |v95|, s34
	v_cndmask_b32_e32 v95, v95, v103, vcc
	v_cndmask_b32_e64 v100, 0, v213, s[22:23]
	v_cndmask_b32_e64 v101, 0, v213, s[24:25]
	v_cndmask_b32_e64 v102, 0, v213, s[26:27]
	v_cndmask_b32_e64 v103, 0, v213, s[28:29]
	v_sub_f32_e32 v92, v92, v100
	v_sub_f32_e32 v93, v93, v101
	v_sub_f32_e32 v94, v94, v102
	v_sub_f32_e32 v95, v95, v103
	v_add_f32_e32 v64, v64, v92
	v_add_f32_e32 v65, v65, v93
	v_add_f32_e32 v66, v66, v94
	v_add_f32_e32 v67, v67, v95
	v_mul_f32_e32 v92, 0xbfb8aa3b, v64
	v_mul_f32_e32 v93, 0xbfb8aa3b, v65
	v_mul_f32_e32 v94, 0xbfb8aa3b, v66
	v_mul_f32_e32 v95, 0xbfb8aa3b, v67
	v_mul_f32_e32 v100, 0x3fb8aa3b, v64
	v_mul_f32_e32 v101, 0x3fb8aa3b, v65
	v_mul_f32_e32 v102, 0x3fb8aa3b, v66
	v_mul_f32_e32 v103, 0x3fb8aa3b, v67
	v_exp_f32_e32 v92, v92
	v_exp_f32_e32 v93, v93
	v_exp_f32_e32 v94, v94
	v_exp_f32_e32 v95, v95
	v_exp_f32_e32 v100, v100
	v_exp_f32_e32 v101, v101
	v_exp_f32_e32 v102, v102
	v_exp_f32_e32 v103, v103
	v_sub_f32_e32 v96, 1.0, v96
	v_sub_f32_e32 v97, 1.0, v97
	v_sub_f32_e32 v98, 1.0, v98
	v_sub_f32_e32 v99, 1.0, v99
	v_mul_f32_e32 v96, v96, v92
	v_mul_f32_e32 v97, v97, v93
	v_mul_f32_e32 v98, v98, v94
	v_mul_f32_e32 v99, v99, v95
	v_lshlrev_b32_e32 v92, 16, v58
	v_and_b32_e32 v93, 0xffff0000, v58
	v_lshlrev_b32_e32 v94, 16, v59
	v_and_b32_e32 v95, 0xffff0000, v59
	v_mul_f32_e32 v92, v92, v100
	v_mul_f32_e32 v93, v93, v101
	v_mul_f32_e32 v94, v94, v102
	v_mul_f32_e32 v95, v95, v103
	v_cvt_pk_bf16_f32 v108, v92, v93
	v_cvt_pk_bf16_f32 v109, v94, v95
	v_cvt_pk_bf16_f32 v110, v96, v97
	v_cvt_pk_bf16_f32 v111, v98, v99
	global_store_dwordx2 v112, v[108:109], s[2:3]
	global_store_dwordx2 v114, v[110:111], s[2:3]
	s_sub_u32 s2, s2, 0x400
	s_subb_u32 s3, s3, 0
	v_mov_b32_e32 v104, v96
	v_mov_b32_e32 v105, v97
	v_mov_b32_e32 v106, v98
	v_mov_b32_e32 v107, v99
	v_lshlrev_b32_e32 v92, 16, v60
	v_and_b32_e32 v93, 0xffff0000, v60
	v_lshlrev_b32_e32 v94, 16, v61
	v_and_b32_e32 v95, 0xffff0000, v61
	v_mul_f32_e32 v92, 0xbfb8aa3b, v92
	v_mul_f32_e32 v93, 0xbfb8aa3b, v93
	v_mul_f32_e32 v94, 0xbfb8aa3b, v94
	v_mul_f32_e32 v95, 0xbfb8aa3b, v95
	v_exp_f32_e32 v92, v92
	v_exp_f32_e32 v93, v93
	v_exp_f32_e32 v94, v94
	v_exp_f32_e32 v95, v95
	v_add_f32_e32 v92, 1.0, v92
	v_add_f32_e32 v93, 1.0, v93
	v_add_f32_e32 v94, 1.0, v94
	v_add_f32_e32 v95, 1.0, v95
	v_rcp_f32_e32 v92, v92
	v_rcp_f32_e32 v93, v93
	v_rcp_f32_e32 v94, v94
	v_rcp_f32_e32 v95, v95
	v_fma_f32 v96, v72, v92, v68
	v_fma_f32 v97, v73, v93, v69
	v_fma_f32 v98, v74, v94, v70
	v_fma_f32 v99, v75, v95, v71
; DEV u16 f2bf(float f) { return (u16)(pack2(f, f) & 0xffffu); }
; DEV float bf2f(u16 h) { return __uint_as_float(((unsigned)h) << 16); }
; DEV float sigmoid_f(float x) { return __builtin_amdgcn_rcpf(1.f + __expf(-x)); }
; DEV void phase_p15(const Params& p, int g) {
;     ...
;     P15_LOAD(0, 0);
;     P15_LOAD(1, 1);
; #pragma unroll
;     for (int j8 = 0; j8 < 8; ++j8) {
;       const int st = j8 % 3;
;       if (j8 < 6) { P15_LOAD((j8 + 2) % 3, j8 + 2); }
; #pragma unroll
;       for (int cc = 0; cc < 2; ++cc) {
;         const int c = tid + 256 * cc;
;         unsigned kb[8];
; #pragma unroll
;         for (int e = 0; e < 8; ++e) {
;           const int jj = j8 * 8 + e;
;           const int j = dir ? 63 - jj : jj;
;           const size_t tok = (size_t)cidx * 64 + j;
;           const float f = lb[cc] + (1.f - lb[cc]) * sigmoid_f(bf2f(xr[st][cc][e]));
;           G[cc] += __logf(f);
;           const float eg = __expf(G[cc]), ig = __expf(-G[cc]);
;           Qp[tok * 512 + c] = f2bf(bf2f(qr[st][cc][e]) * eg);
;           const u16 kk = f2bf((1.f - f) * ig);
;           Kp[tok * 512 + c] = kk;
;           kb[e] = kk;
;         }
;         const int s0 = dir ? 56 - 8 * j8 : 8 * j8;
;         uint4 w;
;         w.x = dir ? (kb[7] | (kb[6] << 16)) : (kb[0] | (kb[1] << 16));
;         w.y = dir ? (kb[5] | (kb[4] << 16)) : (kb[2] | (kb[3] << 16));
;         w.z = dir ? (kb[3] | (kb[2] << 16)) : (kb[4] | (kb[5] << 16));
;         w.w = dir ? (kb[1] | (kb[0] << 16)) : (kb[6] | (kb[7] << 16));
;         *(uint4*)(KT + (((size_t)cidx * 2 + dir) * 512 + c) * 64 + s0) = w;
;       }
	v_cmp_gt_f32_e64 s[22:23], s30, v96
	v_cmp_gt_f32_e64 s[24:25], s30, v97
	v_cmp_gt_f32_e64 s[26:27], s30, v98
	v_cmp_gt_f32_e64 s[28:29], s30, v99
	v_cndmask_b32_e64 v92, 0, 32, s[22:23]
	v_cndmask_b32_e64 v93, 0, 32, s[24:25]
	v_cndmask_b32_e64 v94, 0, 32, s[26:27]
	v_cndmask_b32_e64 v95, 0, 32, s[28:29]
	v_ldexp_f32 v92, v96, v92
	v_ldexp_f32 v93, v97, v93
	v_ldexp_f32 v94, v98, v94
	v_ldexp_f32 v95, v99, v95
	v_log_f32_e32 v92, v92
	v_log_f32_e32 v93, v93
	v_log_f32_e32 v94, v94
	v_log_f32_e32 v95, v95
	v_mul_f32_e32 v100, 0x3f317217, v92
	v_mul_f32_e32 v101, 0x3f317217, v93
	v_mul_f32_e32 v102, 0x3f317217, v94
	v_mul_f32_e32 v103, 0x3f317217, v95
	v_fma_f32 v100, v92, s31, -v100
	v_fma_f32 v101, v93, s31, -v101
	v_fma_f32 v102, v94, s31, -v102
	v_fma_f32 v103, v95, s31, -v103
	v_fmac_f32_e32 v100, 0x3377d1cf, v92
	v_fmac_f32_e32 v101, 0x3377d1cf, v93
	v_fmac_f32_e32 v102, 0x3377d1cf, v94
	v_fmac_f32_e32 v103, 0x3377d1cf, v95
	v_fmac_f32_e32 v100, 0x3f317217, v92
	v_fmac_f32_e32 v101, 0x3f317217, v93
	v_fmac_f32_e32 v102, 0x3f317217, v94
	v_fmac_f32_e32 v103, 0x3f317217, v95
	v_cmp_lt_f32_e64 vcc, |v92|, s34
	v_cndmask_b32_e32 v92, v92, v100, vcc
	v_cmp_lt_f32_e64 vcc, |v93|, s34
	v_cndmask_b32_e32 v93, v93, v101, vcc
	v_cmp_lt_f32_e64 vcc, |v94|, s34
	v_cndmask_b32_e32 v94, v94, v102, vcc
	v_cmp_lt_f32_e64 vcc, |v95|, s34
	v_cndmask_b32_e32 v95, v95, v103, vcc
	v_cndmask_b32_e64 v100, 0, v213, s[22:23]
	v_cndmask_b32_e64 v101, 0, v213, s[24:25]
	v_cndmask_b32_e64 v102, 0, v213, s[26:27]
	v_cndmask_b32_e64 v103, 0, v213, s[28:29]
	v_sub_f32_e32 v92, v92, v100
	v_sub_f32_e32 v93, v93, v101
	v_sub_f32_e32 v94, v94, v102
	v_sub_f32_e32 v95, v95, v103
	v_add_f32_e32 v64, v64, v92
	v_add_f32_e32 v65, v65, v93
	v_add_f32_e32 v66, v66, v94
	v_add_f32_e32 v67, v67, v95
	v_mul_f32_e32 v92, 0xbfb8aa3b, v64
	v_mul_f32_e32 v93, 0xbfb8aa3b, v65
	v_mul_f32_e32 v94, 0xbfb8aa3b, v66
	v_mul_f32_e32 v95, 0xbfb8aa3b, v67
	v_mul_f32_e32 v100, 0x3fb8aa3b, v64
	v_mul_f32_e32 v101, 0x3fb8aa3b, v65
	v_mul_f32_e32 v102, 0x3fb8aa3b, v66
	v_mul_f32_e32 v103, 0x3fb8aa3b, v67
	v_exp_f32_e32 v92, v92
	v_exp_f32_e32 v93, v93
	v_exp_f32_e32 v94, v94
	v_exp_f32_e32 v95, v95
	v_exp_f32_e32 v100, v100
	v_exp_f32_e32 v101, v101
	v_exp_f32_e32 v102, v102
	v_exp_f32_e32 v103, v103
	v_sub_f32_e32 v96, 1.0, v96
	v_sub_f32_e32 v97, 1.0, v97
	v_sub_f32_e32 v98, 1.0, v98
	v_sub_f32_e32 v99, 1.0, v99
	v_mul_f32_e32 v96, v96, v92
	v_mul_f32_e32 v97, v97, v93
	v_mul_f32_e32 v98, v98, v94
	v_mul_f32_e32 v99, v99, v95
	v_lshlrev_b32_e32 v92, 16, v62
	v_and_b32_e32 v93, 0xffff0000, v62
	v_lshlrev_b32_e32 v94, 16, v63
	v_and_b32_e32 v95, 0xffff0000, v63
	v_mul_f32_e32 v92, v92, v100
	v_mul_f32_e32 v93, v93, v101
	v_mul_f32_e32 v94, v94, v102
	v_mul_f32_e32 v95, v95, v103
	v_cvt_pk_bf16_f32 v108, v92, v93
	v_cvt_pk_bf16_f32 v109, v94, v95
	v_cvt_pk_bf16_f32 v110, v96, v97
	v_cvt_pk_bf16_f32 v111, v98, v99
	global_store_dwordx2 v112, v[108:109], s[2:3]
	global_store_dwordx2 v114, v[110:111], s[2:3]
	s_sub_u32 s2, s2, 0x400
	s_subb_u32 s3, s3, 0
	v_cvt_pk_bf16_f32 v116, v96, v104
	v_cvt_pk_bf16_f32 v132, v97, v105
	v_cvt_pk_bf16_f32 v166, v98, v106
	v_cvt_pk_bf16_f32 v182, v99, v107
	global_store_dwordx4 v115, v[116:119], s[4:5]
	global_store_dwordx4 v115, v[120:123], s[4:5] offset:16
	global_store_dwordx4 v115, v[124:127], s[4:5] offset:32
	global_store_dwordx4 v115, v[128:131], s[4:5] offset:48
	global_store_dwordx4 v115, v[132:135], s[4:5] offset:128
	global_store_dwordx4 v115, v[136:139], s[4:5] offset:144
	global_store_dwordx4 v115, v[140:143], s[4:5] offset:160
	global_store_dwordx4 v115, v[144:147], s[4:5] offset:176
	global_store_dwordx4 v115, v[166:169], s[4:5] offset:256
	global_store_dwordx4 v115, v[170:173], s[4:5] offset:272
	global_store_dwordx4 v115, v[174:177], s[4:5] offset:288
	global_store_dwordx4 v115, v[178:181], s[4:5] offset:304
	global_store_dwordx4 v115, v[182:185], s[4:5] offset:384
	global_store_dwordx4 v115, v[186:189], s[4:5] offset:400
	global_store_dwordx4 v115, v[190:193], s[4:5] offset:416
	global_store_dwordx4 v115, v[194:197], s[4:5] offset:432
	s_sub_u32 s4, s4, 64
	s_subb_u32 s5, s5, 0
	global_load_dwordx2 v[32:33], v113, s[0:1]
	global_load_dwordx2 v[34:35], v112, s[0:1]
	s_sub_u32 s0, s0, 0x1400
	s_subb_u32 s1, s1, 0
	global_load_dwordx2 v[36:37], v113, s[0:1]
	global_load_dwordx2 v[38:39], v112, s[0:1]
	s_sub_u32 s0, s0, 0x1400
	s_subb_u32 s1, s1, 0
	global_load_dwordx2 v[40:41], v113, s[0:1]
	global_load_dwordx2 v[42:43], v112, s[0:1]
	s_sub_u32 s0, s0, 0x1400
	s_subb_u32 s1, s1, 0
	global_load_dwordx2 v[44:45], v113, s[0:1]
	global_load_dwordx2 v[46:47], v112, s[0:1]
	s_sub_u32 s0, s0, 0x1400
	s_subb_u32 s1, s1, 0
	global_load_dwordx2 v[48:49], v113, s[0:1]
	global_load_dwordx2 v[50:51], v112, s[0:1]
	s_sub_u32 s0, s0, 0x1400
	s_subb_u32 s1, s1, 0
	global_load_dwordx2 v[52:53], v113, s[0:1]
	global_load_dwordx2 v[54:55], v112, s[0:1]
	s_sub_u32 s0, s0, 0x1400
	s_subb_u32 s1, s1, 0
	global_load_dwordx2 v[56:57], v113, s[0:1]
	global_load_dwordx2 v[58:59], v112, s[0:1]
	s_sub_u32 s0, s0, 0x1400
	s_subb_u32 s1, s1, 0
	global_load_dwordx2 v[60:61], v113, s[0:1]
	global_load_dwordx2 v[62:63], v112, s[0:1]
	s_sub_u32 s0, s0, 0x1400
	s_subb_u32 s1, s1, 0
	s_add_u32 s35, s35, 1
	s_cmp_lt_u32 s35, 2
	s_cbranch_scc1 .Lp15_d1_loop
